# removed the duplicate s_waitcnt lgkmcnt(0) after s_setprio 1 in all GEMM compute intervals (36 sites)
# speedup vs baseline: 1.0152x; 1.0152x over previous
; #define PG8_STAGE(bufoff, gbase) do { _Pragma("unroll") for (int _i = 0; _i < 2; ++_i) \
;         __builtin_amdgcn_global_load_lds((const unsigned*)((const char*)(gbase) + voff[_i]), (LAS unsigned*)(lds + (bufoff) + ldsw + _i * 8192), 16, 0, 0); } while (0)
; #define PG8_LDA(dst, b, h) do { _Pragma("unroll") for (int m = 0; m < 4; ++m) _Pragma("unroll") for (int k = 0; k < 2; ++k) dst[m][k] = *(const LAS bf16x8*)(lds + PG8_SA(b, h) + aoff + m * 2048 + k * 1024); } while (0)
; #define PG8_LDB(dst, b, h) do { _Pragma("unroll") for (int n = 0; n < 2; ++n) _Pragma("unroll") for (int k = 0; k < 2; ++k) dst[n][k] = *(const LAS bf16x8*)(lds + PG8_SB(b, h) + boff + n * 2048 + k * 1024); } while (0)
; #define PG8_MMA(ai, bj, At, Bt) do { __builtin_amdgcn_s_setprio(1); _Pragma("unroll") for (int m = 0; m < 4; ++m) _Pragma("unroll") for (int n = 0; n < 2; ++n) _Pragma("unroll") for (int k = 0; k < 2; ++k) \
;         acc[ai][bj][m][n] = __builtin_amdgcn_mfma_f32_16x16x32_bf16(Bt[n][k], At[m][k], acc[ai][bj][m][n], 0, 0, 0); __builtin_amdgcn_s_setprio(0); } while (0)
; #define PG8_WAIT_L(n) asm volatile("s_waitcnt lgkmcnt(" #n ")" ::: "memory")
; #define PG8_BAR __builtin_amdgcn_s_barrier()
; #define PG8_SCHED __builtin_amdgcn_sched_barrier(0)
; template <class Epi>
; DI void gemm_phase(LAS unsigned char* lds, const Gemm g, const StaticOrder& S, const Epi& E) {
;     ...
;         for (int t = 0; t < nt; t += 2) {
;             const bool last = (t == nt - 2);
;             const char* a1 = cA + (size_t)(t + 1) * kstep;
;             const char* a2 = last ? nA : cA + (size_t)(t + 2) * kstep; const char* b2 = last ? nB : cB + (size_t)(t + 2) * kstep;
;             const char* a3 = a2 + kstep; const char* b3 = b2 + kstep;
;             PG8_LDB(B0, 0, 0); PG8_SCHED; PG8_LDA(At, 0, 0); PG8_STAGE(PG8_SA(1, 1), a1 + hstep);
;             PG8_WAIT_L(8); PG8_BAR; PG8_WAIT_L(0); PG8_MMA(0, 0, At, B0); PG8_BAR; PG8_SCHED;
;             PG8_LDB(B1, 0, 1); PG8_STAGE(PG8_SB(0, 0), b2);
;             PG8_BAR; PG8_WAIT_L(0); PG8_MMA(0, 1, At, B1); PG8_BAR;
;             PG8_LDA(At, 0, 1); PG8_STAGE(PG8_SA(0, 0), a2);
;             PG8_BAR; PG8_WAIT_L(0); PG8_MMA(1, 0, At, B0); PG8_BAR; PG8_SCHED;
.LBB0_37:
	s_add_u32 s20, s18, 0xfff80080
	s_addc_u32 s21, s19, -1
	s_add_i32 s39, 0, 0x10000
	v_add_u32_e32 v150, s39, v135
	ds_read_b128 v[138:141], v150
	ds_read_b128 v[142:145], v150 offset:1024
	ds_read_b128 v[146:149], v150 offset:2048
	ds_read_b128 v[150:153], v150 offset:3072
	s_cmp_eq_u32 s38, 28
	s_cselect_b32 s23, s4, s21
	s_cselect_b32 s22, s5, s20
	s_cselect_b32 s21, s9, s37
	s_cselect_b32 s20, s11, s33
	v_lshl_add_u64 v[154:155], s[18:19], 0, v[130:131]
	s_add_i32 m0, s28, 0xc000
	ds_read_b128 v[186:189], v137
	ds_read_b128 v[190:193], v137 offset:1024
	ds_read_b128 v[194:197], v137 offset:2048
	ds_read_b128 v[198:201], v137 offset:3072
	ds_read_b128 v[202:205], v137 offset:4096
	ds_read_b128 v[206:209], v137 offset:5120
	ds_read_b128 v[210:213], v137 offset:6144
	ds_read_b128 v[214:217], v137 offset:7168
	global_load_lds_dwordx4 v[154:155], off
	v_lshl_add_u64 v[154:155], s[18:19], 0, v[132:133]
	s_add_i32 m0, s28, 0xe000
	s_nop 0
	global_load_lds_dwordx4 v[154:155], off
	s_waitcnt lgkmcnt(8)
	s_barrier
	s_waitcnt lgkmcnt(0)
	s_setprio 1
	v_mfma_f32_16x16x32_bf16 v[124:127], v[138:141], v[186:189], v[124:127]
	v_mfma_f32_16x16x32_bf16 v[120:123], v[146:149], v[186:189], v[120:123]
	v_mfma_f32_16x16x32_bf16 v[108:111], v[138:141], v[194:197], v[108:111]
	v_mfma_f32_16x16x32_bf16 v[104:107], v[146:149], v[194:197], v[104:107]
	v_mfma_f32_16x16x32_bf16 v[92:95], v[138:141], v[202:205], v[92:95]
	v_mfma_f32_16x16x32_bf16 v[88:91], v[146:149], v[202:205], v[88:91]
	v_mfma_f32_16x16x32_bf16 v[76:79], v[138:141], v[210:213], v[76:79]
	v_mfma_f32_16x16x32_bf16 v[72:75], v[146:149], v[210:213], v[72:75]
	v_mfma_f32_16x16x32_bf16 v[124:127], v[142:145], v[190:193], v[124:127]
	v_mfma_f32_16x16x32_bf16 v[120:123], v[150:153], v[190:193], v[120:123]
	v_mfma_f32_16x16x32_bf16 v[108:111], v[142:145], v[198:201], v[108:111]
	v_mfma_f32_16x16x32_bf16 v[104:107], v[150:153], v[198:201], v[104:107]
	v_mfma_f32_16x16x32_bf16 v[92:95], v[142:145], v[206:209], v[92:95]
	v_mfma_f32_16x16x32_bf16 v[88:91], v[150:153], v[206:209], v[88:91]
	v_mfma_f32_16x16x32_bf16 v[76:79], v[142:145], v[214:217], v[76:79]
	v_mfma_f32_16x16x32_bf16 v[72:75], v[150:153], v[214:217], v[72:75]
	s_setprio 0
	s_barrier
	s_add_i32 s42, 0, 0x14000
	v_add_u32_e32 v154, s42, v135
	s_add_i32 s39, s39, s27
	ds_read_b128 v[226:229], v154
	ds_read_b128 v[230:233], v154 offset:1024
	ds_read_b128 v[234:237], v154 offset:2048
	ds_read_b128 v[238:241], v154 offset:3072
	v_lshl_add_u64 v[154:155], s[20:21], 0, v[158:159]
	s_mov_b32 m0, s39
	v_lshl_add_u64 v[218:219], s[20:21], 0, v[128:129]
	global_load_lds_dwordx4 v[154:155], off
	s_add_i32 m0, s39, 0x2000
	s_nop 0
	global_load_lds_dwordx4 v[218:219], off
	s_barrier
	s_waitcnt lgkmcnt(0)
	s_setprio 1
	v_mfma_f32_16x16x32_bf16 v[116:119], v[226:229], v[186:189], v[116:119]
	v_mfma_f32_16x16x32_bf16 v[112:115], v[234:237], v[186:189], v[112:115]
	v_mfma_f32_16x16x32_bf16 v[100:103], v[226:229], v[194:197], v[100:103]
	v_mfma_f32_16x16x32_bf16 v[96:99], v[234:237], v[194:197], v[96:99]
	v_mfma_f32_16x16x32_bf16 v[84:87], v[226:229], v[202:205], v[84:87]
	v_mfma_f32_16x16x32_bf16 v[80:83], v[234:237], v[202:205], v[80:83]
	v_mfma_f32_16x16x32_bf16 v[68:71], v[226:229], v[210:213], v[68:71]
	v_mfma_f32_16x16x32_bf16 v[64:67], v[234:237], v[210:213], v[64:67]
	v_mfma_f32_16x16x32_bf16 v[116:119], v[230:233], v[190:193], v[116:119]
	v_mfma_f32_16x16x32_bf16 v[112:115], v[238:241], v[190:193], v[112:115]
	v_mfma_f32_16x16x32_bf16 v[100:103], v[230:233], v[198:201], v[100:103]
	v_mfma_f32_16x16x32_bf16 v[96:99], v[238:241], v[198:201], v[96:99]
	v_mfma_f32_16x16x32_bf16 v[84:87], v[230:233], v[206:209], v[84:87]
	v_mfma_f32_16x16x32_bf16 v[80:83], v[238:241], v[206:209], v[80:83]
	v_mfma_f32_16x16x32_bf16 v[68:71], v[230:233], v[214:217], v[68:71]
	v_mfma_f32_16x16x32_bf16 v[64:67], v[238:241], v[214:217], v[64:67]
	s_setprio 0
	s_mov_b32 m0, s28
	v_lshl_add_u64 v[220:221], s[22:23], 0, v[158:159]
	s_barrier
	ds_read_b128 v[186:189], v137 offset:16384
	ds_read_b128 v[190:193], v137 offset:17408
	ds_read_b128 v[194:197], v137 offset:18432
	ds_read_b128 v[198:201], v137 offset:19456
	ds_read_b128 v[202:205], v137 offset:20480
	ds_read_b128 v[206:209], v137 offset:21504
	ds_read_b128 v[210:213], v137 offset:22528
	ds_read_b128 v[214:217], v137 offset:23552
	global_load_lds_dwordx4 v[220:221], off
	v_lshl_add_u64 v[242:243], s[22:23], 0, v[128:129]
	s_mov_b32 m0, s29
	s_nop 0
	global_load_lds_dwordx4 v[242:243], off
	s_barrier
	s_waitcnt lgkmcnt(0)
	s_setprio 1
	v_mfma_f32_16x16x32_bf16 v[60:63], v[138:141], v[186:189], v[60:63]
	v_mfma_f32_16x16x32_bf16 v[56:59], v[146:149], v[186:189], v[56:59]
	v_mfma_f32_16x16x32_bf16 v[44:47], v[138:141], v[194:197], v[44:47]
	v_mfma_f32_16x16x32_bf16 v[40:43], v[146:149], v[194:197], v[40:43]
	v_mfma_f32_16x16x32_bf16 v[28:31], v[138:141], v[202:205], v[28:31]
	v_mfma_f32_16x16x32_bf16 v[24:27], v[146:149], v[202:205], v[24:27]
	v_mfma_f32_16x16x32_bf16 v[12:15], v[138:141], v[210:213], v[12:15]
	v_mfma_f32_16x16x32_bf16 v[8:11], v[146:149], v[210:213], v[8:11]
	v_mfma_f32_16x16x32_bf16 v[60:63], v[142:145], v[190:193], v[60:63]
	v_mfma_f32_16x16x32_bf16 v[56:59], v[150:153], v[190:193], v[56:59]
	v_mfma_f32_16x16x32_bf16 v[44:47], v[142:145], v[198:201], v[44:47]
	v_mfma_f32_16x16x32_bf16 v[40:43], v[150:153], v[198:201], v[40:43]
	v_mfma_f32_16x16x32_bf16 v[28:31], v[142:145], v[206:209], v[28:31]
	v_mfma_f32_16x16x32_bf16 v[24:27], v[150:153], v[206:209], v[24:27]
	v_mfma_f32_16x16x32_bf16 v[12:15], v[142:145], v[214:217], v[12:15]
	v_mfma_f32_16x16x32_bf16 v[8:11], v[150:153], v[214:217], v[8:11]
	s_setprio 0
	s_barrier
; #define PG8_STAGE(bufoff, gbase) do { _Pragma("unroll") for (int _i = 0; _i < 2; ++_i) \
;         __builtin_amdgcn_global_load_lds((const unsigned*)((const char*)(gbase) + voff[_i]), (LAS unsigned*)(lds + (bufoff) + ldsw + _i * 8192), 16, 0, 0); } while (0)
; #define PG8_LDA(dst, b, h) do { _Pragma("unroll") for (int m = 0; m < 4; ++m) _Pragma("unroll") for (int k = 0; k < 2; ++k) dst[m][k] = *(const LAS bf16x8*)(lds + PG8_SA(b, h) + aoff + m * 2048 + k * 1024); } while (0)
; #define PG8_LDB(dst, b, h) do { _Pragma("unroll") for (int n = 0; n < 2; ++n) _Pragma("unroll") for (int k = 0; k < 2; ++k) dst[n][k] = *(const LAS bf16x8*)(lds + PG8_SB(b, h) + boff + n * 2048 + k * 1024); } while (0)
; #define PG8_MMA(ai, bj, At, Bt) do { __builtin_amdgcn_s_setprio(1); _Pragma("unroll") for (int m = 0; m < 4; ++m) _Pragma("unroll") for (int n = 0; n < 2; ++n) _Pragma("unroll") for (int k = 0; k < 2; ++k) \
;         acc[ai][bj][m][n] = __builtin_amdgcn_mfma_f32_16x16x32_bf16(Bt[n][k], At[m][k], acc[ai][bj][m][n], 0, 0, 0); __builtin_amdgcn_s_setprio(0); } while (0)
; #define PG8_WAIT_V(n) asm volatile("s_waitcnt vmcnt(" #n ")" ::: "memory")
; #define PG8_WAIT_L(n) asm volatile("s_waitcnt lgkmcnt(" #n ")" ::: "memory")
; #define PG8_BAR __builtin_amdgcn_s_barrier()
; #define PG8_SCHED __builtin_amdgcn_sched_barrier(0)
; template <class Epi>
; DI void gemm_phase(LAS unsigned char* lds, const Gemm g, const StaticOrder& S, const Epi& E) {
;     ...
;             PG8_STAGE(PG8_SB(0, 1), b2 + hstep);
;             PG8_WAIT_V(6); PG8_BAR; PG8_MMA(1, 1, At, B1); PG8_BAR;
;             PG8_LDB(B0, 1, 0); PG8_SCHED; PG8_LDA(At, 1, 0); PG8_STAGE(PG8_SA(0, 1), a2 + hstep);
;             PG8_WAIT_L(8); PG8_BAR; PG8_WAIT_L(0); PG8_MMA(0, 0, At, B0); PG8_BAR; PG8_SCHED;
;             PG8_LDB(B1, 1, 1); PG8_STAGE(PG8_SB(1, 0), b3);
;             PG8_BAR; PG8_WAIT_L(0); PG8_MMA(0, 1, At, B1); PG8_BAR;
;             PG8_LDA(At, 1, 1); PG8_STAGE(PG8_SA(1, 0), a3);
;             PG8_BAR; PG8_WAIT_L(0); PG8_MMA(1, 0, At, B0); PG8_BAR; PG8_SCHED;
	s_add_u32 s40, s20, 0x80000
	s_addc_u32 s41, s21, 0
	s_add_i32 s39, s42, s27
	v_lshl_add_u64 v[138:139], s[40:41], 0, v[158:159]
	s_mov_b32 m0, s39
	s_nop 0
	global_load_lds_dwordx4 v[138:139], off
	v_lshl_add_u64 v[138:139], s[40:41], 0, v[128:129]
	s_add_i32 m0, s39, 0x2000
	s_nop 0
	global_load_lds_dwordx4 v[138:139], off
	s_waitcnt vmcnt(6)
	s_barrier
	s_setprio 1
	v_mfma_f32_16x16x32_bf16 v[52:55], v[226:229], v[186:189], v[52:55]
	v_mfma_f32_16x16x32_bf16 v[48:51], v[234:237], v[186:189], v[48:51]
	v_mfma_f32_16x16x32_bf16 v[36:39], v[226:229], v[194:197], v[36:39]
	v_mfma_f32_16x16x32_bf16 v[32:35], v[234:237], v[194:197], v[32:35]
	v_mfma_f32_16x16x32_bf16 v[20:23], v[226:229], v[202:205], v[20:23]
	v_mfma_f32_16x16x32_bf16 v[16:19], v[234:237], v[202:205], v[16:19]
	v_mfma_f32_16x16x32_bf16 v[4:7], v[226:229], v[210:213], v[4:7]
	v_mfma_f32_16x16x32_bf16 v[0:3], v[234:237], v[210:213], v[0:3]
	v_mfma_f32_16x16x32_bf16 v[52:55], v[230:233], v[190:193], v[52:55]
	v_mfma_f32_16x16x32_bf16 v[48:51], v[238:241], v[190:193], v[48:51]
	v_mfma_f32_16x16x32_bf16 v[36:39], v[230:233], v[198:201], v[36:39]
	v_mfma_f32_16x16x32_bf16 v[32:35], v[238:241], v[198:201], v[32:35]
	v_mfma_f32_16x16x32_bf16 v[20:23], v[230:233], v[206:209], v[20:23]
	v_mfma_f32_16x16x32_bf16 v[16:19], v[238:241], v[206:209], v[16:19]
	v_mfma_f32_16x16x32_bf16 v[4:7], v[230:233], v[214:217], v[4:7]
	v_mfma_f32_16x16x32_bf16 v[0:3], v[238:241], v[214:217], v[0:3]
	s_setprio 0
	s_add_i32 s39, 0, 0x18000
	v_add_u32_e32 v150, s39, v135
	s_barrier
	ds_read_b128 v[138:141], v150
	ds_read_b128 v[142:145], v150 offset:1024
	ds_read_b128 v[146:149], v150 offset:2048
	ds_read_b128 v[150:153], v150 offset:3072
	s_add_u32 s22, s22, 0x80000
	s_addc_u32 s23, s23, 0
	s_mov_b32 m0, s30
	v_lshl_add_u64 v[226:227], s[22:23], 0, v[158:159]
	ds_read_b128 v[186:189], v137 offset:32768
	ds_read_b128 v[190:193], v137 offset:33792
	ds_read_b128 v[194:197], v137 offset:34816
	ds_read_b128 v[198:201], v137 offset:35840
	ds_read_b128 v[202:205], v137 offset:36864
	ds_read_b128 v[206:209], v137 offset:37888
	ds_read_b128 v[210:213], v137 offset:38912
	ds_read_b128 v[214:217], v137 offset:39936
	global_load_lds_dwordx4 v[226:227], off
	v_lshl_add_u64 v[226:227], s[22:23], 0, v[128:129]
	s_mov_b32 m0, s31
	s_nop 0
	global_load_lds_dwordx4 v[226:227], off
	s_waitcnt lgkmcnt(8)
	s_barrier
	s_waitcnt lgkmcnt(0)
	s_setprio 1
	v_mfma_f32_16x16x32_bf16 v[124:127], v[138:141], v[186:189], v[124:127]
	v_mfma_f32_16x16x32_bf16 v[120:123], v[146:149], v[186:189], v[120:123]
	v_mfma_f32_16x16x32_bf16 v[108:111], v[138:141], v[194:197], v[108:111]
	v_mfma_f32_16x16x32_bf16 v[104:107], v[146:149], v[194:197], v[104:107]
	v_mfma_f32_16x16x32_bf16 v[92:95], v[138:141], v[202:205], v[92:95]
	v_mfma_f32_16x16x32_bf16 v[88:91], v[146:149], v[202:205], v[88:91]
	v_mfma_f32_16x16x32_bf16 v[76:79], v[138:141], v[210:213], v[76:79]
	v_mfma_f32_16x16x32_bf16 v[72:75], v[146:149], v[210:213], v[72:75]
	v_mfma_f32_16x16x32_bf16 v[124:127], v[142:145], v[190:193], v[124:127]
	v_mfma_f32_16x16x32_bf16 v[120:123], v[150:153], v[190:193], v[120:123]
	v_mfma_f32_16x16x32_bf16 v[108:111], v[142:145], v[198:201], v[108:111]
	v_mfma_f32_16x16x32_bf16 v[104:107], v[150:153], v[198:201], v[104:107]
	v_mfma_f32_16x16x32_bf16 v[92:95], v[142:145], v[206:209], v[92:95]
	v_mfma_f32_16x16x32_bf16 v[88:91], v[150:153], v[206:209], v[88:91]
	v_mfma_f32_16x16x32_bf16 v[76:79], v[142:145], v[214:217], v[76:79]
	v_mfma_f32_16x16x32_bf16 v[72:75], v[150:153], v[214:217], v[72:75]
	s_setprio 0
	s_barrier
	s_add_i32 s22, 0, 0x1c000
	s_add_i32 s23, s39, s27
	v_add_u32_e32 v225, s22, v135
	v_lshl_add_u64 v[154:155], v[154:155], 0, s[94:95]
	s_mov_b32 m0, s23
	ds_read_b128 v[226:229], v225
	ds_read_b128 v[230:233], v225 offset:1024
	ds_read_b128 v[234:237], v225 offset:2048
	ds_read_b128 v[238:241], v225 offset:3072
	global_load_lds_dwordx4 v[154:155], off
	v_lshl_add_u64 v[154:155], v[218:219], 0, s[94:95]
	s_add_i32 m0, s23, 0x2000
	s_nop 0
	global_load_lds_dwordx4 v[154:155], off
	s_barrier
	s_waitcnt lgkmcnt(0)
	s_setprio 1
	v_mfma_f32_16x16x32_bf16 v[116:119], v[226:229], v[186:189], v[116:119]
	v_mfma_f32_16x16x32_bf16 v[112:115], v[234:237], v[186:189], v[112:115]
	v_mfma_f32_16x16x32_bf16 v[100:103], v[226:229], v[194:197], v[100:103]
	v_mfma_f32_16x16x32_bf16 v[96:99], v[234:237], v[194:197], v[96:99]
	v_mfma_f32_16x16x32_bf16 v[84:87], v[226:229], v[202:205], v[84:87]
	v_mfma_f32_16x16x32_bf16 v[80:83], v[234:237], v[202:205], v[80:83]
	v_mfma_f32_16x16x32_bf16 v[68:71], v[226:229], v[210:213], v[68:71]
	v_mfma_f32_16x16x32_bf16 v[64:67], v[234:237], v[210:213], v[64:67]
	v_mfma_f32_16x16x32_bf16 v[116:119], v[230:233], v[190:193], v[116:119]
	v_mfma_f32_16x16x32_bf16 v[112:115], v[238:241], v[190:193], v[112:115]
	v_mfma_f32_16x16x32_bf16 v[100:103], v[230:233], v[198:201], v[100:103]
	v_mfma_f32_16x16x32_bf16 v[96:99], v[238:241], v[198:201], v[96:99]
	v_mfma_f32_16x16x32_bf16 v[84:87], v[230:233], v[206:209], v[84:87]
	v_mfma_f32_16x16x32_bf16 v[80:83], v[238:241], v[206:209], v[80:83]
	v_mfma_f32_16x16x32_bf16 v[68:71], v[230:233], v[214:217], v[68:71]
	v_mfma_f32_16x16x32_bf16 v[64:67], v[238:241], v[214:217], v[64:67]
	s_setprio 0
	s_mov_b32 m0, s34
	v_lshl_add_u64 v[154:155], v[220:221], 0, s[94:95]
	s_barrier
	ds_read_b128 v[186:189], v137 offset:49152
	ds_read_b128 v[190:193], v137 offset:50176
	ds_read_b128 v[194:197], v137 offset:51200
	ds_read_b128 v[198:201], v137 offset:52224
	ds_read_b128 v[202:205], v137 offset:53248
	ds_read_b128 v[206:209], v137 offset:54272
	ds_read_b128 v[210:213], v137 offset:55296
	ds_read_b128 v[214:217], v137 offset:56320
	global_load_lds_dwordx4 v[154:155], off
	v_lshl_add_u64 v[154:155], v[242:243], 0, s[94:95]
	s_mov_b32 m0, s35
	s_nop 0
	global_load_lds_dwordx4 v[154:155], off
	s_barrier
; #define PG8_STAGE(bufoff, gbase) do { _Pragma("unroll") for (int _i = 0; _i < 2; ++_i) \
;         __builtin_amdgcn_global_load_lds((const unsigned*)((const char*)(gbase) + voff[_i]), (LAS unsigned*)(lds + (bufoff) + ldsw + _i * 8192), 16, 0, 0); } while (0)
; #define PG8_MMA(ai, bj, At, Bt) do { __builtin_amdgcn_s_setprio(1); _Pragma("unroll") for (int m = 0; m < 4; ++m) _Pragma("unroll") for (int n = 0; n < 2; ++n) _Pragma("unroll") for (int k = 0; k < 2; ++k) \
;         acc[ai][bj][m][n] = __builtin_amdgcn_mfma_f32_16x16x32_bf16(Bt[n][k], At[m][k], acc[ai][bj][m][n], 0, 0, 0); __builtin_amdgcn_s_setprio(0); } while (0)
; #define PG8_WAIT_V(n) asm volatile("s_waitcnt vmcnt(" #n ")" ::: "memory")
; #define PG8_WAIT_L(n) asm volatile("s_waitcnt lgkmcnt(" #n ")" ::: "memory")
; #define PG8_BAR __builtin_amdgcn_s_barrier()
; #define PG8_SCHED __builtin_amdgcn_sched_barrier(0)
; template <class Epi>
; DI void gemm_phase(LAS unsigned char* lds, const Gemm g, const StaticOrder& S, const Epi& E) {
;     ...
;             PG8_BAR; PG8_WAIT_L(0); PG8_MMA(1, 0, At, B0); PG8_BAR; PG8_SCHED;
;             PG8_STAGE(PG8_SB(1, 1), b3 + hstep);
;             PG8_WAIT_V(6); PG8_BAR; PG8_MMA(1, 1, At, B1); PG8_BAR;
;         }
;     DI void operator()(const f32x4 (&acc)[2][2][4][2], const Unit& u, int wr, int wc, int fr, int fq) const {
;     ...
;             for (int m = 0; m < 4; ++m) { float hv[8];
; #pragma unroll
;                 for (int n = 0; n < 2; ++n)
; #pragma unroll
;                     for (int e = 0; e < 4; ++e) { const float gt = acc[ai][0][m][n][e], up = acc[ai][1][m][n][e];
;                         hv[n * 4 + e] = gt * __builtin_amdgcn_rcpf(1.f + __builtin_amdgcn_exp2f(-1.4426950408889634f * gt)) * up; }
;                 *(u32x4*)(H + (size_t)(row0 + ai * HALF + m * 16) * DFF + col0) = (u32x4){pk(hv[0], hv[1]), pk(hv[2], hv[3]), pk(hv[4], hv[5]), pk(hv[6], hv[7])}; }
	s_waitcnt lgkmcnt(0)
	s_setprio 1
	v_mfma_f32_16x16x32_bf16 v[60:63], v[138:141], v[186:189], v[60:63]
	v_mfma_f32_16x16x32_bf16 v[56:59], v[146:149], v[186:189], v[56:59]
	v_mfma_f32_16x16x32_bf16 v[44:47], v[138:141], v[194:197], v[44:47]
	v_mfma_f32_16x16x32_bf16 v[40:43], v[146:149], v[194:197], v[40:43]
	v_mfma_f32_16x16x32_bf16 v[28:31], v[138:141], v[202:205], v[28:31]
	v_mfma_f32_16x16x32_bf16 v[24:27], v[146:149], v[202:205], v[24:27]
	v_mfma_f32_16x16x32_bf16 v[12:15], v[138:141], v[210:213], v[12:15]
	v_mfma_f32_16x16x32_bf16 v[8:11], v[146:149], v[210:213], v[8:11]
	v_mfma_f32_16x16x32_bf16 v[60:63], v[142:145], v[190:193], v[60:63]
	v_mfma_f32_16x16x32_bf16 v[56:59], v[150:153], v[190:193], v[56:59]
	v_mfma_f32_16x16x32_bf16 v[44:47], v[142:145], v[198:201], v[44:47]
	v_mfma_f32_16x16x32_bf16 v[40:43], v[150:153], v[198:201], v[40:43]
	v_mfma_f32_16x16x32_bf16 v[28:31], v[142:145], v[206:209], v[28:31]
	v_mfma_f32_16x16x32_bf16 v[24:27], v[150:153], v[206:209], v[24:27]
	v_mfma_f32_16x16x32_bf16 v[12:15], v[142:145], v[214:217], v[12:15]
	v_mfma_f32_16x16x32_bf16 v[8:11], v[150:153], v[214:217], v[8:11]
	s_setprio 0
	s_barrier
	s_add_u32 s20, s20, 0x80080
	s_addc_u32 s21, s21, 0
	s_add_i32 s22, s22, s27
	v_lshl_add_u64 v[138:139], s[20:21], 0, v[158:159]
	s_mov_b32 m0, s22
	s_nop 0
	global_load_lds_dwordx4 v[138:139], off
	v_lshl_add_u64 v[138:139], s[20:21], 0, v[128:129]
	s_add_i32 m0, s22, 0x2000
	s_nop 0
	global_load_lds_dwordx4 v[138:139], off
	s_waitcnt vmcnt(6)
	s_barrier
	s_setprio 1
	v_mfma_f32_16x16x32_bf16 v[52:55], v[226:229], v[186:189], v[52:55]
	v_mfma_f32_16x16x32_bf16 v[48:51], v[234:237], v[186:189], v[48:51]
	v_mfma_f32_16x16x32_bf16 v[36:39], v[226:229], v[194:197], v[36:39]
	v_mfma_f32_16x16x32_bf16 v[32:35], v[234:237], v[194:197], v[32:35]
	v_mfma_f32_16x16x32_bf16 v[20:23], v[226:229], v[202:205], v[20:23]
	v_mfma_f32_16x16x32_bf16 v[16:19], v[234:237], v[202:205], v[16:19]
	v_mfma_f32_16x16x32_bf16 v[4:7], v[226:229], v[210:213], v[4:7]
	v_mfma_f32_16x16x32_bf16 v[0:3], v[234:237], v[210:213], v[0:3]
	v_mfma_f32_16x16x32_bf16 v[52:55], v[230:233], v[190:193], v[52:55]
	v_mfma_f32_16x16x32_bf16 v[48:51], v[238:241], v[190:193], v[48:51]
	v_mfma_f32_16x16x32_bf16 v[36:39], v[230:233], v[198:201], v[36:39]
	v_mfma_f32_16x16x32_bf16 v[32:35], v[238:241], v[198:201], v[32:35]
	v_mfma_f32_16x16x32_bf16 v[20:23], v[230:233], v[206:209], v[20:23]
	v_mfma_f32_16x16x32_bf16 v[16:19], v[238:241], v[206:209], v[16:19]
	v_mfma_f32_16x16x32_bf16 v[4:7], v[230:233], v[214:217], v[4:7]
	v_mfma_f32_16x16x32_bf16 v[0:3], v[238:241], v[214:217], v[0:3]
	s_setprio 0
	s_add_i32 s38, s38, 2
	s_add_u32 s18, s18, 0x100
	s_addc_u32 s19, s19, 0
	s_add_u32 s33, s33, 0x100
	s_addc_u32 s37, s37, 0
	s_cmp_gt_u32 s38, 29
	s_barrier
	s_cbranch_scc0 .LBB0_37
	v_mul_f32_e32 v139, 0xbfb8aa3b, v124
	v_exp_f32_e32 v139, v139
	v_lshl_or_b32 v140, s2, 7, v136
	v_lshl_add_u32 v138, s3, 8, v134
	v_ashrrev_i32_e32 v141, 31, v140
	v_add_f32_e32 v139, 1.0, v139
	v_rcp_f32_e32 v142, v139
	v_mul_f32_e32 v139, 0xbfb8aa3b, v125
	v_exp_f32_e32 v139, v139
	s_movk_i32 s4, 0x2c00
	s_and_b64 vcc, exec, s[6:7]
	s_mov_b64 s[20:21], s[16:17]
	v_add_f32_e32 v139, 1.0, v139
	v_rcp_f32_e32 v143, v139
	v_mul_f32_e32 v139, 0xbfb8aa3b, v126
	v_exp_f32_e32 v139, v139
	s_mov_b64 s[18:19], s[14:15]
	v_pk_mul_f32 v[124:125], v[124:125], v[142:143]
	v_add_f32_e32 v139, 1.0, v139
	v_rcp_f32_e32 v144, v139
	v_mul_f32_e32 v139, 0xbfb8aa3b, v127
	v_exp_f32_e32 v139, v139
	v_pk_mul_f32 v[116:117], v[124:125], v[116:117]
	v_add_f32_e32 v139, 1.0, v139
	v_rcp_f32_e32 v145, v139
	v_mul_f32_e32 v139, 0xbfb8aa3b, v120
	v_exp_f32_e32 v139, v139
	v_cvt_pk_bf16_f32 v116, v116, v117
	v_pk_mul_f32 v[124:125], v[126:127], v[144:145]
	v_add_f32_e32 v139, 1.0, v139
	v_rcp_f32_e32 v146, v139
	v_mul_f32_e32 v139, 0xbfb8aa3b, v121
	v_exp_f32_e32 v139, v139
	v_pk_mul_f32 v[118:119], v[124:125], v[118:119]
	v_add_f32_e32 v139, 1.0, v139
	v_rcp_f32_e32 v147, v139
	v_mul_f32_e32 v139, 0xbfb8aa3b, v122
	v_exp_f32_e32 v139, v139
	v_cvt_pk_bf16_f32 v117, v118, v119
	v_pk_mul_f32 v[118:119], v[120:121], v[146:147]
	v_add_f32_e32 v139, 1.0, v139
	v_rcp_f32_e32 v148, v139
	v_mul_f32_e32 v139, 0xbfb8aa3b, v123
	v_exp_f32_e32 v139, v139
	v_pk_mul_f32 v[112:113], v[118:119], v[112:113]
	v_add_f32_e32 v139, 1.0, v139
	v_rcp_f32_e32 v149, v139
	v_cvt_pk_bf16_f32 v118, v112, v113
	v_pk_mul_f32 v[112:113], v[122:123], v[148:149]
	s_nop 0
	v_pk_mul_f32 v[112:113], v[112:113], v[114:115]
	v_lshlrev_b64 v[114:115], 1, v[140:141]
	v_cvt_pk_bf16_f32 v119, v112, v113
	v_mov_b64_e32 v[112:113], s[54:55]
	v_mad_i64_i32 v[120:121], s[2:3], v138, s4, v[112:113]
	v_lshl_add_u64 v[120:121], v[120:121], 0, v[114:115]
	global_store_dwordx4 v[120:121], v[116:119], off
	v_mul_f32_e32 v120, 0xbfb8aa3b, v104
	v_mul_f32_e32 v121, 0xbfb8aa3b, v105
	v_mul_f32_e32 v116, 0xbfb8aa3b, v108
	v_mul_f32_e32 v117, 0xbfb8aa3b, v109
	v_exp_f32_e32 v116, v116
	v_exp_f32_e32 v117, v117
	v_mul_f32_e32 v118, 0xbfb8aa3b, v110
	v_mul_f32_e32 v119, 0xbfb8aa3b, v111
	v_exp_f32_e32 v118, v118
	v_exp_f32_e32 v119, v119
	v_exp_f32_e32 v120, v120
	v_exp_f32_e32 v121, v121
	v_add_f32_e32 v116, 1.0, v116
	v_add_f32_e32 v117, 1.0, v117
	v_mul_f32_e32 v122, 0xbfb8aa3b, v106
	v_mul_f32_e32 v123, 0xbfb8aa3b, v107
	v_rcp_f32_e32 v116, v116
	v_rcp_f32_e32 v117, v117
	v_add_f32_e32 v118, 1.0, v118
	v_add_f32_e32 v119, 1.0, v119
	v_exp_f32_e32 v122, v122
	v_exp_f32_e32 v123, v123
	v_rcp_f32_e32 v118, v118
	v_rcp_f32_e32 v119, v119
	v_add_f32_e32 v120, 1.0, v120
	v_add_f32_e32 v121, 1.0, v121
	v_rcp_f32_e32 v120, v120
	v_rcp_f32_e32 v121, v121
;     DI void operator()(const f32x4 (&acc)[2][2][4][2], const Unit& u, int wr, int wc, int fr, int fq) const {
;     ...
;         for (int ai = 0; ai < 2; ++ai)
; #pragma unroll
;             for (int m = 0; m < 4; ++m) { float hv[8];
; #pragma unroll
;                 for (int n = 0; n < 2; ++n)
; #pragma unroll
;                     for (int e = 0; e < 4; ++e) { const float gt = acc[ai][0][m][n][e], up = acc[ai][1][m][n][e];
;                         hv[n * 4 + e] = gt * __builtin_amdgcn_rcpf(1.f + __builtin_amdgcn_exp2f(-1.4426950408889634f * gt)) * up; }
;                 *(u32x4*)(H + (size_t)(row0 + ai * HALF + m * 16) * DFF + col0) = (u32x4){pk(hv[0], hv[1]), pk(hv[2], hv[3]), pk(hv[4], hv[5]), pk(hv[6], hv[7])}; }
	v_add_f32_e32 v122, 1.0, v122
	v_add_f32_e32 v123, 1.0, v123
	v_pk_mul_f32 v[108:109], v[108:109], v[116:117]
	v_rcp_f32_e32 v122, v122
	v_rcp_f32_e32 v123, v123
	v_pk_mul_f32 v[100:101], v[108:109], v[100:101]
	v_pk_mul_f32 v[108:109], v[110:111], v[118:119]
	v_cvt_pk_bf16_f32 v100, v100, v101
	v_pk_mul_f32 v[102:103], v[108:109], v[102:103]
	s_nop 0
	v_cvt_pk_bf16_f32 v101, v102, v103
	v_pk_mul_f32 v[102:103], v[104:105], v[120:121]
	s_nop 0
	v_pk_mul_f32 v[96:97], v[102:103], v[96:97]
	s_nop 0
	v_cvt_pk_bf16_f32 v102, v96, v97
	v_pk_mul_f32 v[96:97], v[106:107], v[122:123]
	s_nop 0
	v_pk_mul_f32 v[96:97], v[96:97], v[98:99]
	v_mul_f32_e32 v98, 0xbfb8aa3b, v94
	v_cvt_pk_bf16_f32 v103, v96, v97
	v_or_b32_e32 v96, 16, v138
	v_mad_i64_i32 v[96:97], s[2:3], v96, s4, v[112:113]
	v_lshl_add_u64 v[96:97], v[96:97], 0, v[114:115]
	global_store_dwordx4 v[96:97], v[100:103], off
	v_mul_f32_e32 v96, 0xbfb8aa3b, v92
	v_mul_f32_e32 v97, 0xbfb8aa3b, v93
	v_exp_f32_e32 v96, v96
	v_exp_f32_e32 v97, v97
	v_mul_f32_e32 v99, 0xbfb8aa3b, v95
	v_exp_f32_e32 v98, v98
	v_exp_f32_e32 v99, v99
	v_mul_f32_e32 v100, 0xbfb8aa3b, v88
	v_mul_f32_e32 v101, 0xbfb8aa3b, v89
	v_exp_f32_e32 v100, v100
	v_exp_f32_e32 v101, v101
	v_add_f32_e32 v96, 1.0, v96
	v_add_f32_e32 v97, 1.0, v97
	v_mul_f32_e32 v102, 0xbfb8aa3b, v90
	v_mul_f32_e32 v103, 0xbfb8aa3b, v91
	v_rcp_f32_e32 v96, v96
	v_rcp_f32_e32 v97, v97
	v_add_f32_e32 v98, 1.0, v98
	v_add_f32_e32 v99, 1.0, v99
	v_exp_f32_e32 v102, v102
	v_exp_f32_e32 v103, v103
	v_rcp_f32_e32 v98, v98
	v_rcp_f32_e32 v99, v99
	v_add_f32_e32 v100, 1.0, v100
	v_add_f32_e32 v101, 1.0, v101
	v_rcp_f32_e32 v100, v100
	v_rcp_f32_e32 v101, v101
	v_add_f32_e32 v102, 1.0, v102
	v_add_f32_e32 v103, 1.0, v103
	v_pk_mul_f32 v[92:93], v[92:93], v[96:97]
	v_rcp_f32_e32 v102, v102
	v_rcp_f32_e32 v103, v103
	v_pk_mul_f32 v[84:85], v[92:93], v[84:85]
	v_pk_mul_f32 v[92:93], v[94:95], v[98:99]
	v_cvt_pk_bf16_f32 v84, v84, v85
	v_pk_mul_f32 v[86:87], v[92:93], v[86:87]
	s_nop 0
	v_cvt_pk_bf16_f32 v85, v86, v87
	v_pk_mul_f32 v[86:87], v[88:89], v[100:101]
	s_nop 0
	v_pk_mul_f32 v[80:81], v[86:87], v[80:81]
	s_nop 0
	v_cvt_pk_bf16_f32 v86, v80, v81
	v_pk_mul_f32 v[80:81], v[90:91], v[102:103]
	s_nop 0
	v_pk_mul_f32 v[80:81], v[80:81], v[82:83]
	v_mul_f32_e32 v82, 0xbfb8aa3b, v78
	v_cvt_pk_bf16_f32 v87, v80, v81
	v_or_b32_e32 v80, 32, v138
	v_mad_i64_i32 v[80:81], s[2:3], v80, s4, v[112:113]
	v_lshl_add_u64 v[80:81], v[80:81], 0, v[114:115]
	global_store_dwordx4 v[80:81], v[84:87], off
	v_mul_f32_e32 v80, 0xbfb8aa3b, v76
	v_mul_f32_e32 v81, 0xbfb8aa3b, v77
	v_exp_f32_e32 v80, v80
	v_exp_f32_e32 v81, v81
	v_mul_f32_e32 v83, 0xbfb8aa3b, v79
	v_exp_f32_e32 v82, v82
	v_exp_f32_e32 v83, v83
	v_mul_f32_e32 v84, 0xbfb8aa3b, v72
	v_mul_f32_e32 v85, 0xbfb8aa3b, v73
	v_exp_f32_e32 v84, v84
	v_exp_f32_e32 v85, v85
	v_add_f32_e32 v80, 1.0, v80
	v_add_f32_e32 v81, 1.0, v81
	v_mul_f32_e32 v86, 0xbfb8aa3b, v74
	v_mul_f32_e32 v87, 0xbfb8aa3b, v75
	v_rcp_f32_e32 v80, v80
	v_rcp_f32_e32 v81, v81
	v_add_f32_e32 v82, 1.0, v82
	v_add_f32_e32 v83, 1.0, v83
	v_exp_f32_e32 v86, v86
	v_exp_f32_e32 v87, v87
	v_rcp_f32_e32 v82, v82
	v_rcp_f32_e32 v83, v83
	v_add_f32_e32 v84, 1.0, v84
	v_add_f32_e32 v85, 1.0, v85
	v_rcp_f32_e32 v84, v84
	v_rcp_f32_e32 v85, v85
	v_add_f32_e32 v86, 1.0, v86
	v_add_f32_e32 v87, 1.0, v87
	v_pk_mul_f32 v[76:77], v[76:77], v[80:81]
	v_rcp_f32_e32 v86, v86
	v_rcp_f32_e32 v87, v87
	v_pk_mul_f32 v[68:69], v[76:77], v[68:69]
	v_pk_mul_f32 v[76:77], v[78:79], v[82:83]
	v_cvt_pk_bf16_f32 v68, v68, v69
	v_pk_mul_f32 v[70:71], v[76:77], v[70:71]
	s_nop 0
	v_cvt_pk_bf16_f32 v69, v70, v71
	v_pk_mul_f32 v[70:71], v[72:73], v[84:85]
	v_add_u32_e32 v72, 0x80, v138
	v_pk_mul_f32 v[64:65], v[70:71], v[64:65]
	s_nop 0
	v_cvt_pk_bf16_f32 v70, v64, v65
	v_pk_mul_f32 v[64:65], v[74:75], v[86:87]
	s_nop 0
	v_pk_mul_f32 v[64:65], v[64:65], v[66:67]
	v_mul_f32_e32 v66, 0xbfb8aa3b, v62
	v_cvt_pk_bf16_f32 v71, v64, v65
	v_or_b32_e32 v64, 48, v138
	v_mad_i64_i32 v[64:65], s[2:3], v64, s4, v[112:113]
	v_lshl_add_u64 v[64:65], v[64:65], 0, v[114:115]
	global_store_dwordx4 v[64:65], v[68:71], off
	v_mul_f32_e32 v64, 0xbfb8aa3b, v60
	v_mul_f32_e32 v65, 0xbfb8aa3b, v61
	v_exp_f32_e32 v64, v64
	v_exp_f32_e32 v65, v65
	v_mul_f32_e32 v67, 0xbfb8aa3b, v63
	v_exp_f32_e32 v66, v66
	v_exp_f32_e32 v67, v67
	v_mul_f32_e32 v68, 0xbfb8aa3b, v56
	v_mul_f32_e32 v69, 0xbfb8aa3b, v57
	v_exp_f32_e32 v68, v68
	v_exp_f32_e32 v69, v69
	v_add_f32_e32 v64, 1.0, v64
	v_add_f32_e32 v65, 1.0, v65
	v_mul_f32_e32 v70, 0xbfb8aa3b, v58
	v_mul_f32_e32 v71, 0xbfb8aa3b, v59
	v_rcp_f32_e32 v64, v64
	v_rcp_f32_e32 v65, v65
	v_add_f32_e32 v66, 1.0, v66
	v_add_f32_e32 v67, 1.0, v67
	v_exp_f32_e32 v70, v70
	v_exp_f32_e32 v71, v71
	v_rcp_f32_e32 v66, v66
	v_rcp_f32_e32 v67, v67
	v_add_f32_e32 v68, 1.0, v68
	v_add_f32_e32 v69, 1.0, v69
	v_rcp_f32_e32 v68, v68
	v_rcp_f32_e32 v69, v69
	v_add_f32_e32 v70, 1.0, v70
	v_add_f32_e32 v71, 1.0, v71
	v_pk_mul_f32 v[60:61], v[60:61], v[64:65]
	v_rcp_f32_e32 v70, v70
	v_rcp_f32_e32 v71, v71
	v_pk_mul_f32 v[52:53], v[60:61], v[52:53]
	v_pk_mul_f32 v[60:61], v[62:63], v[66:67]
	v_cvt_pk_bf16_f32 v52, v52, v53
	v_pk_mul_f32 v[54:55], v[60:61], v[54:55]
	s_nop 0
	v_cvt_pk_bf16_f32 v53, v54, v55
	v_pk_mul_f32 v[54:55], v[56:57], v[68:69]
; #define PG8_WAIT_V(n) asm volatile("s_waitcnt vmcnt(" #n ")" ::: "memory")
; #define PG8_BAR __builtin_amdgcn_s_barrier()
; template <class Epi>
; DI void gemm_phase(LAS unsigned char* lds, const Gemm g, const StaticOrder& S, const Epi& E) {
;     ...
;         E(acc, cur, wr, wc, fr, fq);
;         if (!has_next) break;
; #pragma unroll
;         for (int a = 0; a < 2; ++a)
; #pragma unroll
;             for (int b = 0; b < 2; ++b)
; #pragma unroll
;                 for (int m = 0; m < 4; ++m)
; #pragma unroll
;                     for (int n = 0; n < 2; ++n) acc[a][b][m][n] = (f32x4){0.f, 0.f, 0.f, 0.f};
;         cur = nxt; cA = nA; cB = nB; ++ui;
;     }
;     PG8_WAIT_V(0);
;     if (wr == 0) PG8_BAR;
;     DI void operator()(const f32x4 (&acc)[2][2][4][2], const Unit& u, int wr, int wc, int fr, int fq) const {
;     ...
;         for (int ai = 0; ai < 2; ++ai)
; #pragma unroll
;             for (int m = 0; m < 4; ++m) { float hv[8];
; #pragma unroll
;                 for (int n = 0; n < 2; ++n)
; #pragma unroll
;                     for (int e = 0; e < 4; ++e) { const float gt = acc[ai][0][m][n][e], up = acc[ai][1][m][n][e];
;                         hv[n * 4 + e] = gt * __builtin_amdgcn_rcpf(1.f + __builtin_amdgcn_exp2f(-1.4426950408889634f * gt)) * up; }
;                 *(u32x4*)(H + (size_t)(row0 + ai * HALF + m * 16) * DFF + col0) = (u32x4){pk(hv[0], hv[1]), pk(hv[2], hv[3]), pk(hv[4], hv[5]), pk(hv[6], hv[7])}; }
	s_nop 0
	v_pk_mul_f32 v[48:49], v[54:55], v[48:49]
	s_nop 0
	v_cvt_pk_bf16_f32 v54, v48, v49
	v_pk_mul_f32 v[48:49], v[58:59], v[70:71]
	s_nop 0
	v_pk_mul_f32 v[48:49], v[48:49], v[50:51]
	v_mul_f32_e32 v50, 0xbfb8aa3b, v46
	v_cvt_pk_bf16_f32 v55, v48, v49
	v_mad_i64_i32 v[48:49], s[2:3], v72, s4, v[112:113]
	v_lshl_add_u64 v[48:49], v[48:49], 0, v[114:115]
	global_store_dwordx4 v[48:49], v[52:55], off
	v_mul_f32_e32 v48, 0xbfb8aa3b, v44
	v_mul_f32_e32 v49, 0xbfb8aa3b, v45
	v_exp_f32_e32 v48, v48
	v_exp_f32_e32 v49, v49
	v_mul_f32_e32 v51, 0xbfb8aa3b, v47
	v_exp_f32_e32 v50, v50
	v_exp_f32_e32 v51, v51
	v_mul_f32_e32 v52, 0xbfb8aa3b, v40
	v_mul_f32_e32 v53, 0xbfb8aa3b, v41
	v_exp_f32_e32 v52, v52
	v_exp_f32_e32 v53, v53
	v_add_f32_e32 v48, 1.0, v48
	v_add_f32_e32 v49, 1.0, v49
	v_mul_f32_e32 v54, 0xbfb8aa3b, v42
	v_mul_f32_e32 v55, 0xbfb8aa3b, v43
	v_rcp_f32_e32 v48, v48
	v_rcp_f32_e32 v49, v49
	v_add_f32_e32 v50, 1.0, v50
	v_add_f32_e32 v51, 1.0, v51
	v_exp_f32_e32 v54, v54
	v_exp_f32_e32 v55, v55
	v_rcp_f32_e32 v50, v50
	v_rcp_f32_e32 v51, v51
	v_add_f32_e32 v52, 1.0, v52
	v_add_f32_e32 v53, 1.0, v53
	v_rcp_f32_e32 v52, v52
	v_rcp_f32_e32 v53, v53
	v_add_f32_e32 v54, 1.0, v54
	v_add_f32_e32 v55, 1.0, v55
	v_pk_mul_f32 v[44:45], v[44:45], v[48:49]
	v_rcp_f32_e32 v54, v54
	v_rcp_f32_e32 v55, v55
	v_pk_mul_f32 v[36:37], v[44:45], v[36:37]
	v_pk_mul_f32 v[44:45], v[46:47], v[50:51]
	v_cvt_pk_bf16_f32 v36, v36, v37
	v_pk_mul_f32 v[38:39], v[44:45], v[38:39]
	s_nop 0
	v_cvt_pk_bf16_f32 v37, v38, v39
	v_pk_mul_f32 v[38:39], v[40:41], v[52:53]
	s_nop 0
	v_pk_mul_f32 v[32:33], v[38:39], v[32:33]
	s_nop 0
	v_cvt_pk_bf16_f32 v38, v32, v33
	v_pk_mul_f32 v[32:33], v[42:43], v[54:55]
	s_nop 0
	v_pk_mul_f32 v[32:33], v[32:33], v[34:35]
	v_mul_f32_e32 v34, 0xbfb8aa3b, v30
	v_cvt_pk_bf16_f32 v39, v32, v33
	v_add_u32_e32 v32, 0x90, v138
	v_mad_i64_i32 v[32:33], s[2:3], v32, s4, v[112:113]
	v_lshl_add_u64 v[32:33], v[32:33], 0, v[114:115]
	global_store_dwordx4 v[32:33], v[36:39], off
	v_mul_f32_e32 v32, 0xbfb8aa3b, v28
	v_mul_f32_e32 v33, 0xbfb8aa3b, v29
	v_exp_f32_e32 v32, v32
	v_exp_f32_e32 v33, v33
	v_mul_f32_e32 v35, 0xbfb8aa3b, v31
	v_exp_f32_e32 v34, v34
	v_exp_f32_e32 v35, v35
	v_mul_f32_e32 v36, 0xbfb8aa3b, v24
	v_mul_f32_e32 v37, 0xbfb8aa3b, v25
	v_exp_f32_e32 v36, v36
	v_exp_f32_e32 v37, v37
	v_add_f32_e32 v32, 1.0, v32
	v_add_f32_e32 v33, 1.0, v33
	v_mul_f32_e32 v38, 0xbfb8aa3b, v26
	v_mul_f32_e32 v39, 0xbfb8aa3b, v27
	v_rcp_f32_e32 v32, v32
	v_rcp_f32_e32 v33, v33
	v_add_f32_e32 v34, 1.0, v34
	v_add_f32_e32 v35, 1.0, v35
	v_exp_f32_e32 v38, v38
	v_exp_f32_e32 v39, v39
	v_rcp_f32_e32 v34, v34
	v_rcp_f32_e32 v35, v35
	v_add_f32_e32 v36, 1.0, v36
	v_add_f32_e32 v37, 1.0, v37
	v_rcp_f32_e32 v36, v36
	v_rcp_f32_e32 v37, v37
	v_add_f32_e32 v38, 1.0, v38
	v_add_f32_e32 v39, 1.0, v39
	v_pk_mul_f32 v[28:29], v[28:29], v[32:33]
	v_rcp_f32_e32 v38, v38
	v_rcp_f32_e32 v39, v39
	v_pk_mul_f32 v[20:21], v[28:29], v[20:21]
	v_pk_mul_f32 v[28:29], v[30:31], v[34:35]
	v_cvt_pk_bf16_f32 v20, v20, v21
	v_pk_mul_f32 v[22:23], v[28:29], v[22:23]
	s_nop 0
	v_cvt_pk_bf16_f32 v21, v22, v23
	v_pk_mul_f32 v[22:23], v[24:25], v[36:37]
	s_nop 0
	v_pk_mul_f32 v[16:17], v[22:23], v[16:17]
	s_nop 0
	v_cvt_pk_bf16_f32 v22, v16, v17
	v_pk_mul_f32 v[16:17], v[26:27], v[38:39]
	s_nop 0
	v_pk_mul_f32 v[16:17], v[16:17], v[18:19]
	v_mul_f32_e32 v18, 0xbfb8aa3b, v14
	v_cvt_pk_bf16_f32 v23, v16, v17
	v_add_u32_e32 v16, 0xa0, v138
	v_mad_i64_i32 v[16:17], s[2:3], v16, s4, v[112:113]
	v_lshl_add_u64 v[16:17], v[16:17], 0, v[114:115]
	global_store_dwordx4 v[16:17], v[20:23], off
	v_mul_f32_e32 v16, 0xbfb8aa3b, v12
	v_mul_f32_e32 v17, 0xbfb8aa3b, v13
	v_exp_f32_e32 v16, v16
	v_exp_f32_e32 v17, v17
	v_mul_f32_e32 v19, 0xbfb8aa3b, v15
	v_exp_f32_e32 v18, v18
	v_exp_f32_e32 v19, v19
	v_mul_f32_e32 v20, 0xbfb8aa3b, v8
	v_mul_f32_e32 v21, 0xbfb8aa3b, v9
	v_exp_f32_e32 v20, v20
	v_exp_f32_e32 v21, v21
	v_add_f32_e32 v16, 1.0, v16
	v_add_f32_e32 v17, 1.0, v17
	v_mul_f32_e32 v22, 0xbfb8aa3b, v10
	v_mul_f32_e32 v23, 0xbfb8aa3b, v11
	v_rcp_f32_e32 v16, v16
	v_rcp_f32_e32 v17, v17
	v_add_f32_e32 v18, 1.0, v18
	v_add_f32_e32 v19, 1.0, v19
	v_exp_f32_e32 v22, v22
	v_exp_f32_e32 v23, v23
	v_rcp_f32_e32 v18, v18
	v_rcp_f32_e32 v19, v19
	v_add_f32_e32 v20, 1.0, v20
	v_add_f32_e32 v21, 1.0, v21
	v_rcp_f32_e32 v20, v20
	v_rcp_f32_e32 v21, v21
	v_add_f32_e32 v22, 1.0, v22
	v_add_f32_e32 v23, 1.0, v23
	v_pk_mul_f32 v[12:13], v[12:13], v[16:17]
	v_rcp_f32_e32 v22, v22
	v_rcp_f32_e32 v23, v23
	v_pk_mul_f32 v[4:5], v[12:13], v[4:5]
	v_pk_mul_f32 v[12:13], v[14:15], v[18:19]
	v_cvt_pk_bf16_f32 v4, v4, v5
	v_pk_mul_f32 v[6:7], v[12:13], v[6:7]
	s_nop 0
	v_cvt_pk_bf16_f32 v5, v6, v7
	v_pk_mul_f32 v[6:7], v[8:9], v[20:21]
	s_nop 0
	v_pk_mul_f32 v[0:1], v[6:7], v[0:1]
	s_nop 0
	v_cvt_pk_bf16_f32 v6, v0, v1
	v_pk_mul_f32 v[0:1], v[10:11], v[22:23]
	s_nop 0
	v_pk_mul_f32 v[0:1], v[0:1], v[2:3]
	s_nop 0
	v_cvt_pk_bf16_f32 v7, v0, v1
	v_add_u32_e32 v0, 0xb0, v138
	v_mad_i64_i32 v[0:1], s[2:3], v0, s4, v[112:113]
	v_lshl_add_u64 v[0:1], v[0:1], 0, v[114:115]
	s_mov_b32 s2, s8
	s_mov_b32 s3, s10
	global_store_dwordx4 v[0:1], v[4:7], off
	s_cbranch_vccz .LBB0_34
	s_waitcnt vmcnt(0)
	s_cmpk_gt_u32 s24, 0xff
	s_cbranch_scc1 .LBB0_41
	s_barrier

; #define PG8_STAGE(bufoff, gbase) do { _Pragma("unroll") for (int _i = 0; _i < 2; ++_i) \
;         __builtin_amdgcn_global_load_lds((const unsigned*)((const char*)(gbase) + voff[_i]), (LAS unsigned*)(lds + (bufoff) + ldsw + _i * 8192), 16, 0, 0); } while (0)
; #define PG8_LDA(dst, b, h) do { _Pragma("unroll") for (int m = 0; m < 4; ++m) _Pragma("unroll") for (int k = 0; k < 2; ++k) dst[m][k] = *(const LAS bf16x8*)(lds + PG8_SA(b, h) + aoff + m * 2048 + k * 1024); } while (0)
; #define PG8_LDB(dst, b, h) do { _Pragma("unroll") for (int n = 0; n < 2; ++n) _Pragma("unroll") for (int k = 0; k < 2; ++k) dst[n][k] = *(const LAS bf16x8*)(lds + PG8_SB(b, h) + boff + n * 2048 + k * 1024); } while (0)
; #define PG8_MMA(ai, bj, At, Bt) do { __builtin_amdgcn_s_setprio(1); _Pragma("unroll") for (int m = 0; m < 4; ++m) _Pragma("unroll") for (int n = 0; n < 2; ++n) _Pragma("unroll") for (int k = 0; k < 2; ++k) \
;         acc[ai][bj][m][n] = __builtin_amdgcn_mfma_f32_16x16x32_bf16(Bt[n][k], At[m][k], acc[ai][bj][m][n], 0, 0, 0); __builtin_amdgcn_s_setprio(0); } while (0)
; #define PG8_WAIT_L(n) asm volatile("s_waitcnt lgkmcnt(" #n ")" ::: "memory")
; #define PG8_BAR __builtin_amdgcn_s_barrier()
; #define PG8_SCHED __builtin_amdgcn_sched_barrier(0)
; template <class Epi>
; DI void gemm_phase(LAS unsigned char* lds, const Gemm g, const StaticOrder& S, const Epi& E) {
;     ...
;         for (int t = 0; t < nt; t += 2) {
;             const bool last = (t == nt - 2);
;             const char* a1 = cA + (size_t)(t + 1) * kstep;
;             const char* a2 = last ? nA : cA + (size_t)(t + 2) * kstep; const char* b2 = last ? nB : cB + (size_t)(t + 2) * kstep;
;             const char* a3 = a2 + kstep; const char* b3 = b2 + kstep;
;             PG8_LDB(B0, 0, 0); PG8_SCHED; PG8_LDA(At, 0, 0); PG8_STAGE(PG8_SA(1, 1), a1 + hstep);
;             PG8_WAIT_L(8); PG8_BAR; PG8_WAIT_L(0); PG8_MMA(0, 0, At, B0); PG8_BAR; PG8_SCHED;
;             PG8_LDB(B1, 0, 1); PG8_STAGE(PG8_SB(0, 0), b2);
;             PG8_BAR; PG8_WAIT_L(0); PG8_MMA(0, 1, At, B1); PG8_BAR;
;             PG8_LDA(At, 0, 1); PG8_STAGE(PG8_SA(0, 0), a2);
;             PG8_BAR; PG8_WAIT_L(0); PG8_MMA(1, 0, At, B0); PG8_BAR; PG8_SCHED;
.LBB0_77:
	s_add_u32 s22, s20, 0x100
	s_addc_u32 s23, s21, 0
	s_add_i32 s43, 0, 0x10000
	v_add_u32_e32 v140, s43, v226
	ds_read_b128 v[128:131], v140
	ds_read_b128 v[132:135], v140 offset:1024
	ds_read_b128 v[136:139], v140 offset:2048
	ds_read_b128 v[140:143], v140 offset:3072
	s_cmp_eq_u32 s33, 32
	s_cselect_b32 s27, s9, s23
	s_cselect_b32 s26, s8, s22
	s_cselect_b32 s25, s11, s5
	s_cselect_b32 s24, s10, s4
	v_lshl_add_u64 v[214:215], s[20:21], 0, v[190:191]
	s_add_i32 m0, s34, 0xc000
	ds_read_b128 v[144:147], v228
	ds_read_b128 v[148:151], v228 offset:1024
	ds_read_b128 v[152:155], v228 offset:2048
	ds_read_b128 v[194:197], v228 offset:3072
	ds_read_b128 v[198:201], v228 offset:4096
	ds_read_b128 v[202:205], v228 offset:5120
	ds_read_b128 v[206:209], v228 offset:6144
	ds_read_b128 v[210:213], v228 offset:7168
	global_load_lds_dwordx4 v[214:215], off
	v_lshl_add_u64 v[214:215], s[20:21], 0, v[192:193]
	s_add_i32 m0, s34, 0xe000
	s_nop 0
	global_load_lds_dwordx4 v[214:215], off
	s_waitcnt lgkmcnt(8)
	s_barrier
	s_waitcnt lgkmcnt(0)
	s_setprio 1
	v_mfma_f32_16x16x32_bf16 v[124:127], v[128:131], v[144:147], v[124:127]
	v_mfma_f32_16x16x32_bf16 v[120:123], v[136:139], v[144:147], v[120:123]
	v_mfma_f32_16x16x32_bf16 v[116:119], v[128:131], v[152:155], v[116:119]
	v_mfma_f32_16x16x32_bf16 v[112:115], v[136:139], v[152:155], v[112:115]
	v_mfma_f32_16x16x32_bf16 v[108:111], v[128:131], v[198:201], v[108:111]
	v_mfma_f32_16x16x32_bf16 v[104:107], v[136:139], v[198:201], v[104:107]
	v_mfma_f32_16x16x32_bf16 v[100:103], v[128:131], v[206:209], v[100:103]
	v_mfma_f32_16x16x32_bf16 v[96:99], v[136:139], v[206:209], v[96:99]
	v_mfma_f32_16x16x32_bf16 v[124:127], v[132:135], v[148:151], v[124:127]
	v_mfma_f32_16x16x32_bf16 v[120:123], v[140:143], v[148:151], v[120:123]
	v_mfma_f32_16x16x32_bf16 v[116:119], v[132:135], v[194:197], v[116:119]
	v_mfma_f32_16x16x32_bf16 v[112:115], v[140:143], v[194:197], v[112:115]
	v_mfma_f32_16x16x32_bf16 v[108:111], v[132:135], v[202:205], v[108:111]
	v_mfma_f32_16x16x32_bf16 v[104:107], v[140:143], v[202:205], v[104:107]
	v_mfma_f32_16x16x32_bf16 v[100:103], v[132:135], v[210:213], v[100:103]
	v_mfma_f32_16x16x32_bf16 v[96:99], v[140:143], v[210:213], v[96:99]
	s_setprio 0
	s_barrier
	s_add_i32 s44, 0, 0x14000
	s_add_i32 s20, s43, s31
	v_add_u32_e32 v158, s44, v226
	v_lshl_add_u64 v[218:219], s[24:25], 0, v[188:189]
	s_mov_b32 m0, s20
	ds_read_b128 v[214:217], v158
	ds_read_b128 v[230:233], v158 offset:1024
	ds_read_b128 v[234:237], v158 offset:2048
	ds_read_b128 v[238:241], v158 offset:3072
	global_load_lds_dwordx4 v[218:219], off
	v_lshl_add_u64 v[220:221], s[24:25], 0, v[186:187]
	s_add_i32 m0, s20, 0x2000
	s_nop 0
	global_load_lds_dwordx4 v[220:221], off
	s_barrier
	s_waitcnt lgkmcnt(0)
	s_setprio 1
	v_mfma_f32_16x16x32_bf16 v[60:63], v[214:217], v[144:147], v[60:63]
	v_mfma_f32_16x16x32_bf16 v[56:59], v[234:237], v[144:147], v[56:59]
	v_mfma_f32_16x16x32_bf16 v[52:55], v[214:217], v[152:155], v[52:55]
	v_mfma_f32_16x16x32_bf16 v[48:51], v[234:237], v[152:155], v[48:51]
	v_mfma_f32_16x16x32_bf16 v[44:47], v[214:217], v[198:201], v[44:47]
	v_mfma_f32_16x16x32_bf16 v[40:43], v[234:237], v[198:201], v[40:43]
	v_mfma_f32_16x16x32_bf16 v[36:39], v[214:217], v[206:209], v[36:39]
	v_mfma_f32_16x16x32_bf16 v[32:35], v[234:237], v[206:209], v[32:35]
	v_mfma_f32_16x16x32_bf16 v[60:63], v[230:233], v[148:151], v[60:63]
	v_mfma_f32_16x16x32_bf16 v[56:59], v[238:241], v[148:151], v[56:59]
	v_mfma_f32_16x16x32_bf16 v[52:55], v[230:233], v[194:197], v[52:55]
	v_mfma_f32_16x16x32_bf16 v[48:51], v[238:241], v[194:197], v[48:51]
	v_mfma_f32_16x16x32_bf16 v[44:47], v[230:233], v[202:205], v[44:47]
	v_mfma_f32_16x16x32_bf16 v[40:43], v[238:241], v[202:205], v[40:43]
	v_mfma_f32_16x16x32_bf16 v[36:39], v[230:233], v[210:213], v[36:39]
	v_mfma_f32_16x16x32_bf16 v[32:35], v[238:241], v[210:213], v[32:35]
	s_setprio 0
	s_mov_b32 m0, s34
	v_lshl_add_u64 v[242:243], s[26:27], 0, v[188:189]
	s_barrier
	ds_read_b128 v[144:147], v228 offset:16384
	ds_read_b128 v[148:151], v228 offset:17408
	ds_read_b128 v[152:155], v228 offset:18432
	ds_read_b128 v[194:197], v228 offset:19456
	ds_read_b128 v[198:201], v228 offset:20480
	ds_read_b128 v[202:205], v228 offset:21504
	ds_read_b128 v[206:209], v228 offset:22528
	ds_read_b128 v[210:213], v228 offset:23552
	global_load_lds_dwordx4 v[242:243], off
	v_lshl_add_u64 v[244:245], s[26:27], 0, v[186:187]
	s_mov_b32 m0, s35
	s_nop 0
	global_load_lds_dwordx4 v[244:245], off
	s_barrier
	s_waitcnt lgkmcnt(0)
	s_setprio 1
	v_mfma_f32_16x16x32_bf16 v[92:95], v[128:131], v[144:147], v[92:95]
	v_mfma_f32_16x16x32_bf16 v[88:91], v[136:139], v[144:147], v[88:91]
	v_mfma_f32_16x16x32_bf16 v[84:87], v[128:131], v[152:155], v[84:87]
	v_mfma_f32_16x16x32_bf16 v[80:83], v[136:139], v[152:155], v[80:83]
	v_mfma_f32_16x16x32_bf16 v[76:79], v[128:131], v[198:201], v[76:79]
	v_mfma_f32_16x16x32_bf16 v[72:75], v[136:139], v[198:201], v[72:75]
	v_mfma_f32_16x16x32_bf16 v[68:71], v[128:131], v[206:209], v[68:71]
	v_mfma_f32_16x16x32_bf16 v[64:67], v[136:139], v[206:209], v[64:67]
	v_mfma_f32_16x16x32_bf16 v[92:95], v[132:135], v[148:151], v[92:95]
	v_mfma_f32_16x16x32_bf16 v[88:91], v[140:143], v[148:151], v[88:91]
	v_mfma_f32_16x16x32_bf16 v[84:87], v[132:135], v[194:197], v[84:87]
	v_mfma_f32_16x16x32_bf16 v[80:83], v[140:143], v[194:197], v[80:83]
	v_mfma_f32_16x16x32_bf16 v[76:79], v[132:135], v[202:205], v[76:79]
	v_mfma_f32_16x16x32_bf16 v[72:75], v[140:143], v[202:205], v[72:75]
	v_mfma_f32_16x16x32_bf16 v[68:71], v[132:135], v[210:213], v[68:71]
	v_mfma_f32_16x16x32_bf16 v[64:67], v[140:143], v[210:213], v[64:67]
	s_setprio 0
	s_barrier
; #define PG8_STAGE(bufoff, gbase) do { _Pragma("unroll") for (int _i = 0; _i < 2; ++_i) \
;         __builtin_amdgcn_global_load_lds((const unsigned*)((const char*)(gbase) + voff[_i]), (LAS unsigned*)(lds + (bufoff) + ldsw + _i * 8192), 16, 0, 0); } while (0)
; #define PG8_LDA(dst, b, h) do { _Pragma("unroll") for (int m = 0; m < 4; ++m) _Pragma("unroll") for (int k = 0; k < 2; ++k) dst[m][k] = *(const LAS bf16x8*)(lds + PG8_SA(b, h) + aoff + m * 2048 + k * 1024); } while (0)
; #define PG8_LDB(dst, b, h) do { _Pragma("unroll") for (int n = 0; n < 2; ++n) _Pragma("unroll") for (int k = 0; k < 2; ++k) dst[n][k] = *(const LAS bf16x8*)(lds + PG8_SB(b, h) + boff + n * 2048 + k * 1024); } while (0)
; #define PG8_MMA(ai, bj, At, Bt) do { __builtin_amdgcn_s_setprio(1); _Pragma("unroll") for (int m = 0; m < 4; ++m) _Pragma("unroll") for (int n = 0; n < 2; ++n) _Pragma("unroll") for (int k = 0; k < 2; ++k) \
;         acc[ai][bj][m][n] = __builtin_amdgcn_mfma_f32_16x16x32_bf16(Bt[n][k], At[m][k], acc[ai][bj][m][n], 0, 0, 0); __builtin_amdgcn_s_setprio(0); } while (0)
; #define PG8_WAIT_V(n) asm volatile("s_waitcnt vmcnt(" #n ")" ::: "memory")
; #define PG8_WAIT_L(n) asm volatile("s_waitcnt lgkmcnt(" #n ")" ::: "memory")
; #define PG8_BAR __builtin_amdgcn_s_barrier()
; #define PG8_SCHED __builtin_amdgcn_sched_barrier(0)
; template <class Epi>
; DI void gemm_phase(LAS unsigned char* lds, const Gemm g, const StaticOrder& S, const Epi& E) {
;     ...
;             PG8_STAGE(PG8_SB(0, 1), b2 + hstep);
;             PG8_WAIT_V(6); PG8_BAR; PG8_MMA(1, 1, At, B1); PG8_BAR;
;             PG8_LDB(B0, 1, 0); PG8_SCHED; PG8_LDA(At, 1, 0); PG8_STAGE(PG8_SA(0, 1), a2 + hstep);
;             PG8_WAIT_L(8); PG8_BAR; PG8_WAIT_L(0); PG8_MMA(0, 0, At, B0); PG8_BAR; PG8_SCHED;
;             PG8_LDB(B1, 1, 1); PG8_STAGE(PG8_SB(1, 0), b3);
;             PG8_BAR; PG8_WAIT_L(0); PG8_MMA(0, 1, At, B1); PG8_BAR;
;             PG8_LDA(At, 1, 1); PG8_STAGE(PG8_SA(1, 0), a3);
;             PG8_BAR; PG8_WAIT_L(0); PG8_MMA(1, 0, At, B0); PG8_BAR; PG8_SCHED;
	s_add_u32 s20, s24, 0x90000
	s_addc_u32 s21, s25, 0
	s_add_i32 s43, s44, s31
	v_lshl_add_u64 v[128:129], s[20:21], 0, v[188:189]
	s_mov_b32 m0, s43
	s_nop 0
	global_load_lds_dwordx4 v[128:129], off
	v_lshl_add_u64 v[128:129], s[20:21], 0, v[186:187]
	s_add_i32 m0, s43, 0x2000
	s_nop 0
	global_load_lds_dwordx4 v[128:129], off
	s_waitcnt vmcnt(6)
	s_barrier
	s_setprio 1
	v_mfma_f32_16x16x32_bf16 v[28:31], v[214:217], v[144:147], v[28:31]
	v_mfma_f32_16x16x32_bf16 v[24:27], v[234:237], v[144:147], v[24:27]
	v_mfma_f32_16x16x32_bf16 v[20:23], v[214:217], v[152:155], v[20:23]
	v_mfma_f32_16x16x32_bf16 v[16:19], v[234:237], v[152:155], v[16:19]
	v_mfma_f32_16x16x32_bf16 v[12:15], v[214:217], v[198:201], v[12:15]
	v_mfma_f32_16x16x32_bf16 v[8:11], v[234:237], v[198:201], v[8:11]
	v_mfma_f32_16x16x32_bf16 v[4:7], v[214:217], v[206:209], v[4:7]
	v_mfma_f32_16x16x32_bf16 v[0:3], v[234:237], v[206:209], v[0:3]
	v_mfma_f32_16x16x32_bf16 v[28:31], v[230:233], v[148:151], v[28:31]
	v_mfma_f32_16x16x32_bf16 v[24:27], v[238:241], v[148:151], v[24:27]
	v_mfma_f32_16x16x32_bf16 v[20:23], v[230:233], v[194:197], v[20:23]
	v_mfma_f32_16x16x32_bf16 v[16:19], v[238:241], v[194:197], v[16:19]
	v_mfma_f32_16x16x32_bf16 v[12:15], v[230:233], v[202:205], v[12:15]
	v_mfma_f32_16x16x32_bf16 v[8:11], v[238:241], v[202:205], v[8:11]
	v_mfma_f32_16x16x32_bf16 v[4:7], v[230:233], v[210:213], v[4:7]
	v_mfma_f32_16x16x32_bf16 v[0:3], v[238:241], v[210:213], v[0:3]
	s_setprio 0
	s_add_i32 s43, 0, 0x18000
	v_add_u32_e32 v140, s43, v226
	s_barrier
	ds_read_b128 v[128:131], v140
	ds_read_b128 v[132:135], v140 offset:1024
	ds_read_b128 v[136:139], v140 offset:2048
	ds_read_b128 v[140:143], v140 offset:3072
	s_add_u32 s20, s26, 0x90000
	s_addc_u32 s21, s27, 0
	s_mov_b32 m0, s36
	v_lshl_add_u64 v[214:215], s[20:21], 0, v[188:189]
	ds_read_b128 v[144:147], v228 offset:32768
	ds_read_b128 v[148:151], v228 offset:33792
	ds_read_b128 v[152:155], v228 offset:34816
	ds_read_b128 v[194:197], v228 offset:35840
	ds_read_b128 v[198:201], v228 offset:36864
	ds_read_b128 v[202:205], v228 offset:37888
	ds_read_b128 v[206:209], v228 offset:38912
	ds_read_b128 v[210:213], v228 offset:39936
	global_load_lds_dwordx4 v[214:215], off
	v_lshl_add_u64 v[214:215], s[20:21], 0, v[186:187]
	s_mov_b32 m0, s37
	s_nop 0
	global_load_lds_dwordx4 v[214:215], off
	s_waitcnt lgkmcnt(8)
	s_barrier
	s_waitcnt lgkmcnt(0)
	s_setprio 1
	v_mfma_f32_16x16x32_bf16 v[124:127], v[128:131], v[144:147], v[124:127]
	v_mfma_f32_16x16x32_bf16 v[120:123], v[136:139], v[144:147], v[120:123]
	v_mfma_f32_16x16x32_bf16 v[116:119], v[128:131], v[152:155], v[116:119]
	v_mfma_f32_16x16x32_bf16 v[112:115], v[136:139], v[152:155], v[112:115]
	v_mfma_f32_16x16x32_bf16 v[108:111], v[128:131], v[198:201], v[108:111]
	v_mfma_f32_16x16x32_bf16 v[104:107], v[136:139], v[198:201], v[104:107]
	v_mfma_f32_16x16x32_bf16 v[100:103], v[128:131], v[206:209], v[100:103]
	v_mfma_f32_16x16x32_bf16 v[96:99], v[136:139], v[206:209], v[96:99]
	v_mfma_f32_16x16x32_bf16 v[124:127], v[132:135], v[148:151], v[124:127]
	v_mfma_f32_16x16x32_bf16 v[120:123], v[140:143], v[148:151], v[120:123]
	v_mfma_f32_16x16x32_bf16 v[116:119], v[132:135], v[194:197], v[116:119]
	v_mfma_f32_16x16x32_bf16 v[112:115], v[140:143], v[194:197], v[112:115]
	v_mfma_f32_16x16x32_bf16 v[108:111], v[132:135], v[202:205], v[108:111]
	v_mfma_f32_16x16x32_bf16 v[104:107], v[140:143], v[202:205], v[104:107]
	v_mfma_f32_16x16x32_bf16 v[100:103], v[132:135], v[210:213], v[100:103]
	v_mfma_f32_16x16x32_bf16 v[96:99], v[140:143], v[210:213], v[96:99]
	s_setprio 0
	s_barrier
	s_add_i32 s26, 0, 0x1c000
	s_add_i32 s20, s43, s31
	v_add_u32_e32 v158, s26, v226
	v_lshl_add_u64 v[218:219], v[218:219], 0, s[94:95]
	s_mov_b32 m0, s20
	ds_read_b128 v[214:217], v158
	ds_read_b128 v[230:233], v158 offset:1024
	ds_read_b128 v[234:237], v158 offset:2048
	ds_read_b128 v[238:241], v158 offset:3072
	global_load_lds_dwordx4 v[218:219], off
	v_lshl_add_u64 v[218:219], v[220:221], 0, s[94:95]
	s_add_i32 m0, s20, 0x2000
	s_nop 0
	global_load_lds_dwordx4 v[218:219], off
	s_barrier
	s_waitcnt lgkmcnt(0)
	s_setprio 1
	v_mfma_f32_16x16x32_bf16 v[60:63], v[214:217], v[144:147], v[60:63]
	v_mfma_f32_16x16x32_bf16 v[56:59], v[234:237], v[144:147], v[56:59]
	v_mfma_f32_16x16x32_bf16 v[52:55], v[214:217], v[152:155], v[52:55]
	v_mfma_f32_16x16x32_bf16 v[48:51], v[234:237], v[152:155], v[48:51]
	v_mfma_f32_16x16x32_bf16 v[44:47], v[214:217], v[198:201], v[44:47]
	v_mfma_f32_16x16x32_bf16 v[40:43], v[234:237], v[198:201], v[40:43]
	v_mfma_f32_16x16x32_bf16 v[36:39], v[214:217], v[206:209], v[36:39]
	v_mfma_f32_16x16x32_bf16 v[32:35], v[234:237], v[206:209], v[32:35]
	v_mfma_f32_16x16x32_bf16 v[60:63], v[230:233], v[148:151], v[60:63]
	v_mfma_f32_16x16x32_bf16 v[56:59], v[238:241], v[148:151], v[56:59]
	v_mfma_f32_16x16x32_bf16 v[52:55], v[230:233], v[194:197], v[52:55]
	v_mfma_f32_16x16x32_bf16 v[48:51], v[238:241], v[194:197], v[48:51]
	v_mfma_f32_16x16x32_bf16 v[44:47], v[230:233], v[202:205], v[44:47]
	v_mfma_f32_16x16x32_bf16 v[40:43], v[238:241], v[202:205], v[40:43]
	v_mfma_f32_16x16x32_bf16 v[36:39], v[230:233], v[210:213], v[36:39]
	v_mfma_f32_16x16x32_bf16 v[32:35], v[238:241], v[210:213], v[32:35]
	s_setprio 0
	s_mov_b32 m0, s38
	v_lshl_add_u64 v[218:219], v[242:243], 0, s[94:95]
	s_barrier
	ds_read_b128 v[144:147], v228 offset:49152
	ds_read_b128 v[148:151], v228 offset:50176
	ds_read_b128 v[152:155], v228 offset:51200
	ds_read_b128 v[194:197], v228 offset:52224
	ds_read_b128 v[198:201], v228 offset:53248
	ds_read_b128 v[202:205], v228 offset:54272
	ds_read_b128 v[206:209], v228 offset:55296
	ds_read_b128 v[210:213], v228 offset:56320
	global_load_lds_dwordx4 v[218:219], off
	v_lshl_add_u64 v[218:219], v[244:245], 0, s[94:95]
	s_mov_b32 m0, s39
	s_nop 0
	global_load_lds_dwordx4 v[218:219], off
	s_barrier
; #define PG8_WAIT_V(n) asm volatile("s_waitcnt vmcnt(" #n ")" ::: "memory")
; #define PG8_WAIT_L(n) asm volatile("s_waitcnt lgkmcnt(" #n ")" ::: "memory")
; #define PG8_BAR __builtin_amdgcn_s_barrier()
; template <class Epi>
; DI void gemm_phase(LAS unsigned char* lds, const Gemm g, const StaticOrder& S, const Epi& E) {
;     ...
;             PG8_BAR; PG8_WAIT_L(0); PG8_MMA(1, 0, At, B0); PG8_BAR; PG8_SCHED;
;             PG8_STAGE(PG8_SB(1, 1), b3 + hstep);
;             PG8_WAIT_V(6); PG8_BAR; PG8_MMA(1, 1, At, B1); PG8_BAR;
;         }
;     template <bool LN, int BJ, int LO, int HI> DI void batch(const f32x4 (&acc)[2][2][4][2], unsigned row0, unsigned col0, const f32x4 (&gv)[2], const f32x4 (&bv)[2]) const {
;         f32x4 r[HI - LO]; float mean[(HI - LO) / 2], rstd[(HI - LO) / 2];
; #pragma unroll
;         for (int i = LO; i < HI; ++i) { const int ai = i >> 3, m = (i >> 1) & 3, n = i & 1; const unsigned row = row0 + ai * HALF + m * 16;
;             if (n == 0) { mean[(i - LO) >> 1] = 0.f; rstd[(i - LO) >> 1] = 1.f;
;                 if (LN) { const float2 st = *(const float2*)(stats + row * 2u); mean[(i - LO) >> 1] = st.x; rstd[(i - LO) >> 1] = st.y; } }
;             r[i - LO] = *(const f32x4*)(src + (row * (unsigned)DM + col0 + BJ * HALF + n * 16)); }
; #pragma unroll
;         for (int i = LO; i < HI; ++i) { const int ai = i >> 3, m = (i >> 1) & 3, n = i & 1; const unsigned row = row0 + ai * HALF + m * 16;
;             *(f32x4*)(Y + (row * (unsigned)DM + col0 + BJ * HALF + n * 16)) = acc[ai][BJ][m][n] + ((r[i - LO] - mean[(i - LO) >> 1]) * rstd[(i - LO) >> 1]) * gv[n] + bv[n]; }
;         __builtin_amdgcn_sched_barrier(0);
;     }
;     template <bool LN, int BJ> DI void load_gb(unsigned col0, f32x4 (&gv)[2], f32x4 (&bv)[2]) const {
; #pragma unroll
;         for (int n = 0; n < 2; ++n) {
;             if (LN) { gv[n] = *(const f32x4*)(gam + col0 + BJ * HALF + n * 16) * ALPHA; bv[n] = *(const f32x4*)(bet + col0 + BJ * HALF + n * 16) * ALPHA; }
;             else { gv[n] = (f32x4){ALPHA, ALPHA, ALPHA, ALPHA}; bv[n] = (f32x4){0.f, 0.f, 0.f, 0.f}; }
;         }
;     }
;     template <bool LN> DI void run(const f32x4 (&acc)[2][2][4][2], const Unit& u, int wr, int wc, int fr, int fq) const {
;         const unsigned row0 = u.pm * BM + wr * 64 + fr, col0 = u.pn * BM + wc * 32 + 4 * fq;
;         f32x4 gv[2], bv[2];
;         load_gb<LN, 0>(col0, gv, bv);
	s_waitcnt lgkmcnt(0)
	s_setprio 1
	v_mfma_f32_16x16x32_bf16 v[92:95], v[128:131], v[144:147], v[92:95]
	v_mfma_f32_16x16x32_bf16 v[88:91], v[136:139], v[144:147], v[88:91]
	v_mfma_f32_16x16x32_bf16 v[84:87], v[128:131], v[152:155], v[84:87]
	v_mfma_f32_16x16x32_bf16 v[80:83], v[136:139], v[152:155], v[80:83]
	v_mfma_f32_16x16x32_bf16 v[76:79], v[128:131], v[198:201], v[76:79]
	v_mfma_f32_16x16x32_bf16 v[72:75], v[136:139], v[198:201], v[72:75]
	v_mfma_f32_16x16x32_bf16 v[68:71], v[128:131], v[206:209], v[68:71]
	v_mfma_f32_16x16x32_bf16 v[64:67], v[136:139], v[206:209], v[64:67]
	v_mfma_f32_16x16x32_bf16 v[92:95], v[132:135], v[148:151], v[92:95]
	v_mfma_f32_16x16x32_bf16 v[88:91], v[140:143], v[148:151], v[88:91]
	v_mfma_f32_16x16x32_bf16 v[84:87], v[132:135], v[194:197], v[84:87]
	v_mfma_f32_16x16x32_bf16 v[80:83], v[140:143], v[194:197], v[80:83]
	v_mfma_f32_16x16x32_bf16 v[76:79], v[132:135], v[202:205], v[76:79]
	v_mfma_f32_16x16x32_bf16 v[72:75], v[140:143], v[202:205], v[72:75]
	v_mfma_f32_16x16x32_bf16 v[68:71], v[132:135], v[210:213], v[68:71]
	v_mfma_f32_16x16x32_bf16 v[64:67], v[140:143], v[210:213], v[64:67]
	s_setprio 0
	s_barrier
	s_add_u32 s20, s24, 0x90080
	s_addc_u32 s21, s25, 0
	s_add_i32 s24, s26, s31
	v_lshl_add_u64 v[128:129], s[20:21], 0, v[188:189]
	s_mov_b32 m0, s24
	s_nop 0
	global_load_lds_dwordx4 v[128:129], off
	v_lshl_add_u64 v[128:129], s[20:21], 0, v[186:187]
	s_add_i32 m0, s24, 0x2000
	s_nop 0
	global_load_lds_dwordx4 v[128:129], off
	s_waitcnt vmcnt(6)
	s_barrier
	s_setprio 1
	v_mfma_f32_16x16x32_bf16 v[28:31], v[214:217], v[144:147], v[28:31]
	v_mfma_f32_16x16x32_bf16 v[24:27], v[234:237], v[144:147], v[24:27]
	v_mfma_f32_16x16x32_bf16 v[20:23], v[214:217], v[152:155], v[20:23]
	v_mfma_f32_16x16x32_bf16 v[16:19], v[234:237], v[152:155], v[16:19]
	v_mfma_f32_16x16x32_bf16 v[12:15], v[214:217], v[198:201], v[12:15]
	v_mfma_f32_16x16x32_bf16 v[8:11], v[234:237], v[198:201], v[8:11]
	v_mfma_f32_16x16x32_bf16 v[4:7], v[214:217], v[206:209], v[4:7]
	v_mfma_f32_16x16x32_bf16 v[0:3], v[234:237], v[206:209], v[0:3]
	v_mfma_f32_16x16x32_bf16 v[28:31], v[230:233], v[148:151], v[28:31]
	v_mfma_f32_16x16x32_bf16 v[24:27], v[238:241], v[148:151], v[24:27]
	v_mfma_f32_16x16x32_bf16 v[20:23], v[230:233], v[194:197], v[20:23]
	v_mfma_f32_16x16x32_bf16 v[16:19], v[238:241], v[194:197], v[16:19]
	v_mfma_f32_16x16x32_bf16 v[12:15], v[230:233], v[202:205], v[12:15]
	v_mfma_f32_16x16x32_bf16 v[8:11], v[238:241], v[202:205], v[8:11]
	v_mfma_f32_16x16x32_bf16 v[4:7], v[230:233], v[210:213], v[4:7]
	v_mfma_f32_16x16x32_bf16 v[0:3], v[238:241], v[210:213], v[0:3]
	s_setprio 0
	s_add_i32 s33, s33, 2
	s_add_u32 s4, s4, 0x100
	s_addc_u32 s5, s5, 0
	s_cmp_gt_u32 s33, 33
	s_mov_b64 s[20:21], s[22:23]
	s_barrier
	s_cbranch_scc0 .LBB0_77
	v_lshl_add_u32 v206, s3, 8, v225
	v_lshl_or_b32 v158, s2, 8, v227
	v_lshlrev_b32_e32 v232, 11, v206
	s_andn2_b64 vcc, exec, s[14:15]
	v_or_b32_e32 v231, 16, v158
	v_add_u32_e32 v194, v232, v158
	v_or_b32_e32 v230, 0x80, v158
	v_or_b32_e32 v229, 0x90, v158
	s_cbranch_vccnz .LBB0_80
	v_lshlrev_b64 v[132:133], 2, v[158:159]
	v_lshl_add_u64 v[140:141], s[16:17], 0, v[132:133]
	global_load_dwordx4 v[128:131], v[140:141], off
	v_lshl_add_u64 v[142:143], s[18:19], 0, v[132:133]
	v_readlane_b32 s2, v253, 8
	v_mov_b32_e32 v195, v159
	v_lshlrev_b32_e32 v136, 1, v206
	v_mov_b32_e32 v137, v159
	v_readlane_b32 s3, v253, 9
	v_lshlrev_b64 v[212:213], 2, v[194:195]
	v_add_u32_e32 v146, v232, v231
	v_lshl_add_u64 v[144:145], v[136:137], 2, s[2:3]
	v_lshl_add_u64 v[136:137], s[88:89], 0, v[212:213]
	v_mov_b32_e32 v147, v159
	v_lshl_add_u64 v[146:147], v[146:147], 2, s[88:89]
	v_or_b32_e32 v195, 16, v206
	v_mov_b32_e32 v201, v159
	v_mov_b32_e32 v209, v159
	v_lshl_add_u64 v[212:213], s[90:91], 0, v[212:213]
	s_waitcnt vmcnt(0)
	v_pk_mul_f32 v[152:153], v[130:131], s[78:79] op_sel_hi:[1,0]
	v_pk_mul_f32 v[154:155], v[128:129], s[78:79] op_sel_hi:[1,0]
	global_load_dwordx4 v[132:135], v[142:143], off
	global_load_dwordx4 v[128:131], v[140:141], off offset:64
	global_load_dwordx2 v[204:205], v[144:145], off
	global_load_dwordx4 v[196:199], v[146:147], off
	v_lshlrev_b32_e32 v146, 1, v195
	global_load_dwordx4 v[136:139], v[136:137], off
	v_lshlrev_b32_e32 v195, 11, v195
	v_mov_b32_e32 v147, v159
	v_add_u32_e32 v200, v195, v158
	v_lshl_add_u64 v[146:147], v[146:147], 2, s[2:3]
	v_lshl_add_u64 v[200:201], v[200:201], 2, s[88:89]
	global_load_dwordx2 v[214:215], v[146:147], off
	v_add_u32_e32 v208, v195, v231
	global_load_dwordx4 v[200:203], v[200:201], off
	v_lshl_add_u64 v[208:209], v[208:209], 2, s[88:89]
	global_load_dwordx4 v[208:211], v[208:209], off
	s_waitcnt vmcnt(0)
	v_pk_mul_f32 v[148:149], v[130:131], s[78:79] op_sel_hi:[1,0]
	v_pk_mul_f32 v[150:151], v[128:129], s[78:79] op_sel_hi:[1,0]
	global_load_dwordx4 v[128:131], v[142:143], off offset:64
	v_sub_f32_e32 v137, v137, v204
	v_sub_f32_e32 v136, v136, v204
	v_sub_f32_e32 v139, v139, v204
	v_sub_f32_e32 v138, v138, v204
	v_pk_mul_f32 v[138:139], v[204:205], v[138:139] op_sel:[1,0]
	v_pk_mul_f32 v[136:137], v[204:205], v[136:137] op_sel:[1,0]
	v_pk_fma_f32 v[138:139], v[152:153], v[138:139], v[126:127]
	v_pk_fma_f32 v[136:137], v[154:155], v[136:137], v[124:125]
	v_pk_fma_f32 v[138:139], v[134:135], s[78:79], v[138:139] op_sel_hi:[1,0,1]
	v_pk_fma_f32 v[136:137], v[132:133], s[78:79], v[136:137] op_sel_hi:[1,0,1]
	global_store_dwordx4 v[212:213], v[136:139], off
	s_nop 1
	v_sub_f32_e32 v137, v197, v204
	v_sub_f32_e32 v136, v196, v204
	v_sub_f32_e32 v139, v199, v204
	v_sub_f32_e32 v138, v198, v204
	v_pk_mul_f32 v[138:139], v[204:205], v[138:139] op_sel:[1,0]
	v_pk_mul_f32 v[136:137], v[204:205], v[136:137] op_sel:[1,0]
	v_pk_fma_f32 v[138:139], v[148:149], v[138:139], v[122:123]
	v_pk_fma_f32 v[136:137], v[150:151], v[136:137], v[120:121]
	v_or_b32_e32 v196, 16, v194
	v_mov_b32_e32 v197, v159
	v_lshl_add_u64 v[196:197], v[196:197], 2, s[90:91]
	s_waitcnt vmcnt(0)
;     template <bool LN, int BJ, int LO, int HI> DI void batch(const f32x4 (&acc)[2][2][4][2], unsigned row0, unsigned col0, const f32x4 (&gv)[2], const f32x4 (&bv)[2]) const {
;         f32x4 r[HI - LO]; float mean[(HI - LO) / 2], rstd[(HI - LO) / 2];
; #pragma unroll
;         for (int i = LO; i < HI; ++i) { const int ai = i >> 3, m = (i >> 1) & 3, n = i & 1; const unsigned row = row0 + ai * HALF + m * 16;
;             if (n == 0) { mean[(i - LO) >> 1] = 0.f; rstd[(i - LO) >> 1] = 1.f;
;                 if (LN) { const float2 st = *(const float2*)(stats + row * 2u); mean[(i - LO) >> 1] = st.x; rstd[(i - LO) >> 1] = st.y; } }
;             r[i - LO] = *(const f32x4*)(src + (row * (unsigned)DM + col0 + BJ * HALF + n * 16)); }
; #pragma unroll
;         for (int i = LO; i < HI; ++i) { const int ai = i >> 3, m = (i >> 1) & 3, n = i & 1; const unsigned row = row0 + ai * HALF + m * 16;
;             *(f32x4*)(Y + (row * (unsigned)DM + col0 + BJ * HALF + n * 16)) = acc[ai][BJ][m][n] + ((r[i - LO] - mean[(i - LO) >> 1]) * rstd[(i - LO) >> 1]) * gv[n] + bv[n]; }
;         __builtin_amdgcn_sched_barrier(0);
;     }
;     template <bool LN, int BJ> DI void load_gb(unsigned col0, f32x4 (&gv)[2], f32x4 (&bv)[2]) const {
; #pragma unroll
;         for (int n = 0; n < 2; ++n) {
;             if (LN) { gv[n] = *(const f32x4*)(gam + col0 + BJ * HALF + n * 16) * ALPHA; bv[n] = *(const f32x4*)(bet + col0 + BJ * HALF + n * 16) * ALPHA; }
;             else { gv[n] = (f32x4){ALPHA, ALPHA, ALPHA, ALPHA}; bv[n] = (f32x4){0.f, 0.f, 0.f, 0.f}; }
;         }
;     }
;     template <bool LN> DI void run(const f32x4 (&acc)[2][2][4][2], const Unit& u, int wr, int wc, int fr, int fq) const {
;         const unsigned row0 = u.pm * BM + wr * 64 + fr, col0 = u.pn * BM + wc * 32 + 4 * fq;
;         f32x4 gv[2], bv[2];
;         load_gb<LN, 0>(col0, gv, bv);
;         batch<LN, 0, 0, 4>(acc, row0, col0, gv, bv);
;         batch<LN, 0, 4, 8>(acc, row0, col0, gv, bv);
;         batch<LN, 0, 8, 12>(acc, row0, col0, gv, bv);
;         batch<LN, 0, 12, 16>(acc, row0, col0, gv, bv);
;         load_gb<LN, 1>(col0, gv, bv);
;         batch<LN, 1, 0, 8>(acc, row0, col0, gv, bv);
;         batch<LN, 1, 8, 16>(acc, row0, col0, gv, bv);
	v_pk_fma_f32 v[138:139], v[130:131], s[78:79], v[138:139] op_sel_hi:[1,0,1]
	v_pk_fma_f32 v[136:137], v[128:129], s[78:79], v[136:137] op_sel_hi:[1,0,1]
	global_store_dwordx4 v[196:197], v[136:139], off
	v_add_u32_e32 v196, 0x8000, v194
	v_mov_b32_e32 v197, v159
	v_sub_f32_e32 v137, v201, v214
	v_sub_f32_e32 v136, v200, v214
	v_sub_f32_e32 v139, v203, v214
	v_sub_f32_e32 v138, v202, v214
	v_pk_mul_f32 v[138:139], v[214:215], v[138:139] op_sel:[1,0]
	v_pk_mul_f32 v[136:137], v[214:215], v[136:137] op_sel:[1,0]
	v_pk_fma_f32 v[138:139], v[152:153], v[138:139], v[118:119]
	v_pk_fma_f32 v[136:137], v[154:155], v[136:137], v[116:117]
	v_pk_fma_f32 v[138:139], v[134:135], s[78:79], v[138:139] op_sel_hi:[1,0,1]
	v_pk_fma_f32 v[136:137], v[132:133], s[78:79], v[136:137] op_sel_hi:[1,0,1]
	v_lshl_add_u64 v[196:197], v[196:197], 2, s[90:91]
	global_store_dwordx4 v[196:197], v[136:139], off
	v_add_u32_e32 v196, 0x8010, v194
	v_mov_b32_e32 v197, v159
	v_sub_f32_e32 v137, v209, v214
	v_sub_f32_e32 v136, v208, v214
	v_sub_f32_e32 v139, v211, v214
	v_sub_f32_e32 v138, v210, v214
	v_pk_mul_f32 v[138:139], v[214:215], v[138:139] op_sel:[1,0]
	v_pk_mul_f32 v[136:137], v[214:215], v[136:137] op_sel:[1,0]
	v_pk_fma_f32 v[138:139], v[148:149], v[138:139], v[114:115]
	v_pk_fma_f32 v[136:137], v[150:151], v[136:137], v[112:113]
	v_pk_fma_f32 v[138:139], v[130:131], s[78:79], v[138:139] op_sel_hi:[1,0,1]
	v_pk_fma_f32 v[136:137], v[128:129], s[78:79], v[136:137] op_sel_hi:[1,0,1]
	v_lshl_add_u64 v[196:197], v[196:197], 2, s[90:91]
	global_store_dwordx4 v[196:197], v[136:139], off
	s_nop 1
	v_or_b32_e32 v138, 32, v206
	v_lshlrev_b32_e32 v136, 1, v138
	v_mov_b32_e32 v137, v159
	v_lshlrev_b32_e32 v236, 11, v138
	v_lshl_add_u64 v[200:201], v[136:137], 2, s[2:3]
	v_add_u32_e32 v136, v236, v158
	v_lshl_add_u64 v[136:137], v[136:137], 2, s[88:89]
	global_load_dwordx2 v[204:205], v[200:201], off
	v_add_u32_e32 v196, v236, v231
	global_load_dwordx4 v[136:139], v[136:137], off
	v_mov_b32_e32 v197, v159
	v_lshl_add_u64 v[196:197], v[196:197], 2, s[88:89]
	global_load_dwordx4 v[196:199], v[196:197], off
	v_or_b32_e32 v207, 48, v206
	v_lshlrev_b32_e32 v235, 11, v207
	v_lshlrev_b32_e32 v202, 1, v207
	v_mov_b32_e32 v203, v159
	v_add_u32_e32 v208, v235, v158
	v_mov_b32_e32 v209, v159
	v_lshl_add_u64 v[202:203], v[202:203], 2, s[2:3]
	v_lshl_add_u64 v[208:209], v[208:209], 2, s[88:89]
	global_load_dwordx2 v[216:217], v[202:203], off
	v_add_u32_e32 v212, v235, v231
	global_load_dwordx4 v[208:211], v[208:209], off
	v_mov_b32_e32 v213, v159
	v_lshl_add_u64 v[212:213], v[212:213], 2, s[88:89]
	global_load_dwordx4 v[212:215], v[212:213], off
	v_add_u32_e32 v218, 0x10000, v194
	v_mov_b32_e32 v219, v159
	v_lshl_add_u64 v[218:219], v[218:219], 2, s[90:91]
	s_waitcnt vmcnt(0)
	v_sub_f32_e32 v137, v137, v204
	v_sub_f32_e32 v136, v136, v204
	v_sub_f32_e32 v139, v139, v204
	v_sub_f32_e32 v138, v138, v204
	v_pk_mul_f32 v[138:139], v[204:205], v[138:139] op_sel:[1,0]
	v_pk_mul_f32 v[136:137], v[204:205], v[136:137] op_sel:[1,0]
	v_pk_fma_f32 v[138:139], v[152:153], v[138:139], v[110:111]
	v_pk_fma_f32 v[136:137], v[154:155], v[136:137], v[108:109]
	v_pk_fma_f32 v[138:139], v[134:135], s[78:79], v[138:139] op_sel_hi:[1,0,1]
	v_pk_fma_f32 v[136:137], v[132:133], s[78:79], v[136:137] op_sel_hi:[1,0,1]
	global_store_dwordx4 v[218:219], v[136:139], off
	s_nop 1
	v_sub_f32_e32 v137, v197, v204
	v_sub_f32_e32 v136, v196, v204
	v_sub_f32_e32 v139, v199, v204
	v_sub_f32_e32 v138, v198, v204
	v_pk_mul_f32 v[138:139], v[204:205], v[138:139] op_sel:[1,0]
	v_pk_mul_f32 v[136:137], v[204:205], v[136:137] op_sel:[1,0]
	v_pk_fma_f32 v[138:139], v[148:149], v[138:139], v[106:107]
	v_pk_fma_f32 v[136:137], v[150:151], v[136:137], v[104:105]
	v_add_u32_e32 v196, 0x10010, v194
	v_mov_b32_e32 v197, v159
	v_pk_fma_f32 v[138:139], v[130:131], s[78:79], v[138:139] op_sel_hi:[1,0,1]
	v_pk_fma_f32 v[136:137], v[128:129], s[78:79], v[136:137] op_sel_hi:[1,0,1]
	v_lshl_add_u64 v[196:197], v[196:197], 2, s[90:91]
	global_store_dwordx4 v[196:197], v[136:139], off
	v_add_u32_e32 v196, 0x18000, v194
	v_mov_b32_e32 v197, v159
	v_sub_f32_e32 v137, v209, v216
	v_sub_f32_e32 v136, v208, v216
	v_sub_f32_e32 v139, v211, v216
	v_sub_f32_e32 v138, v210, v216
	v_pk_mul_f32 v[138:139], v[216:217], v[138:139] op_sel:[1,0]
	v_pk_mul_f32 v[136:137], v[216:217], v[136:137] op_sel:[1,0]
	v_pk_fma_f32 v[138:139], v[152:153], v[138:139], v[102:103]
	v_pk_fma_f32 v[136:137], v[154:155], v[136:137], v[100:101]
	v_pk_fma_f32 v[138:139], v[134:135], s[78:79], v[138:139] op_sel_hi:[1,0,1]
	v_pk_fma_f32 v[136:137], v[132:133], s[78:79], v[136:137] op_sel_hi:[1,0,1]
	v_lshl_add_u64 v[196:197], v[196:197], 2, s[90:91]
	global_store_dwordx4 v[196:197], v[136:139], off
	v_add_u32_e32 v196, 0x18010, v194
	v_mov_b32_e32 v197, v159
	v_sub_f32_e32 v137, v213, v216
	v_sub_f32_e32 v136, v212, v216
	v_sub_f32_e32 v139, v215, v216
	v_sub_f32_e32 v138, v214, v216
	v_pk_mul_f32 v[138:139], v[216:217], v[138:139] op_sel:[1,0]
	v_pk_mul_f32 v[136:137], v[216:217], v[136:137] op_sel:[1,0]
	v_pk_fma_f32 v[138:139], v[148:149], v[138:139], v[98:99]
	v_pk_fma_f32 v[136:137], v[150:151], v[136:137], v[96:97]
	v_pk_fma_f32 v[138:139], v[130:131], s[78:79], v[138:139] op_sel_hi:[1,0,1]
	v_pk_fma_f32 v[136:137], v[128:129], s[78:79], v[136:137] op_sel_hi:[1,0,1]
	v_lshl_add_u64 v[196:197], v[196:197], 2, s[90:91]
	global_store_dwordx4 v[196:197], v[136:139], off
	s_nop 1
	v_add_u32_e32 v138, 0x80, v206
	v_lshlrev_b32_e32 v136, 1, v138
	v_mov_b32_e32 v137, v159
	v_lshlrev_b32_e32 v233, 11, v138
	v_lshl_add_u64 v[196:197], v[136:137], 2, s[2:3]
	v_add_u32_e32 v136, v233, v158
	v_lshl_add_u64 v[136:137], v[136:137], 2, s[88:89]
	global_load_dwordx2 v[204:205], v[196:197], off
	v_add_u32_e32 v198, v233, v231
	global_load_dwordx4 v[136:139], v[136:137], off
	v_mov_b32_e32 v199, v159
	v_add_u32_e32 v207, 0x90, v206
	v_lshl_add_u64 v[198:199], v[198:199], 2, s[88:89]
	v_lshlrev_b32_e32 v234, 11, v207
	global_load_dwordx4 v[208:211], v[198:199], off
	v_add_u32_e32 v212, v234, v158
	v_mov_b32_e32 v213, v159
	v_lshl_add_u64 v[212:213], v[212:213], 2, s[88:89]
	global_load_dwordx4 v[212:215], v[212:213], off
	v_lshlrev_b32_e32 v198, 1, v207
	v_mov_b32_e32 v199, v159
	v_lshl_add_u64 v[198:199], v[198:199], 2, s[2:3]
	global_load_dwordx2 v[220:221], v[198:199], off
	v_add_u32_e32 v216, v234, v231
	v_mov_b32_e32 v217, v159
	v_lshl_add_u64 v[216:217], v[216:217], 2, s[88:89]
	global_load_dwordx4 v[216:219], v[216:217], off
	v_add_u32_e32 v238, 0x40000, v194
	v_mov_b32_e32 v239, v159
	v_lshl_add_u64 v[238:239], v[238:239], 2, s[90:91]
	s_waitcnt vmcnt(0)
;     template <bool LN, int BJ, int LO, int HI> DI void batch(const f32x4 (&acc)[2][2][4][2], unsigned row0, unsigned col0, const f32x4 (&gv)[2], const f32x4 (&bv)[2]) const {
;         f32x4 r[HI - LO]; float mean[(HI - LO) / 2], rstd[(HI - LO) / 2];
; #pragma unroll
;         for (int i = LO; i < HI; ++i) { const int ai = i >> 3, m = (i >> 1) & 3, n = i & 1; const unsigned row = row0 + ai * HALF + m * 16;
;             if (n == 0) { mean[(i - LO) >> 1] = 0.f; rstd[(i - LO) >> 1] = 1.f;
;                 if (LN) { const float2 st = *(const float2*)(stats + row * 2u); mean[(i - LO) >> 1] = st.x; rstd[(i - LO) >> 1] = st.y; } }
;             r[i - LO] = *(const f32x4*)(src + (row * (unsigned)DM + col0 + BJ * HALF + n * 16)); }
; #pragma unroll
;         for (int i = LO; i < HI; ++i) { const int ai = i >> 3, m = (i >> 1) & 3, n = i & 1; const unsigned row = row0 + ai * HALF + m * 16;
;             *(f32x4*)(Y + (row * (unsigned)DM + col0 + BJ * HALF + n * 16)) = acc[ai][BJ][m][n] + ((r[i - LO] - mean[(i - LO) >> 1]) * rstd[(i - LO) >> 1]) * gv[n] + bv[n]; }
;         __builtin_amdgcn_sched_barrier(0);
;     }
;     template <bool LN, int BJ> DI void load_gb(unsigned col0, f32x4 (&gv)[2], f32x4 (&bv)[2]) const {
; #pragma unroll
;         for (int n = 0; n < 2; ++n) {
;             if (LN) { gv[n] = *(const f32x4*)(gam + col0 + BJ * HALF + n * 16) * ALPHA; bv[n] = *(const f32x4*)(bet + col0 + BJ * HALF + n * 16) * ALPHA; }
;             else { gv[n] = (f32x4){ALPHA, ALPHA, ALPHA, ALPHA}; bv[n] = (f32x4){0.f, 0.f, 0.f, 0.f}; }
;         }
;     }
;     template <bool LN> DI void run(const f32x4 (&acc)[2][2][4][2], const Unit& u, int wr, int wc, int fr, int fq) const {
;         const unsigned row0 = u.pm * BM + wr * 64 + fr, col0 = u.pn * BM + wc * 32 + 4 * fq;
;         f32x4 gv[2], bv[2];
;         load_gb<LN, 0>(col0, gv, bv);
;         batch<LN, 0, 0, 4>(acc, row0, col0, gv, bv);
;         batch<LN, 0, 4, 8>(acc, row0, col0, gv, bv);
;         batch<LN, 0, 8, 12>(acc, row0, col0, gv, bv);
;         batch<LN, 0, 12, 16>(acc, row0, col0, gv, bv);
;         load_gb<LN, 1>(col0, gv, bv);
;         batch<LN, 1, 0, 8>(acc, row0, col0, gv, bv);
;         batch<LN, 1, 8, 16>(acc, row0, col0, gv, bv);
	v_sub_f32_e32 v137, v137, v204
	v_sub_f32_e32 v136, v136, v204
	v_sub_f32_e32 v139, v139, v204
	v_sub_f32_e32 v138, v138, v204
	v_pk_mul_f32 v[138:139], v[204:205], v[138:139] op_sel:[1,0]
	v_pk_mul_f32 v[136:137], v[204:205], v[136:137] op_sel:[1,0]
	v_pk_fma_f32 v[138:139], v[152:153], v[138:139], v[94:95]
	v_pk_fma_f32 v[136:137], v[154:155], v[136:137], v[92:93]
	v_pk_fma_f32 v[138:139], v[134:135], s[78:79], v[138:139] op_sel_hi:[1,0,1]
	v_pk_fma_f32 v[136:137], v[132:133], s[78:79], v[136:137] op_sel_hi:[1,0,1]
	global_store_dwordx4 v[238:239], v[136:139], off
	s_nop 1
	v_sub_f32_e32 v137, v209, v204
	v_sub_f32_e32 v136, v208, v204
	v_sub_f32_e32 v139, v211, v204
	v_sub_f32_e32 v138, v210, v204
	v_pk_mul_f32 v[138:139], v[204:205], v[138:139] op_sel:[1,0]
	v_pk_mul_f32 v[136:137], v[204:205], v[136:137] op_sel:[1,0]
	v_pk_fma_f32 v[138:139], v[148:149], v[138:139], v[90:91]
	v_pk_fma_f32 v[136:137], v[150:151], v[136:137], v[88:89]
	v_add_u32_e32 v204, 0x40010, v194
	v_mov_b32_e32 v205, v159
	v_pk_fma_f32 v[138:139], v[130:131], s[78:79], v[138:139] op_sel_hi:[1,0,1]
	v_pk_fma_f32 v[136:137], v[128:129], s[78:79], v[136:137] op_sel_hi:[1,0,1]
	v_lshl_add_u64 v[204:205], v[204:205], 2, s[90:91]
	global_store_dwordx4 v[204:205], v[136:139], off
	v_add_u32_e32 v204, 0x48000, v194
	v_mov_b32_e32 v205, v159
	v_sub_f32_e32 v137, v213, v220
	v_sub_f32_e32 v136, v212, v220
	v_sub_f32_e32 v139, v215, v220
	v_sub_f32_e32 v138, v214, v220
	v_pk_mul_f32 v[138:139], v[220:221], v[138:139] op_sel:[1,0]
	v_pk_mul_f32 v[136:137], v[220:221], v[136:137] op_sel:[1,0]
	v_pk_fma_f32 v[138:139], v[152:153], v[138:139], v[86:87]
	v_pk_fma_f32 v[136:137], v[154:155], v[136:137], v[84:85]
	v_pk_fma_f32 v[138:139], v[134:135], s[78:79], v[138:139] op_sel_hi:[1,0,1]
	v_pk_fma_f32 v[136:137], v[132:133], s[78:79], v[136:137] op_sel_hi:[1,0,1]
	v_lshl_add_u64 v[204:205], v[204:205], 2, s[90:91]
	global_store_dwordx4 v[204:205], v[136:139], off
	v_add_u32_e32 v204, 0x48010, v194
	v_mov_b32_e32 v205, v159
	v_sub_f32_e32 v137, v217, v220
	v_sub_f32_e32 v136, v216, v220
	v_sub_f32_e32 v139, v219, v220
	v_sub_f32_e32 v138, v218, v220
	v_pk_mul_f32 v[138:139], v[220:221], v[138:139] op_sel:[1,0]
	v_pk_mul_f32 v[136:137], v[220:221], v[136:137] op_sel:[1,0]
	v_pk_fma_f32 v[138:139], v[148:149], v[138:139], v[82:83]
	v_pk_fma_f32 v[136:137], v[150:151], v[136:137], v[80:81]
	v_pk_fma_f32 v[138:139], v[130:131], s[78:79], v[138:139] op_sel_hi:[1,0,1]
	v_pk_fma_f32 v[136:137], v[128:129], s[78:79], v[136:137] op_sel_hi:[1,0,1]
	v_lshl_add_u64 v[204:205], v[204:205], 2, s[90:91]
	global_store_dwordx4 v[204:205], v[136:139], off
	s_nop 1
	v_add_u32_e32 v138, 0xa0, v206
	v_lshlrev_b32_e32 v136, 1, v138
	v_mov_b32_e32 v137, v159
	v_lshlrev_b32_e32 v237, 11, v138
	v_lshl_add_u64 v[204:205], v[136:137], 2, s[2:3]
	v_add_u32_e32 v136, v237, v158
	v_lshl_add_u64 v[136:137], v[136:137], 2, s[88:89]
	global_load_dwordx2 v[220:221], v[204:205], off
	v_add_u32_e32 v208, v237, v231
	global_load_dwordx4 v[136:139], v[136:137], off
	v_mov_b32_e32 v209, v159
	v_lshl_add_u64 v[208:209], v[208:209], 2, s[88:89]
	global_load_dwordx4 v[212:215], v[208:209], off
	v_add_u32_e32 v208, 0xb0, v206
	v_lshlrev_b32_e32 v206, 1, v208
	v_mov_b32_e32 v207, v159
	v_lshlrev_b32_e32 v238, 11, v208
	v_lshl_add_u64 v[210:211], v[206:207], 2, s[2:3]
	v_add_u32_e32 v206, v238, v158
	v_lshl_add_u64 v[206:207], v[206:207], 2, s[88:89]
	global_load_dwordx2 v[240:241], v[210:211], off
	v_add_u32_e32 v216, v238, v231
	global_load_dwordx4 v[206:209], v[206:207], off
	v_mov_b32_e32 v217, v159
	v_lshl_add_u64 v[216:217], v[216:217], 2, s[88:89]
	global_load_dwordx4 v[216:219], v[216:217], off
	v_add_u32_e32 v242, 0x50000, v194
	v_mov_b32_e32 v243, v159
	v_lshl_add_u64 v[242:243], v[242:243], 2, s[90:91]
	s_waitcnt vmcnt(0)
	v_sub_f32_e32 v137, v137, v220
	v_sub_f32_e32 v136, v136, v220
	v_sub_f32_e32 v139, v139, v220
	v_sub_f32_e32 v138, v138, v220
	v_pk_mul_f32 v[138:139], v[220:221], v[138:139] op_sel:[1,0]
	v_pk_mul_f32 v[136:137], v[220:221], v[136:137] op_sel:[1,0]
	v_pk_fma_f32 v[138:139], v[152:153], v[138:139], v[78:79]
	v_pk_fma_f32 v[136:137], v[154:155], v[136:137], v[76:77]
	v_pk_fma_f32 v[138:139], v[134:135], s[78:79], v[138:139] op_sel_hi:[1,0,1]
	v_pk_fma_f32 v[136:137], v[132:133], s[78:79], v[136:137] op_sel_hi:[1,0,1]
	global_store_dwordx4 v[242:243], v[136:139], off
	s_nop 1
	v_sub_f32_e32 v137, v213, v220
	v_sub_f32_e32 v136, v212, v220
	v_sub_f32_e32 v139, v215, v220
	v_sub_f32_e32 v138, v214, v220
	v_pk_mul_f32 v[138:139], v[220:221], v[138:139] op_sel:[1,0]
	v_pk_mul_f32 v[136:137], v[220:221], v[136:137] op_sel:[1,0]
	v_pk_fma_f32 v[138:139], v[148:149], v[138:139], v[74:75]
	v_pk_fma_f32 v[136:137], v[150:151], v[136:137], v[72:73]
	v_add_u32_e32 v212, 0x50010, v194
	v_mov_b32_e32 v213, v159
	v_pk_fma_f32 v[138:139], v[130:131], s[78:79], v[138:139] op_sel_hi:[1,0,1]
	v_pk_fma_f32 v[136:137], v[128:129], s[78:79], v[136:137] op_sel_hi:[1,0,1]
	v_lshl_add_u64 v[212:213], v[212:213], 2, s[90:91]
	global_store_dwordx4 v[212:213], v[136:139], off
	s_nop 1
	v_sub_f32_e32 v137, v207, v240
	v_sub_f32_e32 v136, v206, v240
	v_sub_f32_e32 v139, v209, v240
	v_sub_f32_e32 v138, v208, v240
	v_pk_mul_f32 v[136:137], v[240:241], v[136:137] op_sel:[1,0]
	v_pk_mul_f32 v[138:139], v[240:241], v[138:139] op_sel:[1,0]
	v_pk_fma_f32 v[136:137], v[154:155], v[136:137], v[68:69]
	v_pk_fma_f32 v[138:139], v[152:153], v[138:139], v[70:71]
	v_pk_fma_f32 v[132:133], v[132:133], s[78:79], v[136:137] op_sel_hi:[1,0,1]
	v_add_u32_e32 v136, 0x58000, v194
	v_mov_b32_e32 v137, v159
	v_pk_fma_f32 v[134:135], v[134:135], s[78:79], v[138:139] op_sel_hi:[1,0,1]
	v_lshl_add_u64 v[136:137], v[136:137], 2, s[90:91]
	global_store_dwordx4 v[136:137], v[132:135], off
	s_nop 1
	v_sub_f32_e32 v133, v217, v240
	v_sub_f32_e32 v132, v216, v240
	v_sub_f32_e32 v135, v219, v240
	v_sub_f32_e32 v134, v218, v240
	v_pk_mul_f32 v[132:133], v[240:241], v[132:133] op_sel:[1,0]
	v_pk_mul_f32 v[134:135], v[240:241], v[134:135] op_sel:[1,0]
	v_pk_fma_f32 v[132:133], v[150:151], v[132:133], v[64:65]
	v_pk_fma_f32 v[134:135], v[148:149], v[134:135], v[66:67]
	v_pk_fma_f32 v[128:129], v[128:129], s[78:79], v[132:133] op_sel_hi:[1,0,1]
	v_add_u32_e32 v132, 0x58010, v194
	v_mov_b32_e32 v133, v159
	v_pk_fma_f32 v[130:131], v[130:131], s[78:79], v[134:135] op_sel_hi:[1,0,1]
	v_lshl_add_u64 v[132:133], v[132:133], 2, s[90:91]
	global_store_dwordx4 v[132:133], v[128:131], off
	global_load_dwordx4 v[128:131], v[140:141], off offset:512
	v_add_u32_e32 v136, v232, v230
	v_mov_b32_e32 v137, v159
	v_lshl_add_u64 v[136:137], v[136:137], 2, s[88:89]
	s_waitcnt vmcnt(0)
;     template <bool LN, int BJ, int LO, int HI> DI void batch(const f32x4 (&acc)[2][2][4][2], unsigned row0, unsigned col0, const f32x4 (&gv)[2], const f32x4 (&bv)[2]) const {
;         f32x4 r[HI - LO]; float mean[(HI - LO) / 2], rstd[(HI - LO) / 2];
; #pragma unroll
;         for (int i = LO; i < HI; ++i) { const int ai = i >> 3, m = (i >> 1) & 3, n = i & 1; const unsigned row = row0 + ai * HALF + m * 16;
;             if (n == 0) { mean[(i - LO) >> 1] = 0.f; rstd[(i - LO) >> 1] = 1.f;
;                 if (LN) { const float2 st = *(const float2*)(stats + row * 2u); mean[(i - LO) >> 1] = st.x; rstd[(i - LO) >> 1] = st.y; } }
;             r[i - LO] = *(const f32x4*)(src + (row * (unsigned)DM + col0 + BJ * HALF + n * 16)); }
; #pragma unroll
;         for (int i = LO; i < HI; ++i) { const int ai = i >> 3, m = (i >> 1) & 3, n = i & 1; const unsigned row = row0 + ai * HALF + m * 16;
;             *(f32x4*)(Y + (row * (unsigned)DM + col0 + BJ * HALF + n * 16)) = acc[ai][BJ][m][n] + ((r[i - LO] - mean[(i - LO) >> 1]) * rstd[(i - LO) >> 1]) * gv[n] + bv[n]; }
;         __builtin_amdgcn_sched_barrier(0);
;     }
;     template <bool LN, int BJ> DI void load_gb(unsigned col0, f32x4 (&gv)[2], f32x4 (&bv)[2]) const {
; #pragma unroll
;         for (int n = 0; n < 2; ++n) {
;             if (LN) { gv[n] = *(const f32x4*)(gam + col0 + BJ * HALF + n * 16) * ALPHA; bv[n] = *(const f32x4*)(bet + col0 + BJ * HALF + n * 16) * ALPHA; }
;             else { gv[n] = (f32x4){ALPHA, ALPHA, ALPHA, ALPHA}; bv[n] = (f32x4){0.f, 0.f, 0.f, 0.f}; }
;         }
;     }
;     template <bool LN> DI void run(const f32x4 (&acc)[2][2][4][2], const Unit& u, int wr, int wc, int fr, int fq) const {
;         const unsigned row0 = u.pm * BM + wr * 64 + fr, col0 = u.pn * BM + wc * 32 + 4 * fq;
;         f32x4 gv[2], bv[2];
;         load_gb<LN, 0>(col0, gv, bv);
;         batch<LN, 0, 0, 4>(acc, row0, col0, gv, bv);
;         batch<LN, 0, 4, 8>(acc, row0, col0, gv, bv);
;         batch<LN, 0, 8, 12>(acc, row0, col0, gv, bv);
;         batch<LN, 0, 12, 16>(acc, row0, col0, gv, bv);
;         load_gb<LN, 1>(col0, gv, bv);
;         batch<LN, 1, 0, 8>(acc, row0, col0, gv, bv);
;         batch<LN, 1, 8, 16>(acc, row0, col0, gv, bv);
	v_pk_mul_f32 v[212:213], v[130:131], s[78:79] op_sel_hi:[1,0]
	v_pk_mul_f32 v[214:215], v[128:129], s[78:79] op_sel_hi:[1,0]
	global_load_dwordx4 v[132:135], v[142:143], off offset:512
	global_load_dwordx4 v[128:131], v[140:141], off offset:576
	s_waitcnt vmcnt(0)
	v_pk_mul_f32 v[206:207], v[130:131], s[78:79] op_sel_hi:[1,0]
	v_pk_mul_f32 v[208:209], v[128:129], s[78:79] op_sel_hi:[1,0]
	global_load_dwordx4 v[128:131], v[142:143], off offset:576
	global_load_dwordx2 v[220:221], v[144:145], off
	global_load_dwordx4 v[240:243], v[136:137], off
	v_add_u32_e32 v136, v232, v229
	v_mov_b32_e32 v137, v159
	v_lshl_add_u64 v[136:137], v[136:137], 2, s[88:89]
	global_load_dwordx4 v[244:247], v[136:137], off
	global_load_dwordx2 v[218:219], v[146:147], off
	v_add_u32_e32 v136, v195, v230
	v_mov_b32_e32 v137, v159
	v_lshl_add_u64 v[136:137], v[136:137], 2, s[88:89]
	global_load_dwordx4 v[248:251], v[136:137], off
	v_add_u32_e32 v136, v195, v229
	v_mov_b32_e32 v137, v159
	v_lshl_add_u64 v[136:137], v[136:137], 2, s[88:89]
	global_load_dwordx4 v[152:155], v[136:137], off
	global_load_dwordx2 v[216:217], v[200:201], off
	v_add_u32_e32 v136, v236, v230
	v_mov_b32_e32 v137, v159
	v_lshl_add_u64 v[136:137], v[136:137], 2, s[88:89]
	global_load_dwordx4 v[148:151], v[136:137], off
	v_add_u32_e32 v136, v236, v229
	v_mov_b32_e32 v137, v159
	v_lshl_add_u64 v[136:137], v[136:137], 2, s[88:89]
	global_load_dwordx4 v[144:147], v[136:137], off
	global_load_dwordx2 v[200:201], v[202:203], off
	v_add_u32_e32 v136, v235, v230
	v_mov_b32_e32 v137, v159
	v_lshl_add_u64 v[136:137], v[136:137], 2, s[88:89]
	global_load_dwordx4 v[140:143], v[136:137], off
	v_add_u32_e32 v136, v235, v229
	v_mov_b32_e32 v137, v159
	v_lshl_add_u64 v[136:137], v[136:137], 2, s[88:89]
	global_load_dwordx4 v[136:139], v[136:137], off
	v_add_u32_e32 v202, 0x80, v194
	v_mov_b32_e32 v203, v159
	v_lshl_add_u64 v[202:203], v[202:203], 2, s[90:91]
	s_waitcnt vmcnt(0)
	v_sub_f32_e32 v241, v241, v220
	v_sub_f32_e32 v240, v240, v220
	v_sub_f32_e32 v243, v243, v220
	v_sub_f32_e32 v242, v242, v220
	v_pk_mul_f32 v[242:243], v[220:221], v[242:243] op_sel:[1,0]
	v_pk_mul_f32 v[240:241], v[220:221], v[240:241] op_sel:[1,0]
	v_pk_fma_f32 v[242:243], v[212:213], v[242:243], v[62:63]
	v_pk_fma_f32 v[240:241], v[214:215], v[240:241], v[60:61]
	v_pk_fma_f32 v[242:243], v[134:135], s[78:79], v[242:243] op_sel_hi:[1,0,1]
	v_pk_fma_f32 v[240:241], v[132:133], s[78:79], v[240:241] op_sel_hi:[1,0,1]
	global_store_dwordx4 v[202:203], v[240:243], off
	v_sub_f32_e32 v203, v245, v220
	v_sub_f32_e32 v202, v244, v220
	v_sub_f32_e32 v241, v247, v220
	v_sub_f32_e32 v240, v246, v220
	v_pk_mul_f32 v[202:203], v[220:221], v[202:203] op_sel:[1,0]
	v_pk_mul_f32 v[240:241], v[220:221], v[240:241] op_sel:[1,0]
	v_pk_fma_f32 v[202:203], v[208:209], v[202:203], v[56:57]
	v_pk_fma_f32 v[220:221], v[206:207], v[240:241], v[58:59]
	v_pk_fma_f32 v[240:241], v[128:129], s[78:79], v[202:203] op_sel_hi:[1,0,1]
	v_add_u32_e32 v202, 0x90, v194
	v_mov_b32_e32 v203, v159
	v_pk_fma_f32 v[242:243], v[130:131], s[78:79], v[220:221] op_sel_hi:[1,0,1]
	v_lshl_add_u64 v[202:203], v[202:203], 2, s[90:91]
	global_store_dwordx4 v[202:203], v[240:243], off
	v_sub_f32_e32 v203, v249, v218
	v_sub_f32_e32 v202, v248, v218
	v_sub_f32_e32 v221, v251, v218
	v_sub_f32_e32 v220, v250, v218
	v_pk_mul_f32 v[202:203], v[218:219], v[202:203] op_sel:[1,0]
	v_pk_mul_f32 v[220:221], v[218:219], v[220:221] op_sel:[1,0]
	v_pk_fma_f32 v[202:203], v[214:215], v[202:203], v[52:53]
	v_pk_fma_f32 v[220:221], v[212:213], v[220:221], v[54:55]
	v_pk_fma_f32 v[240:241], v[132:133], s[78:79], v[202:203] op_sel_hi:[1,0,1]
	v_add_u32_e32 v202, 0x8080, v194
	v_mov_b32_e32 v203, v159
	v_sub_f32_e32 v153, v153, v218
	v_sub_f32_e32 v152, v152, v218
	v_sub_f32_e32 v155, v155, v218
	v_sub_f32_e32 v154, v154, v218
	v_pk_fma_f32 v[242:243], v[134:135], s[78:79], v[220:221] op_sel_hi:[1,0,1]
	v_lshl_add_u64 v[202:203], v[202:203], 2, s[90:91]
	v_pk_mul_f32 v[154:155], v[218:219], v[154:155] op_sel:[1,0]
	v_pk_mul_f32 v[152:153], v[218:219], v[152:153] op_sel:[1,0]
	global_store_dwordx4 v[202:203], v[240:243], off
	v_pk_fma_f32 v[152:153], v[208:209], v[152:153], v[48:49]
	v_pk_fma_f32 v[154:155], v[206:207], v[154:155], v[50:51]
	v_add_u32_e32 v202, 0x8090, v194
	v_mov_b32_e32 v203, v159
	v_sub_f32_e32 v149, v149, v216
	v_sub_f32_e32 v148, v148, v216
	v_sub_f32_e32 v151, v151, v216
	v_sub_f32_e32 v150, v150, v216
	v_pk_fma_f32 v[154:155], v[130:131], s[78:79], v[154:155] op_sel_hi:[1,0,1]
	v_pk_fma_f32 v[152:153], v[128:129], s[78:79], v[152:153] op_sel_hi:[1,0,1]
	v_lshl_add_u64 v[202:203], v[202:203], 2, s[90:91]
	v_pk_mul_f32 v[150:151], v[216:217], v[150:151] op_sel:[1,0]
	v_pk_mul_f32 v[148:149], v[216:217], v[148:149] op_sel:[1,0]
	global_store_dwordx4 v[202:203], v[152:155], off
	v_pk_fma_f32 v[148:149], v[214:215], v[148:149], v[44:45]
	v_pk_fma_f32 v[150:151], v[212:213], v[150:151], v[46:47]
	v_add_u32_e32 v152, 0x10080, v194
	v_mov_b32_e32 v153, v159
	v_sub_f32_e32 v145, v145, v216
	v_sub_f32_e32 v144, v144, v216
	v_sub_f32_e32 v147, v147, v216
	v_sub_f32_e32 v146, v146, v216
	v_pk_fma_f32 v[150:151], v[134:135], s[78:79], v[150:151] op_sel_hi:[1,0,1]
	v_pk_fma_f32 v[148:149], v[132:133], s[78:79], v[148:149] op_sel_hi:[1,0,1]
	v_lshl_add_u64 v[152:153], v[152:153], 2, s[90:91]
	v_pk_mul_f32 v[146:147], v[216:217], v[146:147] op_sel:[1,0]
	v_pk_mul_f32 v[144:145], v[216:217], v[144:145] op_sel:[1,0]
	global_store_dwordx4 v[152:153], v[148:151], off
	v_pk_fma_f32 v[144:145], v[208:209], v[144:145], v[40:41]
	v_pk_fma_f32 v[146:147], v[206:207], v[146:147], v[42:43]
;     template <bool LN, int BJ, int LO, int HI> DI void batch(const f32x4 (&acc)[2][2][4][2], unsigned row0, unsigned col0, const f32x4 (&gv)[2], const f32x4 (&bv)[2]) const {
;         f32x4 r[HI - LO]; float mean[(HI - LO) / 2], rstd[(HI - LO) / 2];
; #pragma unroll
;         for (int i = LO; i < HI; ++i) { const int ai = i >> 3, m = (i >> 1) & 3, n = i & 1; const unsigned row = row0 + ai * HALF + m * 16;
;             if (n == 0) { mean[(i - LO) >> 1] = 0.f; rstd[(i - LO) >> 1] = 1.f;
;                 if (LN) { const float2 st = *(const float2*)(stats + row * 2u); mean[(i - LO) >> 1] = st.x; rstd[(i - LO) >> 1] = st.y; } }
;             r[i - LO] = *(const f32x4*)(src + (row * (unsigned)DM + col0 + BJ * HALF + n * 16)); }
; #pragma unroll
;         for (int i = LO; i < HI; ++i) { const int ai = i >> 3, m = (i >> 1) & 3, n = i & 1; const unsigned row = row0 + ai * HALF + m * 16;
;             *(f32x4*)(Y + (row * (unsigned)DM + col0 + BJ * HALF + n * 16)) = acc[ai][BJ][m][n] + ((r[i - LO] - mean[(i - LO) >> 1]) * rstd[(i - LO) >> 1]) * gv[n] + bv[n]; }
;         __builtin_amdgcn_sched_barrier(0);
;     }
;     template <bool LN, int BJ> DI void load_gb(unsigned col0, f32x4 (&gv)[2], f32x4 (&bv)[2]) const {
; #pragma unroll
;         for (int n = 0; n < 2; ++n) {
;             if (LN) { gv[n] = *(const f32x4*)(gam + col0 + BJ * HALF + n * 16) * ALPHA; bv[n] = *(const f32x4*)(bet + col0 + BJ * HALF + n * 16) * ALPHA; }
;             else { gv[n] = (f32x4){ALPHA, ALPHA, ALPHA, ALPHA}; bv[n] = (f32x4){0.f, 0.f, 0.f, 0.f}; }
;         }
;     }
;     template <bool LN> DI void run(const f32x4 (&acc)[2][2][4][2], const Unit& u, int wr, int wc, int fr, int fq) const {
;         const unsigned row0 = u.pm * BM + wr * 64 + fr, col0 = u.pn * BM + wc * 32 + 4 * fq;
;         f32x4 gv[2], bv[2];
;         load_gb<LN, 0>(col0, gv, bv);
;         batch<LN, 0, 0, 4>(acc, row0, col0, gv, bv);
;         batch<LN, 0, 4, 8>(acc, row0, col0, gv, bv);
;         batch<LN, 0, 8, 12>(acc, row0, col0, gv, bv);
;         batch<LN, 0, 12, 16>(acc, row0, col0, gv, bv);
;         load_gb<LN, 1>(col0, gv, bv);
;         batch<LN, 1, 0, 8>(acc, row0, col0, gv, bv);
;         batch<LN, 1, 8, 16>(acc, row0, col0, gv, bv);
	v_add_u32_e32 v148, 0x10090, v194
	v_mov_b32_e32 v149, v159
	v_sub_f32_e32 v141, v141, v200
	v_sub_f32_e32 v140, v140, v200
	v_sub_f32_e32 v143, v143, v200
	v_sub_f32_e32 v142, v142, v200
	v_pk_fma_f32 v[146:147], v[130:131], s[78:79], v[146:147] op_sel_hi:[1,0,1]
	v_pk_fma_f32 v[144:145], v[128:129], s[78:79], v[144:145] op_sel_hi:[1,0,1]
	v_lshl_add_u64 v[148:149], v[148:149], 2, s[90:91]
	v_pk_mul_f32 v[142:143], v[200:201], v[142:143] op_sel:[1,0]
	v_pk_mul_f32 v[140:141], v[200:201], v[140:141] op_sel:[1,0]
	global_store_dwordx4 v[148:149], v[144:147], off
	v_pk_fma_f32 v[140:141], v[214:215], v[140:141], v[36:37]
	v_pk_fma_f32 v[142:143], v[212:213], v[142:143], v[38:39]
	v_add_u32_e32 v144, 0x18080, v194
	v_mov_b32_e32 v145, v159
	v_sub_f32_e32 v137, v137, v200
	v_sub_f32_e32 v136, v136, v200
	v_sub_f32_e32 v139, v139, v200
	v_sub_f32_e32 v138, v138, v200
	v_pk_fma_f32 v[142:143], v[134:135], s[78:79], v[142:143] op_sel_hi:[1,0,1]
	v_pk_fma_f32 v[140:141], v[132:133], s[78:79], v[140:141] op_sel_hi:[1,0,1]
	v_lshl_add_u64 v[144:145], v[144:145], 2, s[90:91]
	v_pk_mul_f32 v[138:139], v[200:201], v[138:139] op_sel:[1,0]
	v_pk_mul_f32 v[136:137], v[200:201], v[136:137] op_sel:[1,0]
	global_store_dwordx4 v[144:145], v[140:143], off
	v_pk_fma_f32 v[136:137], v[208:209], v[136:137], v[32:33]
	v_pk_fma_f32 v[138:139], v[206:207], v[138:139], v[34:35]
	v_add_u32_e32 v140, 0x18090, v194
	v_mov_b32_e32 v141, v159
	v_pk_fma_f32 v[138:139], v[130:131], s[78:79], v[138:139] op_sel_hi:[1,0,1]
	v_pk_fma_f32 v[136:137], v[128:129], s[78:79], v[136:137] op_sel_hi:[1,0,1]
	v_lshl_add_u64 v[140:141], v[140:141], 2, s[90:91]
	global_store_dwordx4 v[140:141], v[136:139], off
	s_nop 1
	v_add_u32_e32 v136, v233, v230
	v_mov_b32_e32 v137, v159
	v_lshl_add_u64 v[136:137], v[136:137], 2, s[88:89]
	global_load_dwordx2 v[220:221], v[196:197], off
	global_load_dwordx4 v[216:219], v[136:137], off
	v_add_u32_e32 v136, v233, v229
	v_mov_b32_e32 v137, v159
	v_lshl_add_u64 v[136:137], v[136:137], 2, s[88:89]
	global_load_dwordx4 v[240:243], v[136:137], off
	global_load_dwordx2 v[200:201], v[198:199], off
	v_add_u32_e32 v136, v234, v230
	v_mov_b32_e32 v137, v159
	v_lshl_add_u64 v[136:137], v[136:137], 2, s[88:89]
	global_load_dwordx4 v[244:247], v[136:137], off
	v_add_u32_e32 v136, v234, v229
	v_mov_b32_e32 v137, v159
	v_lshl_add_u64 v[136:137], v[136:137], 2, s[88:89]
	global_load_dwordx4 v[152:155], v[136:137], off
	global_load_dwordx2 v[198:199], v[204:205], off
	v_add_u32_e32 v136, v237, v230
	v_mov_b32_e32 v137, v159
	v_lshl_add_u64 v[136:137], v[136:137], 2, s[88:89]
	global_load_dwordx4 v[148:151], v[136:137], off
	v_add_u32_e32 v136, v237, v229
	v_mov_b32_e32 v137, v159
	v_lshl_add_u64 v[136:137], v[136:137], 2, s[88:89]
	global_load_dwordx4 v[144:147], v[136:137], off
	global_load_dwordx2 v[196:197], v[210:211], off
	v_add_u32_e32 v136, v238, v230
	v_mov_b32_e32 v137, v159
	v_lshl_add_u64 v[136:137], v[136:137], 2, s[88:89]
	global_load_dwordx4 v[140:143], v[136:137], off
	v_add_u32_e32 v136, v238, v229
	v_mov_b32_e32 v137, v159
	v_lshl_add_u64 v[136:137], v[136:137], 2, s[88:89]
	global_load_dwordx4 v[136:139], v[136:137], off
	v_add_u32_e32 v210, 0x40080, v194
	v_mov_b32_e32 v211, v159
	v_lshl_add_u64 v[210:211], v[210:211], 2, s[90:91]
	s_waitcnt vmcnt(0)
;     template <bool LN, int BJ, int LO, int HI> DI void batch(const f32x4 (&acc)[2][2][4][2], unsigned row0, unsigned col0, const f32x4 (&gv)[2], const f32x4 (&bv)[2]) const {
;         f32x4 r[HI - LO]; float mean[(HI - LO) / 2], rstd[(HI - LO) / 2];
; #pragma unroll
;         for (int i = LO; i < HI; ++i) { const int ai = i >> 3, m = (i >> 1) & 3, n = i & 1; const unsigned row = row0 + ai * HALF + m * 16;
;             if (n == 0) { mean[(i - LO) >> 1] = 0.f; rstd[(i - LO) >> 1] = 1.f;
;                 if (LN) { const float2 st = *(const float2*)(stats + row * 2u); mean[(i - LO) >> 1] = st.x; rstd[(i - LO) >> 1] = st.y; } }
;             r[i - LO] = *(const f32x4*)(src + (row * (unsigned)DM + col0 + BJ * HALF + n * 16)); }
; #pragma unroll
;         for (int i = LO; i < HI; ++i) { const int ai = i >> 3, m = (i >> 1) & 3, n = i & 1; const unsigned row = row0 + ai * HALF + m * 16;
;             *(f32x4*)(Y + (row * (unsigned)DM + col0 + BJ * HALF + n * 16)) = acc[ai][BJ][m][n] + ((r[i - LO] - mean[(i - LO) >> 1]) * rstd[(i - LO) >> 1]) * gv[n] + bv[n]; }
;         __builtin_amdgcn_sched_barrier(0);
;     }
;     template <bool LN, int BJ> DI void load_gb(unsigned col0, f32x4 (&gv)[2], f32x4 (&bv)[2]) const {
; #pragma unroll
;         for (int n = 0; n < 2; ++n) {
;             if (LN) { gv[n] = *(const f32x4*)(gam + col0 + BJ * HALF + n * 16) * ALPHA; bv[n] = *(const f32x4*)(bet + col0 + BJ * HALF + n * 16) * ALPHA; }
;             else { gv[n] = (f32x4){ALPHA, ALPHA, ALPHA, ALPHA}; bv[n] = (f32x4){0.f, 0.f, 0.f, 0.f}; }
;         }
;     }
;     template <bool LN> DI void run(const f32x4 (&acc)[2][2][4][2], const Unit& u, int wr, int wc, int fr, int fq) const {
;         const unsigned row0 = u.pm * BM + wr * 64 + fr, col0 = u.pn * BM + wc * 32 + 4 * fq;
;         f32x4 gv[2], bv[2];
;         load_gb<LN, 0>(col0, gv, bv);
;         batch<LN, 0, 0, 4>(acc, row0, col0, gv, bv);
;         batch<LN, 0, 4, 8>(acc, row0, col0, gv, bv);
;         batch<LN, 0, 8, 12>(acc, row0, col0, gv, bv);
;         batch<LN, 0, 12, 16>(acc, row0, col0, gv, bv);
;         load_gb<LN, 1>(col0, gv, bv);
;         batch<LN, 1, 0, 8>(acc, row0, col0, gv, bv);
;         batch<LN, 1, 8, 16>(acc, row0, col0, gv, bv);
	v_sub_f32_e32 v203, v217, v220
	v_sub_f32_e32 v202, v216, v220
	v_sub_f32_e32 v205, v219, v220
	v_sub_f32_e32 v204, v218, v220
	v_pk_mul_f32 v[204:205], v[220:221], v[204:205] op_sel:[1,0]
	v_pk_mul_f32 v[202:203], v[220:221], v[202:203] op_sel:[1,0]
	v_pk_fma_f32 v[204:205], v[212:213], v[204:205], v[30:31]
	v_pk_fma_f32 v[202:203], v[214:215], v[202:203], v[28:29]
	v_pk_fma_f32 v[204:205], v[134:135], s[78:79], v[204:205] op_sel_hi:[1,0,1]
	v_pk_fma_f32 v[202:203], v[132:133], s[78:79], v[202:203] op_sel_hi:[1,0,1]
	global_store_dwordx4 v[210:211], v[202:205], off
	v_add_u32_e32 v210, 0x40090, v194
	v_mov_b32_e32 v211, v159
	v_sub_f32_e32 v203, v241, v220
	v_sub_f32_e32 v202, v240, v220
	v_sub_f32_e32 v205, v243, v220
	v_sub_f32_e32 v204, v242, v220
	v_pk_mul_f32 v[204:205], v[220:221], v[204:205] op_sel:[1,0]
	v_pk_mul_f32 v[202:203], v[220:221], v[202:203] op_sel:[1,0]
	v_pk_fma_f32 v[204:205], v[206:207], v[204:205], v[26:27]
	v_pk_fma_f32 v[202:203], v[208:209], v[202:203], v[24:25]
	v_pk_fma_f32 v[204:205], v[130:131], s[78:79], v[204:205] op_sel_hi:[1,0,1]
	v_pk_fma_f32 v[202:203], v[128:129], s[78:79], v[202:203] op_sel_hi:[1,0,1]
	v_lshl_add_u64 v[210:211], v[210:211], 2, s[90:91]
	global_store_dwordx4 v[210:211], v[202:205], off
	v_sub_f32_e32 v149, v149, v198
	v_sub_f32_e32 v148, v148, v198
	v_sub_f32_e32 v203, v245, v200
	v_sub_f32_e32 v202, v244, v200
	v_sub_f32_e32 v141, v141, v196
	v_sub_f32_e32 v140, v140, v196
	v_sub_f32_e32 v205, v247, v200
	v_sub_f32_e32 v204, v246, v200
	v_pk_mul_f32 v[202:203], v[200:201], v[202:203] op_sel:[1,0]
	v_sub_f32_e32 v151, v151, v198
	v_sub_f32_e32 v150, v150, v198
	v_pk_mul_f32 v[148:149], v[198:199], v[148:149] op_sel:[1,0]
	v_sub_f32_e32 v143, v143, v196
	v_sub_f32_e32 v142, v142, v196
	v_pk_mul_f32 v[140:141], v[196:197], v[140:141] op_sel:[1,0]
	v_pk_mul_f32 v[204:205], v[200:201], v[204:205] op_sel:[1,0]
	v_pk_fma_f32 v[202:203], v[214:215], v[202:203], v[20:21]
	v_sub_f32_e32 v153, v153, v200
	v_sub_f32_e32 v152, v152, v200
	v_sub_f32_e32 v155, v155, v200
	v_sub_f32_e32 v154, v154, v200
	v_pk_mul_f32 v[150:151], v[198:199], v[150:151] op_sel:[1,0]
	v_pk_fma_f32 v[148:149], v[214:215], v[148:149], v[12:13]
	v_pk_mul_f32 v[142:143], v[196:197], v[142:143] op_sel:[1,0]
	v_pk_fma_f32 v[140:141], v[214:215], v[140:141], v[4:5]
	v_pk_fma_f32 v[204:205], v[212:213], v[204:205], v[22:23]
	v_pk_fma_f32 v[202:203], v[132:133], s[78:79], v[202:203] op_sel_hi:[1,0,1]
	v_pk_mul_f32 v[154:155], v[200:201], v[154:155] op_sel:[1,0]
	v_pk_mul_f32 v[152:153], v[200:201], v[152:153] op_sel:[1,0]
	v_pk_fma_f32 v[150:151], v[212:213], v[150:151], v[14:15]
	v_pk_fma_f32 v[148:149], v[132:133], s[78:79], v[148:149] op_sel_hi:[1,0,1]
	v_pk_fma_f32 v[142:143], v[212:213], v[142:143], v[6:7]
	v_pk_fma_f32 v[132:133], v[132:133], s[78:79], v[140:141] op_sel_hi:[1,0,1]
	v_add_u32_e32 v140, 0x58080, v194
	v_mov_b32_e32 v141, v159
	v_pk_fma_f32 v[204:205], v[134:135], s[78:79], v[204:205] op_sel_hi:[1,0,1]
	v_pk_fma_f32 v[152:153], v[208:209], v[152:153], v[16:17]
	v_pk_fma_f32 v[154:155], v[206:207], v[154:155], v[18:19]
	v_add_u32_e32 v200, 0x48090, v194
	v_mov_b32_e32 v201, v159
	v_pk_fma_f32 v[150:151], v[134:135], s[78:79], v[150:151] op_sel_hi:[1,0,1]
	v_pk_fma_f32 v[134:135], v[134:135], s[78:79], v[142:143] op_sel_hi:[1,0,1]
	v_lshl_add_u64 v[140:141], v[140:141], 2, s[90:91]
	v_pk_fma_f32 v[154:155], v[130:131], s[78:79], v[154:155] op_sel_hi:[1,0,1]
	v_pk_fma_f32 v[152:153], v[128:129], s[78:79], v[152:153] op_sel_hi:[1,0,1]
	v_lshl_add_u64 v[200:201], v[200:201], 2, s[90:91]
	v_sub_f32_e32 v145, v145, v198
	v_sub_f32_e32 v144, v144, v198
	global_store_dwordx4 v[140:141], v[132:135], off
	global_store_dwordx4 v[200:201], v[152:155], off
	v_sub_f32_e32 v147, v147, v198
	v_sub_f32_e32 v133, v137, v196
	v_sub_f32_e32 v132, v136, v196
	v_add_u32_e32 v152, 0x50080, v194
	v_mov_b32_e32 v153, v159
	v_sub_f32_e32 v146, v146, v198
	v_pk_mul_f32 v[144:145], v[198:199], v[144:145] op_sel:[1,0]
	v_sub_f32_e32 v135, v139, v196
	v_sub_f32_e32 v134, v138, v196
	v_pk_mul_f32 v[132:133], v[196:197], v[132:133] op_sel:[1,0]
	v_lshl_add_u64 v[152:153], v[152:153], 2, s[90:91]
	v_pk_mul_f32 v[146:147], v[198:199], v[146:147] op_sel:[1,0]
	v_pk_fma_f32 v[144:145], v[208:209], v[144:145], v[8:9]
	v_pk_mul_f32 v[134:135], v[196:197], v[134:135] op_sel:[1,0]
	v_pk_fma_f32 v[132:133], v[208:209], v[132:133], v[0:1]
	v_add_u32_e32 v210, 0x48080, v194
	v_mov_b32_e32 v211, v159
	global_store_dwordx4 v[152:153], v[148:151], off
	v_pk_fma_f32 v[146:147], v[206:207], v[146:147], v[10:11]
	v_pk_fma_f32 v[144:145], v[128:129], s[78:79], v[144:145] op_sel_hi:[1,0,1]
	v_add_u32_e32 v148, 0x50090, v194
	v_mov_b32_e32 v149, v159
	v_pk_fma_f32 v[134:135], v[206:207], v[134:135], v[2:3]
	v_pk_fma_f32 v[128:129], v[128:129], s[78:79], v[132:133] op_sel_hi:[1,0,1]
	v_add_u32_e32 v132, 0x58090, v194
	v_mov_b32_e32 v133, v159
	v_lshl_add_u64 v[210:211], v[210:211], 2, s[90:91]
	v_pk_fma_f32 v[146:147], v[130:131], s[78:79], v[146:147] op_sel_hi:[1,0,1]
	v_lshl_add_u64 v[148:149], v[148:149], 2, s[90:91]
	v_pk_fma_f32 v[130:131], v[130:131], s[78:79], v[134:135] op_sel_hi:[1,0,1]
	v_lshl_add_u64 v[132:133], v[132:133], 2, s[90:91]
	global_store_dwordx4 v[210:211], v[202:205], off
	global_store_dwordx4 v[148:149], v[144:147], off
	global_store_dwordx4 v[132:133], v[128:131], off
	s_mov_b64 s[20:21], 0
	s_branch .LBB0_81

; #define PG8_STAGE(bufoff, gbase) do { _Pragma("unroll") for (int _i = 0; _i < 2; ++_i) \
;         __builtin_amdgcn_global_load_lds((const unsigned*)((const char*)(gbase) + voff[_i]), (LAS unsigned*)(lds + (bufoff) + ldsw + _i * 8192), 16, 0, 0); } while (0)
; #define PG8_LDA(dst, b, h) do { _Pragma("unroll") for (int m = 0; m < 4; ++m) _Pragma("unroll") for (int k = 0; k < 2; ++k) dst[m][k] = *(const LAS bf16x8*)(lds + PG8_SA(b, h) + aoff + m * 2048 + k * 1024); } while (0)
; #define PG8_LDB(dst, b, h) do { _Pragma("unroll") for (int n = 0; n < 2; ++n) _Pragma("unroll") for (int k = 0; k < 2; ++k) dst[n][k] = *(const LAS bf16x8*)(lds + PG8_SB(b, h) + boff + n * 2048 + k * 1024); } while (0)
; #define PG8_MMA(ai, bj, At, Bt) do { __builtin_amdgcn_s_setprio(1); _Pragma("unroll") for (int m = 0; m < 4; ++m) _Pragma("unroll") for (int n = 0; n < 2; ++n) _Pragma("unroll") for (int k = 0; k < 2; ++k) \
;         acc[ai][bj][m][n] = __builtin_amdgcn_mfma_f32_16x16x32_bf16(Bt[n][k], At[m][k], acc[ai][bj][m][n], 0, 0, 0); __builtin_amdgcn_s_setprio(0); } while (0)
; #define PG8_WAIT_L(n) asm volatile("s_waitcnt lgkmcnt(" #n ")" ::: "memory")
; #define PG8_BAR __builtin_amdgcn_s_barrier()
; #define PG8_SCHED __builtin_amdgcn_sched_barrier(0)
; template <class Epi>
; DI void gemm_phase(LAS unsigned char* lds, const Gemm g, const StaticOrder& S, const Epi& E) {
;     ...
;         for (int t = 0; t < nt; t += 2) {
;             const bool last = (t == nt - 2);
;             const char* a1 = cA + (size_t)(t + 1) * kstep;
;             const char* a2 = last ? nA : cA + (size_t)(t + 2) * kstep; const char* b2 = last ? nB : cB + (size_t)(t + 2) * kstep;
;             const char* a3 = a2 + kstep; const char* b3 = b2 + kstep;
;             PG8_LDB(B0, 0, 0); PG8_SCHED; PG8_LDA(At, 0, 0); PG8_STAGE(PG8_SA(1, 1), a1 + hstep);
;             PG8_WAIT_L(8); PG8_BAR; PG8_WAIT_L(0); PG8_MMA(0, 0, At, B0); PG8_BAR; PG8_SCHED;
;             PG8_LDB(B1, 0, 1); PG8_STAGE(PG8_SB(0, 0), b2);
;             PG8_BAR; PG8_WAIT_L(0); PG8_MMA(0, 1, At, B1); PG8_BAR;
;             PG8_LDA(At, 0, 1); PG8_STAGE(PG8_SA(0, 0), a2);
;             PG8_BAR; PG8_WAIT_L(0); PG8_MMA(1, 0, At, B0); PG8_BAR; PG8_SCHED;
.LBB0_134:
	s_add_u32 s18, s16, 0x100
	s_addc_u32 s19, s17, 0
	s_add_i32 s39, 0, 0x10000
	v_add_u32_e32 v148, s39, v199
	ds_read_b128 v[96:99], v148
	ds_read_b128 v[100:103], v148 offset:1024
	ds_read_b128 v[136:139], v148 offset:2048
	ds_read_b128 v[148:151], v148 offset:3072
	s_cmpk_eq_i32 s33, 0x54
	s_cselect_b32 s23, s9, s19
	s_cselect_b32 s22, s8, s18
	s_cselect_b32 s21, s11, s5
	s_cselect_b32 s20, s10, s4
	v_lshl_add_u64 v[218:219], s[16:17], 0, v[144:145]
	s_add_i32 m0, s28, 0xc000
	ds_read_b128 v[152:155], v201
	ds_read_b128 v[186:189], v201 offset:1024
	ds_read_b128 v[190:193], v201 offset:2048
	ds_read_b128 v[194:197], v201 offset:3072
	ds_read_b128 v[202:205], v201 offset:4096
	ds_read_b128 v[206:209], v201 offset:5120
	ds_read_b128 v[210:213], v201 offset:6144
	ds_read_b128 v[214:217], v201 offset:7168
	global_load_lds_dwordx4 v[218:219], off
	v_lshl_add_u64 v[218:219], s[16:17], 0, v[146:147]
	s_add_i32 m0, s28, 0xe000
	s_nop 0
	global_load_lds_dwordx4 v[218:219], off
	s_waitcnt lgkmcnt(8)
	s_barrier
	s_waitcnt lgkmcnt(0)
	s_setprio 1
	v_mfma_f32_16x16x32_bf16 v[132:135], v[96:99], v[152:155], v[132:135]
	v_mfma_f32_16x16x32_bf16 v[128:131], v[136:139], v[152:155], v[128:131]
	v_mfma_f32_16x16x32_bf16 v[124:127], v[96:99], v[190:193], v[124:127]
	v_mfma_f32_16x16x32_bf16 v[120:123], v[136:139], v[190:193], v[120:123]
	v_mfma_f32_16x16x32_bf16 v[116:119], v[96:99], v[202:205], v[116:119]
	v_mfma_f32_16x16x32_bf16 v[112:115], v[136:139], v[202:205], v[112:115]
	v_mfma_f32_16x16x32_bf16 v[108:111], v[96:99], v[210:213], v[108:111]
	v_mfma_f32_16x16x32_bf16 v[104:107], v[136:139], v[210:213], v[104:107]
	v_mfma_f32_16x16x32_bf16 v[132:135], v[100:103], v[186:189], v[132:135]
	v_mfma_f32_16x16x32_bf16 v[128:131], v[148:151], v[186:189], v[128:131]
	v_mfma_f32_16x16x32_bf16 v[124:127], v[100:103], v[194:197], v[124:127]
	v_mfma_f32_16x16x32_bf16 v[120:123], v[148:151], v[194:197], v[120:123]
	v_mfma_f32_16x16x32_bf16 v[116:119], v[100:103], v[206:209], v[116:119]
	v_mfma_f32_16x16x32_bf16 v[112:115], v[148:151], v[206:209], v[112:115]
	v_mfma_f32_16x16x32_bf16 v[108:111], v[100:103], v[214:217], v[108:111]
	v_mfma_f32_16x16x32_bf16 v[104:107], v[148:151], v[214:217], v[104:107]
	s_setprio 0
	s_barrier
	s_add_i32 s40, 0, 0x14000
	s_add_i32 s16, s39, s27
	v_add_u32_e32 v158, s40, v199
	v_lshl_add_u64 v[218:219], s[20:21], 0, v[142:143]
	s_mov_b32 m0, s16
	ds_read_b128 v[226:229], v158
	ds_read_b128 v[230:233], v158 offset:1024
	ds_read_b128 v[234:237], v158 offset:2048
	ds_read_b128 v[238:241], v158 offset:3072
	global_load_lds_dwordx4 v[218:219], off
	v_lshl_add_u64 v[220:221], s[20:21], 0, v[140:141]
	s_add_i32 m0, s16, 0x2000
	s_nop 0
	global_load_lds_dwordx4 v[220:221], off
	s_barrier
	s_waitcnt lgkmcnt(0)
	s_setprio 1
	v_mfma_f32_16x16x32_bf16 v[60:63], v[226:229], v[152:155], v[60:63]
	v_mfma_f32_16x16x32_bf16 v[56:59], v[234:237], v[152:155], v[56:59]
	v_mfma_f32_16x16x32_bf16 v[52:55], v[226:229], v[190:193], v[52:55]
	v_mfma_f32_16x16x32_bf16 v[48:51], v[234:237], v[190:193], v[48:51]
	v_mfma_f32_16x16x32_bf16 v[44:47], v[226:229], v[202:205], v[44:47]
	v_mfma_f32_16x16x32_bf16 v[40:43], v[234:237], v[202:205], v[40:43]
	v_mfma_f32_16x16x32_bf16 v[36:39], v[226:229], v[210:213], v[36:39]
	v_mfma_f32_16x16x32_bf16 v[32:35], v[234:237], v[210:213], v[32:35]
	v_mfma_f32_16x16x32_bf16 v[60:63], v[230:233], v[186:189], v[60:63]
	v_mfma_f32_16x16x32_bf16 v[56:59], v[238:241], v[186:189], v[56:59]
	v_mfma_f32_16x16x32_bf16 v[52:55], v[230:233], v[194:197], v[52:55]
	v_mfma_f32_16x16x32_bf16 v[48:51], v[238:241], v[194:197], v[48:51]
	v_mfma_f32_16x16x32_bf16 v[44:47], v[230:233], v[206:209], v[44:47]
	v_mfma_f32_16x16x32_bf16 v[40:43], v[238:241], v[206:209], v[40:43]
	v_mfma_f32_16x16x32_bf16 v[36:39], v[230:233], v[214:217], v[36:39]
	v_mfma_f32_16x16x32_bf16 v[32:35], v[238:241], v[214:217], v[32:35]
	s_setprio 0
	s_mov_b32 m0, s28
	v_lshl_add_u64 v[242:243], s[22:23], 0, v[142:143]
	s_barrier
	ds_read_b128 v[152:155], v201 offset:16384
	ds_read_b128 v[186:189], v201 offset:17408
	ds_read_b128 v[190:193], v201 offset:18432
	ds_read_b128 v[194:197], v201 offset:19456
	ds_read_b128 v[202:205], v201 offset:20480
	ds_read_b128 v[206:209], v201 offset:21504
	ds_read_b128 v[210:213], v201 offset:22528
	ds_read_b128 v[214:217], v201 offset:23552
	global_load_lds_dwordx4 v[242:243], off
	v_lshl_add_u64 v[244:245], s[22:23], 0, v[140:141]
	s_mov_b32 m0, s29
	s_nop 0
	global_load_lds_dwordx4 v[244:245], off
	s_barrier
	s_waitcnt lgkmcnt(0)
	s_setprio 1
	v_mfma_f32_16x16x32_bf16 v[92:95], v[96:99], v[152:155], v[92:95]
	v_mfma_f32_16x16x32_bf16 v[88:91], v[136:139], v[152:155], v[88:91]
	v_mfma_f32_16x16x32_bf16 v[84:87], v[96:99], v[190:193], v[84:87]
	v_mfma_f32_16x16x32_bf16 v[80:83], v[136:139], v[190:193], v[80:83]
	v_mfma_f32_16x16x32_bf16 v[76:79], v[96:99], v[202:205], v[76:79]
	v_mfma_f32_16x16x32_bf16 v[72:75], v[136:139], v[202:205], v[72:75]
	v_mfma_f32_16x16x32_bf16 v[68:71], v[96:99], v[210:213], v[68:71]
	v_mfma_f32_16x16x32_bf16 v[64:67], v[136:139], v[210:213], v[64:67]
	v_mfma_f32_16x16x32_bf16 v[92:95], v[100:103], v[186:189], v[92:95]
	v_mfma_f32_16x16x32_bf16 v[88:91], v[148:151], v[186:189], v[88:91]
	v_mfma_f32_16x16x32_bf16 v[84:87], v[100:103], v[194:197], v[84:87]
	v_mfma_f32_16x16x32_bf16 v[80:83], v[148:151], v[194:197], v[80:83]
	v_mfma_f32_16x16x32_bf16 v[76:79], v[100:103], v[206:209], v[76:79]
	v_mfma_f32_16x16x32_bf16 v[72:75], v[148:151], v[206:209], v[72:75]
	v_mfma_f32_16x16x32_bf16 v[68:71], v[100:103], v[214:217], v[68:71]
	v_mfma_f32_16x16x32_bf16 v[64:67], v[148:151], v[214:217], v[64:67]
	s_setprio 0
	s_barrier
; #define PG8_STAGE(bufoff, gbase) do { _Pragma("unroll") for (int _i = 0; _i < 2; ++_i) \
;         __builtin_amdgcn_global_load_lds((const unsigned*)((const char*)(gbase) + voff[_i]), (LAS unsigned*)(lds + (bufoff) + ldsw + _i * 8192), 16, 0, 0); } while (0)
; #define PG8_LDA(dst, b, h) do { _Pragma("unroll") for (int m = 0; m < 4; ++m) _Pragma("unroll") for (int k = 0; k < 2; ++k) dst[m][k] = *(const LAS bf16x8*)(lds + PG8_SA(b, h) + aoff + m * 2048 + k * 1024); } while (0)
; #define PG8_LDB(dst, b, h) do { _Pragma("unroll") for (int n = 0; n < 2; ++n) _Pragma("unroll") for (int k = 0; k < 2; ++k) dst[n][k] = *(const LAS bf16x8*)(lds + PG8_SB(b, h) + boff + n * 2048 + k * 1024); } while (0)
; #define PG8_MMA(ai, bj, At, Bt) do { __builtin_amdgcn_s_setprio(1); _Pragma("unroll") for (int m = 0; m < 4; ++m) _Pragma("unroll") for (int n = 0; n < 2; ++n) _Pragma("unroll") for (int k = 0; k < 2; ++k) \
;         acc[ai][bj][m][n] = __builtin_amdgcn_mfma_f32_16x16x32_bf16(Bt[n][k], At[m][k], acc[ai][bj][m][n], 0, 0, 0); __builtin_amdgcn_s_setprio(0); } while (0)
; #define PG8_WAIT_V(n) asm volatile("s_waitcnt vmcnt(" #n ")" ::: "memory")
; #define PG8_WAIT_L(n) asm volatile("s_waitcnt lgkmcnt(" #n ")" ::: "memory")
; #define PG8_BAR __builtin_amdgcn_s_barrier()
; #define PG8_SCHED __builtin_amdgcn_sched_barrier(0)
; template <class Epi>
; DI void gemm_phase(LAS unsigned char* lds, const Gemm g, const StaticOrder& S, const Epi& E) {
;     ...
;             PG8_STAGE(PG8_SB(0, 1), b2 + hstep);
;             PG8_WAIT_V(6); PG8_BAR; PG8_MMA(1, 1, At, B1); PG8_BAR;
;             PG8_LDB(B0, 1, 0); PG8_SCHED; PG8_LDA(At, 1, 0); PG8_STAGE(PG8_SA(0, 1), a2 + hstep);
;             PG8_WAIT_L(8); PG8_BAR; PG8_WAIT_L(0); PG8_MMA(0, 0, At, B0); PG8_BAR; PG8_SCHED;
;             PG8_LDB(B1, 1, 1); PG8_STAGE(PG8_SB(1, 0), b3);
;             PG8_BAR; PG8_WAIT_L(0); PG8_MMA(0, 1, At, B1); PG8_BAR;
;             PG8_LDA(At, 1, 1); PG8_STAGE(PG8_SA(1, 0), a3);
;             PG8_BAR; PG8_WAIT_L(0); PG8_MMA(1, 0, At, B0); PG8_BAR; PG8_SCHED;
	s_add_u32 s16, s20, 0x160000
	s_addc_u32 s17, s21, 0
	s_add_i32 s39, s40, s27
	v_lshl_add_u64 v[96:97], s[16:17], 0, v[142:143]
	s_mov_b32 m0, s39
	s_nop 0
	global_load_lds_dwordx4 v[96:97], off
	v_lshl_add_u64 v[96:97], s[16:17], 0, v[140:141]
	s_add_i32 m0, s39, 0x2000
	s_nop 0
	global_load_lds_dwordx4 v[96:97], off
	s_waitcnt vmcnt(6)
	s_barrier
	s_setprio 1
	v_mfma_f32_16x16x32_bf16 v[28:31], v[226:229], v[152:155], v[28:31]
	v_mfma_f32_16x16x32_bf16 v[24:27], v[234:237], v[152:155], v[24:27]
	v_mfma_f32_16x16x32_bf16 v[20:23], v[226:229], v[190:193], v[20:23]
	v_mfma_f32_16x16x32_bf16 v[16:19], v[234:237], v[190:193], v[16:19]
	v_mfma_f32_16x16x32_bf16 v[12:15], v[226:229], v[202:205], v[12:15]
	v_mfma_f32_16x16x32_bf16 v[8:11], v[234:237], v[202:205], v[8:11]
	v_mfma_f32_16x16x32_bf16 v[4:7], v[226:229], v[210:213], v[4:7]
	v_mfma_f32_16x16x32_bf16 v[0:3], v[234:237], v[210:213], v[0:3]
	v_mfma_f32_16x16x32_bf16 v[28:31], v[230:233], v[186:189], v[28:31]
	v_mfma_f32_16x16x32_bf16 v[24:27], v[238:241], v[186:189], v[24:27]
	v_mfma_f32_16x16x32_bf16 v[20:23], v[230:233], v[194:197], v[20:23]
	v_mfma_f32_16x16x32_bf16 v[16:19], v[238:241], v[194:197], v[16:19]
	v_mfma_f32_16x16x32_bf16 v[12:15], v[230:233], v[206:209], v[12:15]
	v_mfma_f32_16x16x32_bf16 v[8:11], v[238:241], v[206:209], v[8:11]
	v_mfma_f32_16x16x32_bf16 v[4:7], v[230:233], v[214:217], v[4:7]
	v_mfma_f32_16x16x32_bf16 v[0:3], v[238:241], v[214:217], v[0:3]
	s_setprio 0
	s_add_i32 s39, 0, 0x18000
	v_add_u32_e32 v148, s39, v199
	s_barrier
	ds_read_b128 v[96:99], v148
	ds_read_b128 v[100:103], v148 offset:1024
	ds_read_b128 v[136:139], v148 offset:2048
	ds_read_b128 v[148:151], v148 offset:3072
	s_add_u32 s16, s22, 0x160000
	s_addc_u32 s17, s23, 0
	s_mov_b32 m0, s30
	v_lshl_add_u64 v[226:227], s[16:17], 0, v[142:143]
	ds_read_b128 v[152:155], v201 offset:32768
	ds_read_b128 v[186:189], v201 offset:33792
	ds_read_b128 v[190:193], v201 offset:34816
	ds_read_b128 v[194:197], v201 offset:35840
	ds_read_b128 v[202:205], v201 offset:36864
	ds_read_b128 v[206:209], v201 offset:37888
	ds_read_b128 v[210:213], v201 offset:38912
	ds_read_b128 v[214:217], v201 offset:39936
	global_load_lds_dwordx4 v[226:227], off
	v_lshl_add_u64 v[226:227], s[16:17], 0, v[140:141]
	s_mov_b32 m0, s31
	s_nop 0
	global_load_lds_dwordx4 v[226:227], off
	s_waitcnt lgkmcnt(8)
	s_barrier
	s_waitcnt lgkmcnt(0)
	s_setprio 1
	v_mfma_f32_16x16x32_bf16 v[132:135], v[96:99], v[152:155], v[132:135]
	v_mfma_f32_16x16x32_bf16 v[128:131], v[136:139], v[152:155], v[128:131]
	v_mfma_f32_16x16x32_bf16 v[124:127], v[96:99], v[190:193], v[124:127]
	v_mfma_f32_16x16x32_bf16 v[120:123], v[136:139], v[190:193], v[120:123]
	v_mfma_f32_16x16x32_bf16 v[116:119], v[96:99], v[202:205], v[116:119]
	v_mfma_f32_16x16x32_bf16 v[112:115], v[136:139], v[202:205], v[112:115]
	v_mfma_f32_16x16x32_bf16 v[108:111], v[96:99], v[210:213], v[108:111]
	v_mfma_f32_16x16x32_bf16 v[104:107], v[136:139], v[210:213], v[104:107]
	v_mfma_f32_16x16x32_bf16 v[132:135], v[100:103], v[186:189], v[132:135]
	v_mfma_f32_16x16x32_bf16 v[128:131], v[148:151], v[186:189], v[128:131]
	v_mfma_f32_16x16x32_bf16 v[124:127], v[100:103], v[194:197], v[124:127]
	v_mfma_f32_16x16x32_bf16 v[120:123], v[148:151], v[194:197], v[120:123]
	v_mfma_f32_16x16x32_bf16 v[116:119], v[100:103], v[206:209], v[116:119]
	v_mfma_f32_16x16x32_bf16 v[112:115], v[148:151], v[206:209], v[112:115]
	v_mfma_f32_16x16x32_bf16 v[108:111], v[100:103], v[214:217], v[108:111]
	v_mfma_f32_16x16x32_bf16 v[104:107], v[148:151], v[214:217], v[104:107]
	s_setprio 0
	s_barrier
	s_add_i32 s22, 0, 0x1c000
	s_add_i32 s16, s39, s27
	v_add_u32_e32 v158, s22, v199
	v_lshl_add_u64 v[218:219], v[218:219], 0, s[94:95]
	s_mov_b32 m0, s16
	ds_read_b128 v[226:229], v158
	ds_read_b128 v[230:233], v158 offset:1024
	ds_read_b128 v[234:237], v158 offset:2048
	ds_read_b128 v[238:241], v158 offset:3072
	global_load_lds_dwordx4 v[218:219], off
	v_lshl_add_u64 v[218:219], v[220:221], 0, s[94:95]
	s_add_i32 m0, s16, 0x2000
	s_nop 0
	global_load_lds_dwordx4 v[218:219], off
	s_barrier
	s_waitcnt lgkmcnt(0)
	s_setprio 1
	v_mfma_f32_16x16x32_bf16 v[60:63], v[226:229], v[152:155], v[60:63]
	v_mfma_f32_16x16x32_bf16 v[56:59], v[234:237], v[152:155], v[56:59]
	v_mfma_f32_16x16x32_bf16 v[52:55], v[226:229], v[190:193], v[52:55]
	v_mfma_f32_16x16x32_bf16 v[48:51], v[234:237], v[190:193], v[48:51]
	v_mfma_f32_16x16x32_bf16 v[44:47], v[226:229], v[202:205], v[44:47]
	v_mfma_f32_16x16x32_bf16 v[40:43], v[234:237], v[202:205], v[40:43]
	v_mfma_f32_16x16x32_bf16 v[36:39], v[226:229], v[210:213], v[36:39]
	v_mfma_f32_16x16x32_bf16 v[32:35], v[234:237], v[210:213], v[32:35]
	v_mfma_f32_16x16x32_bf16 v[60:63], v[230:233], v[186:189], v[60:63]
	v_mfma_f32_16x16x32_bf16 v[56:59], v[238:241], v[186:189], v[56:59]
	v_mfma_f32_16x16x32_bf16 v[52:55], v[230:233], v[194:197], v[52:55]
	v_mfma_f32_16x16x32_bf16 v[48:51], v[238:241], v[194:197], v[48:51]
	v_mfma_f32_16x16x32_bf16 v[44:47], v[230:233], v[206:209], v[44:47]
	v_mfma_f32_16x16x32_bf16 v[40:43], v[238:241], v[206:209], v[40:43]
	v_mfma_f32_16x16x32_bf16 v[36:39], v[230:233], v[214:217], v[36:39]
	v_mfma_f32_16x16x32_bf16 v[32:35], v[238:241], v[214:217], v[32:35]
	s_setprio 0
	s_mov_b32 m0, s34
	v_lshl_add_u64 v[218:219], v[242:243], 0, s[94:95]
	s_barrier
	ds_read_b128 v[152:155], v201 offset:49152
	ds_read_b128 v[186:189], v201 offset:50176
	ds_read_b128 v[190:193], v201 offset:51200
	ds_read_b128 v[194:197], v201 offset:52224
	ds_read_b128 v[202:205], v201 offset:53248
	ds_read_b128 v[206:209], v201 offset:54272
	ds_read_b128 v[210:213], v201 offset:55296
	ds_read_b128 v[214:217], v201 offset:56320
	global_load_lds_dwordx4 v[218:219], off
	v_lshl_add_u64 v[218:219], v[244:245], 0, s[94:95]
	s_mov_b32 m0, s35
	s_nop 0
	global_load_lds_dwordx4 v[218:219], off
	s_barrier
; #define PG8_WAIT_V(n) asm volatile("s_waitcnt vmcnt(" #n ")" ::: "memory")
; #define PG8_WAIT_L(n) asm volatile("s_waitcnt lgkmcnt(" #n ")" ::: "memory")
; #define PG8_BAR __builtin_amdgcn_s_barrier()
; template <class Epi>
; DI void gemm_phase(LAS unsigned char* lds, const Gemm g, const StaticOrder& S, const Epi& E) {
;     ...
;             PG8_BAR; PG8_WAIT_L(0); PG8_MMA(1, 0, At, B0); PG8_BAR; PG8_SCHED;
;             PG8_STAGE(PG8_SB(1, 1), b3 + hstep);
;             PG8_WAIT_V(6); PG8_BAR; PG8_MMA(1, 1, At, B1); PG8_BAR;
;         }
;     template <bool LN, int BJ, int LO, int HI> DI void batch(const f32x4 (&acc)[2][2][4][2], unsigned row0, unsigned col0, const f32x4 (&gv)[2], const f32x4 (&bv)[2]) const {
;         f32x4 r[HI - LO]; float mean[(HI - LO) / 2], rstd[(HI - LO) / 2];
; #pragma unroll
;         for (int i = LO; i < HI; ++i) { const int ai = i >> 3, m = (i >> 1) & 3, n = i & 1; const unsigned row = row0 + ai * HALF + m * 16;
;             if (n == 0) { mean[(i - LO) >> 1] = 0.f; rstd[(i - LO) >> 1] = 1.f;
;                 if (LN) { const float2 st = *(const float2*)(stats + row * 2u); mean[(i - LO) >> 1] = st.x; rstd[(i - LO) >> 1] = st.y; } }
;             r[i - LO] = *(const f32x4*)(src + (row * (unsigned)DM + col0 + BJ * HALF + n * 16)); }
; #pragma unroll
;         for (int i = LO; i < HI; ++i) { const int ai = i >> 3, m = (i >> 1) & 3, n = i & 1; const unsigned row = row0 + ai * HALF + m * 16;
;             *(f32x4*)(Y + (row * (unsigned)DM + col0 + BJ * HALF + n * 16)) = acc[ai][BJ][m][n] + ((r[i - LO] - mean[(i - LO) >> 1]) * rstd[(i - LO) >> 1]) * gv[n] + bv[n]; }
;         __builtin_amdgcn_sched_barrier(0);
;     }
;     template <bool LN, int BJ> DI void load_gb(unsigned col0, f32x4 (&gv)[2], f32x4 (&bv)[2]) const {
; #pragma unroll
;         for (int n = 0; n < 2; ++n) {
;             if (LN) { gv[n] = *(const f32x4*)(gam + col0 + BJ * HALF + n * 16) * ALPHA; bv[n] = *(const f32x4*)(bet + col0 + BJ * HALF + n * 16) * ALPHA; }
;             else { gv[n] = (f32x4){ALPHA, ALPHA, ALPHA, ALPHA}; bv[n] = (f32x4){0.f, 0.f, 0.f, 0.f}; }
;         }
;     }
;     template <bool LN> DI void run(const f32x4 (&acc)[2][2][4][2], const Unit& u, int wr, int wc, int fr, int fq) const {
;         const unsigned row0 = u.pm * BM + wr * 64 + fr, col0 = u.pn * BM + wc * 32 + 4 * fq;
;         f32x4 gv[2], bv[2];
;         load_gb<LN, 0>(col0, gv, bv);
	s_waitcnt lgkmcnt(0)
	s_setprio 1
	v_mfma_f32_16x16x32_bf16 v[92:95], v[96:99], v[152:155], v[92:95]
	v_mfma_f32_16x16x32_bf16 v[88:91], v[136:139], v[152:155], v[88:91]
	v_mfma_f32_16x16x32_bf16 v[84:87], v[96:99], v[190:193], v[84:87]
	v_mfma_f32_16x16x32_bf16 v[80:83], v[136:139], v[190:193], v[80:83]
	v_mfma_f32_16x16x32_bf16 v[76:79], v[96:99], v[202:205], v[76:79]
	v_mfma_f32_16x16x32_bf16 v[72:75], v[136:139], v[202:205], v[72:75]
	v_mfma_f32_16x16x32_bf16 v[68:71], v[96:99], v[210:213], v[68:71]
	v_mfma_f32_16x16x32_bf16 v[64:67], v[136:139], v[210:213], v[64:67]
	v_mfma_f32_16x16x32_bf16 v[92:95], v[100:103], v[186:189], v[92:95]
	v_mfma_f32_16x16x32_bf16 v[88:91], v[148:151], v[186:189], v[88:91]
	v_mfma_f32_16x16x32_bf16 v[84:87], v[100:103], v[194:197], v[84:87]
	v_mfma_f32_16x16x32_bf16 v[80:83], v[148:151], v[194:197], v[80:83]
	v_mfma_f32_16x16x32_bf16 v[76:79], v[100:103], v[206:209], v[76:79]
	v_mfma_f32_16x16x32_bf16 v[72:75], v[148:151], v[206:209], v[72:75]
	v_mfma_f32_16x16x32_bf16 v[68:71], v[100:103], v[214:217], v[68:71]
	v_mfma_f32_16x16x32_bf16 v[64:67], v[148:151], v[214:217], v[64:67]
	s_setprio 0
	s_barrier
	s_add_u32 s16, s20, 0x160080
	s_addc_u32 s17, s21, 0
	s_add_i32 s20, s22, s27
	v_lshl_add_u64 v[96:97], s[16:17], 0, v[142:143]
	s_mov_b32 m0, s20
	s_nop 0
	global_load_lds_dwordx4 v[96:97], off
	v_lshl_add_u64 v[96:97], s[16:17], 0, v[140:141]
	s_add_i32 m0, s20, 0x2000
	s_nop 0
	global_load_lds_dwordx4 v[96:97], off
	s_waitcnt vmcnt(6)
	s_barrier
	s_setprio 1
	v_mfma_f32_16x16x32_bf16 v[28:31], v[226:229], v[152:155], v[28:31]
	v_mfma_f32_16x16x32_bf16 v[24:27], v[234:237], v[152:155], v[24:27]
	v_mfma_f32_16x16x32_bf16 v[20:23], v[226:229], v[190:193], v[20:23]
	v_mfma_f32_16x16x32_bf16 v[16:19], v[234:237], v[190:193], v[16:19]
	v_mfma_f32_16x16x32_bf16 v[12:15], v[226:229], v[202:205], v[12:15]
	v_mfma_f32_16x16x32_bf16 v[8:11], v[234:237], v[202:205], v[8:11]
	v_mfma_f32_16x16x32_bf16 v[4:7], v[226:229], v[210:213], v[4:7]
	v_mfma_f32_16x16x32_bf16 v[0:3], v[234:237], v[210:213], v[0:3]
	v_mfma_f32_16x16x32_bf16 v[28:31], v[230:233], v[186:189], v[28:31]
	v_mfma_f32_16x16x32_bf16 v[24:27], v[238:241], v[186:189], v[24:27]
	v_mfma_f32_16x16x32_bf16 v[20:23], v[230:233], v[194:197], v[20:23]
	v_mfma_f32_16x16x32_bf16 v[16:19], v[238:241], v[194:197], v[16:19]
	v_mfma_f32_16x16x32_bf16 v[12:15], v[230:233], v[206:209], v[12:15]
	v_mfma_f32_16x16x32_bf16 v[8:11], v[238:241], v[206:209], v[8:11]
	v_mfma_f32_16x16x32_bf16 v[4:7], v[230:233], v[214:217], v[4:7]
	v_mfma_f32_16x16x32_bf16 v[0:3], v[238:241], v[214:217], v[0:3]
	s_setprio 0
	s_add_i32 s33, s33, 2
	s_add_u32 s4, s4, 0x100
	s_addc_u32 s5, s5, 0
	s_cmpk_gt_u32 s33, 0x55
	s_mov_b64 s[16:17], s[18:19]
	s_barrier
	s_cbranch_scc0 .LBB0_134
	v_lshl_or_b32 v158, s2, 8, v200
	v_lshlrev_b64 v[100:101], 2, v[158:159]
	v_lshl_add_u64 v[150:151], s[12:13], 0, v[100:101]
	global_load_dwordx4 v[96:99], v[150:151], off
	v_lshl_add_u64 v[152:153], s[14:15], 0, v[100:101]
	v_lshl_add_u32 v203, s3, 8, v198
	v_lshlrev_b32_e32 v202, 11, v203
	v_add_u32_e32 v148, v202, v158
	v_mov_b32_e32 v149, v159
	v_lshlrev_b32_e32 v136, 1, v203
	v_mov_b32_e32 v137, v159
	v_lshlrev_b64 v[220:221], 2, v[148:149]
	v_lshl_add_u64 v[154:155], v[136:137], 2, s[96:97]
	v_lshl_add_u64 v[136:137], s[90:91], 0, v[220:221]
	v_or_b32_e32 v204, 16, v158
	v_or_b32_e32 v138, 16, v203
	v_lshlrev_b32_e32 v149, 11, v138
	s_waitcnt vmcnt(0)
	v_pk_mul_f32 v[192:193], v[98:99], s[78:79] op_sel_hi:[1,0]
	v_pk_mul_f32 v[194:195], v[96:97], s[78:79] op_sel_hi:[1,0]
	global_load_dwordx4 v[100:103], v[152:153], off
	global_load_dwordx4 v[96:99], v[150:151], off offset:64
	global_load_dwordx2 v[218:219], v[154:155], off
	global_load_dwordx4 v[206:209], v[136:137], off
	v_add_u32_e32 v136, v202, v204
	v_mov_b32_e32 v137, v159
	v_lshl_add_u64 v[136:137], v[136:137], 2, s[90:91]
	global_load_dwordx4 v[210:213], v[136:137], off
	v_lshlrev_b32_e32 v136, 1, v138
	v_mov_b32_e32 v137, v159
	v_lshl_add_u64 v[186:187], v[136:137], 2, s[96:97]
	v_add_u32_e32 v136, v149, v158
	v_lshl_add_u64 v[136:137], v[136:137], 2, s[90:91]
	global_load_dwordx2 v[196:197], v[186:187], off
	global_load_dwordx4 v[214:217], v[136:137], off
	v_add_u32_e32 v136, v149, v204
	v_mov_b32_e32 v137, v159
	v_lshl_add_u64 v[136:137], v[136:137], 2, s[90:91]
	global_load_dwordx4 v[136:139], v[136:137], off
	s_waitcnt vmcnt(0)
	v_pk_mul_f32 v[188:189], v[98:99], s[78:79] op_sel_hi:[1,0]
	v_pk_mul_f32 v[190:191], v[96:97], s[78:79] op_sel_hi:[1,0]
	global_load_dwordx4 v[96:99], v[152:153], off offset:64
	v_sub_f32_e32 v207, v207, v218
	v_sub_f32_e32 v206, v206, v218
	v_sub_f32_e32 v209, v209, v218
	v_sub_f32_e32 v208, v208, v218
	v_pk_mul_f32 v[208:209], v[218:219], v[208:209] op_sel:[1,0]
	v_pk_mul_f32 v[206:207], v[218:219], v[206:207] op_sel:[1,0]
	v_pk_fma_f32 v[134:135], v[192:193], v[208:209], v[134:135]
	v_pk_fma_f32 v[132:133], v[194:195], v[206:207], v[132:133]
	v_pk_fma_f32 v[134:135], v[102:103], s[78:79], v[134:135] op_sel_hi:[1,0,1]
	v_pk_fma_f32 v[132:133], v[100:101], s[78:79], v[132:133] op_sel_hi:[1,0,1]
	v_lshl_add_u64 v[206:207], s[88:89], 0, v[220:221]
	global_store_dwordx4 v[206:207], v[132:135], off
	s_nop 1
	v_sub_f32_e32 v133, v211, v218
	v_sub_f32_e32 v132, v210, v218
	v_sub_f32_e32 v135, v213, v218
	v_sub_f32_e32 v134, v212, v218
	v_pk_mul_f32 v[134:135], v[218:219], v[134:135] op_sel:[1,0]
	v_pk_mul_f32 v[132:133], v[218:219], v[132:133] op_sel:[1,0]
	v_pk_fma_f32 v[130:131], v[188:189], v[134:135], v[130:131]
	v_pk_fma_f32 v[128:129], v[190:191], v[132:133], v[128:129]
	v_or_b32_e32 v132, 16, v148
	v_mov_b32_e32 v133, v159
	v_lshl_add_u64 v[132:133], v[132:133], 2, s[88:89]
	s_waitcnt vmcnt(0)
;     template <bool LN, int BJ, int LO, int HI> DI void batch(const f32x4 (&acc)[2][2][4][2], unsigned row0, unsigned col0, const f32x4 (&gv)[2], const f32x4 (&bv)[2]) const {
;         f32x4 r[HI - LO]; float mean[(HI - LO) / 2], rstd[(HI - LO) / 2];
; #pragma unroll
;         for (int i = LO; i < HI; ++i) { const int ai = i >> 3, m = (i >> 1) & 3, n = i & 1; const unsigned row = row0 + ai * HALF + m * 16;
;             if (n == 0) { mean[(i - LO) >> 1] = 0.f; rstd[(i - LO) >> 1] = 1.f;
;                 if (LN) { const float2 st = *(const float2*)(stats + row * 2u); mean[(i - LO) >> 1] = st.x; rstd[(i - LO) >> 1] = st.y; } }
;             r[i - LO] = *(const f32x4*)(src + (row * (unsigned)DM + col0 + BJ * HALF + n * 16)); }
; #pragma unroll
;         for (int i = LO; i < HI; ++i) { const int ai = i >> 3, m = (i >> 1) & 3, n = i & 1; const unsigned row = row0 + ai * HALF + m * 16;
;             *(f32x4*)(Y + (row * (unsigned)DM + col0 + BJ * HALF + n * 16)) = acc[ai][BJ][m][n] + ((r[i - LO] - mean[(i - LO) >> 1]) * rstd[(i - LO) >> 1]) * gv[n] + bv[n]; }
;         __builtin_amdgcn_sched_barrier(0);
;     }
;     template <bool LN, int BJ> DI void load_gb(unsigned col0, f32x4 (&gv)[2], f32x4 (&bv)[2]) const {
; #pragma unroll
;         for (int n = 0; n < 2; ++n) {
;             if (LN) { gv[n] = *(const f32x4*)(gam + col0 + BJ * HALF + n * 16) * ALPHA; bv[n] = *(const f32x4*)(bet + col0 + BJ * HALF + n * 16) * ALPHA; }
;             else { gv[n] = (f32x4){ALPHA, ALPHA, ALPHA, ALPHA}; bv[n] = (f32x4){0.f, 0.f, 0.f, 0.f}; }
;         }
;     }
;     template <bool LN> DI void run(const f32x4 (&acc)[2][2][4][2], const Unit& u, int wr, int wc, int fr, int fq) const {
;         const unsigned row0 = u.pm * BM + wr * 64 + fr, col0 = u.pn * BM + wc * 32 + 4 * fq;
;         f32x4 gv[2], bv[2];
;         load_gb<LN, 0>(col0, gv, bv);
;         batch<LN, 0, 0, 4>(acc, row0, col0, gv, bv);
;         batch<LN, 0, 4, 8>(acc, row0, col0, gv, bv);
;         batch<LN, 0, 8, 12>(acc, row0, col0, gv, bv);
;         batch<LN, 0, 12, 16>(acc, row0, col0, gv, bv);
;         load_gb<LN, 1>(col0, gv, bv);
;         batch<LN, 1, 0, 8>(acc, row0, col0, gv, bv);
;         batch<LN, 1, 8, 16>(acc, row0, col0, gv, bv);
	v_pk_fma_f32 v[130:131], v[98:99], s[78:79], v[130:131] op_sel_hi:[1,0,1]
	v_pk_fma_f32 v[128:129], v[96:97], s[78:79], v[128:129] op_sel_hi:[1,0,1]
	global_store_dwordx4 v[132:133], v[128:131], off
	s_nop 1
	v_sub_f32_e32 v129, v215, v196
	v_sub_f32_e32 v128, v214, v196
	v_sub_f32_e32 v131, v217, v196
	v_sub_f32_e32 v130, v216, v196
	v_pk_mul_f32 v[130:131], v[196:197], v[130:131] op_sel:[1,0]
	v_pk_mul_f32 v[128:129], v[196:197], v[128:129] op_sel:[1,0]
	v_pk_fma_f32 v[126:127], v[192:193], v[130:131], v[126:127]
	v_pk_fma_f32 v[124:125], v[194:195], v[128:129], v[124:125]
	v_add_u32_e32 v128, 0x8000, v148
	v_mov_b32_e32 v129, v159
	v_pk_fma_f32 v[126:127], v[102:103], s[78:79], v[126:127] op_sel_hi:[1,0,1]
	v_pk_fma_f32 v[124:125], v[100:101], s[78:79], v[124:125] op_sel_hi:[1,0,1]
	v_lshl_add_u64 v[128:129], v[128:129], 2, s[88:89]
	global_store_dwordx4 v[128:129], v[124:127], off
	s_nop 1
	v_sub_f32_e32 v125, v137, v196
	v_sub_f32_e32 v124, v136, v196
	v_sub_f32_e32 v127, v139, v196
	v_sub_f32_e32 v126, v138, v196
	v_pk_mul_f32 v[126:127], v[196:197], v[126:127] op_sel:[1,0]
	v_pk_mul_f32 v[124:125], v[196:197], v[124:125] op_sel:[1,0]
	v_pk_fma_f32 v[122:123], v[188:189], v[126:127], v[122:123]
	v_pk_fma_f32 v[120:121], v[190:191], v[124:125], v[120:121]
	v_add_u32_e32 v124, 0x8010, v148
	v_mov_b32_e32 v125, v159
	v_pk_fma_f32 v[122:123], v[98:99], s[78:79], v[122:123] op_sel_hi:[1,0,1]
	v_pk_fma_f32 v[120:121], v[96:97], s[78:79], v[120:121] op_sel_hi:[1,0,1]
	v_lshl_add_u64 v[124:125], v[124:125], 2, s[88:89]
	global_store_dwordx4 v[124:125], v[120:123], off
	s_nop 1
	v_or_b32_e32 v122, 32, v203
	v_lshlrev_b32_e32 v124, 11, v122
	v_lshlrev_b32_e32 v120, 1, v122
	v_mov_b32_e32 v121, v159
	v_add_u32_e32 v122, v124, v158
	v_mov_b32_e32 v123, v159
	v_lshl_add_u64 v[120:121], v[120:121], 2, s[96:97]
	v_lshl_add_u64 v[122:123], v[122:123], 2, s[90:91]
	global_load_dwordx2 v[138:139], v[120:121], off
	global_load_dwordx4 v[126:129], v[122:123], off
	v_add_u32_e32 v122, v124, v204
	v_mov_b32_e32 v123, v159
	v_lshl_add_u64 v[122:123], v[122:123], 2, s[90:91]
	global_load_dwordx4 v[130:133], v[122:123], off
	v_or_b32_e32 v125, 48, v203
	v_lshlrev_b32_e32 v122, 1, v125
	v_lshlrev_b32_e32 v125, 11, v125
	v_mov_b32_e32 v123, v159
	v_add_u32_e32 v134, v125, v158
	v_mov_b32_e32 v135, v159
	v_lshl_add_u64 v[122:123], v[122:123], 2, s[96:97]
	v_lshl_add_u64 v[134:135], v[134:135], 2, s[90:91]
	global_load_dwordx2 v[196:197], v[122:123], off
	v_add_u32_e32 v206, v125, v204
	global_load_dwordx4 v[134:137], v[134:135], off
	v_mov_b32_e32 v207, v159
	v_lshl_add_u64 v[206:207], v[206:207], 2, s[90:91]
	global_load_dwordx4 v[206:209], v[206:207], off
	s_waitcnt vmcnt(0)
	v_sub_f32_e32 v127, v127, v138
	v_sub_f32_e32 v126, v126, v138
	v_sub_f32_e32 v129, v129, v138
	v_sub_f32_e32 v128, v128, v138
	v_pk_mul_f32 v[128:129], v[138:139], v[128:129] op_sel:[1,0]
	v_pk_mul_f32 v[126:127], v[138:139], v[126:127] op_sel:[1,0]
	v_pk_fma_f32 v[118:119], v[192:193], v[128:129], v[118:119]
	v_pk_fma_f32 v[116:117], v[194:195], v[126:127], v[116:117]
	v_add_u32_e32 v126, 0x10000, v148
	v_mov_b32_e32 v127, v159
	v_pk_fma_f32 v[118:119], v[102:103], s[78:79], v[118:119] op_sel_hi:[1,0,1]
	v_pk_fma_f32 v[116:117], v[100:101], s[78:79], v[116:117] op_sel_hi:[1,0,1]
	v_lshl_add_u64 v[126:127], v[126:127], 2, s[88:89]
	global_store_dwordx4 v[126:127], v[116:119], off
	s_nop 1
	v_sub_f32_e32 v117, v131, v138
	v_sub_f32_e32 v116, v130, v138
	v_sub_f32_e32 v119, v133, v138
	v_sub_f32_e32 v118, v132, v138
	v_pk_mul_f32 v[118:119], v[138:139], v[118:119] op_sel:[1,0]
	v_pk_mul_f32 v[116:117], v[138:139], v[116:117] op_sel:[1,0]
	v_pk_fma_f32 v[114:115], v[188:189], v[118:119], v[114:115]
	v_pk_fma_f32 v[112:113], v[190:191], v[116:117], v[112:113]
	v_add_u32_e32 v116, 0x10010, v148
	v_mov_b32_e32 v117, v159
	v_pk_fma_f32 v[114:115], v[98:99], s[78:79], v[114:115] op_sel_hi:[1,0,1]
	v_pk_fma_f32 v[112:113], v[96:97], s[78:79], v[112:113] op_sel_hi:[1,0,1]
	v_lshl_add_u64 v[116:117], v[116:117], 2, s[88:89]
	global_store_dwordx4 v[116:117], v[112:115], off
	s_nop 1
	v_sub_f32_e32 v113, v135, v196
	v_sub_f32_e32 v112, v134, v196
	v_sub_f32_e32 v115, v137, v196
	v_sub_f32_e32 v114, v136, v196
	v_pk_mul_f32 v[114:115], v[196:197], v[114:115] op_sel:[1,0]
	v_pk_mul_f32 v[112:113], v[196:197], v[112:113] op_sel:[1,0]
	v_pk_fma_f32 v[110:111], v[192:193], v[114:115], v[110:111]
	v_pk_fma_f32 v[108:109], v[194:195], v[112:113], v[108:109]
	v_add_u32_e32 v112, 0x18000, v148
	v_mov_b32_e32 v113, v159
	v_pk_fma_f32 v[110:111], v[102:103], s[78:79], v[110:111] op_sel_hi:[1,0,1]
	v_pk_fma_f32 v[108:109], v[100:101], s[78:79], v[108:109] op_sel_hi:[1,0,1]
	v_lshl_add_u64 v[112:113], v[112:113], 2, s[88:89]
	global_store_dwordx4 v[112:113], v[108:111], off
	s_nop 1
	v_sub_f32_e32 v109, v207, v196
	v_sub_f32_e32 v108, v206, v196
	v_sub_f32_e32 v111, v209, v196
	v_sub_f32_e32 v110, v208, v196
	v_pk_mul_f32 v[110:111], v[196:197], v[110:111] op_sel:[1,0]
	v_pk_mul_f32 v[108:109], v[196:197], v[108:109] op_sel:[1,0]
	v_pk_fma_f32 v[106:107], v[188:189], v[110:111], v[106:107]
	v_pk_fma_f32 v[104:105], v[190:191], v[108:109], v[104:105]
	v_add_u32_e32 v108, 0x18010, v148
	v_mov_b32_e32 v109, v159
	v_pk_fma_f32 v[106:107], v[98:99], s[78:79], v[106:107] op_sel_hi:[1,0,1]
	v_pk_fma_f32 v[104:105], v[96:97], s[78:79], v[104:105] op_sel_hi:[1,0,1]
	v_lshl_add_u64 v[108:109], v[108:109], 2, s[88:89]
	global_store_dwordx4 v[108:109], v[104:107], off
	s_nop 1
	v_add_u32_e32 v106, 0x80, v203
	v_lshlrev_b32_e32 v114, 11, v106
	v_lshlrev_b32_e32 v104, 1, v106
	v_mov_b32_e32 v105, v159
	v_add_u32_e32 v106, v114, v158
	v_mov_b32_e32 v107, v159
	v_lshl_add_u64 v[104:105], v[104:105], 2, s[96:97]
	v_lshl_add_u64 v[106:107], v[106:107], 2, s[90:91]
	global_load_dwordx2 v[112:113], v[104:105], off
	global_load_dwordx4 v[108:111], v[106:107], off
	v_add_u32_e32 v106, v114, v204
	v_mov_b32_e32 v107, v159
	v_lshl_add_u64 v[106:107], v[106:107], 2, s[90:91]
	global_load_dwordx4 v[116:119], v[106:107], off
	v_add_u32_e32 v115, 0x90, v203
	v_lshlrev_b32_e32 v106, 1, v115
	v_lshlrev_b32_e32 v115, 11, v115
	v_mov_b32_e32 v107, v159
	v_add_u32_e32 v126, v115, v158
	v_mov_b32_e32 v127, v159
	v_lshl_add_u64 v[106:107], v[106:107], 2, s[96:97]
	v_lshl_add_u64 v[126:127], v[126:127], 2, s[90:91]
	global_load_dwordx2 v[134:135], v[106:107], off
	v_add_u32_e32 v130, v115, v204
	global_load_dwordx4 v[126:129], v[126:127], off
	v_mov_b32_e32 v131, v159
	v_lshl_add_u64 v[130:131], v[130:131], 2, s[90:91]
	global_load_dwordx4 v[130:133], v[130:131], off
	s_waitcnt vmcnt(0)
;     template <bool LN, int BJ, int LO, int HI> DI void batch(const f32x4 (&acc)[2][2][4][2], unsigned row0, unsigned col0, const f32x4 (&gv)[2], const f32x4 (&bv)[2]) const {
;         f32x4 r[HI - LO]; float mean[(HI - LO) / 2], rstd[(HI - LO) / 2];
; #pragma unroll
;         for (int i = LO; i < HI; ++i) { const int ai = i >> 3, m = (i >> 1) & 3, n = i & 1; const unsigned row = row0 + ai * HALF + m * 16;
;             if (n == 0) { mean[(i - LO) >> 1] = 0.f; rstd[(i - LO) >> 1] = 1.f;
;                 if (LN) { const float2 st = *(const float2*)(stats + row * 2u); mean[(i - LO) >> 1] = st.x; rstd[(i - LO) >> 1] = st.y; } }
;             r[i - LO] = *(const f32x4*)(src + (row * (unsigned)DM + col0 + BJ * HALF + n * 16)); }
; #pragma unroll
;         for (int i = LO; i < HI; ++i) { const int ai = i >> 3, m = (i >> 1) & 3, n = i & 1; const unsigned row = row0 + ai * HALF + m * 16;
;             *(f32x4*)(Y + (row * (unsigned)DM + col0 + BJ * HALF + n * 16)) = acc[ai][BJ][m][n] + ((r[i - LO] - mean[(i - LO) >> 1]) * rstd[(i - LO) >> 1]) * gv[n] + bv[n]; }
;         __builtin_amdgcn_sched_barrier(0);
;     }
;     template <bool LN, int BJ> DI void load_gb(unsigned col0, f32x4 (&gv)[2], f32x4 (&bv)[2]) const {
; #pragma unroll
;         for (int n = 0; n < 2; ++n) {
;             if (LN) { gv[n] = *(const f32x4*)(gam + col0 + BJ * HALF + n * 16) * ALPHA; bv[n] = *(const f32x4*)(bet + col0 + BJ * HALF + n * 16) * ALPHA; }
;             else { gv[n] = (f32x4){ALPHA, ALPHA, ALPHA, ALPHA}; bv[n] = (f32x4){0.f, 0.f, 0.f, 0.f}; }
;         }
;     }
;     template <bool LN> DI void run(const f32x4 (&acc)[2][2][4][2], const Unit& u, int wr, int wc, int fr, int fq) const {
;         const unsigned row0 = u.pm * BM + wr * 64 + fr, col0 = u.pn * BM + wc * 32 + 4 * fq;
;         f32x4 gv[2], bv[2];
;         load_gb<LN, 0>(col0, gv, bv);
;         batch<LN, 0, 0, 4>(acc, row0, col0, gv, bv);
;         batch<LN, 0, 4, 8>(acc, row0, col0, gv, bv);
;         batch<LN, 0, 8, 12>(acc, row0, col0, gv, bv);
;         batch<LN, 0, 12, 16>(acc, row0, col0, gv, bv);
;         load_gb<LN, 1>(col0, gv, bv);
;         batch<LN, 1, 0, 8>(acc, row0, col0, gv, bv);
;         batch<LN, 1, 8, 16>(acc, row0, col0, gv, bv);
	v_sub_f32_e32 v109, v109, v112
	v_sub_f32_e32 v108, v108, v112
	v_sub_f32_e32 v111, v111, v112
	v_sub_f32_e32 v110, v110, v112
	v_pk_mul_f32 v[110:111], v[112:113], v[110:111] op_sel:[1,0]
	v_pk_mul_f32 v[108:109], v[112:113], v[108:109] op_sel:[1,0]
	v_pk_fma_f32 v[94:95], v[192:193], v[110:111], v[94:95]
	v_pk_fma_f32 v[92:93], v[194:195], v[108:109], v[92:93]
	v_add_u32_e32 v108, 0x40000, v148
	v_mov_b32_e32 v109, v159
	v_pk_fma_f32 v[94:95], v[102:103], s[78:79], v[94:95] op_sel_hi:[1,0,1]
	v_pk_fma_f32 v[92:93], v[100:101], s[78:79], v[92:93] op_sel_hi:[1,0,1]
	v_lshl_add_u64 v[108:109], v[108:109], 2, s[88:89]
	global_store_dwordx4 v[108:109], v[92:95], off
	s_nop 1
	v_sub_f32_e32 v93, v117, v112
	v_sub_f32_e32 v92, v116, v112
	v_sub_f32_e32 v95, v119, v112
	v_sub_f32_e32 v94, v118, v112
	v_pk_mul_f32 v[94:95], v[112:113], v[94:95] op_sel:[1,0]
	v_pk_mul_f32 v[92:93], v[112:113], v[92:93] op_sel:[1,0]
	v_pk_fma_f32 v[90:91], v[188:189], v[94:95], v[90:91]
	v_pk_fma_f32 v[88:89], v[190:191], v[92:93], v[88:89]
	v_add_u32_e32 v92, 0x40010, v148
	v_mov_b32_e32 v93, v159
	v_pk_fma_f32 v[90:91], v[98:99], s[78:79], v[90:91] op_sel_hi:[1,0,1]
	v_pk_fma_f32 v[88:89], v[96:97], s[78:79], v[88:89] op_sel_hi:[1,0,1]
	v_lshl_add_u64 v[92:93], v[92:93], 2, s[88:89]
	global_store_dwordx4 v[92:93], v[88:91], off
	s_nop 1
	v_sub_f32_e32 v89, v127, v134
	v_sub_f32_e32 v88, v126, v134
	v_sub_f32_e32 v91, v129, v134
	v_sub_f32_e32 v90, v128, v134
	v_pk_mul_f32 v[90:91], v[134:135], v[90:91] op_sel:[1,0]
	v_pk_mul_f32 v[88:89], v[134:135], v[88:89] op_sel:[1,0]
	v_pk_fma_f32 v[86:87], v[192:193], v[90:91], v[86:87]
	v_pk_fma_f32 v[84:85], v[194:195], v[88:89], v[84:85]
	v_add_u32_e32 v88, 0x48000, v148
	v_mov_b32_e32 v89, v159
	v_pk_fma_f32 v[86:87], v[102:103], s[78:79], v[86:87] op_sel_hi:[1,0,1]
	v_pk_fma_f32 v[84:85], v[100:101], s[78:79], v[84:85] op_sel_hi:[1,0,1]
	v_lshl_add_u64 v[88:89], v[88:89], 2, s[88:89]
	global_store_dwordx4 v[88:89], v[84:87], off
	s_nop 1
	v_sub_f32_e32 v85, v131, v134
	v_sub_f32_e32 v84, v130, v134
	v_sub_f32_e32 v87, v133, v134
	v_sub_f32_e32 v86, v132, v134
	v_pk_mul_f32 v[86:87], v[134:135], v[86:87] op_sel:[1,0]
	v_pk_mul_f32 v[84:85], v[134:135], v[84:85] op_sel:[1,0]
	v_pk_fma_f32 v[82:83], v[188:189], v[86:87], v[82:83]
	v_pk_fma_f32 v[80:81], v[190:191], v[84:85], v[80:81]
	v_add_u32_e32 v84, 0x48010, v148
	v_mov_b32_e32 v85, v159
	v_pk_fma_f32 v[82:83], v[98:99], s[78:79], v[82:83] op_sel_hi:[1,0,1]
	v_pk_fma_f32 v[80:81], v[96:97], s[78:79], v[80:81] op_sel_hi:[1,0,1]
	v_lshl_add_u64 v[84:85], v[84:85], 2, s[88:89]
	global_store_dwordx4 v[84:85], v[80:83], off
	s_nop 1
	v_add_u32_e32 v82, 0xa0, v203
	v_lshlrev_b32_e32 v80, 1, v82
	v_mov_b32_e32 v81, v159
	v_lshlrev_b32_e32 v116, 11, v82
	v_lshl_add_u64 v[108:109], v[80:81], 2, s[96:97]
	v_add_u32_e32 v80, v116, v158
	v_lshl_add_u64 v[80:81], v[80:81], 2, s[90:91]
	global_load_dwordx2 v[112:113], v[108:109], off
	v_add_u32_e32 v84, v116, v204
	global_load_dwordx4 v[80:83], v[80:81], off
	v_mov_b32_e32 v85, v159
	v_lshl_add_u64 v[84:85], v[84:85], 2, s[90:91]
	global_load_dwordx4 v[84:87], v[84:85], off
	v_add_u32_e32 v90, 0xb0, v203
	v_lshlrev_b32_e32 v88, 1, v90
	v_mov_b32_e32 v89, v159
	v_lshlrev_b32_e32 v117, 11, v90
	v_lshl_add_u64 v[110:111], v[88:89], 2, s[96:97]
	v_add_u32_e32 v88, v117, v158
	v_lshl_add_u64 v[88:89], v[88:89], 2, s[90:91]
	global_load_dwordx2 v[118:119], v[110:111], off
	v_add_u32_e32 v92, v117, v204
	global_load_dwordx4 v[88:91], v[88:89], off
	v_mov_b32_e32 v93, v159
	v_lshl_add_u64 v[92:93], v[92:93], 2, s[90:91]
	global_load_dwordx4 v[92:95], v[92:93], off
	s_waitcnt vmcnt(0)
	v_sub_f32_e32 v81, v81, v112
	v_sub_f32_e32 v80, v80, v112
	v_sub_f32_e32 v83, v83, v112
	v_sub_f32_e32 v82, v82, v112
	v_pk_mul_f32 v[82:83], v[112:113], v[82:83] op_sel:[1,0]
	v_pk_mul_f32 v[80:81], v[112:113], v[80:81] op_sel:[1,0]
	v_pk_fma_f32 v[78:79], v[192:193], v[82:83], v[78:79]
	v_pk_fma_f32 v[76:77], v[194:195], v[80:81], v[76:77]
	v_add_u32_e32 v80, 0x50000, v148
	v_mov_b32_e32 v81, v159
	v_pk_fma_f32 v[78:79], v[102:103], s[78:79], v[78:79] op_sel_hi:[1,0,1]
	v_pk_fma_f32 v[76:77], v[100:101], s[78:79], v[76:77] op_sel_hi:[1,0,1]
	v_lshl_add_u64 v[80:81], v[80:81], 2, s[88:89]
	global_store_dwordx4 v[80:81], v[76:79], off
	s_nop 1
	v_sub_f32_e32 v77, v85, v112
	v_sub_f32_e32 v76, v84, v112
	v_sub_f32_e32 v79, v87, v112
	v_sub_f32_e32 v78, v86, v112
	v_pk_mul_f32 v[78:79], v[112:113], v[78:79] op_sel:[1,0]
	v_pk_mul_f32 v[76:77], v[112:113], v[76:77] op_sel:[1,0]
	v_pk_fma_f32 v[74:75], v[188:189], v[78:79], v[74:75]
	v_pk_fma_f32 v[72:73], v[190:191], v[76:77], v[72:73]
	v_add_u32_e32 v76, 0x50010, v148
	v_mov_b32_e32 v77, v159
	v_pk_fma_f32 v[74:75], v[98:99], s[78:79], v[74:75] op_sel_hi:[1,0,1]
	v_pk_fma_f32 v[72:73], v[96:97], s[78:79], v[72:73] op_sel_hi:[1,0,1]
	v_lshl_add_u64 v[76:77], v[76:77], 2, s[88:89]
	global_store_dwordx4 v[76:77], v[72:75], off
	s_nop 1
	v_sub_f32_e32 v73, v89, v118
	v_sub_f32_e32 v72, v88, v118
	v_sub_f32_e32 v75, v91, v118
	v_sub_f32_e32 v74, v90, v118
	v_pk_mul_f32 v[74:75], v[118:119], v[74:75] op_sel:[1,0]
	v_pk_mul_f32 v[72:73], v[118:119], v[72:73] op_sel:[1,0]
	v_pk_fma_f32 v[70:71], v[192:193], v[74:75], v[70:71]
	v_pk_fma_f32 v[68:69], v[194:195], v[72:73], v[68:69]
	v_add_u32_e32 v72, 0x58000, v148
	v_mov_b32_e32 v73, v159
	v_pk_fma_f32 v[70:71], v[102:103], s[78:79], v[70:71] op_sel_hi:[1,0,1]
	v_pk_fma_f32 v[68:69], v[100:101], s[78:79], v[68:69] op_sel_hi:[1,0,1]
	v_lshl_add_u64 v[72:73], v[72:73], 2, s[88:89]
	global_store_dwordx4 v[72:73], v[68:71], off
	s_nop 1
	v_sub_f32_e32 v69, v93, v118
	v_sub_f32_e32 v68, v92, v118
	v_sub_f32_e32 v71, v95, v118
	v_sub_f32_e32 v70, v94, v118
	v_pk_mul_f32 v[70:71], v[118:119], v[70:71] op_sel:[1,0]
	v_pk_mul_f32 v[68:69], v[118:119], v[68:69] op_sel:[1,0]
	v_pk_fma_f32 v[66:67], v[188:189], v[70:71], v[66:67]
	v_pk_fma_f32 v[64:65], v[190:191], v[68:69], v[64:65]
	v_add_u32_e32 v68, 0x58010, v148
	v_mov_b32_e32 v69, v159
	v_pk_fma_f32 v[66:67], v[98:99], s[78:79], v[66:67] op_sel_hi:[1,0,1]
	v_pk_fma_f32 v[64:65], v[96:97], s[78:79], v[64:65] op_sel_hi:[1,0,1]
	v_lshl_add_u64 v[68:69], v[68:69], 2, s[88:89]
	global_store_dwordx4 v[68:69], v[64:67], off
	global_load_dwordx4 v[64:67], v[150:151], off offset:512
	v_or_b32_e32 v119, 0x80, v158
	v_add_u32_e32 v72, v202, v119
	v_mov_b32_e32 v73, v159
	v_lshl_add_u64 v[72:73], v[72:73], 2, s[90:91]
	v_or_b32_e32 v118, 0x90, v158
	v_add_u32_e32 v158, v202, v118
	s_waitcnt vmcnt(0)
;     template <bool LN, int BJ, int LO, int HI> DI void batch(const f32x4 (&acc)[2][2][4][2], unsigned row0, unsigned col0, const f32x4 (&gv)[2], const f32x4 (&bv)[2]) const {
;         f32x4 r[HI - LO]; float mean[(HI - LO) / 2], rstd[(HI - LO) / 2];
; #pragma unroll
;         for (int i = LO; i < HI; ++i) { const int ai = i >> 3, m = (i >> 1) & 3, n = i & 1; const unsigned row = row0 + ai * HALF + m * 16;
;             if (n == 0) { mean[(i - LO) >> 1] = 0.f; rstd[(i - LO) >> 1] = 1.f;
;                 if (LN) { const float2 st = *(const float2*)(stats + row * 2u); mean[(i - LO) >> 1] = st.x; rstd[(i - LO) >> 1] = st.y; } }
;             r[i - LO] = *(const f32x4*)(src + (row * (unsigned)DM + col0 + BJ * HALF + n * 16)); }
; #pragma unroll
;         for (int i = LO; i < HI; ++i) { const int ai = i >> 3, m = (i >> 1) & 3, n = i & 1; const unsigned row = row0 + ai * HALF + m * 16;
;             *(f32x4*)(Y + (row * (unsigned)DM + col0 + BJ * HALF + n * 16)) = acc[ai][BJ][m][n] + ((r[i - LO] - mean[(i - LO) >> 1]) * rstd[(i - LO) >> 1]) * gv[n] + bv[n]; }
;         __builtin_amdgcn_sched_barrier(0);
;     }
;     template <bool LN, int BJ> DI void load_gb(unsigned col0, f32x4 (&gv)[2], f32x4 (&bv)[2]) const {
; #pragma unroll
;         for (int n = 0; n < 2; ++n) {
;             if (LN) { gv[n] = *(const f32x4*)(gam + col0 + BJ * HALF + n * 16) * ALPHA; bv[n] = *(const f32x4*)(bet + col0 + BJ * HALF + n * 16) * ALPHA; }
;             else { gv[n] = (f32x4){ALPHA, ALPHA, ALPHA, ALPHA}; bv[n] = (f32x4){0.f, 0.f, 0.f, 0.f}; }
;         }
;     }
;     template <bool LN> DI void run(const f32x4 (&acc)[2][2][4][2], const Unit& u, int wr, int wc, int fr, int fq) const {
;         const unsigned row0 = u.pm * BM + wr * 64 + fr, col0 = u.pn * BM + wc * 32 + 4 * fq;
;         f32x4 gv[2], bv[2];
;         load_gb<LN, 0>(col0, gv, bv);
;         batch<LN, 0, 0, 4>(acc, row0, col0, gv, bv);
;         batch<LN, 0, 4, 8>(acc, row0, col0, gv, bv);
;         batch<LN, 0, 8, 12>(acc, row0, col0, gv, bv);
;         batch<LN, 0, 12, 16>(acc, row0, col0, gv, bv);
;         load_gb<LN, 1>(col0, gv, bv);
;         batch<LN, 1, 0, 8>(acc, row0, col0, gv, bv);
;         batch<LN, 1, 8, 16>(acc, row0, col0, gv, bv);
	v_pk_mul_f32 v[96:97], v[66:67], s[78:79] op_sel_hi:[1,0]
	v_pk_mul_f32 v[98:99], v[64:65], s[78:79] op_sel_hi:[1,0]
	global_load_dwordx4 v[68:71], v[152:153], off offset:512
	global_load_dwordx4 v[64:67], v[150:151], off offset:576
	global_load_dwordx2 v[138:139], v[154:155], off
	global_load_dwordx4 v[126:129], v[72:73], off
	v_lshl_add_u64 v[72:73], v[158:159], 2, s[90:91]
	v_add_u32_e32 v158, v149, v119
	s_waitcnt vmcnt(0)
	v_pk_mul_f32 v[92:93], v[66:67], s[78:79] op_sel_hi:[1,0]
	v_pk_mul_f32 v[94:95], v[64:65], s[78:79] op_sel_hi:[1,0]
	global_load_dwordx4 v[64:67], v[152:153], off offset:576
	global_load_dwordx4 v[130:133], v[72:73], off
	global_load_dwordx2 v[112:113], v[186:187], off
	v_lshl_add_u64 v[72:73], v[158:159], 2, s[90:91]
	global_load_dwordx4 v[134:137], v[72:73], off
	v_add_u32_e32 v158, v149, v118
	v_lshl_add_u64 v[72:73], v[158:159], 2, s[90:91]
	global_load_dwordx4 v[88:91], v[72:73], off
	global_load_dwordx2 v[102:103], v[120:121], off
	v_add_u32_e32 v158, v124, v119
	v_lshl_add_u64 v[72:73], v[158:159], 2, s[90:91]
	global_load_dwordx4 v[84:87], v[72:73], off
	v_add_u32_e32 v158, v124, v118
	v_lshl_add_u64 v[72:73], v[158:159], 2, s[90:91]
	global_load_dwordx4 v[80:83], v[72:73], off
	global_load_dwordx2 v[100:101], v[122:123], off
	v_add_u32_e32 v158, v125, v119
	v_lshl_add_u64 v[72:73], v[158:159], 2, s[90:91]
	global_load_dwordx4 v[76:79], v[72:73], off
	v_add_u32_e32 v158, v125, v118
	v_lshl_add_u64 v[72:73], v[158:159], 2, s[90:91]
	global_load_dwordx4 v[72:75], v[72:73], off
	v_sub_f32_e32 v121, v127, v138
	v_sub_f32_e32 v120, v126, v138
	v_sub_f32_e32 v123, v129, v138
	v_sub_f32_e32 v122, v128, v138
	v_pk_mul_f32 v[122:123], v[138:139], v[122:123] op_sel:[1,0]
	v_pk_mul_f32 v[120:121], v[138:139], v[120:121] op_sel:[1,0]
	v_or_b32_e32 v158, 0x80, v148
	v_pk_fma_f32 v[60:61], v[98:99], v[120:121], v[60:61]
	v_pk_fma_f32 v[62:63], v[96:97], v[122:123], v[62:63]
	v_pk_fma_f32 v[60:61], v[68:69], s[78:79], v[60:61] op_sel_hi:[1,0,1]
	v_pk_fma_f32 v[62:63], v[70:71], s[78:79], v[62:63] op_sel_hi:[1,0,1]
	v_lshl_add_u64 v[120:121], v[158:159], 2, s[88:89]
	global_store_dwordx4 v[120:121], v[60:63], off
	v_or_b32_e32 v158, 0x90, v148
	s_waitcnt vmcnt(0)
	v_sub_f32_e32 v61, v131, v138
	v_sub_f32_e32 v60, v130, v138
	v_sub_f32_e32 v63, v133, v138
	v_sub_f32_e32 v62, v132, v138
	v_pk_mul_f32 v[62:63], v[138:139], v[62:63] op_sel:[1,0]
	v_pk_mul_f32 v[60:61], v[138:139], v[60:61] op_sel:[1,0]
	v_pk_fma_f32 v[58:59], v[92:93], v[62:63], v[58:59]
	v_pk_fma_f32 v[56:57], v[94:95], v[60:61], v[56:57]
	v_pk_fma_f32 v[58:59], v[66:67], s[78:79], v[58:59] op_sel_hi:[1,0,1]
	v_pk_fma_f32 v[56:57], v[64:65], s[78:79], v[56:57] op_sel_hi:[1,0,1]
	v_lshl_add_u64 v[60:61], v[158:159], 2, s[88:89]
	global_store_dwordx4 v[60:61], v[56:59], off
	v_add_u32_e32 v158, 0x8080, v148
	s_nop 0
	v_sub_f32_e32 v57, v135, v112
	v_sub_f32_e32 v56, v134, v112
	v_sub_f32_e32 v59, v137, v112
	v_sub_f32_e32 v58, v136, v112
	v_pk_mul_f32 v[58:59], v[112:113], v[58:59] op_sel:[1,0]
	v_pk_mul_f32 v[56:57], v[112:113], v[56:57] op_sel:[1,0]
	v_pk_fma_f32 v[54:55], v[96:97], v[58:59], v[54:55]
	v_pk_fma_f32 v[52:53], v[98:99], v[56:57], v[52:53]
	v_pk_fma_f32 v[54:55], v[70:71], s[78:79], v[54:55] op_sel_hi:[1,0,1]
	v_pk_fma_f32 v[52:53], v[68:69], s[78:79], v[52:53] op_sel_hi:[1,0,1]
	v_lshl_add_u64 v[56:57], v[158:159], 2, s[88:89]
	global_store_dwordx4 v[56:57], v[52:55], off
	v_add_u32_e32 v158, 0x8090, v148
	s_nop 0
	v_sub_f32_e32 v53, v89, v112
	v_sub_f32_e32 v52, v88, v112
	v_sub_f32_e32 v55, v91, v112
	v_sub_f32_e32 v54, v90, v112
	v_pk_mul_f32 v[54:55], v[112:113], v[54:55] op_sel:[1,0]
	v_pk_mul_f32 v[52:53], v[112:113], v[52:53] op_sel:[1,0]
	v_pk_fma_f32 v[50:51], v[92:93], v[54:55], v[50:51]
	v_pk_fma_f32 v[48:49], v[94:95], v[52:53], v[48:49]
	v_pk_fma_f32 v[50:51], v[66:67], s[78:79], v[50:51] op_sel_hi:[1,0,1]
	v_pk_fma_f32 v[48:49], v[64:65], s[78:79], v[48:49] op_sel_hi:[1,0,1]
	v_lshl_add_u64 v[52:53], v[158:159], 2, s[88:89]
	global_store_dwordx4 v[52:53], v[48:51], off
	v_add_u32_e32 v158, 0x10080, v148
	s_nop 0
	v_sub_f32_e32 v49, v85, v102
	v_sub_f32_e32 v48, v84, v102
	v_sub_f32_e32 v51, v87, v102
	v_sub_f32_e32 v50, v86, v102
	v_pk_mul_f32 v[50:51], v[102:103], v[50:51] op_sel:[1,0]
	v_pk_mul_f32 v[48:49], v[102:103], v[48:49] op_sel:[1,0]
	v_pk_fma_f32 v[46:47], v[96:97], v[50:51], v[46:47]
	v_pk_fma_f32 v[44:45], v[98:99], v[48:49], v[44:45]
	v_pk_fma_f32 v[46:47], v[70:71], s[78:79], v[46:47] op_sel_hi:[1,0,1]
	v_pk_fma_f32 v[44:45], v[68:69], s[78:79], v[44:45] op_sel_hi:[1,0,1]
	v_lshl_add_u64 v[48:49], v[158:159], 2, s[88:89]
	global_store_dwordx4 v[48:49], v[44:47], off
	v_add_u32_e32 v158, 0x10090, v148
	s_nop 0
	v_sub_f32_e32 v45, v81, v102
	v_sub_f32_e32 v44, v80, v102
	v_sub_f32_e32 v47, v83, v102
	v_sub_f32_e32 v46, v82, v102
	v_pk_mul_f32 v[46:47], v[102:103], v[46:47] op_sel:[1,0]
	v_pk_mul_f32 v[44:45], v[102:103], v[44:45] op_sel:[1,0]
	v_pk_fma_f32 v[42:43], v[92:93], v[46:47], v[42:43]
	v_pk_fma_f32 v[40:41], v[94:95], v[44:45], v[40:41]
	v_pk_fma_f32 v[42:43], v[66:67], s[78:79], v[42:43] op_sel_hi:[1,0,1]
	v_pk_fma_f32 v[40:41], v[64:65], s[78:79], v[40:41] op_sel_hi:[1,0,1]
	v_lshl_add_u64 v[44:45], v[158:159], 2, s[88:89]
	global_store_dwordx4 v[44:45], v[40:43], off
	v_add_u32_e32 v158, 0x18080, v148
	s_nop 0
	v_sub_f32_e32 v41, v77, v100
	v_sub_f32_e32 v40, v76, v100
	v_sub_f32_e32 v43, v79, v100
	v_sub_f32_e32 v42, v78, v100
	v_pk_mul_f32 v[42:43], v[100:101], v[42:43] op_sel:[1,0]
	v_pk_mul_f32 v[40:41], v[100:101], v[40:41] op_sel:[1,0]
	v_pk_fma_f32 v[38:39], v[96:97], v[42:43], v[38:39]
;     template <bool LN, int BJ, int LO, int HI> DI void batch(const f32x4 (&acc)[2][2][4][2], unsigned row0, unsigned col0, const f32x4 (&gv)[2], const f32x4 (&bv)[2]) const {
;         f32x4 r[HI - LO]; float mean[(HI - LO) / 2], rstd[(HI - LO) / 2];
; #pragma unroll
;         for (int i = LO; i < HI; ++i) { const int ai = i >> 3, m = (i >> 1) & 3, n = i & 1; const unsigned row = row0 + ai * HALF + m * 16;
;             if (n == 0) { mean[(i - LO) >> 1] = 0.f; rstd[(i - LO) >> 1] = 1.f;
;                 if (LN) { const float2 st = *(const float2*)(stats + row * 2u); mean[(i - LO) >> 1] = st.x; rstd[(i - LO) >> 1] = st.y; } }
;             r[i - LO] = *(const f32x4*)(src + (row * (unsigned)DM + col0 + BJ * HALF + n * 16)); }
; #pragma unroll
;         for (int i = LO; i < HI; ++i) { const int ai = i >> 3, m = (i >> 1) & 3, n = i & 1; const unsigned row = row0 + ai * HALF + m * 16;
;             *(f32x4*)(Y + (row * (unsigned)DM + col0 + BJ * HALF + n * 16)) = acc[ai][BJ][m][n] + ((r[i - LO] - mean[(i - LO) >> 1]) * rstd[(i - LO) >> 1]) * gv[n] + bv[n]; }
;         __builtin_amdgcn_sched_barrier(0);
;     }
;     template <bool LN, int BJ> DI void load_gb(unsigned col0, f32x4 (&gv)[2], f32x4 (&bv)[2]) const {
; #pragma unroll
;         for (int n = 0; n < 2; ++n) {
;             if (LN) { gv[n] = *(const f32x4*)(gam + col0 + BJ * HALF + n * 16) * ALPHA; bv[n] = *(const f32x4*)(bet + col0 + BJ * HALF + n * 16) * ALPHA; }
;             else { gv[n] = (f32x4){ALPHA, ALPHA, ALPHA, ALPHA}; bv[n] = (f32x4){0.f, 0.f, 0.f, 0.f}; }
;         }
;     }
;     template <bool LN> DI void run(const f32x4 (&acc)[2][2][4][2], const Unit& u, int wr, int wc, int fr, int fq) const {
;         const unsigned row0 = u.pm * BM + wr * 64 + fr, col0 = u.pn * BM + wc * 32 + 4 * fq;
;         f32x4 gv[2], bv[2];
;         load_gb<LN, 0>(col0, gv, bv);
;         batch<LN, 0, 0, 4>(acc, row0, col0, gv, bv);
;         batch<LN, 0, 4, 8>(acc, row0, col0, gv, bv);
;         batch<LN, 0, 8, 12>(acc, row0, col0, gv, bv);
;         batch<LN, 0, 12, 16>(acc, row0, col0, gv, bv);
;         load_gb<LN, 1>(col0, gv, bv);
;         batch<LN, 1, 0, 8>(acc, row0, col0, gv, bv);
;         batch<LN, 1, 8, 16>(acc, row0, col0, gv, bv);
	v_pk_fma_f32 v[36:37], v[98:99], v[40:41], v[36:37]
	v_pk_fma_f32 v[38:39], v[70:71], s[78:79], v[38:39] op_sel_hi:[1,0,1]
	v_pk_fma_f32 v[36:37], v[68:69], s[78:79], v[36:37] op_sel_hi:[1,0,1]
	v_lshl_add_u64 v[40:41], v[158:159], 2, s[88:89]
	global_store_dwordx4 v[40:41], v[36:39], off
	v_add_u32_e32 v158, 0x18090, v148
	s_nop 0
	v_sub_f32_e32 v37, v73, v100
	v_sub_f32_e32 v36, v72, v100
	v_sub_f32_e32 v39, v75, v100
	v_sub_f32_e32 v38, v74, v100
	v_pk_mul_f32 v[38:39], v[100:101], v[38:39] op_sel:[1,0]
	v_pk_mul_f32 v[36:37], v[100:101], v[36:37] op_sel:[1,0]
	v_pk_fma_f32 v[34:35], v[92:93], v[38:39], v[34:35]
	v_pk_fma_f32 v[32:33], v[94:95], v[36:37], v[32:33]
	v_pk_fma_f32 v[34:35], v[66:67], s[78:79], v[34:35] op_sel_hi:[1,0,1]
	v_pk_fma_f32 v[32:33], v[64:65], s[78:79], v[32:33] op_sel_hi:[1,0,1]
	v_lshl_add_u64 v[36:37], v[158:159], 2, s[88:89]
	global_store_dwordx4 v[36:37], v[32:35], off
	v_add_u32_e32 v158, v114, v119
	s_nop 0
	v_lshl_add_u64 v[32:33], v[158:159], 2, s[90:91]
	global_load_dwordx2 v[62:63], v[104:105], off
	global_load_dwordx4 v[54:57], v[32:33], off
	v_add_u32_e32 v158, v114, v118
	v_lshl_add_u64 v[32:33], v[158:159], 2, s[90:91]
	global_load_dwordx4 v[58:61], v[32:33], off
	global_load_dwordx2 v[52:53], v[106:107], off
	v_add_u32_e32 v158, v115, v119
	v_lshl_add_u64 v[32:33], v[158:159], 2, s[90:91]
	global_load_dwordx4 v[72:75], v[32:33], off
	v_add_u32_e32 v158, v115, v118
	v_lshl_add_u64 v[32:33], v[158:159], 2, s[90:91]
	global_load_dwordx4 v[76:79], v[32:33], off
	global_load_dwordx2 v[50:51], v[108:109], off
	v_add_u32_e32 v158, v116, v119
	v_lshl_add_u64 v[32:33], v[158:159], 2, s[90:91]
	global_load_dwordx4 v[44:47], v[32:33], off
	v_add_u32_e32 v158, v116, v118
	v_lshl_add_u64 v[32:33], v[158:159], 2, s[90:91]
	global_load_dwordx4 v[40:43], v[32:33], off
	global_load_dwordx2 v[48:49], v[110:111], off
	v_add_u32_e32 v158, v117, v119
	v_lshl_add_u64 v[32:33], v[158:159], 2, s[90:91]
	global_load_dwordx4 v[36:39], v[32:33], off
	v_add_u32_e32 v158, v117, v118
	v_lshl_add_u64 v[32:33], v[158:159], 2, s[90:91]
	global_load_dwordx4 v[32:35], v[32:33], off
	v_add_u32_e32 v158, 0x40080, v148
	s_waitcnt vmcnt(0)
; template <class Epi>
; DI void gemm_phase(LAS unsigned char* lds, const Gemm g, const StaticOrder& S, const Epi& E) {
;     ...
;         E(acc, cur, wr, wc, fr, fq);
;     template <bool LN, int BJ, int LO, int HI> DI void batch(const f32x4 (&acc)[2][2][4][2], unsigned row0, unsigned col0, const f32x4 (&gv)[2], const f32x4 (&bv)[2]) const {
;         f32x4 r[HI - LO]; float mean[(HI - LO) / 2], rstd[(HI - LO) / 2];
; #pragma unroll
;         for (int i = LO; i < HI; ++i) { const int ai = i >> 3, m = (i >> 1) & 3, n = i & 1; const unsigned row = row0 + ai * HALF + m * 16;
;             if (n == 0) { mean[(i - LO) >> 1] = 0.f; rstd[(i - LO) >> 1] = 1.f;
;                 if (LN) { const float2 st = *(const float2*)(stats + row * 2u); mean[(i - LO) >> 1] = st.x; rstd[(i - LO) >> 1] = st.y; } }
;             r[i - LO] = *(const f32x4*)(src + (row * (unsigned)DM + col0 + BJ * HALF + n * 16)); }
; #pragma unroll
;         for (int i = LO; i < HI; ++i) { const int ai = i >> 3, m = (i >> 1) & 3, n = i & 1; const unsigned row = row0 + ai * HALF + m * 16;
;             *(f32x4*)(Y + (row * (unsigned)DM + col0 + BJ * HALF + n * 16)) = acc[ai][BJ][m][n] + ((r[i - LO] - mean[(i - LO) >> 1]) * rstd[(i - LO) >> 1]) * gv[n] + bv[n]; }
;         __builtin_amdgcn_sched_barrier(0);
;     }
;     template <bool LN, int BJ> DI void load_gb(unsigned col0, f32x4 (&gv)[2], f32x4 (&bv)[2]) const {
; #pragma unroll
;         for (int n = 0; n < 2; ++n) {
;             if (LN) { gv[n] = *(const f32x4*)(gam + col0 + BJ * HALF + n * 16) * ALPHA; bv[n] = *(const f32x4*)(bet + col0 + BJ * HALF + n * 16) * ALPHA; }
;             else { gv[n] = (f32x4){ALPHA, ALPHA, ALPHA, ALPHA}; bv[n] = (f32x4){0.f, 0.f, 0.f, 0.f}; }
;         }
;     }
;     template <bool LN> DI void run(const f32x4 (&acc)[2][2][4][2], const Unit& u, int wr, int wc, int fr, int fq) const {
;         const unsigned row0 = u.pm * BM + wr * 64 + fr, col0 = u.pn * BM + wc * 32 + 4 * fq;
;         f32x4 gv[2], bv[2];
;         load_gb<LN, 0>(col0, gv, bv);
;         batch<LN, 0, 0, 4>(acc, row0, col0, gv, bv);
;         batch<LN, 0, 4, 8>(acc, row0, col0, gv, bv);
;         batch<LN, 0, 8, 12>(acc, row0, col0, gv, bv);
;         batch<LN, 0, 12, 16>(acc, row0, col0, gv, bv);
;         load_gb<LN, 1>(col0, gv, bv);
;         batch<LN, 1, 0, 8>(acc, row0, col0, gv, bv);
;         batch<LN, 1, 8, 16>(acc, row0, col0, gv, bv);
	v_sub_f32_e32 v55, v55, v62
	v_sub_f32_e32 v54, v54, v62
	v_sub_f32_e32 v57, v57, v62
	v_sub_f32_e32 v56, v56, v62
	v_pk_mul_f32 v[56:57], v[62:63], v[56:57] op_sel:[1,0]
	v_pk_mul_f32 v[54:55], v[62:63], v[54:55] op_sel:[1,0]
	v_pk_fma_f32 v[30:31], v[96:97], v[56:57], v[30:31]
	v_pk_fma_f32 v[28:29], v[98:99], v[54:55], v[28:29]
	v_pk_fma_f32 v[30:31], v[70:71], s[78:79], v[30:31] op_sel_hi:[1,0,1]
	v_pk_fma_f32 v[28:29], v[68:69], s[78:79], v[28:29] op_sel_hi:[1,0,1]
	v_lshl_add_u64 v[54:55], v[158:159], 2, s[88:89]
	global_store_dwordx4 v[54:55], v[28:31], off
	v_add_u32_e32 v158, 0x40090, v148
	s_nop 0
	v_sub_f32_e32 v29, v59, v62
	v_sub_f32_e32 v28, v58, v62
	v_sub_f32_e32 v31, v61, v62
	v_sub_f32_e32 v30, v60, v62
	v_pk_mul_f32 v[30:31], v[62:63], v[30:31] op_sel:[1,0]
	v_pk_mul_f32 v[28:29], v[62:63], v[28:29] op_sel:[1,0]
	v_pk_fma_f32 v[26:27], v[92:93], v[30:31], v[26:27]
	v_pk_fma_f32 v[24:25], v[94:95], v[28:29], v[24:25]
	v_pk_fma_f32 v[26:27], v[66:67], s[78:79], v[26:27] op_sel_hi:[1,0,1]
	v_pk_fma_f32 v[24:25], v[64:65], s[78:79], v[24:25] op_sel_hi:[1,0,1]
	v_lshl_add_u64 v[28:29], v[158:159], 2, s[88:89]
	global_store_dwordx4 v[28:29], v[24:27], off
	v_add_u32_e32 v158, 0x48080, v148
	s_nop 0
	v_sub_f32_e32 v25, v73, v52
	v_sub_f32_e32 v24, v72, v52
	v_sub_f32_e32 v27, v75, v52
	v_sub_f32_e32 v26, v74, v52
	v_pk_mul_f32 v[26:27], v[52:53], v[26:27] op_sel:[1,0]
	v_pk_mul_f32 v[24:25], v[52:53], v[24:25] op_sel:[1,0]
	v_pk_fma_f32 v[22:23], v[96:97], v[26:27], v[22:23]
	v_pk_fma_f32 v[20:21], v[98:99], v[24:25], v[20:21]
	v_pk_fma_f32 v[22:23], v[70:71], s[78:79], v[22:23] op_sel_hi:[1,0,1]
	v_pk_fma_f32 v[20:21], v[68:69], s[78:79], v[20:21] op_sel_hi:[1,0,1]
	v_lshl_add_u64 v[24:25], v[158:159], 2, s[88:89]
	global_store_dwordx4 v[24:25], v[20:23], off
	v_add_u32_e32 v158, 0x48090, v148
	s_nop 0
	v_sub_f32_e32 v21, v77, v52
	v_sub_f32_e32 v20, v76, v52
	v_sub_f32_e32 v23, v79, v52
	v_sub_f32_e32 v22, v78, v52
	v_pk_mul_f32 v[22:23], v[52:53], v[22:23] op_sel:[1,0]
	v_pk_mul_f32 v[20:21], v[52:53], v[20:21] op_sel:[1,0]
	v_pk_fma_f32 v[18:19], v[92:93], v[22:23], v[18:19]
	v_pk_fma_f32 v[16:17], v[94:95], v[20:21], v[16:17]
	v_pk_fma_f32 v[18:19], v[66:67], s[78:79], v[18:19] op_sel_hi:[1,0,1]
	v_pk_fma_f32 v[16:17], v[64:65], s[78:79], v[16:17] op_sel_hi:[1,0,1]
	v_lshl_add_u64 v[20:21], v[158:159], 2, s[88:89]
	global_store_dwordx4 v[20:21], v[16:19], off
	v_add_u32_e32 v158, 0x50080, v148
	s_nop 0
	v_sub_f32_e32 v17, v45, v50
	v_sub_f32_e32 v16, v44, v50
	v_sub_f32_e32 v19, v47, v50
	v_sub_f32_e32 v18, v46, v50
	v_pk_mul_f32 v[18:19], v[50:51], v[18:19] op_sel:[1,0]
	v_pk_mul_f32 v[16:17], v[50:51], v[16:17] op_sel:[1,0]
	v_pk_fma_f32 v[14:15], v[96:97], v[18:19], v[14:15]
	v_pk_fma_f32 v[12:13], v[98:99], v[16:17], v[12:13]
	v_pk_fma_f32 v[14:15], v[70:71], s[78:79], v[14:15] op_sel_hi:[1,0,1]
	v_pk_fma_f32 v[12:13], v[68:69], s[78:79], v[12:13] op_sel_hi:[1,0,1]
	v_lshl_add_u64 v[16:17], v[158:159], 2, s[88:89]
	global_store_dwordx4 v[16:17], v[12:15], off
	v_add_u32_e32 v158, 0x50090, v148
	s_nop 0
	v_sub_f32_e32 v13, v41, v50
	v_sub_f32_e32 v12, v40, v50
	v_sub_f32_e32 v15, v43, v50
	v_sub_f32_e32 v14, v42, v50
	v_pk_mul_f32 v[14:15], v[50:51], v[14:15] op_sel:[1,0]
	v_pk_mul_f32 v[12:13], v[50:51], v[12:13] op_sel:[1,0]
	v_pk_fma_f32 v[10:11], v[92:93], v[14:15], v[10:11]
	v_pk_fma_f32 v[8:9], v[94:95], v[12:13], v[8:9]
	v_pk_fma_f32 v[10:11], v[66:67], s[78:79], v[10:11] op_sel_hi:[1,0,1]
	v_pk_fma_f32 v[8:9], v[64:65], s[78:79], v[8:9] op_sel_hi:[1,0,1]
	v_lshl_add_u64 v[12:13], v[158:159], 2, s[88:89]
	global_store_dwordx4 v[12:13], v[8:11], off
	v_add_u32_e32 v158, 0x58080, v148
	s_nop 0
	v_sub_f32_e32 v9, v37, v48
	v_sub_f32_e32 v8, v36, v48
	v_sub_f32_e32 v11, v39, v48
	v_sub_f32_e32 v10, v38, v48
	v_pk_mul_f32 v[10:11], v[48:49], v[10:11] op_sel:[1,0]
	v_pk_mul_f32 v[8:9], v[48:49], v[8:9] op_sel:[1,0]
	v_pk_fma_f32 v[6:7], v[96:97], v[10:11], v[6:7]
	v_pk_fma_f32 v[4:5], v[98:99], v[8:9], v[4:5]
	v_pk_fma_f32 v[6:7], v[70:71], s[78:79], v[6:7] op_sel_hi:[1,0,1]
	v_pk_fma_f32 v[4:5], v[68:69], s[78:79], v[4:5] op_sel_hi:[1,0,1]
	v_lshl_add_u64 v[8:9], v[158:159], 2, s[88:89]
	global_store_dwordx4 v[8:9], v[4:7], off
	v_add_u32_e32 v158, 0x58090, v148
	s_nop 0
	v_sub_f32_e32 v5, v33, v48
	v_sub_f32_e32 v4, v32, v48
	v_sub_f32_e32 v7, v35, v48
	v_sub_f32_e32 v6, v34, v48
	v_pk_mul_f32 v[6:7], v[48:49], v[6:7] op_sel:[1,0]
	v_pk_mul_f32 v[4:5], v[48:49], v[4:5] op_sel:[1,0]
	v_pk_fma_f32 v[2:3], v[92:93], v[6:7], v[2:3]
	v_pk_fma_f32 v[0:1], v[94:95], v[4:5], v[0:1]
	v_pk_fma_f32 v[2:3], v[66:67], s[78:79], v[2:3] op_sel_hi:[1,0,1]
	v_pk_fma_f32 v[0:1], v[64:65], s[78:79], v[0:1] op_sel_hi:[1,0,1]
	v_lshl_add_u64 v[4:5], v[158:159], 2, s[88:89]
	global_store_dwordx4 v[4:5], v[0:3], off
	s_and_b64 vcc, exec, s[6:7]
	s_mov_b32 s2, s37
	s_mov_b32 s3, s38
	s_mov_b64 s[18:19], s[10:11]
	s_mov_b64 s[16:17], s[8:9]
	v_readlane_b32 s33, v255, 39
	s_cbranch_vccz .LBB0_123
	s_waitcnt vmcnt(0)
	s_cmpk_gt_u32 s24, 0xff
	s_cbranch_scc1 .LBB0_138
	s_barrier

; #define PG8_STAGE(bufoff, gbase) do { _Pragma("unroll") for (int _i = 0; _i < 2; ++_i) \
;         __builtin_amdgcn_global_load_lds((const unsigned*)((const char*)(gbase) + voff[_i]), (LAS unsigned*)(lds + (bufoff) + ldsw + _i * 8192), 16, 0, 0); } while (0)
; #define PG8_LDA(dst, b, h) do { _Pragma("unroll") for (int m = 0; m < 4; ++m) _Pragma("unroll") for (int k = 0; k < 2; ++k) dst[m][k] = *(const LAS bf16x8*)(lds + PG8_SA(b, h) + aoff + m * 2048 + k * 1024); } while (0)
; #define PG8_LDB(dst, b, h) do { _Pragma("unroll") for (int n = 0; n < 2; ++n) _Pragma("unroll") for (int k = 0; k < 2; ++k) dst[n][k] = *(const LAS bf16x8*)(lds + PG8_SB(b, h) + boff + n * 2048 + k * 1024); } while (0)
; #define PG8_MMA(ai, bj, At, Bt) do { __builtin_amdgcn_s_setprio(1); _Pragma("unroll") for (int m = 0; m < 4; ++m) _Pragma("unroll") for (int n = 0; n < 2; ++n) _Pragma("unroll") for (int k = 0; k < 2; ++k) \
;         acc[ai][bj][m][n] = __builtin_amdgcn_mfma_f32_16x16x32_bf16(Bt[n][k], At[m][k], acc[ai][bj][m][n], 0, 0, 0); __builtin_amdgcn_s_setprio(0); } while (0)
; #define PG8_WAIT_L(n) asm volatile("s_waitcnt lgkmcnt(" #n ")" ::: "memory")
; #define PG8_BAR __builtin_amdgcn_s_barrier()
; #define PG8_SCHED __builtin_amdgcn_sched_barrier(0)
; template <class Epi>
; DI void gemm_phase(LAS unsigned char* lds, const Gemm g, const StaticOrder& S, const Epi& E) {
;     ...
;         for (int t = 0; t < nt; t += 2) {
;             const bool last = (t == nt - 2);
;             const char* a1 = cA + (size_t)(t + 1) * kstep;
;             const char* a2 = last ? nA : cA + (size_t)(t + 2) * kstep; const char* b2 = last ? nB : cB + (size_t)(t + 2) * kstep;
;             const char* a3 = a2 + kstep; const char* b3 = b2 + kstep;
;             PG8_LDB(B0, 0, 0); PG8_SCHED; PG8_LDA(At, 0, 0); PG8_STAGE(PG8_SA(1, 1), a1 + hstep);
;             PG8_WAIT_L(8); PG8_BAR; PG8_WAIT_L(0); PG8_MMA(0, 0, At, B0); PG8_BAR; PG8_SCHED;
;             PG8_LDB(B1, 0, 1); PG8_STAGE(PG8_SB(0, 0), b2);
;             PG8_BAR; PG8_WAIT_L(0); PG8_MMA(0, 1, At, B1); PG8_BAR;
;             PG8_LDA(At, 0, 1); PG8_STAGE(PG8_SA(0, 0), a2);
;             PG8_BAR; PG8_WAIT_L(0); PG8_MMA(1, 0, At, B0); PG8_BAR; PG8_SCHED;
.LBB0_202:
	s_add_u32 s18, s8, 0xfff80080
	s_addc_u32 s19, s9, -1
	s_add_i32 s37, 0, 0x10000
	v_add_u32_e32 v140, s37, v187
	s_waitcnt lgkmcnt(0)
	ds_read_b128 v[128:131], v140
	ds_read_b128 v[132:135], v140 offset:1024
	ds_read_b128 v[136:139], v140 offset:2048
	ds_read_b128 v[190:193], v140 offset:3072
	s_cmp_eq_u32 s36, 28
	s_cselect_b32 s21, s4, s19
	s_cselect_b32 s20, s5, s18
	s_cselect_b32 s19, s11, s35
	s_cselect_b32 s18, s13, s33
	v_lshl_add_u64 v[140:141], s[8:9], 0, v[150:151]
	s_add_i32 m0, s26, 0xc000
	ds_read_b128 v[194:197], v189
	ds_read_b128 v[198:201], v189 offset:1024
	ds_read_b128 v[202:205], v189 offset:2048
	ds_read_b128 v[206:209], v189 offset:3072
	ds_read_b128 v[210:213], v189 offset:4096
	ds_read_b128 v[214:217], v189 offset:5120
	ds_read_b128 v[226:229], v189 offset:6144
	ds_read_b128 v[230:233], v189 offset:7168
	global_load_lds_dwordx4 v[140:141], off
	v_lshl_add_u64 v[140:141], s[8:9], 0, v[152:153]
	s_add_i32 m0, s26, 0xe000
	s_nop 0
	global_load_lds_dwordx4 v[140:141], off
	s_waitcnt lgkmcnt(8)
	s_barrier
	s_waitcnt lgkmcnt(0)
	s_setprio 1
	v_mfma_f32_16x16x32_bf16 v[124:127], v[128:131], v[194:197], v[124:127]
	v_mfma_f32_16x16x32_bf16 v[120:123], v[136:139], v[194:197], v[120:123]
	v_mfma_f32_16x16x32_bf16 v[108:111], v[128:131], v[202:205], v[108:111]
	v_mfma_f32_16x16x32_bf16 v[104:107], v[136:139], v[202:205], v[104:107]
	v_mfma_f32_16x16x32_bf16 v[92:95], v[128:131], v[210:213], v[92:95]
	v_mfma_f32_16x16x32_bf16 v[88:91], v[136:139], v[210:213], v[88:91]
	v_mfma_f32_16x16x32_bf16 v[76:79], v[128:131], v[226:229], v[76:79]
	v_mfma_f32_16x16x32_bf16 v[72:75], v[136:139], v[226:229], v[72:75]
	v_mfma_f32_16x16x32_bf16 v[124:127], v[132:135], v[198:201], v[124:127]
	v_mfma_f32_16x16x32_bf16 v[120:123], v[190:193], v[198:201], v[120:123]
	v_mfma_f32_16x16x32_bf16 v[108:111], v[132:135], v[206:209], v[108:111]
	v_mfma_f32_16x16x32_bf16 v[104:107], v[190:193], v[206:209], v[104:107]
	v_mfma_f32_16x16x32_bf16 v[92:95], v[132:135], v[214:217], v[92:95]
	v_mfma_f32_16x16x32_bf16 v[88:91], v[190:193], v[214:217], v[88:91]
	v_mfma_f32_16x16x32_bf16 v[76:79], v[132:135], v[230:233], v[76:79]
	v_mfma_f32_16x16x32_bf16 v[72:75], v[190:193], v[230:233], v[72:75]
	s_setprio 0
	s_barrier
	s_add_i32 s40, 0, 0x14000
	v_add_u32_e32 v140, s40, v187
	s_add_i32 s37, s37, s25
	ds_read_b128 v[234:237], v140
	ds_read_b128 v[238:241], v140 offset:1024
	ds_read_b128 v[242:245], v140 offset:2048
	ds_read_b128 v[246:249], v140 offset:3072
	v_lshl_add_u64 v[140:141], s[18:19], 0, v[144:145]
	s_mov_b32 m0, s37
	v_lshl_add_u64 v[154:155], s[18:19], 0, v[142:143]
	global_load_lds_dwordx4 v[140:141], off
	s_add_i32 m0, s37, 0x2000
	s_nop 0
	global_load_lds_dwordx4 v[154:155], off
	s_barrier
	s_waitcnt lgkmcnt(0)
	s_setprio 1
	v_mfma_f32_16x16x32_bf16 v[116:119], v[234:237], v[194:197], v[116:119]
	v_mfma_f32_16x16x32_bf16 v[112:115], v[242:245], v[194:197], v[112:115]
	v_mfma_f32_16x16x32_bf16 v[100:103], v[234:237], v[202:205], v[100:103]
	v_mfma_f32_16x16x32_bf16 v[96:99], v[242:245], v[202:205], v[96:99]
	v_mfma_f32_16x16x32_bf16 v[84:87], v[234:237], v[210:213], v[84:87]
	v_mfma_f32_16x16x32_bf16 v[80:83], v[242:245], v[210:213], v[80:83]
	v_mfma_f32_16x16x32_bf16 v[68:71], v[234:237], v[226:229], v[68:71]
	v_mfma_f32_16x16x32_bf16 v[64:67], v[242:245], v[226:229], v[64:67]
	v_mfma_f32_16x16x32_bf16 v[116:119], v[238:241], v[198:201], v[116:119]
	v_mfma_f32_16x16x32_bf16 v[112:115], v[246:249], v[198:201], v[112:115]
	v_mfma_f32_16x16x32_bf16 v[100:103], v[238:241], v[206:209], v[100:103]
	v_mfma_f32_16x16x32_bf16 v[96:99], v[246:249], v[206:209], v[96:99]
	v_mfma_f32_16x16x32_bf16 v[84:87], v[238:241], v[214:217], v[84:87]
	v_mfma_f32_16x16x32_bf16 v[80:83], v[246:249], v[214:217], v[80:83]
	v_mfma_f32_16x16x32_bf16 v[68:71], v[238:241], v[230:233], v[68:71]
	v_mfma_f32_16x16x32_bf16 v[64:67], v[246:249], v[230:233], v[64:67]
	s_setprio 0
	s_mov_b32 m0, s26
	v_lshl_add_u64 v[218:219], s[20:21], 0, v[144:145]
	s_barrier
	ds_read_b128 v[194:197], v189 offset:16384
	ds_read_b128 v[198:201], v189 offset:17408
	ds_read_b128 v[202:205], v189 offset:18432
	ds_read_b128 v[206:209], v189 offset:19456
	ds_read_b128 v[210:213], v189 offset:20480
	ds_read_b128 v[214:217], v189 offset:21504
	ds_read_b128 v[226:229], v189 offset:22528
	ds_read_b128 v[230:233], v189 offset:23552
	global_load_lds_dwordx4 v[218:219], off
	v_lshl_add_u64 v[250:251], s[20:21], 0, v[142:143]
	s_mov_b32 m0, s27
	s_nop 0
	global_load_lds_dwordx4 v[250:251], off
	s_barrier
	s_waitcnt lgkmcnt(0)
	s_setprio 1
	v_mfma_f32_16x16x32_bf16 v[60:63], v[128:131], v[194:197], v[60:63]
	v_mfma_f32_16x16x32_bf16 v[56:59], v[136:139], v[194:197], v[56:59]
	v_mfma_f32_16x16x32_bf16 v[44:47], v[128:131], v[202:205], v[44:47]
	v_mfma_f32_16x16x32_bf16 v[40:43], v[136:139], v[202:205], v[40:43]
	v_mfma_f32_16x16x32_bf16 v[28:31], v[128:131], v[210:213], v[28:31]
	v_mfma_f32_16x16x32_bf16 v[24:27], v[136:139], v[210:213], v[24:27]
	v_mfma_f32_16x16x32_bf16 v[12:15], v[128:131], v[226:229], v[12:15]
	v_mfma_f32_16x16x32_bf16 v[8:11], v[136:139], v[226:229], v[8:11]
	v_mfma_f32_16x16x32_bf16 v[60:63], v[132:135], v[198:201], v[60:63]
	v_mfma_f32_16x16x32_bf16 v[56:59], v[190:193], v[198:201], v[56:59]
	v_mfma_f32_16x16x32_bf16 v[44:47], v[132:135], v[206:209], v[44:47]
	v_mfma_f32_16x16x32_bf16 v[40:43], v[190:193], v[206:209], v[40:43]
	v_mfma_f32_16x16x32_bf16 v[28:31], v[132:135], v[214:217], v[28:31]
	v_mfma_f32_16x16x32_bf16 v[24:27], v[190:193], v[214:217], v[24:27]
	v_mfma_f32_16x16x32_bf16 v[12:15], v[132:135], v[230:233], v[12:15]
	v_mfma_f32_16x16x32_bf16 v[8:11], v[190:193], v[230:233], v[8:11]
	s_setprio 0
	s_barrier
; #define PG8_STAGE(bufoff, gbase) do { _Pragma("unroll") for (int _i = 0; _i < 2; ++_i) \
;         __builtin_amdgcn_global_load_lds((const unsigned*)((const char*)(gbase) + voff[_i]), (LAS unsigned*)(lds + (bufoff) + ldsw + _i * 8192), 16, 0, 0); } while (0)
; #define PG8_LDA(dst, b, h) do { _Pragma("unroll") for (int m = 0; m < 4; ++m) _Pragma("unroll") for (int k = 0; k < 2; ++k) dst[m][k] = *(const LAS bf16x8*)(lds + PG8_SA(b, h) + aoff + m * 2048 + k * 1024); } while (0)
; #define PG8_LDB(dst, b, h) do { _Pragma("unroll") for (int n = 0; n < 2; ++n) _Pragma("unroll") for (int k = 0; k < 2; ++k) dst[n][k] = *(const LAS bf16x8*)(lds + PG8_SB(b, h) + boff + n * 2048 + k * 1024); } while (0)
; #define PG8_MMA(ai, bj, At, Bt) do { __builtin_amdgcn_s_setprio(1); _Pragma("unroll") for (int m = 0; m < 4; ++m) _Pragma("unroll") for (int n = 0; n < 2; ++n) _Pragma("unroll") for (int k = 0; k < 2; ++k) \
;         acc[ai][bj][m][n] = __builtin_amdgcn_mfma_f32_16x16x32_bf16(Bt[n][k], At[m][k], acc[ai][bj][m][n], 0, 0, 0); __builtin_amdgcn_s_setprio(0); } while (0)
; #define PG8_WAIT_V(n) asm volatile("s_waitcnt vmcnt(" #n ")" ::: "memory")
; #define PG8_WAIT_L(n) asm volatile("s_waitcnt lgkmcnt(" #n ")" ::: "memory")
; #define PG8_BAR __builtin_amdgcn_s_barrier()
; #define PG8_SCHED __builtin_amdgcn_sched_barrier(0)
; template <class Epi>
; DI void gemm_phase(LAS unsigned char* lds, const Gemm g, const StaticOrder& S, const Epi& E) {
;     ...
;             PG8_STAGE(PG8_SB(0, 1), b2 + hstep);
;             PG8_WAIT_V(6); PG8_BAR; PG8_MMA(1, 1, At, B1); PG8_BAR;
;             PG8_LDB(B0, 1, 0); PG8_SCHED; PG8_LDA(At, 1, 0); PG8_STAGE(PG8_SA(0, 1), a2 + hstep);
;             PG8_WAIT_L(8); PG8_BAR; PG8_WAIT_L(0); PG8_MMA(0, 0, At, B0); PG8_BAR; PG8_SCHED;
;             PG8_LDB(B1, 1, 1); PG8_STAGE(PG8_SB(1, 0), b3);
	s_add_u32 s38, s18, 0x80000
	s_addc_u32 s39, s19, 0
	s_add_i32 s37, s40, s25
	v_lshl_add_u64 v[128:129], s[38:39], 0, v[144:145]
	s_mov_b32 m0, s37
	s_nop 0
	global_load_lds_dwordx4 v[128:129], off
	v_lshl_add_u64 v[128:129], s[38:39], 0, v[142:143]
	s_add_i32 m0, s37, 0x2000
	s_nop 0
	global_load_lds_dwordx4 v[128:129], off
	s_waitcnt vmcnt(6)
	s_barrier
	s_setprio 1
	v_mfma_f32_16x16x32_bf16 v[52:55], v[234:237], v[194:197], v[52:55]
	v_mfma_f32_16x16x32_bf16 v[48:51], v[242:245], v[194:197], v[48:51]
	v_mfma_f32_16x16x32_bf16 v[36:39], v[234:237], v[202:205], v[36:39]
	v_mfma_f32_16x16x32_bf16 v[32:35], v[242:245], v[202:205], v[32:35]
	v_mfma_f32_16x16x32_bf16 v[20:23], v[234:237], v[210:213], v[20:23]
	v_mfma_f32_16x16x32_bf16 v[16:19], v[242:245], v[210:213], v[16:19]
	v_mfma_f32_16x16x32_bf16 v[4:7], v[234:237], v[226:229], v[4:7]
	v_mfma_f32_16x16x32_bf16 v[0:3], v[242:245], v[226:229], v[0:3]
	v_mfma_f32_16x16x32_bf16 v[52:55], v[238:241], v[198:201], v[52:55]
	v_mfma_f32_16x16x32_bf16 v[48:51], v[246:249], v[198:201], v[48:51]
	v_mfma_f32_16x16x32_bf16 v[36:39], v[238:241], v[206:209], v[36:39]
	v_mfma_f32_16x16x32_bf16 v[32:35], v[246:249], v[206:209], v[32:35]
	v_mfma_f32_16x16x32_bf16 v[20:23], v[238:241], v[214:217], v[20:23]
	v_mfma_f32_16x16x32_bf16 v[16:19], v[246:249], v[214:217], v[16:19]
	v_mfma_f32_16x16x32_bf16 v[4:7], v[238:241], v[230:233], v[4:7]
	v_mfma_f32_16x16x32_bf16 v[0:3], v[246:249], v[230:233], v[0:3]
	s_setprio 0
	s_add_i32 s37, 0, 0x18000
	v_add_u32_e32 v158, s37, v187
	s_barrier
	ds_read_b128 v[128:131], v158
	ds_read_b128 v[132:135], v158 offset:1024
	ds_read_b128 v[136:139], v158 offset:2048
	ds_read_b128 v[190:193], v158 offset:3072
	s_add_u32 s20, s20, 0x80000
	s_addc_u32 s21, s21, 0
	s_mov_b32 m0, s28
	v_lshl_add_u64 v[234:235], s[20:21], 0, v[144:145]
	ds_read_b128 v[194:197], v189 offset:32768
	ds_read_b128 v[198:201], v189 offset:33792
	ds_read_b128 v[202:205], v189 offset:34816
	ds_read_b128 v[206:209], v189 offset:35840
	ds_read_b128 v[210:213], v189 offset:36864
	ds_read_b128 v[214:217], v189 offset:37888
	ds_read_b128 v[226:229], v189 offset:38912
	ds_read_b128 v[230:233], v189 offset:39936
	global_load_lds_dwordx4 v[234:235], off
	v_lshl_add_u64 v[234:235], s[20:21], 0, v[142:143]
	s_mov_b32 m0, s29
	s_nop 0
	global_load_lds_dwordx4 v[234:235], off
	s_waitcnt lgkmcnt(8)
	s_barrier
	s_waitcnt lgkmcnt(0)
	s_setprio 1
	v_mfma_f32_16x16x32_bf16 v[124:127], v[128:131], v[194:197], v[124:127]
	v_mfma_f32_16x16x32_bf16 v[120:123], v[136:139], v[194:197], v[120:123]
	v_mfma_f32_16x16x32_bf16 v[108:111], v[128:131], v[202:205], v[108:111]
	v_mfma_f32_16x16x32_bf16 v[104:107], v[136:139], v[202:205], v[104:107]
	v_mfma_f32_16x16x32_bf16 v[92:95], v[128:131], v[210:213], v[92:95]
	v_mfma_f32_16x16x32_bf16 v[88:91], v[136:139], v[210:213], v[88:91]
	v_mfma_f32_16x16x32_bf16 v[76:79], v[128:131], v[226:229], v[76:79]
	v_mfma_f32_16x16x32_bf16 v[72:75], v[136:139], v[226:229], v[72:75]
	v_mfma_f32_16x16x32_bf16 v[124:127], v[132:135], v[198:201], v[124:127]
	v_mfma_f32_16x16x32_bf16 v[120:123], v[190:193], v[198:201], v[120:123]
	v_mfma_f32_16x16x32_bf16 v[108:111], v[132:135], v[206:209], v[108:111]
	v_mfma_f32_16x16x32_bf16 v[104:107], v[190:193], v[206:209], v[104:107]
	v_mfma_f32_16x16x32_bf16 v[92:95], v[132:135], v[214:217], v[92:95]
	v_mfma_f32_16x16x32_bf16 v[88:91], v[190:193], v[214:217], v[88:91]
	v_mfma_f32_16x16x32_bf16 v[76:79], v[132:135], v[230:233], v[76:79]
	v_mfma_f32_16x16x32_bf16 v[72:75], v[190:193], v[230:233], v[72:75]
	s_setprio 0
	s_barrier
	s_add_i32 s20, 0, 0x1c000
	s_add_i32 s21, s37, s25
	v_add_u32_e32 v158, s20, v187
	v_lshl_add_u64 v[140:141], v[140:141], 0, s[94:95]
	s_mov_b32 m0, s21
	ds_read_b128 v[234:237], v158
	ds_read_b128 v[238:241], v158 offset:1024
	ds_read_b128 v[242:245], v158 offset:2048
	ds_read_b128 v[246:249], v158 offset:3072
	global_load_lds_dwordx4 v[140:141], off
	v_lshl_add_u64 v[140:141], v[154:155], 0, s[94:95]
	s_add_i32 m0, s21, 0x2000
	s_nop 0
	global_load_lds_dwordx4 v[140:141], off
	s_barrier
; #define PG8_STAGE(bufoff, gbase) do { _Pragma("unroll") for (int _i = 0; _i < 2; ++_i) \
;         __builtin_amdgcn_global_load_lds((const unsigned*)((const char*)(gbase) + voff[_i]), (LAS unsigned*)(lds + (bufoff) + ldsw + _i * 8192), 16, 0, 0); } while (0)
; #define PG8_LDA(dst, b, h) do { _Pragma("unroll") for (int m = 0; m < 4; ++m) _Pragma("unroll") for (int k = 0; k < 2; ++k) dst[m][k] = *(const LAS bf16x8*)(lds + PG8_SA(b, h) + aoff + m * 2048 + k * 1024); } while (0)
; #define PG8_MMA(ai, bj, At, Bt) do { __builtin_amdgcn_s_setprio(1); _Pragma("unroll") for (int m = 0; m < 4; ++m) _Pragma("unroll") for (int n = 0; n < 2; ++n) _Pragma("unroll") for (int k = 0; k < 2; ++k) \
;         acc[ai][bj][m][n] = __builtin_amdgcn_mfma_f32_16x16x32_bf16(Bt[n][k], At[m][k], acc[ai][bj][m][n], 0, 0, 0); __builtin_amdgcn_s_setprio(0); } while (0)
; #define PG8_WAIT_V(n) asm volatile("s_waitcnt vmcnt(" #n ")" ::: "memory")
; #define PG8_WAIT_L(n) asm volatile("s_waitcnt lgkmcnt(" #n ")" ::: "memory")
; #define PG8_BAR __builtin_amdgcn_s_barrier()
; #define PG8_SCHED __builtin_amdgcn_sched_barrier(0)
; template <class Epi>
; DI void gemm_phase(LAS unsigned char* lds, const Gemm g, const StaticOrder& S, const Epi& E) {
;     ...
;             PG8_BAR; PG8_WAIT_L(0); PG8_MMA(0, 1, At, B1); PG8_BAR;
;             PG8_LDA(At, 1, 1); PG8_STAGE(PG8_SA(1, 0), a3);
;             PG8_BAR; PG8_WAIT_L(0); PG8_MMA(1, 0, At, B0); PG8_BAR; PG8_SCHED;
;             PG8_STAGE(PG8_SB(1, 1), b3 + hstep);
;             PG8_WAIT_V(6); PG8_BAR; PG8_MMA(1, 1, At, B1); PG8_BAR;
;     DI void operator()(const f32x4 (&acc)[2][2][4][2], const Unit& u, int wr, int wc, int fr, int fq) const {
;         const int row0 = u.pm * BM + wr * 64 + fr, col0 = u.pn * BM + wc * 16 + 4 * fq;
;         const bool rot = u.pn < 18;
; #pragma unroll
;         for (int ai = 0; ai < 2; ++ai)
; #pragma unroll
;             for (int m = 0; m < 4; ++m) { const int row = row0 + ai * HALF + m * 16; u16* rowp = O + (size_t)row * NQKV_DIL + col0;
;                 f32x4 c4 = (f32x4){1.f, 1.f, 1.f, 1.f}, s4 = (f32x4){0.f, 0.f, 0.f, 0.f};
;                 if (rot) { const int pos = row & (SEQ - 1); c4 = *(const f32x4*)(cs + pos * 64 + wc * 16 + 4 * fq); s4 = *(const f32x4*)(sn + pos * 64 + wc * 16 + 4 * fq); }
	s_waitcnt lgkmcnt(0)
	s_setprio 1
	v_mfma_f32_16x16x32_bf16 v[116:119], v[234:237], v[194:197], v[116:119]
	v_mfma_f32_16x16x32_bf16 v[112:115], v[242:245], v[194:197], v[112:115]
	v_mfma_f32_16x16x32_bf16 v[100:103], v[234:237], v[202:205], v[100:103]
	v_mfma_f32_16x16x32_bf16 v[96:99], v[242:245], v[202:205], v[96:99]
	v_mfma_f32_16x16x32_bf16 v[84:87], v[234:237], v[210:213], v[84:87]
	v_mfma_f32_16x16x32_bf16 v[80:83], v[242:245], v[210:213], v[80:83]
	v_mfma_f32_16x16x32_bf16 v[68:71], v[234:237], v[226:229], v[68:71]
	v_mfma_f32_16x16x32_bf16 v[64:67], v[242:245], v[226:229], v[64:67]
	v_mfma_f32_16x16x32_bf16 v[116:119], v[238:241], v[198:201], v[116:119]
	v_mfma_f32_16x16x32_bf16 v[112:115], v[246:249], v[198:201], v[112:115]
	v_mfma_f32_16x16x32_bf16 v[100:103], v[238:241], v[206:209], v[100:103]
	v_mfma_f32_16x16x32_bf16 v[96:99], v[246:249], v[206:209], v[96:99]
	v_mfma_f32_16x16x32_bf16 v[84:87], v[238:241], v[214:217], v[84:87]
	v_mfma_f32_16x16x32_bf16 v[80:83], v[246:249], v[214:217], v[80:83]
	v_mfma_f32_16x16x32_bf16 v[68:71], v[238:241], v[230:233], v[68:71]
	v_mfma_f32_16x16x32_bf16 v[64:67], v[246:249], v[230:233], v[64:67]
	s_setprio 0
	s_mov_b32 m0, s30
	v_lshl_add_u64 v[140:141], v[218:219], 0, s[94:95]
	s_barrier
	ds_read_b128 v[194:197], v189 offset:49152
	ds_read_b128 v[198:201], v189 offset:50176
	ds_read_b128 v[202:205], v189 offset:51200
	ds_read_b128 v[206:209], v189 offset:52224
	ds_read_b128 v[210:213], v189 offset:53248
	ds_read_b128 v[214:217], v189 offset:54272
	ds_read_b128 v[226:229], v189 offset:55296
	ds_read_b128 v[230:233], v189 offset:56320
	global_load_lds_dwordx4 v[140:141], off
	v_lshl_add_u64 v[140:141], v[250:251], 0, s[94:95]
	s_mov_b32 m0, s31
	s_nop 0
	global_load_lds_dwordx4 v[140:141], off
	s_barrier
	s_waitcnt lgkmcnt(0)
	s_setprio 1
	v_mfma_f32_16x16x32_bf16 v[60:63], v[128:131], v[194:197], v[60:63]
	v_mfma_f32_16x16x32_bf16 v[56:59], v[136:139], v[194:197], v[56:59]
	v_mfma_f32_16x16x32_bf16 v[44:47], v[128:131], v[202:205], v[44:47]
	v_mfma_f32_16x16x32_bf16 v[40:43], v[136:139], v[202:205], v[40:43]
	v_mfma_f32_16x16x32_bf16 v[28:31], v[128:131], v[210:213], v[28:31]
	v_mfma_f32_16x16x32_bf16 v[24:27], v[136:139], v[210:213], v[24:27]
	v_mfma_f32_16x16x32_bf16 v[12:15], v[128:131], v[226:229], v[12:15]
	v_mfma_f32_16x16x32_bf16 v[8:11], v[136:139], v[226:229], v[8:11]
	v_mfma_f32_16x16x32_bf16 v[60:63], v[132:135], v[198:201], v[60:63]
	v_mfma_f32_16x16x32_bf16 v[56:59], v[190:193], v[198:201], v[56:59]
	v_mfma_f32_16x16x32_bf16 v[44:47], v[132:135], v[206:209], v[44:47]
	v_mfma_f32_16x16x32_bf16 v[40:43], v[190:193], v[206:209], v[40:43]
	v_mfma_f32_16x16x32_bf16 v[28:31], v[132:135], v[214:217], v[28:31]
	v_mfma_f32_16x16x32_bf16 v[24:27], v[190:193], v[214:217], v[24:27]
	v_mfma_f32_16x16x32_bf16 v[12:15], v[132:135], v[230:233], v[12:15]
	v_mfma_f32_16x16x32_bf16 v[8:11], v[190:193], v[230:233], v[8:11]
	s_setprio 0
	s_barrier
	s_add_u32 s18, s18, 0x80080
	s_addc_u32 s19, s19, 0
	s_add_i32 s20, s20, s25
	v_lshl_add_u64 v[128:129], s[18:19], 0, v[144:145]
	s_mov_b32 m0, s20
	s_nop 0
	global_load_lds_dwordx4 v[128:129], off
	v_lshl_add_u64 v[128:129], s[18:19], 0, v[142:143]
	s_add_i32 m0, s20, 0x2000
	s_nop 0
	global_load_lds_dwordx4 v[128:129], off
	s_waitcnt vmcnt(6)
	s_barrier
	s_setprio 1
	v_mfma_f32_16x16x32_bf16 v[52:55], v[234:237], v[194:197], v[52:55]
	v_mfma_f32_16x16x32_bf16 v[48:51], v[242:245], v[194:197], v[48:51]
	v_mfma_f32_16x16x32_bf16 v[36:39], v[234:237], v[202:205], v[36:39]
	v_mfma_f32_16x16x32_bf16 v[32:35], v[242:245], v[202:205], v[32:35]
	v_mfma_f32_16x16x32_bf16 v[20:23], v[234:237], v[210:213], v[20:23]
	v_mfma_f32_16x16x32_bf16 v[16:19], v[242:245], v[210:213], v[16:19]
	v_mfma_f32_16x16x32_bf16 v[4:7], v[234:237], v[226:229], v[4:7]
	v_mfma_f32_16x16x32_bf16 v[0:3], v[242:245], v[226:229], v[0:3]
	v_mfma_f32_16x16x32_bf16 v[52:55], v[238:241], v[198:201], v[52:55]
	v_mfma_f32_16x16x32_bf16 v[48:51], v[246:249], v[198:201], v[48:51]
	v_mfma_f32_16x16x32_bf16 v[36:39], v[238:241], v[206:209], v[36:39]
	v_mfma_f32_16x16x32_bf16 v[32:35], v[246:249], v[206:209], v[32:35]
	v_mfma_f32_16x16x32_bf16 v[20:23], v[238:241], v[214:217], v[20:23]
	v_mfma_f32_16x16x32_bf16 v[16:19], v[246:249], v[214:217], v[16:19]
	v_mfma_f32_16x16x32_bf16 v[4:7], v[238:241], v[230:233], v[4:7]
	v_mfma_f32_16x16x32_bf16 v[0:3], v[246:249], v[230:233], v[0:3]
	s_setprio 0
	s_add_i32 s36, s36, 2
	s_add_u32 s8, s8, 0x100
	s_addc_u32 s9, s9, 0
	s_add_u32 s33, s33, 0x100
	s_addc_u32 s35, s35, 0
	s_cmp_gt_u32 s36, 29
	s_barrier
	s_cbranch_scc0 .LBB0_202
	s_cmp_lt_i32 s2, 18
	v_lshl_add_u32 v190, s3, 8, v186
	v_mov_b32_e32 v128, 1.0
	v_mov_b32_e32 v132, 0
	s_cselect_b64 s[18:19], -1, 0
	s_cmp_gt_i32 s2, 17
	v_mov_b32_e32 v134, 0
	v_mov_b32_e32 v135, 0
	v_mov_b32_e32 v136, 0
	v_mov_b32_e32 v137, 0
	v_mov_b32_e32 v138, 1.0
	v_mov_b32_e32 v139, 1.0
	v_mov_b32_e32 v140, 1.0
	v_mov_b32_e32 v141, 1.0
	s_cbranch_scc1 .LBB0_205
	v_lshlrev_b32_e32 v129, 8, v190
	v_and_b32_e32 v158, 0xfcf00, v129
	v_lshl_add_u64 v[130:131], v[146:147], 0, v[158:159]
	v_lshl_add_u64 v[134:135], v[148:149], 0, v[158:159]
	global_load_dwordx4 v[138:141], v[130:131], off
	s_nop 0
	global_load_dwordx4 v[134:137], v[134:135], off

; #define PG8_STAGE(bufoff, gbase) do { _Pragma("unroll") for (int _i = 0; _i < 2; ++_i) \
;         __builtin_amdgcn_global_load_lds((const unsigned*)((const char*)(gbase) + voff[_i]), (LAS unsigned*)(lds + (bufoff) + ldsw + _i * 8192), 16, 0, 0); } while (0)
; #define PG8_LDA(dst, b, h) do { _Pragma("unroll") for (int m = 0; m < 4; ++m) _Pragma("unroll") for (int k = 0; k < 2; ++k) dst[m][k] = *(const LAS bf16x8*)(lds + PG8_SA(b, h) + aoff + m * 2048 + k * 1024); } while (0)
; #define PG8_LDB(dst, b, h) do { _Pragma("unroll") for (int n = 0; n < 2; ++n) _Pragma("unroll") for (int k = 0; k < 2; ++k) dst[n][k] = *(const LAS bf16x8*)(lds + PG8_SB(b, h) + boff + n * 2048 + k * 1024); } while (0)
; #define PG8_MMA(ai, bj, At, Bt) do { __builtin_amdgcn_s_setprio(1); _Pragma("unroll") for (int m = 0; m < 4; ++m) _Pragma("unroll") for (int n = 0; n < 2; ++n) _Pragma("unroll") for (int k = 0; k < 2; ++k) \
;         acc[ai][bj][m][n] = __builtin_amdgcn_mfma_f32_16x16x32_bf16(Bt[n][k], At[m][k], acc[ai][bj][m][n], 0, 0, 0); __builtin_amdgcn_s_setprio(0); } while (0)
; #define PG8_WAIT_L(n) asm volatile("s_waitcnt lgkmcnt(" #n ")" ::: "memory")
; #define PG8_BAR __builtin_amdgcn_s_barrier()
; #define PG8_SCHED __builtin_amdgcn_sched_barrier(0)
; template <class Epi>
; DI void gemm_phase(LAS unsigned char* lds, const Gemm g, const StaticOrder& S, const Epi& E) {
;     ...
;         for (int t = 0; t < nt; t += 2) {
;             const bool last = (t == nt - 2);
;             const char* a1 = cA + (size_t)(t + 1) * kstep;
;             const char* a2 = last ? nA : cA + (size_t)(t + 2) * kstep; const char* b2 = last ? nB : cB + (size_t)(t + 2) * kstep;
;             const char* a3 = a2 + kstep; const char* b3 = b2 + kstep;
;             PG8_LDB(B0, 0, 0); PG8_SCHED; PG8_LDA(At, 0, 0); PG8_STAGE(PG8_SA(1, 1), a1 + hstep);
;             PG8_WAIT_L(8); PG8_BAR; PG8_WAIT_L(0); PG8_MMA(0, 0, At, B0); PG8_BAR; PG8_SCHED;
;             PG8_LDB(B1, 0, 1); PG8_STAGE(PG8_SB(0, 0), b2);
;             PG8_BAR; PG8_WAIT_L(0); PG8_MMA(0, 1, At, B1); PG8_BAR;
;             PG8_LDA(At, 0, 1); PG8_STAGE(PG8_SA(0, 0), a2);
;             PG8_BAR; PG8_WAIT_L(0); PG8_MMA(1, 0, At, B0); PG8_BAR; PG8_SCHED;
.LBB0_231:
	s_add_u32 s18, s16, 0xfff80080
	s_addc_u32 s19, s17, -1
	s_add_i32 s37, 0, 0x10000
	v_add_u32_e32 v150, s37, v135
	ds_read_b128 v[138:141], v150
	ds_read_b128 v[142:145], v150 offset:1024
	ds_read_b128 v[146:149], v150 offset:2048
	ds_read_b128 v[150:153], v150 offset:3072
	s_cmp_eq_u32 s36, 28
	s_cselect_b32 s21, s4, s19
	s_cselect_b32 s20, s5, s18
	s_cselect_b32 s19, s9, s35
	s_cselect_b32 s18, s11, s34
	v_lshl_add_u64 v[154:155], s[16:17], 0, v[130:131]
	s_add_i32 m0, s24, 0xc000
	ds_read_b128 v[186:189], v137
	ds_read_b128 v[190:193], v137 offset:1024
	ds_read_b128 v[194:197], v137 offset:2048
	ds_read_b128 v[198:201], v137 offset:3072
	ds_read_b128 v[202:205], v137 offset:4096
	ds_read_b128 v[206:209], v137 offset:5120
	ds_read_b128 v[210:213], v137 offset:6144
	ds_read_b128 v[214:217], v137 offset:7168
	global_load_lds_dwordx4 v[154:155], off
	v_lshl_add_u64 v[154:155], s[16:17], 0, v[132:133]
	s_add_i32 m0, s24, 0xe000
	s_nop 0
	global_load_lds_dwordx4 v[154:155], off
	s_waitcnt lgkmcnt(8)
	s_barrier
	s_waitcnt lgkmcnt(0)
	s_setprio 1
	v_mfma_f32_16x16x32_bf16 v[124:127], v[138:141], v[186:189], v[124:127]
	v_mfma_f32_16x16x32_bf16 v[120:123], v[146:149], v[186:189], v[120:123]
	v_mfma_f32_16x16x32_bf16 v[116:119], v[138:141], v[194:197], v[116:119]
	v_mfma_f32_16x16x32_bf16 v[112:115], v[146:149], v[194:197], v[112:115]
	v_mfma_f32_16x16x32_bf16 v[100:103], v[138:141], v[202:205], v[100:103]
	v_mfma_f32_16x16x32_bf16 v[96:99], v[146:149], v[202:205], v[96:99]
	v_mfma_f32_16x16x32_bf16 v[84:87], v[138:141], v[210:213], v[84:87]
	v_mfma_f32_16x16x32_bf16 v[80:83], v[146:149], v[210:213], v[80:83]
	v_mfma_f32_16x16x32_bf16 v[124:127], v[142:145], v[190:193], v[124:127]
	v_mfma_f32_16x16x32_bf16 v[120:123], v[150:153], v[190:193], v[120:123]
	v_mfma_f32_16x16x32_bf16 v[116:119], v[142:145], v[198:201], v[116:119]
	v_mfma_f32_16x16x32_bf16 v[112:115], v[150:153], v[198:201], v[112:115]
	v_mfma_f32_16x16x32_bf16 v[100:103], v[142:145], v[206:209], v[100:103]
	v_mfma_f32_16x16x32_bf16 v[96:99], v[150:153], v[206:209], v[96:99]
	v_mfma_f32_16x16x32_bf16 v[84:87], v[142:145], v[214:217], v[84:87]
	v_mfma_f32_16x16x32_bf16 v[80:83], v[150:153], v[214:217], v[80:83]
	s_setprio 0
	s_barrier
	s_add_i32 s40, 0, 0x14000
	v_add_u32_e32 v154, s40, v135
	s_add_i32 s37, s37, s23
	ds_read_b128 v[226:229], v154
	ds_read_b128 v[230:233], v154 offset:1024
	ds_read_b128 v[234:237], v154 offset:2048
	ds_read_b128 v[238:241], v154 offset:3072
	v_lshl_add_u64 v[154:155], s[18:19], 0, v[158:159]
	s_mov_b32 m0, s37
	v_lshl_add_u64 v[218:219], s[18:19], 0, v[128:129]
	global_load_lds_dwordx4 v[154:155], off
	s_add_i32 m0, s37, 0x2000
	s_nop 0
	global_load_lds_dwordx4 v[218:219], off
	s_barrier
	s_waitcnt lgkmcnt(0)
	s_setprio 1
	v_mfma_f32_16x16x32_bf16 v[108:111], v[226:229], v[186:189], v[108:111]
	v_mfma_f32_16x16x32_bf16 v[104:107], v[234:237], v[186:189], v[104:107]
	v_mfma_f32_16x16x32_bf16 v[92:95], v[226:229], v[194:197], v[92:95]
	v_mfma_f32_16x16x32_bf16 v[88:91], v[234:237], v[194:197], v[88:91]
	v_mfma_f32_16x16x32_bf16 v[76:79], v[226:229], v[202:205], v[76:79]
	v_mfma_f32_16x16x32_bf16 v[72:75], v[234:237], v[202:205], v[72:75]
	v_mfma_f32_16x16x32_bf16 v[68:71], v[226:229], v[210:213], v[68:71]
	v_mfma_f32_16x16x32_bf16 v[64:67], v[234:237], v[210:213], v[64:67]
	v_mfma_f32_16x16x32_bf16 v[108:111], v[230:233], v[190:193], v[108:111]
	v_mfma_f32_16x16x32_bf16 v[104:107], v[238:241], v[190:193], v[104:107]
	v_mfma_f32_16x16x32_bf16 v[92:95], v[230:233], v[198:201], v[92:95]
	v_mfma_f32_16x16x32_bf16 v[88:91], v[238:241], v[198:201], v[88:91]
	v_mfma_f32_16x16x32_bf16 v[76:79], v[230:233], v[206:209], v[76:79]
	v_mfma_f32_16x16x32_bf16 v[72:75], v[238:241], v[206:209], v[72:75]
	v_mfma_f32_16x16x32_bf16 v[68:71], v[230:233], v[214:217], v[68:71]
	v_mfma_f32_16x16x32_bf16 v[64:67], v[238:241], v[214:217], v[64:67]
	s_setprio 0
	s_mov_b32 m0, s24
	v_lshl_add_u64 v[242:243], s[20:21], 0, v[158:159]
	s_barrier
	ds_read_b128 v[186:189], v137 offset:16384
	ds_read_b128 v[190:193], v137 offset:17408
	ds_read_b128 v[194:197], v137 offset:18432
	ds_read_b128 v[198:201], v137 offset:19456
	ds_read_b128 v[202:205], v137 offset:20480
	ds_read_b128 v[206:209], v137 offset:21504
	ds_read_b128 v[210:213], v137 offset:22528
	ds_read_b128 v[214:217], v137 offset:23552
	global_load_lds_dwordx4 v[242:243], off
	v_lshl_add_u64 v[244:245], s[20:21], 0, v[128:129]
	s_mov_b32 m0, s25
	s_nop 0
	global_load_lds_dwordx4 v[244:245], off
	s_barrier
	s_waitcnt lgkmcnt(0)
	s_setprio 1
	v_mfma_f32_16x16x32_bf16 v[60:63], v[138:141], v[186:189], v[60:63]
	v_mfma_f32_16x16x32_bf16 v[56:59], v[146:149], v[186:189], v[56:59]
	v_mfma_f32_16x16x32_bf16 v[52:55], v[138:141], v[194:197], v[52:55]
	v_mfma_f32_16x16x32_bf16 v[48:51], v[146:149], v[194:197], v[48:51]
	v_mfma_f32_16x16x32_bf16 v[36:39], v[138:141], v[202:205], v[36:39]
	v_mfma_f32_16x16x32_bf16 v[32:35], v[146:149], v[202:205], v[32:35]
	v_mfma_f32_16x16x32_bf16 v[20:23], v[138:141], v[210:213], v[20:23]
	v_mfma_f32_16x16x32_bf16 v[16:19], v[146:149], v[210:213], v[16:19]
	v_mfma_f32_16x16x32_bf16 v[60:63], v[142:145], v[190:193], v[60:63]
	v_mfma_f32_16x16x32_bf16 v[56:59], v[150:153], v[190:193], v[56:59]
	v_mfma_f32_16x16x32_bf16 v[52:55], v[142:145], v[198:201], v[52:55]
	v_mfma_f32_16x16x32_bf16 v[48:51], v[150:153], v[198:201], v[48:51]
	v_mfma_f32_16x16x32_bf16 v[36:39], v[142:145], v[206:209], v[36:39]
	v_mfma_f32_16x16x32_bf16 v[32:35], v[150:153], v[206:209], v[32:35]
	v_mfma_f32_16x16x32_bf16 v[20:23], v[142:145], v[214:217], v[20:23]
	v_mfma_f32_16x16x32_bf16 v[16:19], v[150:153], v[214:217], v[16:19]
	s_setprio 0
	s_barrier
; #define PG8_STAGE(bufoff, gbase) do { _Pragma("unroll") for (int _i = 0; _i < 2; ++_i) \
;         __builtin_amdgcn_global_load_lds((const unsigned*)((const char*)(gbase) + voff[_i]), (LAS unsigned*)(lds + (bufoff) + ldsw + _i * 8192), 16, 0, 0); } while (0)
; #define PG8_LDA(dst, b, h) do { _Pragma("unroll") for (int m = 0; m < 4; ++m) _Pragma("unroll") for (int k = 0; k < 2; ++k) dst[m][k] = *(const LAS bf16x8*)(lds + PG8_SA(b, h) + aoff + m * 2048 + k * 1024); } while (0)
; #define PG8_LDB(dst, b, h) do { _Pragma("unroll") for (int n = 0; n < 2; ++n) _Pragma("unroll") for (int k = 0; k < 2; ++k) dst[n][k] = *(const LAS bf16x8*)(lds + PG8_SB(b, h) + boff + n * 2048 + k * 1024); } while (0)
; #define PG8_MMA(ai, bj, At, Bt) do { __builtin_amdgcn_s_setprio(1); _Pragma("unroll") for (int m = 0; m < 4; ++m) _Pragma("unroll") for (int n = 0; n < 2; ++n) _Pragma("unroll") for (int k = 0; k < 2; ++k) \
;         acc[ai][bj][m][n] = __builtin_amdgcn_mfma_f32_16x16x32_bf16(Bt[n][k], At[m][k], acc[ai][bj][m][n], 0, 0, 0); __builtin_amdgcn_s_setprio(0); } while (0)
; #define PG8_WAIT_V(n) asm volatile("s_waitcnt vmcnt(" #n ")" ::: "memory")
; #define PG8_WAIT_L(n) asm volatile("s_waitcnt lgkmcnt(" #n ")" ::: "memory")
; #define PG8_BAR __builtin_amdgcn_s_barrier()
; #define PG8_SCHED __builtin_amdgcn_sched_barrier(0)
; template <class Epi>
; DI void gemm_phase(LAS unsigned char* lds, const Gemm g, const StaticOrder& S, const Epi& E) {
;     ...
;             PG8_STAGE(PG8_SB(0, 1), b2 + hstep);
;             PG8_WAIT_V(6); PG8_BAR; PG8_MMA(1, 1, At, B1); PG8_BAR;
;             PG8_LDB(B0, 1, 0); PG8_SCHED; PG8_LDA(At, 1, 0); PG8_STAGE(PG8_SA(0, 1), a2 + hstep);
;             PG8_WAIT_L(8); PG8_BAR; PG8_WAIT_L(0); PG8_MMA(0, 0, At, B0); PG8_BAR; PG8_SCHED;
;             PG8_LDB(B1, 1, 1); PG8_STAGE(PG8_SB(1, 0), b3);
;             PG8_BAR; PG8_WAIT_L(0); PG8_MMA(0, 1, At, B1); PG8_BAR;
;             PG8_LDA(At, 1, 1); PG8_STAGE(PG8_SA(1, 0), a3);
	s_add_u32 s38, s18, 0x80000
	s_addc_u32 s39, s19, 0
	s_add_i32 s37, s40, s23
	v_lshl_add_u64 v[138:139], s[38:39], 0, v[158:159]
	s_mov_b32 m0, s37
	s_nop 0
	global_load_lds_dwordx4 v[138:139], off
	v_lshl_add_u64 v[138:139], s[38:39], 0, v[128:129]
	s_add_i32 m0, s37, 0x2000
	s_nop 0
	global_load_lds_dwordx4 v[138:139], off
	s_waitcnt vmcnt(6)
	s_barrier
	s_setprio 1
	v_mfma_f32_16x16x32_bf16 v[44:47], v[226:229], v[186:189], v[44:47]
	v_mfma_f32_16x16x32_bf16 v[40:43], v[234:237], v[186:189], v[40:43]
	v_mfma_f32_16x16x32_bf16 v[28:31], v[226:229], v[194:197], v[28:31]
	v_mfma_f32_16x16x32_bf16 v[24:27], v[234:237], v[194:197], v[24:27]
	v_mfma_f32_16x16x32_bf16 v[12:15], v[226:229], v[202:205], v[12:15]
	v_mfma_f32_16x16x32_bf16 v[8:11], v[234:237], v[202:205], v[8:11]
	v_mfma_f32_16x16x32_bf16 v[4:7], v[226:229], v[210:213], v[4:7]
	v_mfma_f32_16x16x32_bf16 v[0:3], v[234:237], v[210:213], v[0:3]
	v_mfma_f32_16x16x32_bf16 v[44:47], v[230:233], v[190:193], v[44:47]
	v_mfma_f32_16x16x32_bf16 v[40:43], v[238:241], v[190:193], v[40:43]
	v_mfma_f32_16x16x32_bf16 v[28:31], v[230:233], v[198:201], v[28:31]
	v_mfma_f32_16x16x32_bf16 v[24:27], v[238:241], v[198:201], v[24:27]
	v_mfma_f32_16x16x32_bf16 v[12:15], v[230:233], v[206:209], v[12:15]
	v_mfma_f32_16x16x32_bf16 v[8:11], v[238:241], v[206:209], v[8:11]
	v_mfma_f32_16x16x32_bf16 v[4:7], v[230:233], v[214:217], v[4:7]
	v_mfma_f32_16x16x32_bf16 v[0:3], v[238:241], v[214:217], v[0:3]
	s_setprio 0
	s_add_i32 s37, 0, 0x18000
	v_add_u32_e32 v150, s37, v135
	s_barrier
	ds_read_b128 v[138:141], v150
	ds_read_b128 v[142:145], v150 offset:1024
	ds_read_b128 v[146:149], v150 offset:2048
	ds_read_b128 v[150:153], v150 offset:3072
	s_add_u32 s20, s20, 0x80000
	s_addc_u32 s21, s21, 0
	s_mov_b32 m0, s26
	v_lshl_add_u64 v[226:227], s[20:21], 0, v[158:159]
	ds_read_b128 v[186:189], v137 offset:32768
	ds_read_b128 v[190:193], v137 offset:33792
	ds_read_b128 v[194:197], v137 offset:34816
	ds_read_b128 v[198:201], v137 offset:35840
	ds_read_b128 v[202:205], v137 offset:36864
	ds_read_b128 v[206:209], v137 offset:37888
	ds_read_b128 v[210:213], v137 offset:38912
	ds_read_b128 v[214:217], v137 offset:39936
	global_load_lds_dwordx4 v[226:227], off
	v_lshl_add_u64 v[226:227], s[20:21], 0, v[128:129]
	s_mov_b32 m0, s27
	s_nop 0
	global_load_lds_dwordx4 v[226:227], off
	s_waitcnt lgkmcnt(8)
	s_barrier
	s_waitcnt lgkmcnt(0)
	s_setprio 1
	v_mfma_f32_16x16x32_bf16 v[124:127], v[138:141], v[186:189], v[124:127]
	v_mfma_f32_16x16x32_bf16 v[120:123], v[146:149], v[186:189], v[120:123]
	v_mfma_f32_16x16x32_bf16 v[116:119], v[138:141], v[194:197], v[116:119]
	v_mfma_f32_16x16x32_bf16 v[112:115], v[146:149], v[194:197], v[112:115]
	v_mfma_f32_16x16x32_bf16 v[100:103], v[138:141], v[202:205], v[100:103]
	v_mfma_f32_16x16x32_bf16 v[96:99], v[146:149], v[202:205], v[96:99]
	v_mfma_f32_16x16x32_bf16 v[84:87], v[138:141], v[210:213], v[84:87]
	v_mfma_f32_16x16x32_bf16 v[80:83], v[146:149], v[210:213], v[80:83]
	v_mfma_f32_16x16x32_bf16 v[124:127], v[142:145], v[190:193], v[124:127]
	v_mfma_f32_16x16x32_bf16 v[120:123], v[150:153], v[190:193], v[120:123]
	v_mfma_f32_16x16x32_bf16 v[116:119], v[142:145], v[198:201], v[116:119]
	v_mfma_f32_16x16x32_bf16 v[112:115], v[150:153], v[198:201], v[112:115]
	v_mfma_f32_16x16x32_bf16 v[100:103], v[142:145], v[206:209], v[100:103]
	v_mfma_f32_16x16x32_bf16 v[96:99], v[150:153], v[206:209], v[96:99]
	v_mfma_f32_16x16x32_bf16 v[84:87], v[142:145], v[214:217], v[84:87]
	v_mfma_f32_16x16x32_bf16 v[80:83], v[150:153], v[214:217], v[80:83]
	s_setprio 0
	s_barrier
	s_add_i32 s20, 0, 0x1c000
	s_add_i32 s21, s37, s23
	v_add_u32_e32 v220, s20, v135
	v_lshl_add_u64 v[154:155], v[154:155], 0, s[94:95]
	s_mov_b32 m0, s21
	ds_read_b128 v[226:229], v220
	ds_read_b128 v[230:233], v220 offset:1024
	ds_read_b128 v[234:237], v220 offset:2048
	ds_read_b128 v[238:241], v220 offset:3072
	global_load_lds_dwordx4 v[154:155], off
	v_lshl_add_u64 v[154:155], v[218:219], 0, s[94:95]
	s_add_i32 m0, s21, 0x2000
	s_nop 0
	global_load_lds_dwordx4 v[154:155], off
	s_barrier
	s_waitcnt lgkmcnt(0)
	s_setprio 1
	v_mfma_f32_16x16x32_bf16 v[108:111], v[226:229], v[186:189], v[108:111]
	v_mfma_f32_16x16x32_bf16 v[104:107], v[234:237], v[186:189], v[104:107]
	v_mfma_f32_16x16x32_bf16 v[92:95], v[226:229], v[194:197], v[92:95]
	v_mfma_f32_16x16x32_bf16 v[88:91], v[234:237], v[194:197], v[88:91]
	v_mfma_f32_16x16x32_bf16 v[76:79], v[226:229], v[202:205], v[76:79]
	v_mfma_f32_16x16x32_bf16 v[72:75], v[234:237], v[202:205], v[72:75]
	v_mfma_f32_16x16x32_bf16 v[68:71], v[226:229], v[210:213], v[68:71]
	v_mfma_f32_16x16x32_bf16 v[64:67], v[234:237], v[210:213], v[64:67]
	v_mfma_f32_16x16x32_bf16 v[108:111], v[230:233], v[190:193], v[108:111]
	v_mfma_f32_16x16x32_bf16 v[104:107], v[238:241], v[190:193], v[104:107]
	v_mfma_f32_16x16x32_bf16 v[92:95], v[230:233], v[198:201], v[92:95]
	v_mfma_f32_16x16x32_bf16 v[88:91], v[238:241], v[198:201], v[88:91]
	v_mfma_f32_16x16x32_bf16 v[76:79], v[230:233], v[206:209], v[76:79]
	v_mfma_f32_16x16x32_bf16 v[72:75], v[238:241], v[206:209], v[72:75]
	v_mfma_f32_16x16x32_bf16 v[68:71], v[230:233], v[214:217], v[68:71]
	v_mfma_f32_16x16x32_bf16 v[64:67], v[238:241], v[214:217], v[64:67]
	s_setprio 0
	s_mov_b32 m0, s28
	v_lshl_add_u64 v[154:155], v[242:243], 0, s[94:95]
	s_barrier
	ds_read_b128 v[186:189], v137 offset:49152
	ds_read_b128 v[190:193], v137 offset:50176
	ds_read_b128 v[194:197], v137 offset:51200
	ds_read_b128 v[198:201], v137 offset:52224
	ds_read_b128 v[202:205], v137 offset:53248
	ds_read_b128 v[206:209], v137 offset:54272
	ds_read_b128 v[210:213], v137 offset:55296
	ds_read_b128 v[214:217], v137 offset:56320
	global_load_lds_dwordx4 v[154:155], off
	v_lshl_add_u64 v[154:155], v[244:245], 0, s[94:95]
	s_mov_b32 m0, s29
	s_nop 0
	global_load_lds_dwordx4 v[154:155], off
	s_barrier
; #define PG8_STAGE(bufoff, gbase) do { _Pragma("unroll") for (int _i = 0; _i < 2; ++_i) \
;         __builtin_amdgcn_global_load_lds((const unsigned*)((const char*)(gbase) + voff[_i]), (LAS unsigned*)(lds + (bufoff) + ldsw + _i * 8192), 16, 0, 0); } while (0)
; #define PG8_MMA(ai, bj, At, Bt) do { __builtin_amdgcn_s_setprio(1); _Pragma("unroll") for (int m = 0; m < 4; ++m) _Pragma("unroll") for (int n = 0; n < 2; ++n) _Pragma("unroll") for (int k = 0; k < 2; ++k) \
;         acc[ai][bj][m][n] = __builtin_amdgcn_mfma_f32_16x16x32_bf16(Bt[n][k], At[m][k], acc[ai][bj][m][n], 0, 0, 0); __builtin_amdgcn_s_setprio(0); } while (0)
; #define PG8_WAIT_V(n) asm volatile("s_waitcnt vmcnt(" #n ")" ::: "memory")
; #define PG8_WAIT_L(n) asm volatile("s_waitcnt lgkmcnt(" #n ")" ::: "memory")
; #define PG8_BAR __builtin_amdgcn_s_barrier()
; #define PG8_SCHED __builtin_amdgcn_sched_barrier(0)
; template <class Epi>
; DI void gemm_phase(LAS unsigned char* lds, const Gemm g, const StaticOrder& S, const Epi& E) {
;     ...
;             PG8_BAR; PG8_WAIT_L(0); PG8_MMA(1, 0, At, B0); PG8_BAR; PG8_SCHED;
;             PG8_STAGE(PG8_SB(1, 1), b3 + hstep);
;             PG8_WAIT_V(6); PG8_BAR; PG8_MMA(1, 1, At, B1); PG8_BAR;
	s_waitcnt lgkmcnt(0)
	s_setprio 1
	v_mfma_f32_16x16x32_bf16 v[60:63], v[138:141], v[186:189], v[60:63]
	v_mfma_f32_16x16x32_bf16 v[56:59], v[146:149], v[186:189], v[56:59]
	v_mfma_f32_16x16x32_bf16 v[52:55], v[138:141], v[194:197], v[52:55]
	v_mfma_f32_16x16x32_bf16 v[48:51], v[146:149], v[194:197], v[48:51]
	v_mfma_f32_16x16x32_bf16 v[36:39], v[138:141], v[202:205], v[36:39]
	v_mfma_f32_16x16x32_bf16 v[32:35], v[146:149], v[202:205], v[32:35]
	v_mfma_f32_16x16x32_bf16 v[20:23], v[138:141], v[210:213], v[20:23]
	v_mfma_f32_16x16x32_bf16 v[16:19], v[146:149], v[210:213], v[16:19]
	v_mfma_f32_16x16x32_bf16 v[60:63], v[142:145], v[190:193], v[60:63]
	v_mfma_f32_16x16x32_bf16 v[56:59], v[150:153], v[190:193], v[56:59]
	v_mfma_f32_16x16x32_bf16 v[52:55], v[142:145], v[198:201], v[52:55]
	v_mfma_f32_16x16x32_bf16 v[48:51], v[150:153], v[198:201], v[48:51]
	v_mfma_f32_16x16x32_bf16 v[36:39], v[142:145], v[206:209], v[36:39]
	v_mfma_f32_16x16x32_bf16 v[32:35], v[150:153], v[206:209], v[32:35]
	v_mfma_f32_16x16x32_bf16 v[20:23], v[142:145], v[214:217], v[20:23]
	v_mfma_f32_16x16x32_bf16 v[16:19], v[150:153], v[214:217], v[16:19]
	s_setprio 0
	s_barrier
	s_add_u32 s18, s18, 0x80080
	s_addc_u32 s19, s19, 0
	s_add_i32 s20, s20, s23
	v_lshl_add_u64 v[138:139], s[18:19], 0, v[158:159]
	s_mov_b32 m0, s20
	s_nop 0
	global_load_lds_dwordx4 v[138:139], off
	v_lshl_add_u64 v[138:139], s[18:19], 0, v[128:129]
	s_add_i32 m0, s20, 0x2000
	s_nop 0
	global_load_lds_dwordx4 v[138:139], off
	s_waitcnt vmcnt(6)
	s_barrier
	s_setprio 1
	v_mfma_f32_16x16x32_bf16 v[44:47], v[226:229], v[186:189], v[44:47]
	v_mfma_f32_16x16x32_bf16 v[40:43], v[234:237], v[186:189], v[40:43]
	v_mfma_f32_16x16x32_bf16 v[28:31], v[226:229], v[194:197], v[28:31]
	v_mfma_f32_16x16x32_bf16 v[24:27], v[234:237], v[194:197], v[24:27]
	v_mfma_f32_16x16x32_bf16 v[12:15], v[226:229], v[202:205], v[12:15]
	v_mfma_f32_16x16x32_bf16 v[8:11], v[234:237], v[202:205], v[8:11]
	v_mfma_f32_16x16x32_bf16 v[4:7], v[226:229], v[210:213], v[4:7]
	v_mfma_f32_16x16x32_bf16 v[0:3], v[234:237], v[210:213], v[0:3]
	v_mfma_f32_16x16x32_bf16 v[44:47], v[230:233], v[190:193], v[44:47]
	v_mfma_f32_16x16x32_bf16 v[40:43], v[238:241], v[190:193], v[40:43]
	v_mfma_f32_16x16x32_bf16 v[28:31], v[230:233], v[198:201], v[28:31]
	v_mfma_f32_16x16x32_bf16 v[24:27], v[238:241], v[198:201], v[24:27]
	v_mfma_f32_16x16x32_bf16 v[12:15], v[230:233], v[206:209], v[12:15]
	v_mfma_f32_16x16x32_bf16 v[8:11], v[238:241], v[206:209], v[8:11]
	v_mfma_f32_16x16x32_bf16 v[4:7], v[230:233], v[214:217], v[4:7]
	v_mfma_f32_16x16x32_bf16 v[0:3], v[238:241], v[214:217], v[0:3]
	s_setprio 0
	s_add_i32 s36, s36, 2
	s_add_u32 s16, s16, 0x100
	s_addc_u32 s17, s17, 0
	s_add_u32 s34, s34, 0x100
	s_addc_u32 s35, s35, 0
	s_cmp_gt_u32 s36, 29
	s_barrier
	s_cbranch_scc0 .LBB0_231
; #define PG8_WAIT_V(n) asm volatile("s_waitcnt vmcnt(" #n ")" ::: "memory")
; #define PG8_BAR __builtin_amdgcn_s_barrier()
; template <class Epi>
; DI void gemm_phase(LAS unsigned char* lds, const Gemm g, const StaticOrder& S, const Epi& E) {
;     ...
;     PG8_WAIT_V(0);
;     if (wr == 0) PG8_BAR;
;     PG8_BAR;
;     DI void operator()(const f32x4 (&acc)[2][2][4][2], const Unit& u, int wr, int wc, int fr, int fq) const {
;         const int row0 = u.pm * BM + wr * 64 + fr, col0 = u.pn * BM + wc * 32 + 8 * fq;
; #pragma unroll
;         for (int ai = 0; ai < 2; ++ai)
; #pragma unroll
;             for (int m = 0; m < 4; ++m) { u16* rowp = O + (size_t)(row0 + ai * HALF + m * 16) * ldc + col0;
; #pragma unroll
;                 for (int bj = 0; bj < 2; ++bj) { const f32x4 v0 = acc[ai][bj][m][0], v1 = acc[ai][bj][m][1];
;                     *(u32x4*)(rowp + bj * HALF) = (u32x4){pk(v0[0], v0[1]), pk(v0[2], v0[3]), pk(v1[0], v1[1]), pk(v1[2], v1[3])}; } }
	v_lshl_add_u32 v144, s33, 8, v134
	v_lshl_or_b32 v138, s31, 8, v136
	v_ashrrev_i32_e32 v139, 31, v138
	v_mov_b64_e32 v[140:141], s[50:51]
	s_movk_i32 s9, 0x3000
	v_cvt_pk_bf16_f32 v68, v68, v69
	v_cvt_pk_bf16_f32 v69, v70, v71
	v_cvt_pk_bf16_f32 v70, v64, v65
	v_add_u32_e32 v64, 0x80, v144
	v_mad_i64_i32 v[142:143], s[4:5], v144, s9, v[140:141]
	v_lshlrev_b64 v[138:139], 1, v[138:139]
	v_cvt_pk_bf16_f32 v108, v108, v109
	v_cvt_pk_bf16_f32 v109, v110, v111
	v_cvt_pk_bf16_f32 v110, v104, v105
	v_or_b32_e32 v104, 16, v144
	v_mad_i64_i32 v[64:65], s[4:5], v64, s9, v[140:141]
	v_cvt_pk_bf16_f32 v44, v44, v45
	v_cvt_pk_bf16_f32 v45, v46, v47
	v_cvt_pk_bf16_f32 v46, v40, v41
	v_add_u32_e32 v40, 0x90, v144
	v_lshl_add_u64 v[142:143], v[142:143], 0, v[138:139]
	v_cvt_pk_bf16_f32 v111, v106, v107
	v_mad_i64_i32 v[104:105], s[4:5], v104, s9, v[140:141]
	v_cvt_pk_bf16_f32 v92, v92, v93
	v_cvt_pk_bf16_f32 v93, v94, v95
	v_cvt_pk_bf16_f32 v94, v88, v89
	v_or_b32_e32 v88, 32, v144
	v_lshl_add_u64 v[64:65], v[64:65], 0, v[138:139]
	v_cvt_pk_bf16_f32 v47, v42, v43
	v_mad_i64_i32 v[40:41], s[4:5], v40, s9, v[140:141]
	v_cvt_pk_bf16_f32 v28, v28, v29
	v_cvt_pk_bf16_f32 v29, v30, v31
	v_cvt_pk_bf16_f32 v30, v24, v25
	v_add_u32_e32 v24, 0xa0, v144
	global_store_dwordx4 v[142:143], v[108:111], off offset:256
	v_cvt_pk_bf16_f32 v95, v90, v91
	v_mad_i64_i32 v[88:89], s[4:5], v88, s9, v[140:141]
	v_lshl_add_u64 v[108:109], v[104:105], 0, v[138:139]
	v_cvt_pk_bf16_f32 v76, v76, v77
	v_cvt_pk_bf16_f32 v77, v78, v79
	v_cvt_pk_bf16_f32 v78, v72, v73
	v_or_b32_e32 v72, 48, v144
	global_store_dwordx4 v[64:65], v[44:47], off offset:256
	v_cvt_pk_bf16_f32 v31, v26, v27
	v_mad_i64_i32 v[24:25], s[4:5], v24, s9, v[140:141]
	v_lshl_add_u64 v[44:45], v[40:41], 0, v[138:139]
	v_cvt_pk_bf16_f32 v12, v12, v13
	v_cvt_pk_bf16_f32 v13, v14, v15
	v_cvt_pk_bf16_f32 v14, v8, v9
	v_add_u32_e32 v8, 0xb0, v144
	global_store_dwordx4 v[108:109], v[92:95], off offset:256
	v_cvt_pk_bf16_f32 v79, v74, v75
	v_mad_i64_i32 v[72:73], s[4:5], v72, s9, v[140:141]
	v_lshl_add_u64 v[92:93], v[88:89], 0, v[138:139]
	global_store_dwordx4 v[44:45], v[28:31], off offset:256
	v_cvt_pk_bf16_f32 v15, v10, v11
	v_mad_i64_i32 v[8:9], s[4:5], v8, s9, v[140:141]
	v_lshl_add_u64 v[28:29], v[24:25], 0, v[138:139]
	v_cvt_pk_bf16_f32 v124, v124, v125
	v_cvt_pk_bf16_f32 v125, v126, v127
	v_cvt_pk_bf16_f32 v126, v120, v121
	v_cvt_pk_bf16_f32 v127, v122, v123
	v_cvt_pk_bf16_f32 v104, v116, v117
	v_cvt_pk_bf16_f32 v105, v118, v119
	v_cvt_pk_bf16_f32 v106, v112, v113
	v_cvt_pk_bf16_f32 v107, v114, v115
	v_cvt_pk_bf16_f32 v88, v100, v101
	v_cvt_pk_bf16_f32 v89, v102, v103
	v_cvt_pk_bf16_f32 v90, v96, v97
	v_cvt_pk_bf16_f32 v91, v98, v99
	global_store_dwordx4 v[92:93], v[76:79], off offset:256
	v_cvt_pk_bf16_f32 v74, v80, v81
	v_cvt_pk_bf16_f32 v75, v82, v83
	v_lshl_add_u64 v[76:77], v[72:73], 0, v[138:139]
	v_cvt_pk_bf16_f32 v72, v84, v85
	v_cvt_pk_bf16_f32 v73, v86, v87
	v_cvt_pk_bf16_f32 v71, v66, v67
	v_cvt_pk_bf16_f32 v60, v60, v61
	v_cvt_pk_bf16_f32 v61, v62, v63
	v_cvt_pk_bf16_f32 v62, v56, v57
	v_cvt_pk_bf16_f32 v63, v58, v59
	v_cvt_pk_bf16_f32 v40, v52, v53
	v_cvt_pk_bf16_f32 v41, v54, v55
	v_cvt_pk_bf16_f32 v42, v48, v49
	v_cvt_pk_bf16_f32 v43, v50, v51
	v_cvt_pk_bf16_f32 v24, v36, v37
	v_cvt_pk_bf16_f32 v25, v38, v39
	v_cvt_pk_bf16_f32 v26, v32, v33
	v_cvt_pk_bf16_f32 v27, v34, v35
	global_store_dwordx4 v[28:29], v[12:15], off offset:256
	v_cvt_pk_bf16_f32 v10, v16, v17
	v_cvt_pk_bf16_f32 v11, v18, v19
	v_lshl_add_u64 v[12:13], v[8:9], 0, v[138:139]
	v_cvt_pk_bf16_f32 v8, v20, v21
	v_cvt_pk_bf16_f32 v9, v22, v23
	v_cvt_pk_bf16_f32 v4, v4, v5
	v_cvt_pk_bf16_f32 v5, v6, v7
	v_cvt_pk_bf16_f32 v6, v0, v1
	v_cvt_pk_bf16_f32 v7, v2, v3
	s_and_b64 vcc, exec, s[6:7]
	s_mov_b32 s31, s8
	s_mov_b32 s33, s10
	s_mov_b64 s[18:19], s[14:15]
	s_mov_b64 s[16:17], s[12:13]
	global_store_dwordx4 v[142:143], v[124:127], off
	global_store_dwordx4 v[108:109], v[104:107], off
	global_store_dwordx4 v[92:93], v[88:91], off
	global_store_dwordx4 v[76:77], v[72:75], off
	global_store_dwordx4 v[76:77], v[68:71], off offset:256
	global_store_dwordx4 v[64:65], v[60:63], off
	global_store_dwordx4 v[44:45], v[40:43], off
	global_store_dwordx4 v[28:29], v[24:27], off
	global_store_dwordx4 v[12:13], v[8:11], off
	global_store_dwordx4 v[12:13], v[4:7], off offset:256
	s_cbranch_vccz .LBB0_228
	s_waitcnt vmcnt(0)
	s_cmpk_gt_u32 s2, 0xff
	s_cbranch_scc1 .LBB0_235
	s_barrier

; DI void xcd_barrier(const XcdBarrier& b) {
;     asm volatile("s_waitcnt vmcnt(0)" ::: "memory");
;     __syncthreads();
;     if (threadIdx.x == 0) {
;         unsigned* bar = b.bar;
;         __builtin_amdgcn_s_waitcnt(0);
;         unsigned nloc = b.st[0], nx = b.st[1];
;         if (nloc == 0u) { xcd_barrier_complete(bar, b.x, nloc, nx); b.st[0] = nloc; b.st[1] = nx; }
; __global__ void __launch_bounds__(512, 2) mega_fwd(Params p) {
;     ...
;         if (ph + 1 < p.ph_hi) {
;             if (ph == p.ph_lo) { grid.sync(); gb = xcd_barrier_post(barw, bst); }
;             else xcd_barrier(gb);
.LBB0_258:
	s_load_dwordx2 s[4:5], s[0:1], 0x238
	s_add_i32 s2, s33, 1
	s_mov_b64 s[6:7], -1
	s_waitcnt lgkmcnt(0)
	s_cmp_ge_i32 s2, s5
	s_cbranch_scc1 .LBB0_20
	s_load_dwordx2 s[4:5], s[0:1], 0x238
	s_waitcnt lgkmcnt(0)
	s_cmp_lg_u32 s33, s4
	s_cbranch_scc0 .LBB0_360
	s_waitcnt vmcnt(0)
	s_waitcnt vmcnt(0)
	s_barrier
	s_mov_b64 s[6:7], exec
	v_readlane_b32 s4, v253, 6
	v_readlane_b32 s5, v253, 7
	s_and_b64 s[4:5], s[6:7], s[4:5]
	s_mov_b64 exec, s[4:5]
	s_cbranch_execz .LBB0_359
	v_readlane_b32 s3, v255, 7
	s_waitcnt vmcnt(0) expcnt(0) lgkmcnt(0)
	s_nop 0
	v_mov_b32_e32 v0, s3
	ds_read_b32 v2, v0
	v_readlane_b32 s3, v255, 8
	s_waitcnt lgkmcnt(0)
	v_cmp_ne_u32_e32 vcc, 0, v2
	v_mov_b32_e32 v0, s3
	ds_read_b32 v0, v0
	s_cbranch_vccnz .LBB0_276
	s_mov_b32 s3, 1
	s_branch .LBB0_264

; #define PG8_STAGE(bufoff, gbase) do { _Pragma("unroll") for (int _i = 0; _i < 2; ++_i) \
;         __builtin_amdgcn_global_load_lds((const unsigned*)((const char*)(gbase) + voff[_i]), (LAS unsigned*)(lds + (bufoff) + ldsw + _i * 8192), 16, 0, 0); } while (0)
; #define PG8_LDA(dst, b, h) do { _Pragma("unroll") for (int m = 0; m < 4; ++m) _Pragma("unroll") for (int k = 0; k < 2; ++k) dst[m][k] = *(const LAS bf16x8*)(lds + PG8_SA(b, h) + aoff + m * 2048 + k * 1024); } while (0)
; #define PG8_LDB(dst, b, h) do { _Pragma("unroll") for (int n = 0; n < 2; ++n) _Pragma("unroll") for (int k = 0; k < 2; ++k) dst[n][k] = *(const LAS bf16x8*)(lds + PG8_SB(b, h) + boff + n * 2048 + k * 1024); } while (0)
; #define PG8_MMA(ai, bj, At, Bt) do { __builtin_amdgcn_s_setprio(1); _Pragma("unroll") for (int m = 0; m < 4; ++m) _Pragma("unroll") for (int n = 0; n < 2; ++n) _Pragma("unroll") for (int k = 0; k < 2; ++k) \
;         acc[ai][bj][m][n] = __builtin_amdgcn_mfma_f32_16x16x32_bf16(Bt[n][k], At[m][k], acc[ai][bj][m][n], 0, 0, 0); __builtin_amdgcn_s_setprio(0); } while (0)
; #define PG8_WAIT_L(n) asm volatile("s_waitcnt lgkmcnt(" #n ")" ::: "memory")
; #define PG8_BAR __builtin_amdgcn_s_barrier()
; #define PG8_SCHED __builtin_amdgcn_sched_barrier(0)
; template <class Epi>
; DI void gemm_phase(LAS unsigned char* lds, const Gemm g, const StaticOrder& S, const Epi& E) {
;     ...
;         for (int t = 0; t < nt; t += 2) {
;             const bool last = (t == nt - 2);
;             const char* a1 = cA + (size_t)(t + 1) * kstep;
;             const char* a2 = last ? nA : cA + (size_t)(t + 2) * kstep; const char* b2 = last ? nB : cB + (size_t)(t + 2) * kstep;
;             const char* a3 = a2 + kstep; const char* b3 = b2 + kstep;
;             PG8_LDB(B0, 0, 0); PG8_SCHED; PG8_LDA(At, 0, 0); PG8_STAGE(PG8_SA(1, 1), a1 + hstep);
;             PG8_WAIT_L(8); PG8_BAR; PG8_WAIT_L(0); PG8_MMA(0, 0, At, B0); PG8_BAR; PG8_SCHED;
;             PG8_LDB(B1, 0, 1); PG8_STAGE(PG8_SB(0, 0), b2);
;             PG8_BAR; PG8_WAIT_L(0); PG8_MMA(0, 1, At, B1); PG8_BAR;
;             PG8_LDA(At, 0, 1); PG8_STAGE(PG8_SA(0, 0), a2);
;             PG8_BAR; PG8_WAIT_L(0); PG8_MMA(1, 0, At, B0); PG8_BAR; PG8_SCHED;
.LBB0_320:
	s_add_u32 s26, s24, 0x100
	s_addc_u32 s27, s25, 0
	s_add_i32 s47, 0, 0x10000
	v_add_u32_e32 v140, s47, v226
	ds_read_b128 v[128:131], v140
	ds_read_b128 v[132:135], v140 offset:1024
	ds_read_b128 v[136:139], v140 offset:2048
	ds_read_b128 v[140:143], v140 offset:3072
	s_cmp_eq_u32 s46, 28
	s_cselect_b32 s31, s4, s27
	s_cselect_b32 s30, s5, s26
	s_cselect_b32 s29, s9, s45
	s_cselect_b32 s28, s11, s33
	v_lshl_add_u64 v[214:215], s[24:25], 0, v[190:191]
	s_add_i32 m0, s38, 0xc000
	ds_read_b128 v[144:147], v228
	ds_read_b128 v[148:151], v228 offset:1024
	ds_read_b128 v[152:155], v228 offset:2048
	ds_read_b128 v[194:197], v228 offset:3072
	ds_read_b128 v[198:201], v228 offset:4096
	ds_read_b128 v[202:205], v228 offset:5120
	ds_read_b128 v[206:209], v228 offset:6144
	ds_read_b128 v[210:213], v228 offset:7168
	global_load_lds_dwordx4 v[214:215], off
	v_lshl_add_u64 v[214:215], s[24:25], 0, v[192:193]
	s_add_i32 m0, s38, 0xe000
	s_nop 0
	global_load_lds_dwordx4 v[214:215], off
	s_waitcnt lgkmcnt(8)
	s_barrier
	s_waitcnt lgkmcnt(0)
	s_setprio 1
	v_mfma_f32_16x16x32_bf16 v[124:127], v[128:131], v[144:147], v[124:127]
	v_mfma_f32_16x16x32_bf16 v[120:123], v[136:139], v[144:147], v[120:123]
	v_mfma_f32_16x16x32_bf16 v[116:119], v[128:131], v[152:155], v[116:119]
	v_mfma_f32_16x16x32_bf16 v[112:115], v[136:139], v[152:155], v[112:115]
	v_mfma_f32_16x16x32_bf16 v[108:111], v[128:131], v[198:201], v[108:111]
	v_mfma_f32_16x16x32_bf16 v[104:107], v[136:139], v[198:201], v[104:107]
	v_mfma_f32_16x16x32_bf16 v[100:103], v[128:131], v[206:209], v[100:103]
	v_mfma_f32_16x16x32_bf16 v[96:99], v[136:139], v[206:209], v[96:99]
	v_mfma_f32_16x16x32_bf16 v[124:127], v[132:135], v[148:151], v[124:127]
	v_mfma_f32_16x16x32_bf16 v[120:123], v[140:143], v[148:151], v[120:123]
	v_mfma_f32_16x16x32_bf16 v[116:119], v[132:135], v[194:197], v[116:119]
	v_mfma_f32_16x16x32_bf16 v[112:115], v[140:143], v[194:197], v[112:115]
	v_mfma_f32_16x16x32_bf16 v[108:111], v[132:135], v[202:205], v[108:111]
	v_mfma_f32_16x16x32_bf16 v[104:107], v[140:143], v[202:205], v[104:107]
	v_mfma_f32_16x16x32_bf16 v[100:103], v[132:135], v[210:213], v[100:103]
	v_mfma_f32_16x16x32_bf16 v[96:99], v[140:143], v[210:213], v[96:99]
	s_setprio 0
	s_barrier
	s_add_i32 s48, 0, 0x14000
	s_add_i32 s24, s47, s37
	v_add_u32_e32 v158, s48, v226
	v_lshl_add_u64 v[218:219], s[28:29], 0, v[188:189]
	s_mov_b32 m0, s24
	ds_read_b128 v[214:217], v158
	ds_read_b128 v[230:233], v158 offset:1024
	ds_read_b128 v[234:237], v158 offset:2048
	ds_read_b128 v[238:241], v158 offset:3072
	global_load_lds_dwordx4 v[218:219], off
	v_lshl_add_u64 v[220:221], s[28:29], 0, v[186:187]
	s_add_i32 m0, s24, 0x2000
	s_nop 0
	global_load_lds_dwordx4 v[220:221], off
	s_barrier
	s_waitcnt lgkmcnt(0)
	s_setprio 1
	v_mfma_f32_16x16x32_bf16 v[60:63], v[214:217], v[144:147], v[60:63]
	v_mfma_f32_16x16x32_bf16 v[56:59], v[234:237], v[144:147], v[56:59]
	v_mfma_f32_16x16x32_bf16 v[52:55], v[214:217], v[152:155], v[52:55]
	v_mfma_f32_16x16x32_bf16 v[48:51], v[234:237], v[152:155], v[48:51]
	v_mfma_f32_16x16x32_bf16 v[44:47], v[214:217], v[198:201], v[44:47]
	v_mfma_f32_16x16x32_bf16 v[40:43], v[234:237], v[198:201], v[40:43]
	v_mfma_f32_16x16x32_bf16 v[36:39], v[214:217], v[206:209], v[36:39]
	v_mfma_f32_16x16x32_bf16 v[32:35], v[234:237], v[206:209], v[32:35]
	v_mfma_f32_16x16x32_bf16 v[60:63], v[230:233], v[148:151], v[60:63]
	v_mfma_f32_16x16x32_bf16 v[56:59], v[238:241], v[148:151], v[56:59]
	v_mfma_f32_16x16x32_bf16 v[52:55], v[230:233], v[194:197], v[52:55]
	v_mfma_f32_16x16x32_bf16 v[48:51], v[238:241], v[194:197], v[48:51]
	v_mfma_f32_16x16x32_bf16 v[44:47], v[230:233], v[202:205], v[44:47]
	v_mfma_f32_16x16x32_bf16 v[40:43], v[238:241], v[202:205], v[40:43]
	v_mfma_f32_16x16x32_bf16 v[36:39], v[230:233], v[210:213], v[36:39]
	v_mfma_f32_16x16x32_bf16 v[32:35], v[238:241], v[210:213], v[32:35]
	s_setprio 0
	s_mov_b32 m0, s38
	v_lshl_add_u64 v[242:243], s[30:31], 0, v[188:189]
	s_barrier
	ds_read_b128 v[144:147], v228 offset:16384
	ds_read_b128 v[148:151], v228 offset:17408
	ds_read_b128 v[152:155], v228 offset:18432
	ds_read_b128 v[194:197], v228 offset:19456
	ds_read_b128 v[198:201], v228 offset:20480
	ds_read_b128 v[202:205], v228 offset:21504
	ds_read_b128 v[206:209], v228 offset:22528
	ds_read_b128 v[210:213], v228 offset:23552
	global_load_lds_dwordx4 v[242:243], off
	v_lshl_add_u64 v[244:245], s[30:31], 0, v[186:187]
	s_mov_b32 m0, s39
	s_nop 0
	global_load_lds_dwordx4 v[244:245], off
	s_barrier
	s_waitcnt lgkmcnt(0)
	s_setprio 1
	v_mfma_f32_16x16x32_bf16 v[92:95], v[128:131], v[144:147], v[92:95]
	v_mfma_f32_16x16x32_bf16 v[88:91], v[136:139], v[144:147], v[88:91]
	v_mfma_f32_16x16x32_bf16 v[84:87], v[128:131], v[152:155], v[84:87]
	v_mfma_f32_16x16x32_bf16 v[80:83], v[136:139], v[152:155], v[80:83]
	v_mfma_f32_16x16x32_bf16 v[76:79], v[128:131], v[198:201], v[76:79]
	v_mfma_f32_16x16x32_bf16 v[72:75], v[136:139], v[198:201], v[72:75]
	v_mfma_f32_16x16x32_bf16 v[68:71], v[128:131], v[206:209], v[68:71]
	v_mfma_f32_16x16x32_bf16 v[64:67], v[136:139], v[206:209], v[64:67]
	v_mfma_f32_16x16x32_bf16 v[92:95], v[132:135], v[148:151], v[92:95]
	v_mfma_f32_16x16x32_bf16 v[88:91], v[140:143], v[148:151], v[88:91]
	v_mfma_f32_16x16x32_bf16 v[84:87], v[132:135], v[194:197], v[84:87]
	v_mfma_f32_16x16x32_bf16 v[80:83], v[140:143], v[194:197], v[80:83]
	v_mfma_f32_16x16x32_bf16 v[76:79], v[132:135], v[202:205], v[76:79]
	v_mfma_f32_16x16x32_bf16 v[72:75], v[140:143], v[202:205], v[72:75]
	v_mfma_f32_16x16x32_bf16 v[68:71], v[132:135], v[210:213], v[68:71]
	v_mfma_f32_16x16x32_bf16 v[64:67], v[140:143], v[210:213], v[64:67]
	s_setprio 0
	s_barrier
; #define PG8_STAGE(bufoff, gbase) do { _Pragma("unroll") for (int _i = 0; _i < 2; ++_i) \
;         __builtin_amdgcn_global_load_lds((const unsigned*)((const char*)(gbase) + voff[_i]), (LAS unsigned*)(lds + (bufoff) + ldsw + _i * 8192), 16, 0, 0); } while (0)
; #define PG8_LDA(dst, b, h) do { _Pragma("unroll") for (int m = 0; m < 4; ++m) _Pragma("unroll") for (int k = 0; k < 2; ++k) dst[m][k] = *(const LAS bf16x8*)(lds + PG8_SA(b, h) + aoff + m * 2048 + k * 1024); } while (0)
; #define PG8_LDB(dst, b, h) do { _Pragma("unroll") for (int n = 0; n < 2; ++n) _Pragma("unroll") for (int k = 0; k < 2; ++k) dst[n][k] = *(const LAS bf16x8*)(lds + PG8_SB(b, h) + boff + n * 2048 + k * 1024); } while (0)
; #define PG8_MMA(ai, bj, At, Bt) do { __builtin_amdgcn_s_setprio(1); _Pragma("unroll") for (int m = 0; m < 4; ++m) _Pragma("unroll") for (int n = 0; n < 2; ++n) _Pragma("unroll") for (int k = 0; k < 2; ++k) \
;         acc[ai][bj][m][n] = __builtin_amdgcn_mfma_f32_16x16x32_bf16(Bt[n][k], At[m][k], acc[ai][bj][m][n], 0, 0, 0); __builtin_amdgcn_s_setprio(0); } while (0)
; #define PG8_WAIT_V(n) asm volatile("s_waitcnt vmcnt(" #n ")" ::: "memory")
; #define PG8_WAIT_L(n) asm volatile("s_waitcnt lgkmcnt(" #n ")" ::: "memory")
; #define PG8_BAR __builtin_amdgcn_s_barrier()
; #define PG8_SCHED __builtin_amdgcn_sched_barrier(0)
; template <class Epi>
; DI void gemm_phase(LAS unsigned char* lds, const Gemm g, const StaticOrder& S, const Epi& E) {
;     ...
;             PG8_STAGE(PG8_SB(0, 1), b2 + hstep);
;             PG8_WAIT_V(6); PG8_BAR; PG8_MMA(1, 1, At, B1); PG8_BAR;
;             PG8_LDB(B0, 1, 0); PG8_SCHED; PG8_LDA(At, 1, 0); PG8_STAGE(PG8_SA(0, 1), a2 + hstep);
;             PG8_WAIT_L(8); PG8_BAR; PG8_WAIT_L(0); PG8_MMA(0, 0, At, B0); PG8_BAR; PG8_SCHED;
;             PG8_LDB(B1, 1, 1); PG8_STAGE(PG8_SB(1, 0), b3);
;             PG8_BAR; PG8_WAIT_L(0); PG8_MMA(0, 1, At, B1); PG8_BAR;
;             PG8_LDA(At, 1, 1); PG8_STAGE(PG8_SA(1, 0), a3);
	s_add_u32 s24, s28, 0x80000
	s_addc_u32 s25, s29, 0
	s_add_i32 s47, s48, s37
	v_lshl_add_u64 v[128:129], s[24:25], 0, v[188:189]
	s_mov_b32 m0, s47
	s_nop 0
	global_load_lds_dwordx4 v[128:129], off
	v_lshl_add_u64 v[128:129], s[24:25], 0, v[186:187]
	s_add_i32 m0, s47, 0x2000
	s_nop 0
	global_load_lds_dwordx4 v[128:129], off
	s_waitcnt vmcnt(6)
	s_barrier
	s_setprio 1
	v_mfma_f32_16x16x32_bf16 v[28:31], v[214:217], v[144:147], v[28:31]
	v_mfma_f32_16x16x32_bf16 v[24:27], v[234:237], v[144:147], v[24:27]
	v_mfma_f32_16x16x32_bf16 v[20:23], v[214:217], v[152:155], v[20:23]
	v_mfma_f32_16x16x32_bf16 v[16:19], v[234:237], v[152:155], v[16:19]
	v_mfma_f32_16x16x32_bf16 v[12:15], v[214:217], v[198:201], v[12:15]
	v_mfma_f32_16x16x32_bf16 v[8:11], v[234:237], v[198:201], v[8:11]
	v_mfma_f32_16x16x32_bf16 v[4:7], v[214:217], v[206:209], v[4:7]
	v_mfma_f32_16x16x32_bf16 v[0:3], v[234:237], v[206:209], v[0:3]
	v_mfma_f32_16x16x32_bf16 v[28:31], v[230:233], v[148:151], v[28:31]
	v_mfma_f32_16x16x32_bf16 v[24:27], v[238:241], v[148:151], v[24:27]
	v_mfma_f32_16x16x32_bf16 v[20:23], v[230:233], v[194:197], v[20:23]
	v_mfma_f32_16x16x32_bf16 v[16:19], v[238:241], v[194:197], v[16:19]
	v_mfma_f32_16x16x32_bf16 v[12:15], v[230:233], v[202:205], v[12:15]
	v_mfma_f32_16x16x32_bf16 v[8:11], v[238:241], v[202:205], v[8:11]
	v_mfma_f32_16x16x32_bf16 v[4:7], v[230:233], v[210:213], v[4:7]
	v_mfma_f32_16x16x32_bf16 v[0:3], v[238:241], v[210:213], v[0:3]
	s_setprio 0
	s_add_i32 s47, 0, 0x18000
	v_add_u32_e32 v140, s47, v226
	s_barrier
	ds_read_b128 v[128:131], v140
	ds_read_b128 v[132:135], v140 offset:1024
	ds_read_b128 v[136:139], v140 offset:2048
	ds_read_b128 v[140:143], v140 offset:3072
	s_add_u32 s24, s30, 0x80000
	s_addc_u32 s25, s31, 0
	s_mov_b32 m0, s40
	v_lshl_add_u64 v[214:215], s[24:25], 0, v[188:189]
	ds_read_b128 v[144:147], v228 offset:32768
	ds_read_b128 v[148:151], v228 offset:33792
	ds_read_b128 v[152:155], v228 offset:34816
	ds_read_b128 v[194:197], v228 offset:35840
	ds_read_b128 v[198:201], v228 offset:36864
	ds_read_b128 v[202:205], v228 offset:37888
	ds_read_b128 v[206:209], v228 offset:38912
	ds_read_b128 v[210:213], v228 offset:39936
	global_load_lds_dwordx4 v[214:215], off
	v_lshl_add_u64 v[214:215], s[24:25], 0, v[186:187]
	s_mov_b32 m0, s41
	s_nop 0
	global_load_lds_dwordx4 v[214:215], off
	s_waitcnt lgkmcnt(8)
	s_barrier
	s_waitcnt lgkmcnt(0)
	s_setprio 1
	v_mfma_f32_16x16x32_bf16 v[124:127], v[128:131], v[144:147], v[124:127]
	v_mfma_f32_16x16x32_bf16 v[120:123], v[136:139], v[144:147], v[120:123]
	v_mfma_f32_16x16x32_bf16 v[116:119], v[128:131], v[152:155], v[116:119]
	v_mfma_f32_16x16x32_bf16 v[112:115], v[136:139], v[152:155], v[112:115]
	v_mfma_f32_16x16x32_bf16 v[108:111], v[128:131], v[198:201], v[108:111]
	v_mfma_f32_16x16x32_bf16 v[104:107], v[136:139], v[198:201], v[104:107]
	v_mfma_f32_16x16x32_bf16 v[100:103], v[128:131], v[206:209], v[100:103]
	v_mfma_f32_16x16x32_bf16 v[96:99], v[136:139], v[206:209], v[96:99]
	v_mfma_f32_16x16x32_bf16 v[124:127], v[132:135], v[148:151], v[124:127]
	v_mfma_f32_16x16x32_bf16 v[120:123], v[140:143], v[148:151], v[120:123]
	v_mfma_f32_16x16x32_bf16 v[116:119], v[132:135], v[194:197], v[116:119]
	v_mfma_f32_16x16x32_bf16 v[112:115], v[140:143], v[194:197], v[112:115]
	v_mfma_f32_16x16x32_bf16 v[108:111], v[132:135], v[202:205], v[108:111]
	v_mfma_f32_16x16x32_bf16 v[104:107], v[140:143], v[202:205], v[104:107]
	v_mfma_f32_16x16x32_bf16 v[100:103], v[132:135], v[210:213], v[100:103]
	v_mfma_f32_16x16x32_bf16 v[96:99], v[140:143], v[210:213], v[96:99]
	s_setprio 0
	s_barrier
	s_add_i32 s30, 0, 0x1c000
	s_add_i32 s24, s47, s37
	v_add_u32_e32 v158, s30, v226
	v_lshl_add_u64 v[218:219], v[218:219], 0, s[94:95]
	s_mov_b32 m0, s24
	ds_read_b128 v[214:217], v158
	ds_read_b128 v[230:233], v158 offset:1024
	ds_read_b128 v[234:237], v158 offset:2048
	ds_read_b128 v[238:241], v158 offset:3072
	global_load_lds_dwordx4 v[218:219], off
	v_lshl_add_u64 v[218:219], v[220:221], 0, s[94:95]
	s_add_i32 m0, s24, 0x2000
	s_nop 0
	global_load_lds_dwordx4 v[218:219], off
	s_barrier
	s_waitcnt lgkmcnt(0)
	s_setprio 1
	v_mfma_f32_16x16x32_bf16 v[60:63], v[214:217], v[144:147], v[60:63]
	v_mfma_f32_16x16x32_bf16 v[56:59], v[234:237], v[144:147], v[56:59]
	v_mfma_f32_16x16x32_bf16 v[52:55], v[214:217], v[152:155], v[52:55]
	v_mfma_f32_16x16x32_bf16 v[48:51], v[234:237], v[152:155], v[48:51]
	v_mfma_f32_16x16x32_bf16 v[44:47], v[214:217], v[198:201], v[44:47]
	v_mfma_f32_16x16x32_bf16 v[40:43], v[234:237], v[198:201], v[40:43]
	v_mfma_f32_16x16x32_bf16 v[36:39], v[214:217], v[206:209], v[36:39]
	v_mfma_f32_16x16x32_bf16 v[32:35], v[234:237], v[206:209], v[32:35]
	v_mfma_f32_16x16x32_bf16 v[60:63], v[230:233], v[148:151], v[60:63]
	v_mfma_f32_16x16x32_bf16 v[56:59], v[238:241], v[148:151], v[56:59]
	v_mfma_f32_16x16x32_bf16 v[52:55], v[230:233], v[194:197], v[52:55]
	v_mfma_f32_16x16x32_bf16 v[48:51], v[238:241], v[194:197], v[48:51]
	v_mfma_f32_16x16x32_bf16 v[44:47], v[230:233], v[202:205], v[44:47]
	v_mfma_f32_16x16x32_bf16 v[40:43], v[238:241], v[202:205], v[40:43]
	v_mfma_f32_16x16x32_bf16 v[36:39], v[230:233], v[210:213], v[36:39]
	v_mfma_f32_16x16x32_bf16 v[32:35], v[238:241], v[210:213], v[32:35]
	s_setprio 0
	s_mov_b32 m0, s42
	v_lshl_add_u64 v[218:219], v[242:243], 0, s[94:95]
	s_barrier
	ds_read_b128 v[144:147], v228 offset:49152
	ds_read_b128 v[148:151], v228 offset:50176
	ds_read_b128 v[152:155], v228 offset:51200
	ds_read_b128 v[194:197], v228 offset:52224
	ds_read_b128 v[198:201], v228 offset:53248
	ds_read_b128 v[202:205], v228 offset:54272
	ds_read_b128 v[206:209], v228 offset:55296
	ds_read_b128 v[210:213], v228 offset:56320
	global_load_lds_dwordx4 v[218:219], off
	v_lshl_add_u64 v[218:219], v[244:245], 0, s[94:95]
	s_mov_b32 m0, s43
	s_nop 0
	global_load_lds_dwordx4 v[218:219], off
	s_barrier
; #define PG8_BAR __builtin_amdgcn_s_barrier()
; template <class Epi>
; DI void gemm_phase(LAS unsigned char* lds, const Gemm g, const StaticOrder& S, const Epi& E) {
;     ...
;             PG8_BAR; PG8_WAIT_L(0); PG8_MMA(1, 0, At, B0); PG8_BAR; PG8_SCHED;
;             PG8_STAGE(PG8_SB(1, 1), b3 + hstep);
;             PG8_WAIT_V(6); PG8_BAR; PG8_MMA(1, 1, At, B1); PG8_BAR;
;     template <bool LN, int BJ, int LO, int HI> DI void batch(const f32x4 (&acc)[2][2][4][2], unsigned row0, unsigned col0, const f32x4 (&gv)[2], const f32x4 (&bv)[2]) const {
;         f32x4 r[HI - LO]; float mean[(HI - LO) / 2], rstd[(HI - LO) / 2];
; #pragma unroll
;         for (int i = LO; i < HI; ++i) { const int ai = i >> 3, m = (i >> 1) & 3, n = i & 1; const unsigned row = row0 + ai * HALF + m * 16;
;             if (n == 0) { mean[(i - LO) >> 1] = 0.f; rstd[(i - LO) >> 1] = 1.f;
;                 if (LN) { const float2 st = *(const float2*)(stats + row * 2u); mean[(i - LO) >> 1] = st.x; rstd[(i - LO) >> 1] = st.y; } }
;             r[i - LO] = *(const f32x4*)(src + (row * (unsigned)DM + col0 + BJ * HALF + n * 16)); }
; #pragma unroll
;         for (int i = LO; i < HI; ++i) { const int ai = i >> 3, m = (i >> 1) & 3, n = i & 1; const unsigned row = row0 + ai * HALF + m * 16;
;             *(f32x4*)(Y + (row * (unsigned)DM + col0 + BJ * HALF + n * 16)) = acc[ai][BJ][m][n] + ((r[i - LO] - mean[(i - LO) >> 1]) * rstd[(i - LO) >> 1]) * gv[n] + bv[n]; }
;         __builtin_amdgcn_sched_barrier(0);
;     }
;     template <bool LN, int BJ> DI void load_gb(unsigned col0, f32x4 (&gv)[2], f32x4 (&bv)[2]) const {
; #pragma unroll
;         for (int n = 0; n < 2; ++n) {
;             if (LN) { gv[n] = *(const f32x4*)(gam + col0 + BJ * HALF + n * 16) * ALPHA; bv[n] = *(const f32x4*)(bet + col0 + BJ * HALF + n * 16) * ALPHA; }
;             else { gv[n] = (f32x4){ALPHA, ALPHA, ALPHA, ALPHA}; bv[n] = (f32x4){0.f, 0.f, 0.f, 0.f}; }
;         }
;     }
;     template <bool LN> DI void run(const f32x4 (&acc)[2][2][4][2], const Unit& u, int wr, int wc, int fr, int fq) const {
;         const unsigned row0 = u.pm * BM + wr * 64 + fr, col0 = u.pn * BM + wc * 32 + 4 * fq;
;         f32x4 gv[2], bv[2];
;         load_gb<LN, 0>(col0, gv, bv);
;         batch<LN, 0, 0, 4>(acc, row0, col0, gv, bv);
;         batch<LN, 0, 4, 8>(acc, row0, col0, gv, bv);
;         batch<LN, 0, 8, 12>(acc, row0, col0, gv, bv);
	s_waitcnt lgkmcnt(0)
	s_setprio 1
	v_mfma_f32_16x16x32_bf16 v[92:95], v[128:131], v[144:147], v[92:95]
	v_mfma_f32_16x16x32_bf16 v[88:91], v[136:139], v[144:147], v[88:91]
	v_mfma_f32_16x16x32_bf16 v[84:87], v[128:131], v[152:155], v[84:87]
	v_mfma_f32_16x16x32_bf16 v[80:83], v[136:139], v[152:155], v[80:83]
	v_mfma_f32_16x16x32_bf16 v[76:79], v[128:131], v[198:201], v[76:79]
	v_mfma_f32_16x16x32_bf16 v[72:75], v[136:139], v[198:201], v[72:75]
	v_mfma_f32_16x16x32_bf16 v[68:71], v[128:131], v[206:209], v[68:71]
	v_mfma_f32_16x16x32_bf16 v[64:67], v[136:139], v[206:209], v[64:67]
	v_mfma_f32_16x16x32_bf16 v[92:95], v[132:135], v[148:151], v[92:95]
	v_mfma_f32_16x16x32_bf16 v[88:91], v[140:143], v[148:151], v[88:91]
	v_mfma_f32_16x16x32_bf16 v[84:87], v[132:135], v[194:197], v[84:87]
	v_mfma_f32_16x16x32_bf16 v[80:83], v[140:143], v[194:197], v[80:83]
	v_mfma_f32_16x16x32_bf16 v[76:79], v[132:135], v[202:205], v[76:79]
	v_mfma_f32_16x16x32_bf16 v[72:75], v[140:143], v[202:205], v[72:75]
	v_mfma_f32_16x16x32_bf16 v[68:71], v[132:135], v[210:213], v[68:71]
	v_mfma_f32_16x16x32_bf16 v[64:67], v[140:143], v[210:213], v[64:67]
	s_setprio 0
	s_barrier
	s_add_u32 s24, s28, 0x80080
	s_addc_u32 s25, s29, 0
	s_add_i32 s28, s30, s37
	v_lshl_add_u64 v[128:129], s[24:25], 0, v[188:189]
	s_mov_b32 m0, s28
	s_nop 0
	global_load_lds_dwordx4 v[128:129], off
	v_lshl_add_u64 v[128:129], s[24:25], 0, v[186:187]
	s_add_i32 m0, s28, 0x2000
	s_nop 0
	global_load_lds_dwordx4 v[128:129], off
	s_waitcnt vmcnt(6)
	s_barrier
	s_setprio 1
	v_mfma_f32_16x16x32_bf16 v[28:31], v[214:217], v[144:147], v[28:31]
	v_mfma_f32_16x16x32_bf16 v[24:27], v[234:237], v[144:147], v[24:27]
	v_mfma_f32_16x16x32_bf16 v[20:23], v[214:217], v[152:155], v[20:23]
	v_mfma_f32_16x16x32_bf16 v[16:19], v[234:237], v[152:155], v[16:19]
	v_mfma_f32_16x16x32_bf16 v[12:15], v[214:217], v[198:201], v[12:15]
	v_mfma_f32_16x16x32_bf16 v[8:11], v[234:237], v[198:201], v[8:11]
	v_mfma_f32_16x16x32_bf16 v[4:7], v[214:217], v[206:209], v[4:7]
	v_mfma_f32_16x16x32_bf16 v[0:3], v[234:237], v[206:209], v[0:3]
	v_mfma_f32_16x16x32_bf16 v[28:31], v[230:233], v[148:151], v[28:31]
	v_mfma_f32_16x16x32_bf16 v[24:27], v[238:241], v[148:151], v[24:27]
	v_mfma_f32_16x16x32_bf16 v[20:23], v[230:233], v[194:197], v[20:23]
	v_mfma_f32_16x16x32_bf16 v[16:19], v[238:241], v[194:197], v[16:19]
	v_mfma_f32_16x16x32_bf16 v[12:15], v[230:233], v[202:205], v[12:15]
	v_mfma_f32_16x16x32_bf16 v[8:11], v[238:241], v[202:205], v[8:11]
	v_mfma_f32_16x16x32_bf16 v[4:7], v[230:233], v[210:213], v[4:7]
	v_mfma_f32_16x16x32_bf16 v[0:3], v[238:241], v[210:213], v[0:3]
	s_setprio 0
	s_add_i32 s46, s46, 2
	s_add_u32 s33, s33, 0x100
	s_addc_u32 s45, s45, 0
	s_cmp_gt_u32 s46, 29
	s_mov_b64 s[24:25], s[26:27]
	s_barrier
	s_cbranch_scc0 .LBB0_320
	v_lshl_add_u32 v206, s3, 8, v225
	v_lshl_or_b32 v158, s2, 8, v227
	v_lshlrev_b32_e32 v232, 11, v206
	s_andn2_b64 vcc, exec, s[14:15]
	v_or_b32_e32 v231, 16, v158
	v_add_u32_e32 v194, v232, v158
	v_or_b32_e32 v230, 0x80, v158
	v_or_b32_e32 v229, 0x90, v158
	s_cbranch_vccnz .LBB0_323
	v_lshlrev_b64 v[132:133], 2, v[158:159]
	v_lshl_add_u64 v[140:141], s[16:17], 0, v[132:133]
	global_load_dwordx4 v[128:131], v[140:141], off
	v_lshl_add_u64 v[142:143], s[18:19], 0, v[132:133]
	v_readlane_b32 s2, v253, 8
	v_mov_b32_e32 v195, v159
	v_lshlrev_b32_e32 v136, 1, v206
	v_mov_b32_e32 v137, v159
	v_readlane_b32 s3, v253, 9
	v_lshlrev_b64 v[212:213], 2, v[194:195]
	v_add_u32_e32 v146, v232, v231
	v_lshl_add_u64 v[144:145], v[136:137], 2, s[2:3]
	v_lshl_add_u64 v[136:137], s[88:89], 0, v[212:213]
	v_mov_b32_e32 v147, v159
	v_lshl_add_u64 v[146:147], v[146:147], 2, s[88:89]
	v_or_b32_e32 v195, 16, v206
	v_mov_b32_e32 v201, v159
	v_mov_b32_e32 v209, v159
	v_lshl_add_u64 v[212:213], s[90:91], 0, v[212:213]
	s_waitcnt vmcnt(0)
	v_pk_mul_f32 v[152:153], v[130:131], s[78:79] op_sel_hi:[1,0]
	v_pk_mul_f32 v[154:155], v[128:129], s[78:79] op_sel_hi:[1,0]
	global_load_dwordx4 v[132:135], v[142:143], off
	global_load_dwordx4 v[128:131], v[140:141], off offset:64
	global_load_dwordx2 v[204:205], v[144:145], off
	global_load_dwordx4 v[196:199], v[146:147], off
	v_lshlrev_b32_e32 v146, 1, v195
	global_load_dwordx4 v[136:139], v[136:137], off
	v_lshlrev_b32_e32 v195, 11, v195
	v_mov_b32_e32 v147, v159
	v_add_u32_e32 v200, v195, v158
	v_lshl_add_u64 v[146:147], v[146:147], 2, s[2:3]
	v_lshl_add_u64 v[200:201], v[200:201], 2, s[88:89]
	global_load_dwordx2 v[214:215], v[146:147], off
	v_add_u32_e32 v208, v195, v231
	global_load_dwordx4 v[200:203], v[200:201], off
	v_lshl_add_u64 v[208:209], v[208:209], 2, s[88:89]
	global_load_dwordx4 v[208:211], v[208:209], off
	s_waitcnt vmcnt(0)
	v_pk_mul_f32 v[148:149], v[130:131], s[78:79] op_sel_hi:[1,0]
	v_pk_mul_f32 v[150:151], v[128:129], s[78:79] op_sel_hi:[1,0]
	global_load_dwordx4 v[128:131], v[142:143], off offset:64
	v_sub_f32_e32 v137, v137, v204
	v_sub_f32_e32 v136, v136, v204
	v_sub_f32_e32 v139, v139, v204
	v_sub_f32_e32 v138, v138, v204
	v_pk_mul_f32 v[138:139], v[204:205], v[138:139] op_sel:[1,0]
	v_pk_mul_f32 v[136:137], v[204:205], v[136:137] op_sel:[1,0]
	v_pk_fma_f32 v[138:139], v[152:153], v[138:139], v[126:127]
	v_pk_fma_f32 v[136:137], v[154:155], v[136:137], v[124:125]
	v_pk_fma_f32 v[138:139], v[134:135], s[78:79], v[138:139] op_sel_hi:[1,0,1]
	v_pk_fma_f32 v[136:137], v[132:133], s[78:79], v[136:137] op_sel_hi:[1,0,1]
	global_store_dwordx4 v[212:213], v[136:139], off
	s_nop 1
	v_sub_f32_e32 v137, v197, v204
	v_sub_f32_e32 v136, v196, v204
	v_sub_f32_e32 v139, v199, v204
	v_sub_f32_e32 v138, v198, v204
	v_pk_mul_f32 v[138:139], v[204:205], v[138:139] op_sel:[1,0]
	v_pk_mul_f32 v[136:137], v[204:205], v[136:137] op_sel:[1,0]
	v_pk_fma_f32 v[138:139], v[148:149], v[138:139], v[122:123]
	v_pk_fma_f32 v[136:137], v[150:151], v[136:137], v[120:121]
	v_or_b32_e32 v196, 16, v194
	v_mov_b32_e32 v197, v159
	v_lshl_add_u64 v[196:197], v[196:197], 2, s[90:91]
	s_waitcnt vmcnt(0)
;     template <bool LN, int BJ, int LO, int HI> DI void batch(const f32x4 (&acc)[2][2][4][2], unsigned row0, unsigned col0, const f32x4 (&gv)[2], const f32x4 (&bv)[2]) const {
;         f32x4 r[HI - LO]; float mean[(HI - LO) / 2], rstd[(HI - LO) / 2];
; #pragma unroll
;         for (int i = LO; i < HI; ++i) { const int ai = i >> 3, m = (i >> 1) & 3, n = i & 1; const unsigned row = row0 + ai * HALF + m * 16;
;             if (n == 0) { mean[(i - LO) >> 1] = 0.f; rstd[(i - LO) >> 1] = 1.f;
;                 if (LN) { const float2 st = *(const float2*)(stats + row * 2u); mean[(i - LO) >> 1] = st.x; rstd[(i - LO) >> 1] = st.y; } }
;             r[i - LO] = *(const f32x4*)(src + (row * (unsigned)DM + col0 + BJ * HALF + n * 16)); }
; #pragma unroll
;         for (int i = LO; i < HI; ++i) { const int ai = i >> 3, m = (i >> 1) & 3, n = i & 1; const unsigned row = row0 + ai * HALF + m * 16;
;             *(f32x4*)(Y + (row * (unsigned)DM + col0 + BJ * HALF + n * 16)) = acc[ai][BJ][m][n] + ((r[i - LO] - mean[(i - LO) >> 1]) * rstd[(i - LO) >> 1]) * gv[n] + bv[n]; }
	v_pk_fma_f32 v[138:139], v[130:131], s[78:79], v[138:139] op_sel_hi:[1,0,1]
	v_pk_fma_f32 v[136:137], v[128:129], s[78:79], v[136:137] op_sel_hi:[1,0,1]
	global_store_dwordx4 v[196:197], v[136:139], off
	v_add_u32_e32 v196, 0x8000, v194
	v_mov_b32_e32 v197, v159
	v_sub_f32_e32 v137, v201, v214
	v_sub_f32_e32 v136, v200, v214
	v_sub_f32_e32 v139, v203, v214
	v_sub_f32_e32 v138, v202, v214
	v_pk_mul_f32 v[138:139], v[214:215], v[138:139] op_sel:[1,0]
	v_pk_mul_f32 v[136:137], v[214:215], v[136:137] op_sel:[1,0]
	v_pk_fma_f32 v[138:139], v[152:153], v[138:139], v[118:119]
	v_pk_fma_f32 v[136:137], v[154:155], v[136:137], v[116:117]
	v_pk_fma_f32 v[138:139], v[134:135], s[78:79], v[138:139] op_sel_hi:[1,0,1]
	v_pk_fma_f32 v[136:137], v[132:133], s[78:79], v[136:137] op_sel_hi:[1,0,1]
	v_lshl_add_u64 v[196:197], v[196:197], 2, s[90:91]
	global_store_dwordx4 v[196:197], v[136:139], off
	v_add_u32_e32 v196, 0x8010, v194
	v_mov_b32_e32 v197, v159
	v_sub_f32_e32 v137, v209, v214
	v_sub_f32_e32 v136, v208, v214
	v_sub_f32_e32 v139, v211, v214
	v_sub_f32_e32 v138, v210, v214
	v_pk_mul_f32 v[138:139], v[214:215], v[138:139] op_sel:[1,0]
	v_pk_mul_f32 v[136:137], v[214:215], v[136:137] op_sel:[1,0]
	v_pk_fma_f32 v[138:139], v[148:149], v[138:139], v[114:115]
	v_pk_fma_f32 v[136:137], v[150:151], v[136:137], v[112:113]
	v_pk_fma_f32 v[138:139], v[130:131], s[78:79], v[138:139] op_sel_hi:[1,0,1]
	v_pk_fma_f32 v[136:137], v[128:129], s[78:79], v[136:137] op_sel_hi:[1,0,1]
	v_lshl_add_u64 v[196:197], v[196:197], 2, s[90:91]
	global_store_dwordx4 v[196:197], v[136:139], off
	s_nop 1
	v_or_b32_e32 v138, 32, v206
	v_lshlrev_b32_e32 v136, 1, v138
	v_mov_b32_e32 v137, v159
	v_lshlrev_b32_e32 v236, 11, v138
	v_lshl_add_u64 v[200:201], v[136:137], 2, s[2:3]
	v_add_u32_e32 v136, v236, v158
	v_lshl_add_u64 v[136:137], v[136:137], 2, s[88:89]
	global_load_dwordx2 v[204:205], v[200:201], off
	v_add_u32_e32 v196, v236, v231
	global_load_dwordx4 v[136:139], v[136:137], off
	v_mov_b32_e32 v197, v159
	v_lshl_add_u64 v[196:197], v[196:197], 2, s[88:89]
	global_load_dwordx4 v[196:199], v[196:197], off
	v_or_b32_e32 v207, 48, v206
	v_lshlrev_b32_e32 v235, 11, v207
	v_lshlrev_b32_e32 v202, 1, v207
	v_mov_b32_e32 v203, v159
	v_add_u32_e32 v208, v235, v158
	v_mov_b32_e32 v209, v159
	v_lshl_add_u64 v[202:203], v[202:203], 2, s[2:3]
	v_lshl_add_u64 v[208:209], v[208:209], 2, s[88:89]
	global_load_dwordx2 v[216:217], v[202:203], off
	v_add_u32_e32 v212, v235, v231
	global_load_dwordx4 v[208:211], v[208:209], off
	v_mov_b32_e32 v213, v159
	v_lshl_add_u64 v[212:213], v[212:213], 2, s[88:89]
	global_load_dwordx4 v[212:215], v[212:213], off
	v_add_u32_e32 v218, 0x10000, v194
	v_mov_b32_e32 v219, v159
	v_lshl_add_u64 v[218:219], v[218:219], 2, s[90:91]
	s_waitcnt vmcnt(0)
	v_sub_f32_e32 v137, v137, v204
	v_sub_f32_e32 v136, v136, v204
	v_sub_f32_e32 v139, v139, v204
	v_sub_f32_e32 v138, v138, v204
	v_pk_mul_f32 v[138:139], v[204:205], v[138:139] op_sel:[1,0]
	v_pk_mul_f32 v[136:137], v[204:205], v[136:137] op_sel:[1,0]
	v_pk_fma_f32 v[138:139], v[152:153], v[138:139], v[110:111]
	v_pk_fma_f32 v[136:137], v[154:155], v[136:137], v[108:109]
	v_pk_fma_f32 v[138:139], v[134:135], s[78:79], v[138:139] op_sel_hi:[1,0,1]
	v_pk_fma_f32 v[136:137], v[132:133], s[78:79], v[136:137] op_sel_hi:[1,0,1]
	global_store_dwordx4 v[218:219], v[136:139], off
	s_nop 1
	v_sub_f32_e32 v137, v197, v204
	v_sub_f32_e32 v136, v196, v204
	v_sub_f32_e32 v139, v199, v204
	v_sub_f32_e32 v138, v198, v204
	v_pk_mul_f32 v[138:139], v[204:205], v[138:139] op_sel:[1,0]
	v_pk_mul_f32 v[136:137], v[204:205], v[136:137] op_sel:[1,0]
	v_pk_fma_f32 v[138:139], v[148:149], v[138:139], v[106:107]
	v_pk_fma_f32 v[136:137], v[150:151], v[136:137], v[104:105]
	v_add_u32_e32 v196, 0x10010, v194
	v_mov_b32_e32 v197, v159
	v_pk_fma_f32 v[138:139], v[130:131], s[78:79], v[138:139] op_sel_hi:[1,0,1]
	v_pk_fma_f32 v[136:137], v[128:129], s[78:79], v[136:137] op_sel_hi:[1,0,1]
	v_lshl_add_u64 v[196:197], v[196:197], 2, s[90:91]
	global_store_dwordx4 v[196:197], v[136:139], off
	v_add_u32_e32 v196, 0x18000, v194
	v_mov_b32_e32 v197, v159
	v_sub_f32_e32 v137, v209, v216
	v_sub_f32_e32 v136, v208, v216
	v_sub_f32_e32 v139, v211, v216
	v_sub_f32_e32 v138, v210, v216
	v_pk_mul_f32 v[138:139], v[216:217], v[138:139] op_sel:[1,0]
	v_pk_mul_f32 v[136:137], v[216:217], v[136:137] op_sel:[1,0]
	v_pk_fma_f32 v[138:139], v[152:153], v[138:139], v[102:103]
	v_pk_fma_f32 v[136:137], v[154:155], v[136:137], v[100:101]
	v_pk_fma_f32 v[138:139], v[134:135], s[78:79], v[138:139] op_sel_hi:[1,0,1]
	v_pk_fma_f32 v[136:137], v[132:133], s[78:79], v[136:137] op_sel_hi:[1,0,1]
	v_lshl_add_u64 v[196:197], v[196:197], 2, s[90:91]
	global_store_dwordx4 v[196:197], v[136:139], off
	v_add_u32_e32 v196, 0x18010, v194
	v_mov_b32_e32 v197, v159
	v_sub_f32_e32 v137, v213, v216
	v_sub_f32_e32 v136, v212, v216
	v_sub_f32_e32 v139, v215, v216
	v_sub_f32_e32 v138, v214, v216
	v_pk_mul_f32 v[138:139], v[216:217], v[138:139] op_sel:[1,0]
	v_pk_mul_f32 v[136:137], v[216:217], v[136:137] op_sel:[1,0]
	v_pk_fma_f32 v[138:139], v[148:149], v[138:139], v[98:99]
	v_pk_fma_f32 v[136:137], v[150:151], v[136:137], v[96:97]
	v_pk_fma_f32 v[138:139], v[130:131], s[78:79], v[138:139] op_sel_hi:[1,0,1]
	v_pk_fma_f32 v[136:137], v[128:129], s[78:79], v[136:137] op_sel_hi:[1,0,1]
	v_lshl_add_u64 v[196:197], v[196:197], 2, s[90:91]
	global_store_dwordx4 v[196:197], v[136:139], off
	s_nop 1
	v_add_u32_e32 v138, 0x80, v206
	v_lshlrev_b32_e32 v136, 1, v138
	v_mov_b32_e32 v137, v159
	v_lshlrev_b32_e32 v233, 11, v138
	v_lshl_add_u64 v[196:197], v[136:137], 2, s[2:3]
	v_add_u32_e32 v136, v233, v158
	v_lshl_add_u64 v[136:137], v[136:137], 2, s[88:89]
	global_load_dwordx2 v[204:205], v[196:197], off
	v_add_u32_e32 v198, v233, v231
	global_load_dwordx4 v[136:139], v[136:137], off
	v_mov_b32_e32 v199, v159
	v_add_u32_e32 v207, 0x90, v206
	v_lshl_add_u64 v[198:199], v[198:199], 2, s[88:89]
	v_lshlrev_b32_e32 v234, 11, v207
	global_load_dwordx4 v[208:211], v[198:199], off
	v_add_u32_e32 v212, v234, v158
	v_mov_b32_e32 v213, v159
	v_lshl_add_u64 v[212:213], v[212:213], 2, s[88:89]
	global_load_dwordx4 v[212:215], v[212:213], off
	v_lshlrev_b32_e32 v198, 1, v207
	v_mov_b32_e32 v199, v159
	v_lshl_add_u64 v[198:199], v[198:199], 2, s[2:3]
	global_load_dwordx2 v[238:239], v[198:199], off
	v_add_u32_e32 v216, v234, v231
	v_mov_b32_e32 v217, v159
	v_lshl_add_u64 v[216:217], v[216:217], 2, s[88:89]
	global_load_dwordx4 v[216:219], v[216:217], off
	v_add_u32_e32 v240, 0x40000, v194
	v_mov_b32_e32 v241, v159
	v_lshl_add_u64 v[240:241], v[240:241], 2, s[90:91]
	s_waitcnt vmcnt(0)
;     template <bool LN, int BJ, int LO, int HI> DI void batch(const f32x4 (&acc)[2][2][4][2], unsigned row0, unsigned col0, const f32x4 (&gv)[2], const f32x4 (&bv)[2]) const {
;         f32x4 r[HI - LO]; float mean[(HI - LO) / 2], rstd[(HI - LO) / 2];
; #pragma unroll
;         for (int i = LO; i < HI; ++i) { const int ai = i >> 3, m = (i >> 1) & 3, n = i & 1; const unsigned row = row0 + ai * HALF + m * 16;
;             if (n == 0) { mean[(i - LO) >> 1] = 0.f; rstd[(i - LO) >> 1] = 1.f;
;                 if (LN) { const float2 st = *(const float2*)(stats + row * 2u); mean[(i - LO) >> 1] = st.x; rstd[(i - LO) >> 1] = st.y; } }
;             r[i - LO] = *(const f32x4*)(src + (row * (unsigned)DM + col0 + BJ * HALF + n * 16)); }
; #pragma unroll
;         for (int i = LO; i < HI; ++i) { const int ai = i >> 3, m = (i >> 1) & 3, n = i & 1; const unsigned row = row0 + ai * HALF + m * 16;
;             *(f32x4*)(Y + (row * (unsigned)DM + col0 + BJ * HALF + n * 16)) = acc[ai][BJ][m][n] + ((r[i - LO] - mean[(i - LO) >> 1]) * rstd[(i - LO) >> 1]) * gv[n] + bv[n]; }
	v_sub_f32_e32 v137, v137, v204
	v_sub_f32_e32 v136, v136, v204
	v_sub_f32_e32 v139, v139, v204
	v_sub_f32_e32 v138, v138, v204
	v_pk_mul_f32 v[138:139], v[204:205], v[138:139] op_sel:[1,0]
	v_pk_mul_f32 v[136:137], v[204:205], v[136:137] op_sel:[1,0]
	v_pk_fma_f32 v[138:139], v[152:153], v[138:139], v[94:95]
	v_pk_fma_f32 v[136:137], v[154:155], v[136:137], v[92:93]
	v_pk_fma_f32 v[138:139], v[134:135], s[78:79], v[138:139] op_sel_hi:[1,0,1]
	v_pk_fma_f32 v[136:137], v[132:133], s[78:79], v[136:137] op_sel_hi:[1,0,1]
	global_store_dwordx4 v[240:241], v[136:139], off
	s_nop 1
	v_sub_f32_e32 v137, v209, v204
	v_sub_f32_e32 v136, v208, v204
	v_sub_f32_e32 v139, v211, v204
	v_sub_f32_e32 v138, v210, v204
	v_pk_mul_f32 v[138:139], v[204:205], v[138:139] op_sel:[1,0]
	v_pk_mul_f32 v[136:137], v[204:205], v[136:137] op_sel:[1,0]
	v_pk_fma_f32 v[138:139], v[148:149], v[138:139], v[90:91]
	v_pk_fma_f32 v[136:137], v[150:151], v[136:137], v[88:89]
	v_add_u32_e32 v204, 0x40010, v194
	v_mov_b32_e32 v205, v159
	v_pk_fma_f32 v[138:139], v[130:131], s[78:79], v[138:139] op_sel_hi:[1,0,1]
	v_pk_fma_f32 v[136:137], v[128:129], s[78:79], v[136:137] op_sel_hi:[1,0,1]
	v_lshl_add_u64 v[204:205], v[204:205], 2, s[90:91]
	global_store_dwordx4 v[204:205], v[136:139], off
	v_add_u32_e32 v204, 0x48000, v194
	v_mov_b32_e32 v205, v159
	v_sub_f32_e32 v137, v213, v238
	v_sub_f32_e32 v136, v212, v238
	v_sub_f32_e32 v139, v215, v238
	v_sub_f32_e32 v138, v214, v238
	v_pk_mul_f32 v[138:139], v[238:239], v[138:139] op_sel:[1,0]
	v_pk_mul_f32 v[136:137], v[238:239], v[136:137] op_sel:[1,0]
	v_pk_fma_f32 v[138:139], v[152:153], v[138:139], v[86:87]
	v_pk_fma_f32 v[136:137], v[154:155], v[136:137], v[84:85]
	v_pk_fma_f32 v[138:139], v[134:135], s[78:79], v[138:139] op_sel_hi:[1,0,1]
	v_pk_fma_f32 v[136:137], v[132:133], s[78:79], v[136:137] op_sel_hi:[1,0,1]
	v_lshl_add_u64 v[204:205], v[204:205], 2, s[90:91]
	global_store_dwordx4 v[204:205], v[136:139], off
	v_add_u32_e32 v204, 0x48010, v194
	v_mov_b32_e32 v205, v159
	v_sub_f32_e32 v137, v217, v238
	v_sub_f32_e32 v136, v216, v238
	v_sub_f32_e32 v139, v219, v238
	v_sub_f32_e32 v138, v218, v238
	v_pk_mul_f32 v[138:139], v[238:239], v[138:139] op_sel:[1,0]
	v_pk_mul_f32 v[136:137], v[238:239], v[136:137] op_sel:[1,0]
	v_pk_fma_f32 v[138:139], v[148:149], v[138:139], v[82:83]
	v_pk_fma_f32 v[136:137], v[150:151], v[136:137], v[80:81]
	v_pk_fma_f32 v[138:139], v[130:131], s[78:79], v[138:139] op_sel_hi:[1,0,1]
	v_pk_fma_f32 v[136:137], v[128:129], s[78:79], v[136:137] op_sel_hi:[1,0,1]
	v_lshl_add_u64 v[204:205], v[204:205], 2, s[90:91]
	global_store_dwordx4 v[204:205], v[136:139], off
	s_nop 1
	v_add_u32_e32 v138, 0xa0, v206
	v_lshlrev_b32_e32 v136, 1, v138
	v_mov_b32_e32 v137, v159
	v_lshlrev_b32_e32 v237, 11, v138
	v_lshl_add_u64 v[204:205], v[136:137], 2, s[2:3]
	v_add_u32_e32 v136, v237, v158
	v_lshl_add_u64 v[136:137], v[136:137], 2, s[88:89]
	global_load_dwordx2 v[240:241], v[204:205], off
	v_add_u32_e32 v208, v237, v231
	global_load_dwordx4 v[136:139], v[136:137], off
	v_mov_b32_e32 v209, v159
	v_lshl_add_u64 v[208:209], v[208:209], 2, s[88:89]
	global_load_dwordx4 v[212:215], v[208:209], off
	v_add_u32_e32 v208, 0xb0, v206
	v_lshlrev_b32_e32 v206, 1, v208
	v_mov_b32_e32 v207, v159
	v_lshlrev_b32_e32 v238, 11, v208
	v_lshl_add_u64 v[210:211], v[206:207], 2, s[2:3]
	v_add_u32_e32 v206, v238, v158
	v_lshl_add_u64 v[206:207], v[206:207], 2, s[88:89]
	global_load_dwordx2 v[242:243], v[210:211], off
	v_add_u32_e32 v216, v238, v231
	global_load_dwordx4 v[206:209], v[206:207], off
	v_mov_b32_e32 v217, v159
	v_lshl_add_u64 v[216:217], v[216:217], 2, s[88:89]
	global_load_dwordx4 v[216:219], v[216:217], off
	v_add_u32_e32 v244, 0x50000, v194
	v_mov_b32_e32 v245, v159
	v_lshl_add_u64 v[244:245], v[244:245], 2, s[90:91]
	s_waitcnt vmcnt(0)
	v_sub_f32_e32 v137, v137, v240
	v_sub_f32_e32 v136, v136, v240
	v_sub_f32_e32 v139, v139, v240
	v_sub_f32_e32 v138, v138, v240
	v_pk_mul_f32 v[138:139], v[240:241], v[138:139] op_sel:[1,0]
	v_pk_mul_f32 v[136:137], v[240:241], v[136:137] op_sel:[1,0]
	v_pk_fma_f32 v[138:139], v[152:153], v[138:139], v[78:79]
	v_pk_fma_f32 v[136:137], v[154:155], v[136:137], v[76:77]
	v_pk_fma_f32 v[138:139], v[134:135], s[78:79], v[138:139] op_sel_hi:[1,0,1]
	v_pk_fma_f32 v[136:137], v[132:133], s[78:79], v[136:137] op_sel_hi:[1,0,1]
	global_store_dwordx4 v[244:245], v[136:139], off
	s_nop 1
	v_sub_f32_e32 v137, v213, v240
	v_sub_f32_e32 v136, v212, v240
	v_sub_f32_e32 v139, v215, v240
	v_sub_f32_e32 v138, v214, v240
	v_pk_mul_f32 v[138:139], v[240:241], v[138:139] op_sel:[1,0]
	v_pk_mul_f32 v[136:137], v[240:241], v[136:137] op_sel:[1,0]
	v_pk_fma_f32 v[138:139], v[148:149], v[138:139], v[74:75]
	v_pk_fma_f32 v[136:137], v[150:151], v[136:137], v[72:73]
	v_add_u32_e32 v212, 0x50010, v194
	v_mov_b32_e32 v213, v159
	v_pk_fma_f32 v[138:139], v[130:131], s[78:79], v[138:139] op_sel_hi:[1,0,1]
	v_pk_fma_f32 v[136:137], v[128:129], s[78:79], v[136:137] op_sel_hi:[1,0,1]
	v_lshl_add_u64 v[212:213], v[212:213], 2, s[90:91]
	global_store_dwordx4 v[212:213], v[136:139], off
	s_nop 1
	v_sub_f32_e32 v137, v207, v242
	v_sub_f32_e32 v136, v206, v242
	v_sub_f32_e32 v139, v209, v242
	v_sub_f32_e32 v138, v208, v242
	v_pk_mul_f32 v[136:137], v[242:243], v[136:137] op_sel:[1,0]
	v_pk_mul_f32 v[138:139], v[242:243], v[138:139] op_sel:[1,0]
	v_pk_fma_f32 v[136:137], v[154:155], v[136:137], v[68:69]
	v_pk_fma_f32 v[138:139], v[152:153], v[138:139], v[70:71]
	v_pk_fma_f32 v[132:133], v[132:133], s[78:79], v[136:137] op_sel_hi:[1,0,1]
	v_add_u32_e32 v136, 0x58000, v194
	v_mov_b32_e32 v137, v159
	v_pk_fma_f32 v[134:135], v[134:135], s[78:79], v[138:139] op_sel_hi:[1,0,1]
	v_lshl_add_u64 v[136:137], v[136:137], 2, s[90:91]
	global_store_dwordx4 v[136:137], v[132:135], off
	s_nop 1
	v_sub_f32_e32 v133, v217, v242
	v_sub_f32_e32 v132, v216, v242
	v_sub_f32_e32 v135, v219, v242
	v_sub_f32_e32 v134, v218, v242
	v_pk_mul_f32 v[132:133], v[242:243], v[132:133] op_sel:[1,0]
	v_pk_mul_f32 v[134:135], v[242:243], v[134:135] op_sel:[1,0]
	v_pk_fma_f32 v[132:133], v[150:151], v[132:133], v[64:65]
	v_pk_fma_f32 v[134:135], v[148:149], v[134:135], v[66:67]
	v_pk_fma_f32 v[128:129], v[128:129], s[78:79], v[132:133] op_sel_hi:[1,0,1]
	v_add_u32_e32 v132, 0x58010, v194
	v_mov_b32_e32 v133, v159
	v_pk_fma_f32 v[130:131], v[130:131], s[78:79], v[134:135] op_sel_hi:[1,0,1]
	v_lshl_add_u64 v[132:133], v[132:133], 2, s[90:91]
	global_store_dwordx4 v[132:133], v[128:131], off
	global_load_dwordx4 v[128:131], v[140:141], off offset:512
	v_add_u32_e32 v136, v232, v230
	v_mov_b32_e32 v137, v159
	v_lshl_add_u64 v[136:137], v[136:137], 2, s[88:89]
	s_waitcnt vmcnt(0)
;     template <bool LN, int BJ, int LO, int HI> DI void batch(const f32x4 (&acc)[2][2][4][2], unsigned row0, unsigned col0, const f32x4 (&gv)[2], const f32x4 (&bv)[2]) const {
;         f32x4 r[HI - LO]; float mean[(HI - LO) / 2], rstd[(HI - LO) / 2];
; #pragma unroll
;         for (int i = LO; i < HI; ++i) { const int ai = i >> 3, m = (i >> 1) & 3, n = i & 1; const unsigned row = row0 + ai * HALF + m * 16;
;             if (n == 0) { mean[(i - LO) >> 1] = 0.f; rstd[(i - LO) >> 1] = 1.f;
;                 if (LN) { const float2 st = *(const float2*)(stats + row * 2u); mean[(i - LO) >> 1] = st.x; rstd[(i - LO) >> 1] = st.y; } }
;             r[i - LO] = *(const f32x4*)(src + (row * (unsigned)DM + col0 + BJ * HALF + n * 16)); }
; #pragma unroll
;         for (int i = LO; i < HI; ++i) { const int ai = i >> 3, m = (i >> 1) & 3, n = i & 1; const unsigned row = row0 + ai * HALF + m * 16;
;             *(f32x4*)(Y + (row * (unsigned)DM + col0 + BJ * HALF + n * 16)) = acc[ai][BJ][m][n] + ((r[i - LO] - mean[(i - LO) >> 1]) * rstd[(i - LO) >> 1]) * gv[n] + bv[n]; }
;     template <bool LN, int BJ> DI void load_gb(unsigned col0, f32x4 (&gv)[2], f32x4 (&bv)[2]) const {
; #pragma unroll
;         for (int n = 0; n < 2; ++n) {
;             if (LN) { gv[n] = *(const f32x4*)(gam + col0 + BJ * HALF + n * 16) * ALPHA; bv[n] = *(const f32x4*)(bet + col0 + BJ * HALF + n * 16) * ALPHA; }
	v_pk_mul_f32 v[212:213], v[130:131], s[78:79] op_sel_hi:[1,0]
	v_pk_mul_f32 v[214:215], v[128:129], s[78:79] op_sel_hi:[1,0]
	global_load_dwordx4 v[132:135], v[142:143], off offset:512
	global_load_dwordx4 v[128:131], v[140:141], off offset:576
	s_waitcnt vmcnt(0)
	v_pk_mul_f32 v[206:207], v[130:131], s[78:79] op_sel_hi:[1,0]
	v_pk_mul_f32 v[208:209], v[128:129], s[78:79] op_sel_hi:[1,0]
	global_load_dwordx4 v[128:131], v[142:143], off offset:576
	global_load_dwordx2 v[220:221], v[144:145], off
	global_load_dwordx4 v[240:243], v[136:137], off
	v_add_u32_e32 v136, v232, v229
	v_mov_b32_e32 v137, v159
	v_lshl_add_u64 v[136:137], v[136:137], 2, s[88:89]
	global_load_dwordx4 v[244:247], v[136:137], off
	global_load_dwordx2 v[218:219], v[146:147], off
	v_add_u32_e32 v136, v195, v230
	v_mov_b32_e32 v137, v159
	v_lshl_add_u64 v[136:137], v[136:137], 2, s[88:89]
	global_load_dwordx4 v[248:251], v[136:137], off
	v_add_u32_e32 v136, v195, v229
	v_mov_b32_e32 v137, v159
	v_lshl_add_u64 v[136:137], v[136:137], 2, s[88:89]
	global_load_dwordx4 v[152:155], v[136:137], off
	global_load_dwordx2 v[216:217], v[200:201], off
	v_add_u32_e32 v136, v236, v230
	v_mov_b32_e32 v137, v159
	v_lshl_add_u64 v[136:137], v[136:137], 2, s[88:89]
	global_load_dwordx4 v[148:151], v[136:137], off
	v_add_u32_e32 v136, v236, v229
	v_mov_b32_e32 v137, v159
	v_lshl_add_u64 v[136:137], v[136:137], 2, s[88:89]
	global_load_dwordx4 v[144:147], v[136:137], off
	global_load_dwordx2 v[200:201], v[202:203], off
	v_add_u32_e32 v136, v235, v230
	v_mov_b32_e32 v137, v159
	v_lshl_add_u64 v[136:137], v[136:137], 2, s[88:89]
	global_load_dwordx4 v[140:143], v[136:137], off
	v_add_u32_e32 v136, v235, v229
	v_mov_b32_e32 v137, v159
	v_lshl_add_u64 v[136:137], v[136:137], 2, s[88:89]
	global_load_dwordx4 v[136:139], v[136:137], off
	v_add_u32_e32 v202, 0x80, v194
	v_mov_b32_e32 v203, v159
	v_lshl_add_u64 v[202:203], v[202:203], 2, s[90:91]
	s_waitcnt vmcnt(0)
	v_sub_f32_e32 v241, v241, v220
	v_sub_f32_e32 v240, v240, v220
	v_sub_f32_e32 v243, v243, v220
	v_sub_f32_e32 v242, v242, v220
	v_pk_mul_f32 v[242:243], v[220:221], v[242:243] op_sel:[1,0]
	v_pk_mul_f32 v[240:241], v[220:221], v[240:241] op_sel:[1,0]
	v_pk_fma_f32 v[242:243], v[212:213], v[242:243], v[62:63]
	v_pk_fma_f32 v[240:241], v[214:215], v[240:241], v[60:61]
	v_pk_fma_f32 v[242:243], v[134:135], s[78:79], v[242:243] op_sel_hi:[1,0,1]
	v_pk_fma_f32 v[240:241], v[132:133], s[78:79], v[240:241] op_sel_hi:[1,0,1]
	global_store_dwordx4 v[202:203], v[240:243], off
	v_sub_f32_e32 v203, v245, v220
	v_sub_f32_e32 v202, v244, v220
	v_sub_f32_e32 v241, v247, v220
	v_sub_f32_e32 v240, v246, v220
	v_pk_mul_f32 v[202:203], v[220:221], v[202:203] op_sel:[1,0]
	v_pk_mul_f32 v[240:241], v[220:221], v[240:241] op_sel:[1,0]
	v_pk_fma_f32 v[202:203], v[208:209], v[202:203], v[56:57]
	v_pk_fma_f32 v[220:221], v[206:207], v[240:241], v[58:59]
	v_pk_fma_f32 v[240:241], v[128:129], s[78:79], v[202:203] op_sel_hi:[1,0,1]
	v_add_u32_e32 v202, 0x90, v194
	v_mov_b32_e32 v203, v159
	v_pk_fma_f32 v[242:243], v[130:131], s[78:79], v[220:221] op_sel_hi:[1,0,1]
	v_lshl_add_u64 v[202:203], v[202:203], 2, s[90:91]
	global_store_dwordx4 v[202:203], v[240:243], off
	v_sub_f32_e32 v203, v249, v218
	v_sub_f32_e32 v202, v248, v218
	v_sub_f32_e32 v221, v251, v218
	v_sub_f32_e32 v220, v250, v218
	v_pk_mul_f32 v[202:203], v[218:219], v[202:203] op_sel:[1,0]
	v_pk_mul_f32 v[220:221], v[218:219], v[220:221] op_sel:[1,0]
	v_pk_fma_f32 v[202:203], v[214:215], v[202:203], v[52:53]
	v_pk_fma_f32 v[220:221], v[212:213], v[220:221], v[54:55]
	v_pk_fma_f32 v[240:241], v[132:133], s[78:79], v[202:203] op_sel_hi:[1,0,1]
	v_add_u32_e32 v202, 0x8080, v194
	v_mov_b32_e32 v203, v159
	v_sub_f32_e32 v153, v153, v218
	v_sub_f32_e32 v152, v152, v218
	v_sub_f32_e32 v155, v155, v218
	v_sub_f32_e32 v154, v154, v218
	v_pk_fma_f32 v[242:243], v[134:135], s[78:79], v[220:221] op_sel_hi:[1,0,1]
	v_lshl_add_u64 v[202:203], v[202:203], 2, s[90:91]
	v_pk_mul_f32 v[154:155], v[218:219], v[154:155] op_sel:[1,0]
	v_pk_mul_f32 v[152:153], v[218:219], v[152:153] op_sel:[1,0]
	global_store_dwordx4 v[202:203], v[240:243], off
	v_pk_fma_f32 v[152:153], v[208:209], v[152:153], v[48:49]
	v_pk_fma_f32 v[154:155], v[206:207], v[154:155], v[50:51]
	v_add_u32_e32 v202, 0x8090, v194
	v_mov_b32_e32 v203, v159
	v_sub_f32_e32 v149, v149, v216
	v_sub_f32_e32 v148, v148, v216
	v_sub_f32_e32 v151, v151, v216
	v_sub_f32_e32 v150, v150, v216
	v_pk_fma_f32 v[154:155], v[130:131], s[78:79], v[154:155] op_sel_hi:[1,0,1]
	v_pk_fma_f32 v[152:153], v[128:129], s[78:79], v[152:153] op_sel_hi:[1,0,1]
	v_lshl_add_u64 v[202:203], v[202:203], 2, s[90:91]
	v_pk_mul_f32 v[150:151], v[216:217], v[150:151] op_sel:[1,0]
	v_pk_mul_f32 v[148:149], v[216:217], v[148:149] op_sel:[1,0]
	global_store_dwordx4 v[202:203], v[152:155], off
	v_pk_fma_f32 v[148:149], v[214:215], v[148:149], v[44:45]
	v_pk_fma_f32 v[150:151], v[212:213], v[150:151], v[46:47]
	v_add_u32_e32 v152, 0x10080, v194
	v_mov_b32_e32 v153, v159
	v_sub_f32_e32 v145, v145, v216
	v_sub_f32_e32 v144, v144, v216
	v_sub_f32_e32 v147, v147, v216
	v_sub_f32_e32 v146, v146, v216
	v_pk_fma_f32 v[150:151], v[134:135], s[78:79], v[150:151] op_sel_hi:[1,0,1]
	v_pk_fma_f32 v[148:149], v[132:133], s[78:79], v[148:149] op_sel_hi:[1,0,1]
	v_lshl_add_u64 v[152:153], v[152:153], 2, s[90:91]
	v_pk_mul_f32 v[146:147], v[216:217], v[146:147] op_sel:[1,0]
	v_pk_mul_f32 v[144:145], v[216:217], v[144:145] op_sel:[1,0]
	global_store_dwordx4 v[152:153], v[148:151], off
	v_pk_fma_f32 v[144:145], v[208:209], v[144:145], v[40:41]
	v_pk_fma_f32 v[146:147], v[206:207], v[146:147], v[42:43]
;     template <bool LN, int BJ, int LO, int HI> DI void batch(const f32x4 (&acc)[2][2][4][2], unsigned row0, unsigned col0, const f32x4 (&gv)[2], const f32x4 (&bv)[2]) const {
;         f32x4 r[HI - LO]; float mean[(HI - LO) / 2], rstd[(HI - LO) / 2];
; #pragma unroll
;         for (int i = LO; i < HI; ++i) { const int ai = i >> 3, m = (i >> 1) & 3, n = i & 1; const unsigned row = row0 + ai * HALF + m * 16;
;             if (n == 0) { mean[(i - LO) >> 1] = 0.f; rstd[(i - LO) >> 1] = 1.f;
;                 if (LN) { const float2 st = *(const float2*)(stats + row * 2u); mean[(i - LO) >> 1] = st.x; rstd[(i - LO) >> 1] = st.y; } }
;             r[i - LO] = *(const f32x4*)(src + (row * (unsigned)DM + col0 + BJ * HALF + n * 16)); }
; #pragma unroll
;         for (int i = LO; i < HI; ++i) { const int ai = i >> 3, m = (i >> 1) & 3, n = i & 1; const unsigned row = row0 + ai * HALF + m * 16;
;             *(f32x4*)(Y + (row * (unsigned)DM + col0 + BJ * HALF + n * 16)) = acc[ai][BJ][m][n] + ((r[i - LO] - mean[(i - LO) >> 1]) * rstd[(i - LO) >> 1]) * gv[n] + bv[n]; }
	v_add_u32_e32 v148, 0x10090, v194
	v_mov_b32_e32 v149, v159
	v_sub_f32_e32 v141, v141, v200
	v_sub_f32_e32 v140, v140, v200
	v_sub_f32_e32 v143, v143, v200
	v_sub_f32_e32 v142, v142, v200
	v_pk_fma_f32 v[146:147], v[130:131], s[78:79], v[146:147] op_sel_hi:[1,0,1]
	v_pk_fma_f32 v[144:145], v[128:129], s[78:79], v[144:145] op_sel_hi:[1,0,1]
	v_lshl_add_u64 v[148:149], v[148:149], 2, s[90:91]
	v_pk_mul_f32 v[142:143], v[200:201], v[142:143] op_sel:[1,0]
	v_pk_mul_f32 v[140:141], v[200:201], v[140:141] op_sel:[1,0]
	global_store_dwordx4 v[148:149], v[144:147], off
	v_pk_fma_f32 v[140:141], v[214:215], v[140:141], v[36:37]
	v_pk_fma_f32 v[142:143], v[212:213], v[142:143], v[38:39]
	v_add_u32_e32 v144, 0x18080, v194
	v_mov_b32_e32 v145, v159
	v_sub_f32_e32 v137, v137, v200
	v_sub_f32_e32 v136, v136, v200
	v_sub_f32_e32 v139, v139, v200
	v_sub_f32_e32 v138, v138, v200
	v_pk_fma_f32 v[142:143], v[134:135], s[78:79], v[142:143] op_sel_hi:[1,0,1]
	v_pk_fma_f32 v[140:141], v[132:133], s[78:79], v[140:141] op_sel_hi:[1,0,1]
	v_lshl_add_u64 v[144:145], v[144:145], 2, s[90:91]
	v_pk_mul_f32 v[138:139], v[200:201], v[138:139] op_sel:[1,0]
	v_pk_mul_f32 v[136:137], v[200:201], v[136:137] op_sel:[1,0]
	global_store_dwordx4 v[144:145], v[140:143], off
	v_pk_fma_f32 v[136:137], v[208:209], v[136:137], v[32:33]
	v_pk_fma_f32 v[138:139], v[206:207], v[138:139], v[34:35]
	v_add_u32_e32 v140, 0x18090, v194
	v_mov_b32_e32 v141, v159
	v_pk_fma_f32 v[138:139], v[130:131], s[78:79], v[138:139] op_sel_hi:[1,0,1]
	v_pk_fma_f32 v[136:137], v[128:129], s[78:79], v[136:137] op_sel_hi:[1,0,1]
	v_lshl_add_u64 v[140:141], v[140:141], 2, s[90:91]
	global_store_dwordx4 v[140:141], v[136:139], off
	s_nop 1
	v_add_u32_e32 v136, v233, v230
	v_mov_b32_e32 v137, v159
	v_lshl_add_u64 v[136:137], v[136:137], 2, s[88:89]
	global_load_dwordx2 v[220:221], v[196:197], off
	global_load_dwordx4 v[216:219], v[136:137], off
	v_add_u32_e32 v136, v233, v229
	v_mov_b32_e32 v137, v159
	v_lshl_add_u64 v[136:137], v[136:137], 2, s[88:89]
	global_load_dwordx4 v[240:243], v[136:137], off
	global_load_dwordx2 v[200:201], v[198:199], off
	v_add_u32_e32 v136, v234, v230
	v_mov_b32_e32 v137, v159
	v_lshl_add_u64 v[136:137], v[136:137], 2, s[88:89]
	global_load_dwordx4 v[244:247], v[136:137], off
	v_add_u32_e32 v136, v234, v229
	v_mov_b32_e32 v137, v159
	v_lshl_add_u64 v[136:137], v[136:137], 2, s[88:89]
	global_load_dwordx4 v[152:155], v[136:137], off
	global_load_dwordx2 v[198:199], v[204:205], off
	v_add_u32_e32 v136, v237, v230
	v_mov_b32_e32 v137, v159
	v_lshl_add_u64 v[136:137], v[136:137], 2, s[88:89]
	global_load_dwordx4 v[148:151], v[136:137], off
	v_add_u32_e32 v136, v237, v229
	v_mov_b32_e32 v137, v159
	v_lshl_add_u64 v[136:137], v[136:137], 2, s[88:89]
	global_load_dwordx4 v[144:147], v[136:137], off
	global_load_dwordx2 v[196:197], v[210:211], off
	v_add_u32_e32 v136, v238, v230
	v_mov_b32_e32 v137, v159
	v_lshl_add_u64 v[136:137], v[136:137], 2, s[88:89]
	global_load_dwordx4 v[140:143], v[136:137], off
	v_add_u32_e32 v136, v238, v229
	v_mov_b32_e32 v137, v159
	v_lshl_add_u64 v[136:137], v[136:137], 2, s[88:89]
	global_load_dwordx4 v[136:139], v[136:137], off
	v_add_u32_e32 v210, 0x40080, v194
	v_mov_b32_e32 v211, v159
	v_lshl_add_u64 v[210:211], v[210:211], 2, s[90:91]
	s_waitcnt vmcnt(0)
;     template <bool LN, int BJ, int LO, int HI> DI void batch(const f32x4 (&acc)[2][2][4][2], unsigned row0, unsigned col0, const f32x4 (&gv)[2], const f32x4 (&bv)[2]) const {
;         f32x4 r[HI - LO]; float mean[(HI - LO) / 2], rstd[(HI - LO) / 2];
; #pragma unroll
;         for (int i = LO; i < HI; ++i) { const int ai = i >> 3, m = (i >> 1) & 3, n = i & 1; const unsigned row = row0 + ai * HALF + m * 16;
;             if (n == 0) { mean[(i - LO) >> 1] = 0.f; rstd[(i - LO) >> 1] = 1.f;
;                 if (LN) { const float2 st = *(const float2*)(stats + row * 2u); mean[(i - LO) >> 1] = st.x; rstd[(i - LO) >> 1] = st.y; } }
;             r[i - LO] = *(const f32x4*)(src + (row * (unsigned)DM + col0 + BJ * HALF + n * 16)); }
; #pragma unroll
;         for (int i = LO; i < HI; ++i) { const int ai = i >> 3, m = (i >> 1) & 3, n = i & 1; const unsigned row = row0 + ai * HALF + m * 16;
;             *(f32x4*)(Y + (row * (unsigned)DM + col0 + BJ * HALF + n * 16)) = acc[ai][BJ][m][n] + ((r[i - LO] - mean[(i - LO) >> 1]) * rstd[(i - LO) >> 1]) * gv[n] + bv[n]; }
	v_sub_f32_e32 v203, v217, v220
	v_sub_f32_e32 v202, v216, v220
	v_sub_f32_e32 v205, v219, v220
	v_sub_f32_e32 v204, v218, v220
	v_pk_mul_f32 v[204:205], v[220:221], v[204:205] op_sel:[1,0]
	v_pk_mul_f32 v[202:203], v[220:221], v[202:203] op_sel:[1,0]
	v_pk_fma_f32 v[204:205], v[212:213], v[204:205], v[30:31]
	v_pk_fma_f32 v[202:203], v[214:215], v[202:203], v[28:29]
	v_pk_fma_f32 v[204:205], v[134:135], s[78:79], v[204:205] op_sel_hi:[1,0,1]
	v_pk_fma_f32 v[202:203], v[132:133], s[78:79], v[202:203] op_sel_hi:[1,0,1]
	global_store_dwordx4 v[210:211], v[202:205], off
	v_add_u32_e32 v210, 0x40090, v194
	v_mov_b32_e32 v211, v159
	v_sub_f32_e32 v203, v241, v220
	v_sub_f32_e32 v202, v240, v220
	v_sub_f32_e32 v205, v243, v220
	v_sub_f32_e32 v204, v242, v220
	v_pk_mul_f32 v[204:205], v[220:221], v[204:205] op_sel:[1,0]
	v_pk_mul_f32 v[202:203], v[220:221], v[202:203] op_sel:[1,0]
	v_pk_fma_f32 v[204:205], v[206:207], v[204:205], v[26:27]
	v_pk_fma_f32 v[202:203], v[208:209], v[202:203], v[24:25]
	v_pk_fma_f32 v[204:205], v[130:131], s[78:79], v[204:205] op_sel_hi:[1,0,1]
	v_pk_fma_f32 v[202:203], v[128:129], s[78:79], v[202:203] op_sel_hi:[1,0,1]
	v_lshl_add_u64 v[210:211], v[210:211], 2, s[90:91]
	global_store_dwordx4 v[210:211], v[202:205], off
	v_sub_f32_e32 v149, v149, v198
	v_sub_f32_e32 v148, v148, v198
	v_sub_f32_e32 v203, v245, v200
	v_sub_f32_e32 v202, v244, v200
	v_sub_f32_e32 v141, v141, v196
	v_sub_f32_e32 v140, v140, v196
	v_sub_f32_e32 v205, v247, v200
	v_sub_f32_e32 v204, v246, v200
	v_pk_mul_f32 v[202:203], v[200:201], v[202:203] op_sel:[1,0]
	v_sub_f32_e32 v151, v151, v198
	v_sub_f32_e32 v150, v150, v198
	v_pk_mul_f32 v[148:149], v[198:199], v[148:149] op_sel:[1,0]
	v_sub_f32_e32 v143, v143, v196
	v_sub_f32_e32 v142, v142, v196
	v_pk_mul_f32 v[140:141], v[196:197], v[140:141] op_sel:[1,0]
	v_pk_mul_f32 v[204:205], v[200:201], v[204:205] op_sel:[1,0]
	v_pk_fma_f32 v[202:203], v[214:215], v[202:203], v[20:21]
	v_sub_f32_e32 v153, v153, v200
	v_sub_f32_e32 v152, v152, v200
	v_sub_f32_e32 v155, v155, v200
	v_sub_f32_e32 v154, v154, v200
	v_pk_mul_f32 v[150:151], v[198:199], v[150:151] op_sel:[1,0]
	v_pk_fma_f32 v[148:149], v[214:215], v[148:149], v[12:13]
	v_pk_mul_f32 v[142:143], v[196:197], v[142:143] op_sel:[1,0]
	v_pk_fma_f32 v[140:141], v[214:215], v[140:141], v[4:5]
	v_pk_fma_f32 v[204:205], v[212:213], v[204:205], v[22:23]
	v_pk_fma_f32 v[202:203], v[132:133], s[78:79], v[202:203] op_sel_hi:[1,0,1]
	v_pk_mul_f32 v[154:155], v[200:201], v[154:155] op_sel:[1,0]
	v_pk_mul_f32 v[152:153], v[200:201], v[152:153] op_sel:[1,0]
	v_pk_fma_f32 v[150:151], v[212:213], v[150:151], v[14:15]
	v_pk_fma_f32 v[148:149], v[132:133], s[78:79], v[148:149] op_sel_hi:[1,0,1]
	v_pk_fma_f32 v[142:143], v[212:213], v[142:143], v[6:7]
	v_pk_fma_f32 v[132:133], v[132:133], s[78:79], v[140:141] op_sel_hi:[1,0,1]
	v_add_u32_e32 v140, 0x58080, v194
	v_mov_b32_e32 v141, v159
	v_pk_fma_f32 v[204:205], v[134:135], s[78:79], v[204:205] op_sel_hi:[1,0,1]
	v_pk_fma_f32 v[152:153], v[208:209], v[152:153], v[16:17]
	v_pk_fma_f32 v[154:155], v[206:207], v[154:155], v[18:19]
	v_add_u32_e32 v200, 0x48090, v194
	v_mov_b32_e32 v201, v159
	v_pk_fma_f32 v[150:151], v[134:135], s[78:79], v[150:151] op_sel_hi:[1,0,1]
	v_pk_fma_f32 v[134:135], v[134:135], s[78:79], v[142:143] op_sel_hi:[1,0,1]
	v_lshl_add_u64 v[140:141], v[140:141], 2, s[90:91]
	v_pk_fma_f32 v[154:155], v[130:131], s[78:79], v[154:155] op_sel_hi:[1,0,1]
	v_pk_fma_f32 v[152:153], v[128:129], s[78:79], v[152:153] op_sel_hi:[1,0,1]
	v_lshl_add_u64 v[200:201], v[200:201], 2, s[90:91]
	v_sub_f32_e32 v145, v145, v198
	v_sub_f32_e32 v144, v144, v198
	global_store_dwordx4 v[140:141], v[132:135], off
	global_store_dwordx4 v[200:201], v[152:155], off
	v_sub_f32_e32 v147, v147, v198
	v_sub_f32_e32 v133, v137, v196
	v_sub_f32_e32 v132, v136, v196
	v_add_u32_e32 v152, 0x50080, v194
	v_mov_b32_e32 v153, v159
	v_sub_f32_e32 v146, v146, v198
	v_pk_mul_f32 v[144:145], v[198:199], v[144:145] op_sel:[1,0]
	v_sub_f32_e32 v135, v139, v196
	v_sub_f32_e32 v134, v138, v196
	v_pk_mul_f32 v[132:133], v[196:197], v[132:133] op_sel:[1,0]
	v_lshl_add_u64 v[152:153], v[152:153], 2, s[90:91]
	v_pk_mul_f32 v[146:147], v[198:199], v[146:147] op_sel:[1,0]
	v_pk_fma_f32 v[144:145], v[208:209], v[144:145], v[8:9]
	v_pk_mul_f32 v[134:135], v[196:197], v[134:135] op_sel:[1,0]
	v_pk_fma_f32 v[132:133], v[208:209], v[132:133], v[0:1]
	v_add_u32_e32 v210, 0x48080, v194
	v_mov_b32_e32 v211, v159
	global_store_dwordx4 v[152:153], v[148:151], off
	v_pk_fma_f32 v[146:147], v[206:207], v[146:147], v[10:11]
	v_pk_fma_f32 v[144:145], v[128:129], s[78:79], v[144:145] op_sel_hi:[1,0,1]
	v_add_u32_e32 v148, 0x50090, v194
	v_mov_b32_e32 v149, v159
	v_pk_fma_f32 v[134:135], v[206:207], v[134:135], v[2:3]
	v_pk_fma_f32 v[128:129], v[128:129], s[78:79], v[132:133] op_sel_hi:[1,0,1]
	v_add_u32_e32 v132, 0x58090, v194
	v_mov_b32_e32 v133, v159
	v_lshl_add_u64 v[210:211], v[210:211], 2, s[90:91]
	v_pk_fma_f32 v[146:147], v[130:131], s[78:79], v[146:147] op_sel_hi:[1,0,1]
	v_lshl_add_u64 v[148:149], v[148:149], 2, s[90:91]
	v_pk_fma_f32 v[130:131], v[130:131], s[78:79], v[134:135] op_sel_hi:[1,0,1]
	v_lshl_add_u64 v[132:133], v[132:133], 2, s[90:91]
	global_store_dwordx4 v[210:211], v[202:205], off
	global_store_dwordx4 v[148:149], v[144:147], off
	global_store_dwordx4 v[132:133], v[128:131], off
	s_mov_b64 s[24:25], 0
	s_branch .LBB0_324
